# each XCD starts its table sweeps at a different chunk (chunk order rotated by the XCC id) so the eight XCDs do not pull the same table slice from the Infinity Cache at the same time
# baseline (speedup 1.0000x reference)
; #define LAS __attribute__((address_space(3)))
; __device__ __forceinline__ unsigned xb_add(unsigned* p, unsigned v) { return __hip_atomic_fetch_add(p, v, __ATOMIC_RELAXED, __HIP_MEMORY_SCOPE_AGENT); }
; __device__ __forceinline__ unsigned xb_xcc_id() { return (unsigned)__builtin_amdgcn_s_getreg((3 << 11) | 20) & 0xFu; }
; __device__ __forceinline__ XcdBarrier xcd_barrier_post(unsigned* bar, volatile LAS unsigned* st) {
;     XcdBarrier b; b.bar = bar; b.x = xb_xcc_id(); b.st = st;
;     if (threadIdx.x == 0) (void)xb_add(&bar[XB_XCNT(b.x)], 1u);
;     return b;
; __global__ void __launch_bounds__(512, 2) mega_fwd(Args A) {
;     extern __shared__ __attribute__((aligned(16))) unsigned char lds_raw[];
;     LAS unsigned char* lds = (LAS unsigned char*)lds_raw;
;     cg::grid_group grid = cg::this_grid();
;     const int G = gridDim.x;
;     if (threadIdx.x < 4) ((LAS unsigned*)(lds + LDS_BYTES - 32))[threadIdx.x] = 0u;
;     __syncthreads();
;     if (A.ws == nullptr) grid.sync();
;     const XcdBarrier xb = xcd_barrier_post((unsigned*)(A.ws + WS_BAR), (volatile LAS unsigned*)(lds + LDS_BYTES - 32));
.LBB0_14:
	s_add_u32 s90, s50, 0xfc0000
	s_getreg_b32 s3, hwreg(HW_REG_XCC_ID, 0, 4)
	s_addc_u32 s91, s51, 0
	s_and_b32 s3, s3, 15
	s_mov_b32 s32, s3
	v_cmp_eq_u32_e64 s[18:19], 0, v214
	s_and_saveexec_b64 s[4:5], s[18:19]
	s_cbranch_execz .LBB0_17
	s_mov_b64 s[6:7], exec
	v_mbcnt_lo_u32_b32 v0, s6, 0
	v_mbcnt_hi_u32_b32 v0, s7, v0
	v_cmp_eq_u32_e32 vcc, 0, v0
	s_and_b64 s[8:9], exec, vcc
	s_mov_b64 exec, s[8:9]
	s_cbranch_execz .LBB0_17
	s_lshl_b32 s8, s3, 8
	s_bcnt1_i32_b64 s6, s[6:7]
	v_mov_b32_e32 v0, s8
	v_mov_b32_e32 v1, s6
	global_atomic_add v0, v1, s[90:91] offset:1024

; #define LAS __attribute__((address_space(3)))
; __device__ __forceinline__ unsigned f2key(float f) { const unsigned u = __float_as_uint(f); return (u & 0x80000000u) ? ~u : (u | 0x80000000u); }
; __device__ __forceinline__ void peer_tile(const Args& A, LAS unsigned char* lds, int tile) {
;     int tid_o = threadIdx.x; asm volatile("" : "+v"(tid_o)); const int tid = tid_o, lane = tid & 63, w = tid >> 6, g = lane >> 4, l15 = lane & 15;
;     const bf16_t* QRY = (const bf16_t*)(A.ws + WS_QRY);
;     const bf16_t* KEYS = (const bf16_t*)(A.ws + WS_KEYS);
;     const bf16_t* ACT = (const bf16_t*)(A.ws + WS_ACT);
;     const float* MOD = (const float*)(A.ws + WS_MOD);
;     LAS unsigned* idx = (LAS unsigned*)(lds + PE_IDX) + (w * 64 + lane) * 33;
;     LAS u32x2* SEL = (LAS u32x2*)(lds + PE_SEL);
;     {
;         const int tg = w & 3, hg = w >> 2, tl = 16 * tg + l15;
;         const size_t m = (size_t)tile * 64 + tl;
;         unsigned LA[4][2][16];
; #pragma unroll
;         for (int hh = 0; hh < 4; ++hh) {
;             const int h = 4 * hg + hh;
; #pragma unroll
;             for (int p = 0; p < 2; ++p) {
;                 const int hp = 2 * h + p;
;                 unsigned k0[16], k1[16];
;                 { const bf16_t* sp = QRY + m * 2048 + hp * 128 + 32 * g;
;                   const u32x4 s0 = *(const u32x4*)sp, s1 = *(const u32x4*)(sp + 8), s2 = *(const u32x4*)(sp + 16), s3 = *(const u32x4*)(sp + 24);
;                   const unsigned sw[16] = {s0.x, s0.y, s0.z, s0.w, s1.x, s1.y, s1.z, s1.w, s2.x, s2.y, s2.z, s2.w, s3.x, s3.y, s3.z, s3.w};
; #pragma unroll
;                   for (int i = 0; i < 16; ++i) {
;                       const float lo = (float)__builtin_bit_cast(_Float16, (unsigned short)(sw[i] & 0xffffu)), hi = (float)__builtin_bit_cast(_Float16, (unsigned short)(sw[i] >> 16));
;                       const unsigned klo = (f2key(lo) & ~127u) | (unsigned)(127 - (32 * g + 2 * i)), khi = (f2key(hi) & ~127u) | (unsigned)(127 - (32 * g + 2 * i + 1));
;                       if (i < 8) { k0[2 * i] = klo; k0[2 * i + 1] = khi; } else { k1[2 * (i - 8)] = klo; k1[2 * (i - 8) + 1] = khi; } } }
.LBB0_699:
	v_mov_b32_e32 v19, v214
	s_ashr_i32 s3, s2, 31
	v_ashrrev_i32_e32 v7, 6, v19
	v_and_b32_e32 v0, 15, v19
	v_lshlrev_b32_e32 v1, 4, v7
	v_and_or_b32 v13, v1, 48, v0
	s_lshl_b64 s[28:29], s[2:3], 6
	v_or_b32_e32 v0, s28, v13
	v_mov_b32_e32 v1, s29
	v_bfe_u32 v221, v19, 4, 2
	v_ashrrev_i32_e32 v11, 8, v19
	v_lshlrev_b64 v[0:1], 12, v[0:1]
	v_lshlrev_b32_e32 v2, 10, v11
	v_lshl_add_u64 v[0:1], s[54:55], 0, v[0:1]
	v_lshlrev_b32_e32 v112, 6, v221
	v_lshl_add_u64 v[0:1], v[0:1], 0, v[112:113]
	v_ashrrev_i32_e32 v3, 31, v2
	v_lshl_add_u64 v[4:5], v[2:3], 1, v[0:1]
	global_load_dwordx4 v[20:23], v[4:5], off
	global_load_dwordx4 v[24:27], v[4:5], off offset:16
	global_load_dwordx4 v[0:3], v[4:5], off offset:48
	global_load_dwordx4 v[28:31], v[4:5], off offset:32
	v_lshlrev_b32_e32 v15, 5, v221
	v_or_b32_e32 v8, 8, v15
	v_or_b32_e32 v14, 2, v15
	v_or_b32_e32 v12, 4, v15
	v_or_b32_e32 v10, 6, v15
	v_and_b32_e32 v9, 63, v19
	v_cmp_gt_u32_e64 s[0:1], 16, v9
	v_cmp_gt_u32_e64 s[4:5], 32, v9
	v_mul_lo_u32 v6, v19, s17
	s_mov_b32 s3, 8
	s_waitcnt vmcnt(3)
	v_cvt_f32_f16_sdwa v17, v20 dst_sel:DWORD dst_unused:UNUSED_PAD src0_sel:WORD_1
	v_cvt_f32_f16_e32 v16, v20
	v_cvt_f32_f16_sdwa v20, v21 dst_sel:DWORD dst_unused:UNUSED_PAD src0_sel:WORD_1
	v_cvt_f32_f16_e32 v18, v21
	v_cvt_f32_f16_e32 v21, v22
	v_cvt_f32_f16_sdwa v22, v22 dst_sel:DWORD dst_unused:UNUSED_PAD src0_sel:WORD_1
	v_not_b32_e32 v34, v17
	v_or_b32_e32 v35, 0x80000000, v17
	v_cmp_gt_i32_e32 vcc, 0, v17
	v_not_b32_e32 v36, v16
	v_or_b32_e32 v37, 0x80000000, v16
	v_cndmask_b32_e32 v17, v35, v34, vcc
	v_cmp_gt_i32_e32 vcc, 0, v16
	v_cvt_f32_f16_e32 v32, v23
	v_cvt_f32_f16_sdwa v23, v23 dst_sel:DWORD dst_unused:UNUSED_PAD src0_sel:WORD_1
	v_not_b32_e32 v38, v20
	v_or_b32_e32 v39, 0x80000000, v20
	v_cndmask_b32_e32 v16, v37, v36, vcc
	v_cmp_gt_i32_e32 vcc, 0, v20
	v_not_b32_e32 v40, v18
	v_or_b32_e32 v41, 0x80000000, v18
	v_cndmask_b32_e32 v20, v39, v38, vcc
	v_cmp_gt_i32_e32 vcc, 0, v18
	s_waitcnt vmcnt(2)
	v_cvt_f32_f16_e32 v33, v24
	v_cvt_f32_f16_sdwa v24, v24 dst_sel:DWORD dst_unused:UNUSED_PAD src0_sel:WORD_1
	v_not_b32_e32 v42, v22
	v_or_b32_e32 v43, 0x80000000, v22
	v_cndmask_b32_e32 v18, v41, v40, vcc
	v_cmp_gt_i32_e32 vcc, 0, v22
	v_not_b32_e32 v44, v21
	v_or_b32_e32 v45, 0x80000000, v21
	v_cndmask_b32_e32 v22, v43, v42, vcc
	v_cmp_gt_i32_e32 vcc, 0, v21
	v_not_b32_e32 v46, v23
	v_or_b32_e32 v47, 0x80000000, v23
	v_cndmask_b32_e32 v21, v45, v44, vcc
	v_cmp_gt_i32_e32 vcc, 0, v23
	v_not_b32_e32 v48, v32
	v_or_b32_e32 v49, 0x80000000, v32
	v_cndmask_b32_e32 v23, v47, v46, vcc
	v_cmp_gt_i32_e32 vcc, 0, v32
	v_and_b32_e32 v16, 0xffffff80, v16
	v_not_b32_e32 v50, v24
	v_or_b32_e32 v51, 0x80000000, v24
	v_cndmask_b32_e32 v32, v49, v48, vcc
	v_sub_u32_e32 v16, v16, v15
	v_cmp_gt_i32_e32 vcc, 0, v24
	v_add_u32_e32 v35, 0x7f, v16
	v_and_b32_e32 v17, 0xffffff80, v17
	v_cndmask_b32_e32 v16, v51, v50, vcc
	v_and_b32_e32 v16, 0xffffff80, v16
	v_sub_u32_e32 v17, v17, v15
	v_sub_u32_e32 v16, v16, v8
	v_add_u32_e32 v34, 0x7e, v17
	v_add_u32_e32 v41, 0x7e, v16
	v_not_b32_e32 v16, v33
	v_or_b32_e32 v17, 0x80000000, v33
	v_cmp_gt_i32_e32 vcc, 0, v33
	v_and_b32_e32 v20, 0xffffff80, v20
	v_and_b32_e32 v18, 0xffffff80, v18
	v_cndmask_b32_e32 v16, v17, v16, vcc
	v_cvt_f32_f16_sdwa v17, v25 dst_sel:DWORD dst_unused:UNUSED_PAD src0_sel:WORD_1
	v_and_b32_e32 v21, 0xffffff80, v21
	v_sub_u32_e32 v20, v20, v14
	v_sub_u32_e32 v18, v18, v14
	v_sub_u32_e32 v21, v21, v12
	v_add_u32_e32 v36, 0x7e, v20
	v_add_u32_e32 v37, 0x7f, v18
	v_add_u32_e32 v39, 0x7f, v21
	v_and_b32_e32 v16, 0xffffff80, v16
	v_cvt_f32_f16_e32 v18, v25
	v_not_b32_e32 v20, v17
	v_or_b32_e32 v21, 0x80000000, v17
	v_cmp_gt_i32_e32 vcc, 0, v17
	v_sub_u32_e32 v16, v16, v8
	v_add_u32_e32 v33, 0x7f, v16
	v_cndmask_b32_e32 v17, v21, v20, vcc
	v_or_b32_e32 v16, 10, v15
	v_and_b32_e32 v17, 0xffffff80, v17
	v_sub_u32_e32 v17, v17, v16
	v_add_u32_e32 v42, 0x7e, v17
	v_not_b32_e32 v17, v18
	v_or_b32_e32 v20, 0x80000000, v18
	v_cmp_gt_i32_e32 vcc, 0, v18
	v_cvt_f32_f16_sdwa v18, v26 dst_sel:DWORD dst_unused:UNUSED_PAD src0_sel:WORD_1
	v_and_b32_e32 v22, 0xffffff80, v22
	v_sub_u32_e32 v22, v22, v12
	v_cndmask_b32_e32 v17, v20, v17, vcc
	v_add_u32_e32 v38, 0x7e, v22
	v_and_b32_e32 v17, 0xffffff80, v17
	v_cvt_f32_f16_e32 v20, v26
	v_not_b32_e32 v21, v18
	v_or_b32_e32 v22, 0x80000000, v18
	v_cmp_gt_i32_e32 vcc, 0, v18
	v_sub_u32_e32 v17, v17, v16
	v_add_u32_e32 v43, 0x7f, v17
	v_cndmask_b32_e32 v18, v22, v21, vcc
	v_or_b32_e32 v17, 12, v15
	v_and_b32_e32 v18, 0xffffff80, v18
	v_sub_u32_e32 v18, v18, v17
	v_add_u32_e32 v44, 0x7e, v18
	v_not_b32_e32 v18, v20
	v_or_b32_e32 v21, 0x80000000, v20
	v_cmp_gt_i32_e32 vcc, 0, v20
	v_cvt_f32_f16_sdwa v20, v27 dst_sel:DWORD dst_unused:UNUSED_PAD src0_sel:WORD_1
	v_and_b32_e32 v23, 0xffffff80, v23
	v_sub_u32_e32 v23, v23, v10
	v_cndmask_b32_e32 v18, v21, v18, vcc
	v_add_u32_e32 v40, 0x7e, v23
	v_and_b32_e32 v18, 0xffffff80, v18
	v_cvt_f32_f16_e32 v21, v27
	v_not_b32_e32 v22, v20
	v_or_b32_e32 v23, 0x80000000, v20
	v_cmp_gt_i32_e32 vcc, 0, v20
	v_sub_u32_e32 v18, v18, v17
	v_add_u32_e32 v45, 0x7f, v18
	v_cndmask_b32_e32 v20, v23, v22, vcc
	v_or_b32_e32 v18, 14, v15
	v_and_b32_e32 v20, 0xffffff80, v20
	v_sub_u32_e32 v20, v20, v18
	v_add_u32_e32 v27, 0x7e, v20
	v_not_b32_e32 v20, v21
	v_or_b32_e32 v22, 0x80000000, v21
	v_cmp_gt_i32_e32 vcc, 0, v21
	s_waitcnt vmcnt(0)
; __device__ __forceinline__ unsigned f2key(float f) { const unsigned u = __float_as_uint(f); return (u & 0x80000000u) ? ~u : (u | 0x80000000u); }
; #define CE_DESC(a, b) do { const unsigned _mx = (a) > (b) ? (a) : (b), _mn = (a) > (b) ? (b) : (a); (a) = _mx; (b) = _mn; } while (0)
; __device__ __forceinline__ void sort16_desc(unsigned (&k)[16]) {
; #pragma unroll
;     for (int size = 2; size <= 16; size <<= 1)
; #pragma unroll
;         for (int stride = size >> 1; stride > 0; stride >>= 1)
; #pragma unroll
;             for (int i = 0; i < 16; ++i) { const int j = i ^ stride;
;                 if (j > i) { if ((i & size) == 0) CE_DESC(k[i], k[j]); else CE_DESC(k[j], k[i]); } }
; }
; __device__ __forceinline__ void peer_tile(const Args& A, LAS unsigned char* lds, int tile) {
;     ...
;                   for (int i = 0; i < 16; ++i) {
;                       const float lo = (float)__builtin_bit_cast(_Float16, (unsigned short)(sw[i] & 0xffffu)), hi = (float)__builtin_bit_cast(_Float16, (unsigned short)(sw[i] >> 16));
;                       const unsigned klo = (f2key(lo) & ~127u) | (unsigned)(127 - (32 * g + 2 * i)), khi = (f2key(hi) & ~127u) | (unsigned)(127 - (32 * g + 2 * i + 1));
;                       if (i < 8) { k0[2 * i] = klo; k0[2 * i + 1] = khi; } else { k1[2 * (i - 8)] = klo; k1[2 * (i - 8) + 1] = khi; } } }
;                 sort16_desc(k0); sort16_desc(k1); merge16(k0, k1);
	v_cvt_f32_f16_sdwa v21, v28 dst_sel:DWORD dst_unused:UNUSED_PAD src0_sel:WORD_1
	v_and_b32_e32 v32, 0xffffff80, v32
	v_cndmask_b32_e32 v20, v22, v20, vcc
	v_and_b32_e32 v20, 0xffffff80, v20
	v_cvt_f32_f16_e32 v22, v28
	v_not_b32_e32 v23, v21
	v_or_b32_e32 v24, 0x80000000, v21
	v_cmp_gt_i32_e32 vcc, 0, v21
	v_sub_u32_e32 v20, v20, v18
	v_add_u32_e32 v46, 0x7f, v20
	v_cndmask_b32_e32 v21, v24, v23, vcc
	v_or_b32_e32 v20, 16, v15
	v_and_b32_e32 v21, 0xffffff80, v21
	v_sub_u32_e32 v21, v21, v20
	v_add_u32_e32 v47, 0x7e, v21
	v_not_b32_e32 v21, v22
	v_or_b32_e32 v23, 0x80000000, v22
	v_cmp_gt_i32_e32 vcc, 0, v22
	v_cvt_f32_f16_sdwa v22, v29 dst_sel:DWORD dst_unused:UNUSED_PAD src0_sel:WORD_1
	v_sub_u32_e32 v32, v32, v10
	v_cndmask_b32_e32 v21, v23, v21, vcc
	v_and_b32_e32 v21, 0xffffff80, v21
	v_cvt_f32_f16_e32 v23, v29
	v_not_b32_e32 v24, v22
	v_or_b32_e32 v25, 0x80000000, v22
	v_cmp_gt_i32_e32 vcc, 0, v22
	v_sub_u32_e32 v21, v21, v20
	v_add_u32_e32 v48, 0x7f, v21
	v_cndmask_b32_e32 v22, v25, v24, vcc
	v_or_b32_e32 v21, 18, v15
	v_and_b32_e32 v22, 0xffffff80, v22
	v_sub_u32_e32 v22, v22, v21
	v_add_u32_e32 v29, 0x7e, v22
	v_not_b32_e32 v22, v23
	v_or_b32_e32 v24, 0x80000000, v23
	v_cmp_gt_i32_e32 vcc, 0, v23
	v_cvt_f32_f16_sdwa v23, v30 dst_sel:DWORD dst_unused:UNUSED_PAD src0_sel:WORD_1
	v_add_u32_e32 v32, 0x7f, v32
	v_cndmask_b32_e32 v22, v24, v22, vcc
	v_and_b32_e32 v22, 0xffffff80, v22
	v_cvt_f32_f16_e32 v24, v30
	v_not_b32_e32 v25, v23
	v_or_b32_e32 v26, 0x80000000, v23
	v_cmp_gt_i32_e32 vcc, 0, v23
	v_sub_u32_e32 v22, v22, v21
	v_add_u32_e32 v49, 0x7f, v22
	v_cndmask_b32_e32 v23, v26, v25, vcc
	v_or_b32_e32 v22, 20, v15
	v_and_b32_e32 v23, 0xffffff80, v23
	v_sub_u32_e32 v23, v23, v22
	v_add_u32_e32 v30, 0x7e, v23
	v_not_b32_e32 v23, v24
	v_or_b32_e32 v25, 0x80000000, v24
	v_cmp_gt_i32_e32 vcc, 0, v24
	v_cvt_f32_f16_sdwa v24, v31 dst_sel:DWORD dst_unused:UNUSED_PAD src0_sel:WORD_1
	v_max_u32_e32 v64, v48, v47
	v_cndmask_b32_e32 v23, v25, v23, vcc
	v_and_b32_e32 v23, 0xffffff80, v23
	v_cvt_f32_f16_e32 v25, v31
	v_not_b32_e32 v26, v24
	v_or_b32_e32 v28, 0x80000000, v24
	v_cmp_gt_i32_e32 vcc, 0, v24
	v_sub_u32_e32 v23, v23, v22
	v_add_u32_e32 v50, 0x7f, v23
	v_cndmask_b32_e32 v24, v28, v26, vcc
	v_or_b32_e32 v23, 22, v15
	v_and_b32_e32 v24, 0xffffff80, v24
	v_sub_u32_e32 v24, v24, v23
	v_add_u32_e32 v31, 0x7e, v24
	v_not_b32_e32 v24, v25
	v_or_b32_e32 v26, 0x80000000, v25
	v_cmp_gt_i32_e32 vcc, 0, v25
	v_cvt_f32_f16_sdwa v25, v0 dst_sel:DWORD dst_unused:UNUSED_PAD src0_sel:WORD_1
	v_cvt_f32_f16_e32 v0, v0
	v_cndmask_b32_e32 v24, v26, v24, vcc
	v_and_b32_e32 v24, 0xffffff80, v24
	v_not_b32_e32 v26, v25
	v_or_b32_e32 v28, 0x80000000, v25
	v_cmp_gt_i32_e32 vcc, 0, v25
	v_sub_u32_e32 v24, v24, v23
	v_add_u32_e32 v51, 0x7f, v24
	v_cndmask_b32_e32 v25, v28, v26, vcc
	v_or_b32_e32 v24, 24, v15
	v_and_b32_e32 v25, 0xffffff80, v25
	v_sub_u32_e32 v25, v25, v24
	v_add_u32_e32 v52, 0x7e, v25
	v_not_b32_e32 v25, v0
	v_or_b32_e32 v26, 0x80000000, v0
	v_cmp_gt_i32_e32 vcc, 0, v0
	v_min_u32_e32 v47, v48, v47
	v_max_u32_e32 v48, v29, v49
	v_cndmask_b32_e32 v0, v26, v25, vcc
	v_cvt_f32_f16_sdwa v26, v1 dst_sel:DWORD dst_unused:UNUSED_PAD src0_sel:WORD_1
	v_cvt_f32_f16_e32 v1, v1
	v_or_b32_e32 v25, 26, v15
	v_and_b32_e32 v0, 0xffffff80, v0
	v_not_b32_e32 v28, v26
	v_or_b32_e32 v53, 0x80000000, v26
	v_cmp_gt_i32_e32 vcc, 0, v26
	v_sub_u32_e32 v0, v0, v24
	v_add_u32_e32 v0, 0x7f, v0
	v_cndmask_b32_e32 v26, v53, v28, vcc
	v_and_b32_e32 v26, 0xffffff80, v26
	v_sub_u32_e32 v26, v26, v25
	v_add_u32_e32 v53, 0x7e, v26
	v_not_b32_e32 v26, v1
	v_or_b32_e32 v28, 0x80000000, v1
	v_cmp_gt_i32_e32 vcc, 0, v1
	v_min_u32_e32 v29, v29, v49
	v_max_u32_e32 v49, v50, v30
	v_cndmask_b32_e32 v1, v28, v26, vcc
	v_cvt_f32_f16_sdwa v28, v2 dst_sel:DWORD dst_unused:UNUSED_PAD src0_sel:WORD_1
	v_cvt_f32_f16_e32 v2, v2
	v_or_b32_e32 v26, 28, v15
	v_and_b32_e32 v1, 0xffffff80, v1
	v_not_b32_e32 v54, v28
	v_or_b32_e32 v55, 0x80000000, v28
	v_cmp_gt_i32_e32 vcc, 0, v28
	v_sub_u32_e32 v1, v1, v25
	v_add_u32_e32 v1, 0x7f, v1
	v_cndmask_b32_e32 v28, v55, v54, vcc
	v_and_b32_e32 v28, 0xffffff80, v28
	v_sub_u32_e32 v28, v28, v26
	v_add_u32_e32 v54, 0x7e, v28
	v_not_b32_e32 v28, v2
	v_or_b32_e32 v55, 0x80000000, v2
	v_cmp_gt_i32_e32 vcc, 0, v2
	v_min_u32_e32 v30, v50, v30
	v_max_u32_e32 v50, v31, v51
	v_cndmask_b32_e32 v2, v55, v28, vcc
	v_cvt_f32_f16_e32 v55, v3
	v_cvt_f32_f16_sdwa v3, v3 dst_sel:DWORD dst_unused:UNUSED_PAD src0_sel:WORD_1
	v_and_b32_e32 v2, 0xffffff80, v2
	v_or_b32_e32 v28, 30, v15
	v_not_b32_e32 v56, v55
	v_or_b32_e32 v57, 0x80000000, v55
	v_cmp_gt_i32_e32 vcc, 0, v55
	v_sub_u32_e32 v2, v2, v26
	v_add_u32_e32 v2, 0x7f, v2
	v_cndmask_b32_e32 v55, v57, v56, vcc
	v_not_b32_e32 v56, v3
	v_or_b32_e32 v57, 0x80000000, v3
	v_cmp_gt_i32_e32 vcc, 0, v3
	v_and_b32_e32 v55, 0xffffff80, v55
	v_sub_u32_e32 v55, v55, v28
	v_cndmask_b32_e32 v3, v57, v56, vcc
	v_and_b32_e32 v3, 0xffffff80, v3
	v_sub_u32_e32 v3, v3, v28
	v_add_u32_e32 v55, 0x7f, v55
	v_add_u32_e32 v3, 0x7e, v3
	v_max_u32_e32 v56, v35, v34
	v_min_u32_e32 v34, v35, v34
	v_max_u32_e32 v35, v36, v37
	v_min_u32_e32 v36, v36, v37
	v_max_u32_e32 v37, v39, v38
	v_min_u32_e32 v38, v39, v38
	v_max_u32_e32 v39, v40, v32
	v_min_u32_e32 v32, v40, v32
	v_max_u32_e32 v40, v33, v41
	v_min_u32_e32 v33, v33, v41
	v_max_u32_e32 v41, v42, v43
	v_min_u32_e32 v42, v42, v43
	v_max_u32_e32 v43, v45, v44
	v_min_u32_e32 v44, v45, v44
	v_max_u32_e32 v45, v27, v46
	v_min_u32_e32 v27, v27, v46
	v_min_u32_e32 v31, v31, v51
	v_max_u32_e32 v51, v0, v52
	v_min_u32_e32 v0, v0, v52
	v_max_u32_e32 v52, v53, v1
	v_min_u32_e32 v1, v53, v1
	v_max_u32_e32 v53, v2, v54
; #define CE_DESC(a, b) do { const unsigned _mx = (a) > (b) ? (a) : (b), _mn = (a) > (b) ? (b) : (a); (a) = _mx; (b) = _mn; } while (0)
; __device__ __forceinline__ void sort16_desc(unsigned (&k)[16]) {
; #pragma unroll
;     for (int size = 2; size <= 16; size <<= 1)
; #pragma unroll
;         for (int stride = size >> 1; stride > 0; stride >>= 1)
; #pragma unroll
;             for (int i = 0; i < 16; ++i) { const int j = i ^ stride;
;                 if (j > i) { if ((i & size) == 0) CE_DESC(k[i], k[j]); else CE_DESC(k[j], k[i]); } }
; }
	v_min_u32_e32 v2, v2, v54
	v_max_u32_e32 v54, v3, v55
	v_min_u32_e32 v3, v3, v55
	v_max_u32_e32 v46, v56, v36
	v_min_u32_e32 v36, v56, v36
	v_max_u32_e32 v56, v34, v35
	v_min_u32_e32 v34, v34, v35
	v_max_u32_e32 v35, v32, v37
	v_min_u32_e32 v32, v32, v37
	v_max_u32_e32 v37, v39, v38
	v_min_u32_e32 v38, v39, v38
	v_max_u32_e32 v39, v40, v42
	v_min_u32_e32 v40, v40, v42
	v_max_u32_e32 v42, v33, v41
	v_min_u32_e32 v33, v33, v41
	v_max_u32_e32 v41, v27, v43
	v_min_u32_e32 v27, v27, v43
	v_max_u32_e32 v43, v45, v44
	v_min_u32_e32 v44, v45, v44
	v_max_u32_e32 v55, v64, v29
	v_min_u32_e32 v29, v64, v29
	v_max_u32_e32 v64, v47, v48
	v_min_u32_e32 v47, v47, v48
	v_max_u32_e32 v48, v31, v49
	v_min_u32_e32 v31, v31, v49
	v_max_u32_e32 v49, v50, v30
	v_min_u32_e32 v30, v50, v30
	v_max_u32_e32 v50, v51, v1
	v_min_u32_e32 v1, v51, v1
	v_max_u32_e32 v51, v0, v52
	v_min_u32_e32 v0, v0, v52
	v_max_u32_e32 v52, v3, v53
	v_min_u32_e32 v3, v3, v53
	v_max_u32_e32 v53, v54, v2
	v_min_u32_e32 v2, v54, v2
	v_max_u32_e32 v45, v46, v56
	v_min_u32_e32 v46, v46, v56
	v_max_u32_e32 v56, v36, v34
	v_min_u32_e32 v34, v36, v34
	v_max_u32_e32 v36, v38, v32
	v_min_u32_e32 v32, v38, v32
	v_max_u32_e32 v38, v37, v35
	v_min_u32_e32 v35, v37, v35
	v_max_u32_e32 v37, v39, v42
	v_min_u32_e32 v39, v39, v42
	v_max_u32_e32 v42, v40, v33
	v_min_u32_e32 v33, v40, v33
	v_max_u32_e32 v40, v44, v27
	v_min_u32_e32 v27, v44, v27
	v_max_u32_e32 v44, v43, v41
	v_min_u32_e32 v41, v43, v41
	v_max_u32_e32 v54, v55, v64
	v_min_u32_e32 v55, v55, v64
	v_max_u32_e32 v64, v29, v47
	v_min_u32_e32 v29, v29, v47
	v_max_u32_e32 v47, v30, v31
	v_min_u32_e32 v30, v30, v31
	v_max_u32_e32 v31, v49, v48
	v_min_u32_e32 v48, v49, v48
	v_max_u32_e32 v49, v50, v51
	v_min_u32_e32 v50, v50, v51
	v_max_u32_e32 v51, v1, v0
	v_min_u32_e32 v0, v1, v0
	v_max_u32_e32 v1, v2, v3
	v_min_u32_e32 v2, v2, v3
	v_max_u32_e32 v3, v53, v52
	v_min_u32_e32 v52, v53, v52
	v_max_u32_e32 v43, v45, v32
	v_min_u32_e32 v32, v45, v32
	v_max_u32_e32 v45, v46, v36
	v_min_u32_e32 v36, v46, v36
	v_max_u32_e32 v46, v56, v35
	v_min_u32_e32 v35, v56, v35
	v_max_u32_e32 v56, v34, v38
	v_min_u32_e32 v34, v34, v38
	v_max_u32_e32 v38, v27, v37
	v_min_u32_e32 v27, v27, v37
	v_max_u32_e32 v37, v40, v39
	v_min_u32_e32 v39, v40, v39
	v_max_u32_e32 v40, v41, v42
	v_min_u32_e32 v41, v41, v42
	v_max_u32_e32 v42, v44, v33
	v_min_u32_e32 v33, v44, v33
	v_max_u32_e32 v53, v54, v30
	v_min_u32_e32 v30, v54, v30
	v_max_u32_e32 v54, v55, v47
	v_min_u32_e32 v47, v55, v47
	v_max_u32_e32 v55, v64, v48
	v_min_u32_e32 v48, v64, v48
	v_max_u32_e32 v64, v29, v31
	v_min_u32_e32 v29, v29, v31
	v_max_u32_e32 v31, v2, v49
	v_min_u32_e32 v2, v2, v49
	v_max_u32_e32 v49, v1, v50
	v_min_u32_e32 v1, v1, v50
	v_max_u32_e32 v50, v52, v51
	v_min_u32_e32 v51, v52, v51
	v_max_u32_e32 v52, v3, v0
	v_min_u32_e32 v0, v3, v0
	v_max_u32_e32 v44, v43, v46
	v_min_u32_e32 v43, v43, v46
	v_max_u32_e32 v46, v45, v56
	v_min_u32_e32 v45, v45, v56
	v_max_u32_e32 v56, v32, v35
	v_min_u32_e32 v32, v32, v35
	v_max_u32_e32 v35, v36, v34
	v_min_u32_e32 v34, v36, v34
	v_max_u32_e32 v36, v41, v27
	v_min_u32_e32 v27, v41, v27
	v_max_u32_e32 v41, v33, v39
	v_min_u32_e32 v33, v33, v39
	v_max_u32_e32 v39, v40, v38
	v_min_u32_e32 v38, v40, v38
	v_max_u32_e32 v40, v42, v37
	v_min_u32_e32 v37, v42, v37
	v_max_u32_e32 v3, v53, v55
	v_min_u32_e32 v53, v53, v55
	v_max_u32_e32 v55, v54, v64
	v_min_u32_e32 v54, v54, v64
	v_max_u32_e32 v64, v30, v48
	v_min_u32_e32 v30, v30, v48
	v_max_u32_e32 v48, v47, v29
	v_min_u32_e32 v29, v47, v29
	v_max_u32_e32 v47, v51, v2
	v_min_u32_e32 v2, v51, v2
	v_max_u32_e32 v51, v0, v1
	v_min_u32_e32 v0, v0, v1
	v_max_u32_e32 v1, v50, v31
	v_min_u32_e32 v31, v50, v31
	v_max_u32_e32 v50, v52, v49
	v_min_u32_e32 v49, v52, v49
	v_max_u32_e32 v42, v44, v46
	v_min_u32_e32 v44, v44, v46
	v_max_u32_e32 v46, v43, v45
	v_min_u32_e32 v43, v43, v45
	v_max_u32_e32 v45, v56, v35
	v_min_u32_e32 v35, v56, v35
	v_max_u32_e32 v56, v32, v34
	v_min_u32_e32 v32, v32, v34
	v_max_u32_e32 v34, v33, v27
	v_min_u32_e32 v27, v33, v27
	v_max_u32_e32 v33, v41, v36
	v_min_u32_e32 v36, v41, v36
	v_max_u32_e32 v41, v37, v38
	v_min_u32_e32 v37, v37, v38
	v_max_u32_e32 v38, v40, v39
	v_min_u32_e32 v39, v40, v39
	v_max_u32_e32 v52, v3, v55
	v_min_u32_e32 v3, v3, v55
	v_max_u32_e32 v55, v53, v54
	v_min_u32_e32 v53, v53, v54
	v_max_u32_e32 v54, v64, v48
	v_min_u32_e32 v48, v64, v48
	v_max_u32_e32 v64, v30, v29
	v_min_u32_e32 v29, v30, v29
	v_max_u32_e32 v30, v0, v2
	v_min_u32_e32 v0, v0, v2
	v_max_u32_e32 v2, v51, v47
	v_min_u32_e32 v47, v51, v47
	v_max_u32_e32 v51, v49, v31
	v_min_u32_e32 v31, v49, v31
	v_max_u32_e32 v49, v50, v1
	v_min_u32_e32 v1, v50, v1
	v_max_u32_e32 v40, v42, v27
	v_min_u32_e32 v27, v42, v27
	v_max_u32_e32 v42, v44, v34
	v_min_u32_e32 v34, v44, v34
	v_max_u32_e32 v44, v46, v36
	v_min_u32_e32 v36, v46, v36
	v_max_u32_e32 v46, v43, v33
	v_min_u32_e32 v33, v43, v33
	v_max_u32_e32 v43, v45, v37
	v_min_u32_e32 v37, v45, v37
	v_max_u32_e32 v45, v35, v41
	v_min_u32_e32 v35, v35, v41
	v_max_u32_e32 v41, v56, v39
	v_min_u32_e32 v39, v56, v39
	v_max_u32_e32 v56, v32, v38
	v_min_u32_e32 v32, v32, v38
	v_max_u32_e32 v50, v52, v0
	v_min_u32_e32 v0, v52, v0
	v_max_u32_e32 v52, v3, v30
	v_min_u32_e32 v3, v3, v30
	v_max_u32_e32 v30, v55, v47
	v_min_u32_e32 v47, v55, v47
	v_max_u32_e32 v55, v53, v2
	v_min_u32_e32 v2, v53, v2
	v_max_u32_e32 v53, v54, v31
	v_min_u32_e32 v31, v54, v31
	v_max_u32_e32 v54, v48, v51
	v_min_u32_e32 v48, v48, v51
	v_max_u32_e32 v51, v64, v1
	v_min_u32_e32 v1, v64, v1
	v_max_u32_e32 v64, v29, v49
	v_min_u32_e32 v29, v29, v49
	v_max_u32_e32 v38, v40, v43
	v_min_u32_e32 v40, v40, v43
; #define CE_DESC(a, b) do { const unsigned _mx = (a) > (b) ? (a) : (b), _mn = (a) > (b) ? (b) : (a); (a) = _mx; (b) = _mn; } while (0)
; __device__ __forceinline__ void merge16(unsigned (&a)[16], const unsigned (&b)[16]) {
; #pragma unroll
;     for (int i = 0; i < 16; ++i) a[i] = a[i] > b[15 - i] ? a[i] : b[15 - i];
; #pragma unroll
;     for (int stride = 8; stride > 0; stride >>= 1)
; #pragma unroll
;         for (int i = 0; i < 16; ++i) { const int j = i ^ stride; if (j > i) CE_DESC(a[i], a[j]); }
; }
; __device__ __forceinline__ void peer_tile(const Args& A, LAS unsigned char* lds, int tile) {
;     ...
;                 sort16_desc(k0); sort16_desc(k1); merge16(k0, k1);
; #pragma unroll
;                 for (int msk = 16; msk <= 32; msk <<= 1) {
; #pragma unroll
;                     for (int i = 0; i < 16; ++i) k1[i] = (unsigned)__shfl_xor((int)k0[i], msk);
;                     merge16(k0, k1); }
	v_max_u32_e32 v43, v42, v45
	v_min_u32_e32 v42, v42, v45
	v_max_u32_e32 v45, v44, v41
	v_min_u32_e32 v41, v44, v41
	v_max_u32_e32 v44, v46, v56
	v_min_u32_e32 v46, v46, v56
	v_max_u32_e32 v56, v27, v37
	v_min_u32_e32 v27, v27, v37
	v_max_u32_e32 v37, v34, v35
	v_min_u32_e32 v34, v34, v35
	v_max_u32_e32 v35, v36, v39
	v_min_u32_e32 v36, v36, v39
	v_max_u32_e32 v39, v33, v32
	v_min_u32_e32 v32, v33, v32
	v_max_u32_e32 v49, v50, v53
	v_min_u32_e32 v50, v50, v53
	v_max_u32_e32 v53, v52, v54
	v_min_u32_e32 v52, v52, v54
	v_max_u32_e32 v54, v30, v51
	v_min_u32_e32 v30, v30, v51
	v_max_u32_e32 v51, v55, v64
	v_min_u32_e32 v55, v55, v64
	v_max_u32_e32 v64, v0, v31
	v_min_u32_e32 v0, v0, v31
	v_max_u32_e32 v31, v3, v48
	v_min_u32_e32 v3, v3, v48
	v_max_u32_e32 v48, v47, v1
	v_min_u32_e32 v1, v47, v1
	v_max_u32_e32 v47, v2, v29
	v_min_u32_e32 v2, v2, v29
	v_max_u32_e32 v33, v38, v45
	v_min_u32_e32 v38, v38, v45
	v_max_u32_e32 v45, v43, v44
	v_min_u32_e32 v43, v43, v44
	v_max_u32_e32 v44, v40, v41
	v_min_u32_e32 v40, v40, v41
	v_max_u32_e32 v41, v42, v46
	v_min_u32_e32 v42, v42, v46
	v_max_u32_e32 v46, v56, v35
	v_min_u32_e32 v35, v56, v35
	v_max_u32_e32 v56, v37, v39
	v_min_u32_e32 v37, v37, v39
	v_max_u32_e32 v39, v27, v36
	v_min_u32_e32 v27, v27, v36
	v_max_u32_e32 v36, v34, v32
	v_min_u32_e32 v32, v34, v32
	v_max_u32_e32 v29, v49, v54
	v_min_u32_e32 v49, v49, v54
	v_max_u32_e32 v54, v53, v51
	v_min_u32_e32 v51, v53, v51
	v_max_u32_e32 v53, v50, v30
	v_min_u32_e32 v30, v50, v30
	v_max_u32_e32 v50, v52, v55
	v_min_u32_e32 v52, v52, v55
	v_max_u32_e32 v55, v64, v48
	v_min_u32_e32 v48, v64, v48
	v_max_u32_e32 v64, v31, v47
	v_min_u32_e32 v31, v31, v47
	v_max_u32_e32 v47, v0, v1
	v_min_u32_e32 v0, v0, v1
	v_max_u32_e32 v1, v3, v2
	v_min_u32_e32 v2, v3, v2
	v_min_u32_e32 v34, v33, v45
	v_min_u32_e32 v57, v38, v43
	v_min_u32_e32 v58, v44, v41
	v_min_u32_e32 v59, v40, v42
	v_min_u32_e32 v60, v46, v56
	v_min_u32_e32 v61, v35, v37
	v_min_u32_e32 v62, v39, v36
	v_min_u32_e32 v63, v27, v32
	v_min_u32_e32 v3, v29, v54
	v_min_u32_e32 v65, v49, v51
	v_min_u32_e32 v66, v53, v50
	v_min_u32_e32 v67, v30, v52
	v_min_u32_e32 v68, v55, v64
	v_min_u32_e32 v69, v48, v31
	v_min_u32_e32 v70, v47, v1
	v_min_u32_e32 v71, v0, v2
	v_max3_u32 v33, v33, v45, v71
	v_max3_u32 v0, v34, v0, v2
	v_max3_u32 v2, v38, v43, v70
	v_max3_u32 v1, v57, v47, v1
	v_max3_u32 v34, v44, v41, v69
	v_max3_u32 v31, v58, v48, v31
	v_max3_u32 v38, v40, v42, v68
	v_max3_u32 v40, v59, v55, v64
	v_max3_u32 v41, v46, v56, v67
	v_max3_u32 v30, v60, v30, v52
	v_max3_u32 v35, v35, v37, v66
	v_max3_u32 v37, v61, v53, v50
	v_max3_u32 v36, v39, v36, v65
	v_max3_u32 v39, v62, v49, v51
	v_max3_u32 v3, v27, v32, v3
	v_max3_u32 v27, v63, v29, v54
	v_max_u32_e32 v29, v33, v41
	v_min_u32_e32 v32, v33, v41
	v_max_u32_e32 v33, v0, v30
	v_min_u32_e32 v0, v0, v30
	v_max_u32_e32 v30, v2, v35
	v_min_u32_e32 v2, v2, v35
	v_max_u32_e32 v35, v1, v37
	v_min_u32_e32 v1, v1, v37
	v_max_u32_e32 v37, v34, v36
	v_min_u32_e32 v34, v34, v36
	v_max_u32_e32 v36, v31, v39
	v_min_u32_e32 v31, v31, v39
	v_max_u32_e32 v39, v38, v3
	v_min_u32_e32 v3, v38, v3
	v_max_u32_e32 v38, v40, v27
	v_min_u32_e32 v27, v40, v27
	v_max_u32_e32 v40, v29, v37
	v_min_u32_e32 v29, v29, v37
	v_max_u32_e32 v37, v33, v36
	v_min_u32_e32 v33, v33, v36
	v_max_u32_e32 v36, v30, v39
	v_min_u32_e32 v30, v30, v39
	v_max_u32_e32 v39, v35, v38
	v_min_u32_e32 v35, v35, v38
	v_max_u32_e32 v38, v32, v34
	v_min_u32_e32 v32, v32, v34
	v_max_u32_e32 v34, v0, v31
	v_min_u32_e32 v0, v0, v31
	v_max_u32_e32 v31, v2, v3
	v_min_u32_e32 v2, v2, v3
	v_max_u32_e32 v3, v1, v27
	v_min_u32_e32 v1, v1, v27
	v_max_u32_e32 v27, v40, v36
	v_min_u32_e32 v36, v40, v36
	v_max_u32_e32 v40, v37, v39
	v_min_u32_e32 v37, v37, v39
	v_max_u32_e32 v39, v29, v30
	v_min_u32_e32 v29, v29, v30
	v_max_u32_e32 v30, v33, v35
	v_min_u32_e32 v33, v33, v35
	v_max_u32_e32 v35, v38, v31
	v_min_u32_e32 v31, v38, v31
	v_max_u32_e32 v38, v34, v3
	v_min_u32_e32 v3, v34, v3
	v_max_u32_e32 v34, v32, v2
	v_min_u32_e32 v2, v32, v2
	v_max_u32_e32 v32, v0, v1
	v_min_u32_e32 v0, v0, v1
	v_cmp_lt_i32_e32 vcc, v217, v216
	v_max_u32_e32 v41, v36, v37
	v_min_u32_e32 v36, v36, v37
	v_max_u32_e32 v37, v39, v30
	v_min_u32_e32 v30, v39, v30
	v_max_u32_e32 v39, v29, v33
	v_min_u32_e32 v29, v29, v33
	v_max_u32_e32 v33, v35, v38
	v_min_u32_e32 v35, v35, v38
	v_max_u32_e32 v38, v31, v3
	v_min_u32_e32 v3, v31, v3
	v_max_u32_e32 v31, v34, v32
	v_min_u32_e32 v32, v34, v32
	v_max_u32_e32 v34, v2, v0
	v_min_u32_e32 v0, v2, v0
	v_cndmask_b32_e32 v2, v215, v217, vcc
	v_max_u32_e32 v1, v27, v40
	v_min_u32_e32 v40, v27, v40
	v_lshlrev_b32_e32 v27, 2, v2
	ds_bpermute_b32 v2, v27, v1
	ds_bpermute_b32 v42, v27, v40
	ds_bpermute_b32 v43, v27, v41
	ds_bpermute_b32 v44, v27, v36
	ds_bpermute_b32 v45, v27, v37
	ds_bpermute_b32 v46, v27, v30
	ds_bpermute_b32 v47, v27, v39
	ds_bpermute_b32 v48, v27, v29
	ds_bpermute_b32 v49, v27, v33
	ds_bpermute_b32 v50, v27, v35
	ds_bpermute_b32 v51, v27, v38
	ds_bpermute_b32 v52, v27, v0
	ds_bpermute_b32 v53, v27, v34
	ds_bpermute_b32 v54, v27, v32
	ds_bpermute_b32 v55, v27, v31
	ds_bpermute_b32 v56, v27, v3
	s_waitcnt lgkmcnt(4)
	v_max_u32_e32 v1, v1, v52
	s_waitcnt lgkmcnt(3)
	v_max_u32_e32 v40, v40, v53
	s_waitcnt lgkmcnt(2)
	v_max_u32_e32 v41, v41, v54
	s_waitcnt lgkmcnt(1)
	v_max_u32_e32 v36, v36, v55
	s_waitcnt lgkmcnt(0)
; __device__ __forceinline__ void peer_tile(const Args& A, LAS unsigned char* lds, int tile) {
;     ...
;                 { const bf16_t* sp = QRY + m * 2048 + hp * 128 + 32 * g;
;                   const u32x4 s0 = *(const u32x4*)sp, s1 = *(const u32x4*)(sp + 8), s2 = *(const u32x4*)(sp + 16), s3 = *(const u32x4*)(sp + 24);
;     ...
;                 for (int msk = 16; msk <= 32; msk <<= 1) {
; #pragma unroll
;                     for (int i = 0; i < 16; ++i) k1[i] = (unsigned)__shfl_xor((int)k0[i], msk);
;                     merge16(k0, k1); }
	v_max_u32_e32 v37, v37, v56
	v_max_u32_e32 v30, v30, v51
	v_max_u32_e32 v39, v39, v50
	v_max_u32_e32 v29, v29, v49
	v_max_u32_e32 v33, v33, v48
	v_max_u32_e32 v35, v35, v47
	v_max_u32_e32 v38, v38, v46
	v_max_u32_e32 v3, v3, v45
	v_max_u32_e32 v31, v31, v44
	v_max_u32_e32 v32, v32, v43
	v_max_u32_e32 v34, v34, v42
	v_max_u32_e32 v0, v0, v2
	v_max_u32_e32 v2, v1, v33
	v_min_u32_e32 v1, v1, v33
	v_max_u32_e32 v33, v40, v35
	v_min_u32_e32 v35, v40, v35
	v_max_u32_e32 v40, v41, v38
	v_min_u32_e32 v38, v41, v38
	v_max_u32_e32 v41, v36, v3
	v_min_u32_e32 v3, v36, v3
	v_max_u32_e32 v36, v37, v31
	v_min_u32_e32 v31, v37, v31
	v_max_u32_e32 v37, v30, v32
	v_min_u32_e32 v30, v30, v32
	v_max_u32_e32 v32, v39, v34
	v_min_u32_e32 v34, v39, v34
	v_max_u32_e32 v39, v29, v0
	v_min_u32_e32 v0, v29, v0
	v_max_u32_e32 v29, v2, v36
	v_min_u32_e32 v2, v2, v36
	v_max_u32_e32 v36, v33, v37
	v_min_u32_e32 v33, v33, v37
	v_max_u32_e32 v37, v40, v32
	v_min_u32_e32 v32, v40, v32
	v_max_u32_e32 v40, v41, v39
	v_min_u32_e32 v39, v41, v39
	v_max_u32_e32 v41, v1, v31
	v_min_u32_e32 v1, v1, v31
	v_max_u32_e32 v31, v35, v30
	v_min_u32_e32 v30, v35, v30
	v_max_u32_e32 v35, v38, v34
	v_min_u32_e32 v34, v38, v34
	v_max_u32_e32 v38, v3, v0
	v_min_u32_e32 v0, v3, v0
	v_max_u32_e32 v3, v29, v37
	v_min_u32_e32 v29, v29, v37
	v_max_u32_e32 v37, v36, v40
	v_min_u32_e32 v36, v36, v40
	v_max_u32_e32 v40, v2, v32
	v_min_u32_e32 v2, v2, v32
	v_max_u32_e32 v32, v33, v39
	v_min_u32_e32 v33, v33, v39
	v_max_u32_e32 v39, v41, v35
	v_min_u32_e32 v35, v41, v35
	v_max_u32_e32 v41, v31, v38
	v_min_u32_e32 v31, v31, v38
	v_max_u32_e32 v38, v1, v34
	v_min_u32_e32 v1, v1, v34
	v_max_u32_e32 v34, v30, v0
	v_min_u32_e32 v0, v30, v0
	v_cmp_lt_i32_e32 vcc, v218, v216
	v_max_u32_e32 v42, v40, v32
	v_min_u32_e32 v32, v40, v32
	v_max_u32_e32 v40, v2, v33
	v_min_u32_e32 v2, v2, v33
	v_max_u32_e32 v33, v39, v41
	v_min_u32_e32 v39, v39, v41
	v_max_u32_e32 v41, v35, v31
	v_min_u32_e32 v31, v35, v31
	v_max_u32_e32 v35, v38, v34
	v_min_u32_e32 v34, v38, v34
	v_max_u32_e32 v38, v1, v0
	v_min_u32_e32 v0, v1, v0
	v_cndmask_b32_e32 v1, v215, v218, vcc
	v_max_u32_e32 v30, v3, v37
	v_min_u32_e32 v3, v3, v37
	v_max_u32_e32 v37, v29, v36
	v_min_u32_e32 v36, v29, v36
	v_lshlrev_b32_e32 v29, 2, v1
	ds_bpermute_b32 v46, v29, v0
	ds_bpermute_b32 v1, v29, v30
	ds_bpermute_b32 v43, v29, v3
	ds_bpermute_b32 v44, v29, v37
	ds_bpermute_b32 v45, v29, v36
	s_waitcnt lgkmcnt(4)
	v_max_u32_e32 v30, v30, v46
	global_load_dwordx4 v[46:49], v[4:5], off offset:272
	global_load_dwordx4 v[50:53], v[4:5], off offset:256
	ds_bpermute_b32 v54, v29, v42
	ds_bpermute_b32 v55, v29, v32
	ds_bpermute_b32 v56, v29, v40
	ds_bpermute_b32 v57, v29, v2
	ds_bpermute_b32 v58, v29, v33
	ds_bpermute_b32 v59, v29, v39
	ds_bpermute_b32 v60, v29, v41
	ds_bpermute_b32 v61, v29, v31
	ds_bpermute_b32 v62, v29, v35
	ds_bpermute_b32 v63, v29, v38
	ds_bpermute_b32 v64, v29, v34
	s_waitcnt lgkmcnt(4)
	v_max_u32_e32 v32, v32, v60
	s_waitcnt lgkmcnt(3)
	v_max_u32_e32 v42, v42, v61
	s_waitcnt lgkmcnt(2)
	v_max_u32_e32 v36, v36, v62
	s_waitcnt lgkmcnt(1)
	v_max_u32_e32 v3, v3, v63
	s_waitcnt lgkmcnt(0)
	v_max_u32_e32 v37, v37, v64
	v_max_u32_e32 v40, v40, v59
	v_max_u32_e32 v2, v2, v58
	v_max_u32_e32 v33, v33, v57
	v_max_u32_e32 v39, v39, v56
	v_max_u32_e32 v41, v41, v55
	v_max_u32_e32 v31, v31, v54
	v_max_u32_e32 v35, v35, v45
	v_max_u32_e32 v34, v34, v44
	v_max_u32_e32 v38, v38, v43
	v_max_u32_e32 v0, v0, v1
	v_max_u32_e32 v1, v30, v33
	v_min_u32_e32 v30, v30, v33
	v_max_u32_e32 v33, v3, v39
	v_min_u32_e32 v3, v3, v39
	v_max_u32_e32 v39, v37, v41
	v_min_u32_e32 v37, v37, v41
	v_max_u32_e32 v41, v36, v31
	v_min_u32_e32 v31, v36, v31
	v_max_u32_e32 v36, v42, v35
	v_min_u32_e32 v35, v42, v35
	v_max_u32_e32 v42, v32, v34
	v_min_u32_e32 v32, v32, v34
	v_max_u32_e32 v34, v40, v38
	v_min_u32_e32 v38, v40, v38
	v_max_u32_e32 v40, v2, v0
	v_min_u32_e32 v0, v2, v0
	v_max_u32_e32 v2, v1, v36
	v_min_u32_e32 v1, v1, v36
	v_max_u32_e32 v36, v33, v42
	v_min_u32_e32 v33, v33, v42
	v_max_u32_e32 v42, v39, v34
	v_min_u32_e32 v34, v39, v34
	v_max_u32_e32 v39, v41, v40
	v_min_u32_e32 v40, v41, v40
	v_max_u32_e32 v41, v30, v35
	v_min_u32_e32 v30, v30, v35
	v_max_u32_e32 v35, v3, v32
	v_min_u32_e32 v3, v3, v32
	v_max_u32_e32 v32, v37, v38
	v_min_u32_e32 v37, v37, v38
	v_max_u32_e32 v38, v31, v0
	v_min_u32_e32 v0, v31, v0
	v_max_u32_e32 v31, v2, v42
	v_min_u32_e32 v2, v2, v42
	v_max_u32_e32 v42, v36, v39
	v_min_u32_e32 v36, v36, v39
	v_max_u32_e32 v39, v1, v34
	v_min_u32_e32 v1, v1, v34
	v_max_u32_e32 v34, v33, v40
	v_min_u32_e32 v33, v33, v40
	v_max_u32_e32 v54, v41, v32
	v_min_u32_e32 v32, v41, v32
	v_max_u32_e32 v55, v35, v38
	v_min_u32_e32 v56, v35, v38
	v_max_u32_e32 v57, v30, v37
	v_min_u32_e32 v30, v30, v37
	v_max_u32_e32 v58, v3, v0
	v_min_u32_e32 v0, v3, v0
	v_max_u32_e32 v45, v31, v42
	v_min_u32_e32 v44, v31, v42
	v_max_u32_e32 v43, v2, v36
	v_min_u32_e32 v42, v2, v36
	v_max_u32_e32 v41, v39, v34
	v_min_u32_e32 v40, v39, v34
	v_max_u32_e32 v39, v1, v33
	v_min_u32_e32 v38, v1, v33
	v_max_u32_e32 v37, v54, v55
	v_min_u32_e32 v36, v54, v55
	v_max_u32_e32 v35, v32, v56
	v_min_u32_e32 v34, v32, v56
	v_max_u32_e32 v33, v57, v58
	v_min_u32_e32 v32, v57, v58
	v_max_u32_e32 v31, v30, v0
	v_min_u32_e32 v30, v30, v0
	global_load_dwordx4 v[0:3], v[4:5], off offset:304
	global_load_dwordx4 v[54:57], v[4:5], off offset:288
	s_waitcnt vmcnt(2)
; __device__ __forceinline__ unsigned f2key(float f) { const unsigned u = __float_as_uint(f); return (u & 0x80000000u) ? ~u : (u | 0x80000000u); }
; __device__ __forceinline__ void peer_tile(const Args& A, LAS unsigned char* lds, int tile) {
;     ...
;                 { const bf16_t* sp = QRY + m * 2048 + hp * 128 + 32 * g;
;                   const u32x4 s0 = *(const u32x4*)sp, s1 = *(const u32x4*)(sp + 8), s2 = *(const u32x4*)(sp + 16), s3 = *(const u32x4*)(sp + 24);
;                   const unsigned sw[16] = {s0.x, s0.y, s0.z, s0.w, s1.x, s1.y, s1.z, s1.w, s2.x, s2.y, s2.z, s2.w, s3.x, s3.y, s3.z, s3.w};
; #pragma unroll
;                   for (int i = 0; i < 16; ++i) {
;                       const float lo = (float)__builtin_bit_cast(_Float16, (unsigned short)(sw[i] & 0xffffu)), hi = (float)__builtin_bit_cast(_Float16, (unsigned short)(sw[i] >> 16));
;                       const unsigned klo = (f2key(lo) & ~127u) | (unsigned)(127 - (32 * g + 2 * i)), khi = (f2key(hi) & ~127u) | (unsigned)(127 - (32 * g + 2 * i + 1));
;                       if (i < 8) { k0[2 * i] = klo; k0[2 * i + 1] = khi; } else { k1[2 * (i - 8)] = klo; k1[2 * (i - 8) + 1] = khi; } } }
	v_cvt_f32_f16_sdwa v58, v50 dst_sel:DWORD dst_unused:UNUSED_PAD src0_sel:WORD_1
	v_cvt_f32_f16_e32 v50, v50
	v_not_b32_e32 v59, v58
	v_or_b32_e32 v60, 0x80000000, v58
	v_cmp_gt_i32_e32 vcc, 0, v58
	s_nop 1
	v_cndmask_b32_e32 v58, v60, v59, vcc
	v_not_b32_e32 v59, v50
	v_or_b32_e32 v60, 0x80000000, v50
	v_cmp_gt_i32_e32 vcc, 0, v50
	v_and_b32_e32 v58, 0xffffff80, v58
	v_sub_u32_e32 v58, v58, v15
	v_cndmask_b32_e32 v50, v60, v59, vcc
	v_cvt_f32_f16_sdwa v59, v51 dst_sel:DWORD dst_unused:UNUSED_PAD src0_sel:WORD_1
	v_cvt_f32_f16_e32 v51, v51
	v_and_b32_e32 v50, 0xffffff80, v50
	v_sub_u32_e32 v50, v50, v15
	v_not_b32_e32 v60, v59
	v_or_b32_e32 v61, 0x80000000, v59
	v_cmp_gt_i32_e32 vcc, 0, v59
	v_add_u32_e32 v58, 0x7e, v58
	v_add_u32_e32 v50, 0x7f, v50
	v_cndmask_b32_e32 v59, v61, v60, vcc
	v_not_b32_e32 v60, v51
	v_or_b32_e32 v61, 0x80000000, v51
	v_cmp_gt_i32_e32 vcc, 0, v51
	v_and_b32_e32 v59, 0xffffff80, v59
	v_sub_u32_e32 v59, v59, v14
	v_cndmask_b32_e32 v51, v61, v60, vcc
	v_cvt_f32_f16_sdwa v60, v52 dst_sel:DWORD dst_unused:UNUSED_PAD src0_sel:WORD_1
	v_cvt_f32_f16_e32 v52, v52
	v_and_b32_e32 v51, 0xffffff80, v51
	v_sub_u32_e32 v51, v51, v14
	v_not_b32_e32 v61, v60
	v_or_b32_e32 v62, 0x80000000, v60
	v_cmp_gt_i32_e32 vcc, 0, v60
	v_add_u32_e32 v59, 0x7e, v59
	v_add_u32_e32 v51, 0x7f, v51
	v_cndmask_b32_e32 v60, v62, v61, vcc
	v_not_b32_e32 v61, v52
	v_or_b32_e32 v62, 0x80000000, v52
	v_cmp_gt_i32_e32 vcc, 0, v52
	v_and_b32_e32 v60, 0xffffff80, v60
	v_sub_u32_e32 v60, v60, v12
	v_cndmask_b32_e32 v52, v62, v61, vcc
	v_cvt_f32_f16_sdwa v61, v53 dst_sel:DWORD dst_unused:UNUSED_PAD src0_sel:WORD_1
	v_cvt_f32_f16_e32 v53, v53
	v_and_b32_e32 v52, 0xffffff80, v52
	v_sub_u32_e32 v52, v52, v12
	v_not_b32_e32 v62, v61
	v_or_b32_e32 v63, 0x80000000, v61
	v_cmp_gt_i32_e32 vcc, 0, v61
	v_add_u32_e32 v60, 0x7e, v60
	v_add_u32_e32 v52, 0x7f, v52
	v_cndmask_b32_e32 v61, v63, v62, vcc
	v_not_b32_e32 v62, v53
	v_or_b32_e32 v63, 0x80000000, v53
	v_cmp_gt_i32_e32 vcc, 0, v53
	v_and_b32_e32 v61, 0xffffff80, v61
	v_sub_u32_e32 v61, v61, v10
	v_cndmask_b32_e32 v53, v63, v62, vcc
	v_cvt_f32_f16_sdwa v62, v46 dst_sel:DWORD dst_unused:UNUSED_PAD src0_sel:WORD_1
	v_cvt_f32_f16_e32 v46, v46
	v_and_b32_e32 v53, 0xffffff80, v53
	v_sub_u32_e32 v53, v53, v10
	v_not_b32_e32 v63, v62
	v_or_b32_e32 v64, 0x80000000, v62
	v_cmp_gt_i32_e32 vcc, 0, v62
	v_add_u32_e32 v61, 0x7e, v61
	v_add_u32_e32 v53, 0x7f, v53
	v_cndmask_b32_e32 v62, v64, v63, vcc
	v_not_b32_e32 v63, v46
	v_or_b32_e32 v64, 0x80000000, v46
	v_cmp_gt_i32_e32 vcc, 0, v46
	v_and_b32_e32 v62, 0xffffff80, v62
	v_sub_u32_e32 v62, v62, v8
	v_cndmask_b32_e32 v46, v64, v63, vcc
	v_cvt_f32_f16_sdwa v63, v47 dst_sel:DWORD dst_unused:UNUSED_PAD src0_sel:WORD_1
	v_cvt_f32_f16_e32 v47, v47
	v_and_b32_e32 v46, 0xffffff80, v46
	v_sub_u32_e32 v46, v46, v8
	v_not_b32_e32 v64, v63
	v_or_b32_e32 v65, 0x80000000, v63
	v_cmp_gt_i32_e32 vcc, 0, v63
	v_add_u32_e32 v62, 0x7e, v62
	v_add_u32_e32 v46, 0x7f, v46
	v_cndmask_b32_e32 v63, v65, v64, vcc
	v_not_b32_e32 v64, v47
	v_or_b32_e32 v65, 0x80000000, v47
	v_cmp_gt_i32_e32 vcc, 0, v47
	v_and_b32_e32 v63, 0xffffff80, v63
	v_sub_u32_e32 v63, v63, v16
	v_cndmask_b32_e32 v47, v65, v64, vcc
	v_cvt_f32_f16_sdwa v64, v48 dst_sel:DWORD dst_unused:UNUSED_PAD src0_sel:WORD_1
	v_cvt_f32_f16_e32 v48, v48
	v_and_b32_e32 v47, 0xffffff80, v47
	v_sub_u32_e32 v47, v47, v16
	v_not_b32_e32 v65, v64
	v_or_b32_e32 v66, 0x80000000, v64
	v_cmp_gt_i32_e32 vcc, 0, v64
	v_add_u32_e32 v63, 0x7e, v63
	v_add_u32_e32 v47, 0x7f, v47
	v_cndmask_b32_e32 v64, v66, v65, vcc
	v_not_b32_e32 v65, v48
	v_or_b32_e32 v66, 0x80000000, v48
	v_cmp_gt_i32_e32 vcc, 0, v48
	v_and_b32_e32 v64, 0xffffff80, v64
	v_sub_u32_e32 v64, v64, v17
	v_cndmask_b32_e32 v48, v66, v65, vcc
	v_cvt_f32_f16_sdwa v65, v49 dst_sel:DWORD dst_unused:UNUSED_PAD src0_sel:WORD_1
	v_cvt_f32_f16_e32 v49, v49
	v_and_b32_e32 v48, 0xffffff80, v48
	v_sub_u32_e32 v48, v48, v17
	v_not_b32_e32 v66, v65
	v_or_b32_e32 v67, 0x80000000, v65
	v_cmp_gt_i32_e32 vcc, 0, v65
	v_add_u32_e32 v64, 0x7e, v64
	v_add_u32_e32 v48, 0x7f, v48
	v_cndmask_b32_e32 v65, v67, v66, vcc
	v_not_b32_e32 v66, v49
	v_or_b32_e32 v67, 0x80000000, v49
	v_cmp_gt_i32_e32 vcc, 0, v49
	v_and_b32_e32 v65, 0xffffff80, v65
	v_sub_u32_e32 v65, v65, v18
	v_cndmask_b32_e32 v49, v67, v66, vcc
	s_waitcnt vmcnt(0)
; __device__ __forceinline__ unsigned f2key(float f) { const unsigned u = __float_as_uint(f); return (u & 0x80000000u) ? ~u : (u | 0x80000000u); }
; #define CE_DESC(a, b) do { const unsigned _mx = (a) > (b) ? (a) : (b), _mn = (a) > (b) ? (b) : (a); (a) = _mx; (b) = _mn; } while (0)
; __device__ __forceinline__ void sort16_desc(unsigned (&k)[16]) {
; #pragma unroll
;     for (int size = 2; size <= 16; size <<= 1)
; #pragma unroll
;         for (int stride = size >> 1; stride > 0; stride >>= 1)
; #pragma unroll
;             for (int i = 0; i < 16; ++i) { const int j = i ^ stride;
;                 if (j > i) { if ((i & size) == 0) CE_DESC(k[i], k[j]); else CE_DESC(k[j], k[i]); } }
; }
; __device__ __forceinline__ void peer_tile(const Args& A, LAS unsigned char* lds, int tile) {
;     ...
;                   for (int i = 0; i < 16; ++i) {
;                       const float lo = (float)__builtin_bit_cast(_Float16, (unsigned short)(sw[i] & 0xffffu)), hi = (float)__builtin_bit_cast(_Float16, (unsigned short)(sw[i] >> 16));
;                       const unsigned klo = (f2key(lo) & ~127u) | (unsigned)(127 - (32 * g + 2 * i)), khi = (f2key(hi) & ~127u) | (unsigned)(127 - (32 * g + 2 * i + 1));
;                       if (i < 8) { k0[2 * i] = klo; k0[2 * i + 1] = khi; } else { k1[2 * (i - 8)] = klo; k1[2 * (i - 8) + 1] = khi; } } }
;                 sort16_desc(k0); sort16_desc(k1); merge16(k0, k1);
	v_cvt_f32_f16_sdwa v66, v54 dst_sel:DWORD dst_unused:UNUSED_PAD src0_sel:WORD_1
	v_cvt_f32_f16_e32 v54, v54
	v_and_b32_e32 v49, 0xffffff80, v49
	v_sub_u32_e32 v49, v49, v18
	v_not_b32_e32 v67, v66
	v_or_b32_e32 v68, 0x80000000, v66
	v_cmp_gt_i32_e32 vcc, 0, v66
	v_add_u32_e32 v65, 0x7e, v65
	v_add_u32_e32 v49, 0x7f, v49
	v_cndmask_b32_e32 v66, v68, v67, vcc
	v_not_b32_e32 v67, v54
	v_or_b32_e32 v68, 0x80000000, v54
	v_cmp_gt_i32_e32 vcc, 0, v54
	v_and_b32_e32 v66, 0xffffff80, v66
	v_sub_u32_e32 v66, v66, v20
	v_cndmask_b32_e32 v54, v68, v67, vcc
	v_cvt_f32_f16_sdwa v67, v55 dst_sel:DWORD dst_unused:UNUSED_PAD src0_sel:WORD_1
	v_cvt_f32_f16_e32 v55, v55
	v_and_b32_e32 v54, 0xffffff80, v54
	v_sub_u32_e32 v54, v54, v20
	v_not_b32_e32 v68, v67
	v_or_b32_e32 v69, 0x80000000, v67
	v_cmp_gt_i32_e32 vcc, 0, v67
	v_add_u32_e32 v66, 0x7e, v66
	v_add_u32_e32 v54, 0x7f, v54
	v_cndmask_b32_e32 v67, v69, v68, vcc
	v_not_b32_e32 v68, v55
	v_or_b32_e32 v69, 0x80000000, v55
	v_cmp_gt_i32_e32 vcc, 0, v55
	v_and_b32_e32 v67, 0xffffff80, v67
	v_sub_u32_e32 v67, v67, v21
	v_cndmask_b32_e32 v55, v69, v68, vcc
	v_cvt_f32_f16_sdwa v68, v56 dst_sel:DWORD dst_unused:UNUSED_PAD src0_sel:WORD_1
	v_cvt_f32_f16_e32 v56, v56
	v_and_b32_e32 v55, 0xffffff80, v55
	v_sub_u32_e32 v55, v55, v21
	v_not_b32_e32 v69, v68
	v_or_b32_e32 v70, 0x80000000, v68
	v_cmp_gt_i32_e32 vcc, 0, v68
	v_add_u32_e32 v67, 0x7e, v67
	v_add_u32_e32 v55, 0x7f, v55
	v_cndmask_b32_e32 v68, v70, v69, vcc
	v_not_b32_e32 v69, v56
	v_or_b32_e32 v70, 0x80000000, v56
	v_cmp_gt_i32_e32 vcc, 0, v56
	v_and_b32_e32 v68, 0xffffff80, v68
	v_sub_u32_e32 v68, v68, v22
	v_cndmask_b32_e32 v56, v70, v69, vcc
	v_cvt_f32_f16_sdwa v69, v57 dst_sel:DWORD dst_unused:UNUSED_PAD src0_sel:WORD_1
	v_cvt_f32_f16_e32 v57, v57
	v_and_b32_e32 v56, 0xffffff80, v56
	v_sub_u32_e32 v56, v56, v22
	v_not_b32_e32 v70, v69
	v_or_b32_e32 v71, 0x80000000, v69
	v_cmp_gt_i32_e32 vcc, 0, v69
	v_add_u32_e32 v68, 0x7e, v68
	v_add_u32_e32 v56, 0x7f, v56
	v_cndmask_b32_e32 v69, v71, v70, vcc
	v_not_b32_e32 v70, v57
	v_or_b32_e32 v71, 0x80000000, v57
	v_cmp_gt_i32_e32 vcc, 0, v57
	v_and_b32_e32 v69, 0xffffff80, v69
	v_sub_u32_e32 v69, v69, v23
	v_cndmask_b32_e32 v57, v71, v70, vcc
	v_cvt_f32_f16_sdwa v70, v0 dst_sel:DWORD dst_unused:UNUSED_PAD src0_sel:WORD_1
	v_cvt_f32_f16_e32 v0, v0
	v_and_b32_e32 v57, 0xffffff80, v57
	v_sub_u32_e32 v57, v57, v23
	v_not_b32_e32 v71, v70
	v_or_b32_e32 v72, 0x80000000, v70
	v_cmp_gt_i32_e32 vcc, 0, v70
	v_add_u32_e32 v69, 0x7e, v69
	v_add_u32_e32 v57, 0x7f, v57
	v_cndmask_b32_e32 v70, v72, v71, vcc
	v_not_b32_e32 v71, v0
	v_or_b32_e32 v72, 0x80000000, v0
	v_cmp_gt_i32_e32 vcc, 0, v0
	v_and_b32_e32 v70, 0xffffff80, v70
	v_sub_u32_e32 v70, v70, v24
	v_cndmask_b32_e32 v0, v72, v71, vcc
	v_cvt_f32_f16_sdwa v71, v1 dst_sel:DWORD dst_unused:UNUSED_PAD src0_sel:WORD_1
	v_cvt_f32_f16_e32 v1, v1
	v_and_b32_e32 v0, 0xffffff80, v0
	v_sub_u32_e32 v0, v0, v24
	v_not_b32_e32 v72, v71
	v_or_b32_e32 v73, 0x80000000, v71
	v_cmp_gt_i32_e32 vcc, 0, v71
	v_add_u32_e32 v70, 0x7e, v70
	v_add_u32_e32 v0, 0x7f, v0
	v_cndmask_b32_e32 v71, v73, v72, vcc
	v_not_b32_e32 v72, v1
	v_or_b32_e32 v73, 0x80000000, v1
	v_cmp_gt_i32_e32 vcc, 0, v1
	v_and_b32_e32 v71, 0xffffff80, v71
	v_sub_u32_e32 v71, v71, v25
	v_cndmask_b32_e32 v1, v73, v72, vcc
	v_cvt_f32_f16_sdwa v72, v2 dst_sel:DWORD dst_unused:UNUSED_PAD src0_sel:WORD_1
	v_cvt_f32_f16_e32 v2, v2
	v_and_b32_e32 v1, 0xffffff80, v1
	v_sub_u32_e32 v1, v1, v25
	v_not_b32_e32 v73, v72
	v_or_b32_e32 v74, 0x80000000, v72
	v_cmp_gt_i32_e32 vcc, 0, v72
	v_add_u32_e32 v71, 0x7e, v71
	v_add_u32_e32 v1, 0x7f, v1
	v_cndmask_b32_e32 v72, v74, v73, vcc
	v_not_b32_e32 v73, v2
	v_or_b32_e32 v74, 0x80000000, v2
	v_cmp_gt_i32_e32 vcc, 0, v2
	v_and_b32_e32 v72, 0xffffff80, v72
	v_sub_u32_e32 v72, v72, v26
	v_cndmask_b32_e32 v2, v74, v73, vcc
	v_cvt_f32_f16_sdwa v73, v3 dst_sel:DWORD dst_unused:UNUSED_PAD src0_sel:WORD_1
	v_cvt_f32_f16_e32 v3, v3
	v_and_b32_e32 v2, 0xffffff80, v2
	v_sub_u32_e32 v2, v2, v26
	v_not_b32_e32 v74, v73
	v_or_b32_e32 v75, 0x80000000, v73
	v_cmp_gt_i32_e32 vcc, 0, v73
	v_add_u32_e32 v72, 0x7e, v72
	v_add_u32_e32 v2, 0x7f, v2
	v_cndmask_b32_e32 v73, v75, v74, vcc
	v_not_b32_e32 v74, v3
	v_or_b32_e32 v75, 0x80000000, v3
	v_cmp_gt_i32_e32 vcc, 0, v3
	v_and_b32_e32 v73, 0xffffff80, v73
	v_sub_u32_e32 v73, v73, v28
	v_cndmask_b32_e32 v3, v75, v74, vcc
	v_and_b32_e32 v3, 0xffffff80, v3
	v_sub_u32_e32 v3, v3, v28
	v_add_u32_e32 v73, 0x7e, v73
	v_add_u32_e32 v3, 0x7f, v3
	v_max_u32_e32 v74, v50, v58
	v_min_u32_e32 v50, v50, v58
	v_max_u32_e32 v58, v59, v51
	v_min_u32_e32 v51, v59, v51
	v_max_u32_e32 v59, v52, v60
	v_min_u32_e32 v52, v52, v60
	v_max_u32_e32 v60, v61, v53
	v_min_u32_e32 v53, v61, v53
	v_max_u32_e32 v61, v46, v62
	v_min_u32_e32 v46, v46, v62
	v_max_u32_e32 v62, v63, v47
	v_min_u32_e32 v47, v63, v47
	v_max_u32_e32 v63, v48, v64
	v_min_u32_e32 v48, v48, v64
	v_max_u32_e32 v64, v65, v49
	v_min_u32_e32 v49, v65, v49
	v_max_u32_e32 v82, v54, v66
	v_min_u32_e32 v54, v54, v66
	v_max_u32_e32 v66, v67, v55
	v_min_u32_e32 v55, v67, v55
	v_max_u32_e32 v67, v56, v68
	v_min_u32_e32 v56, v56, v68
	v_max_u32_e32 v68, v69, v57
	v_min_u32_e32 v57, v69, v57
	v_max_u32_e32 v69, v0, v70
	v_min_u32_e32 v0, v0, v70
	v_max_u32_e32 v70, v71, v1
	v_min_u32_e32 v1, v71, v1
	v_max_u32_e32 v71, v2, v72
	v_min_u32_e32 v2, v2, v72
	v_max_u32_e32 v72, v73, v3
	v_min_u32_e32 v3, v73, v3
	v_max_u32_e32 v65, v74, v51
	v_min_u32_e32 v51, v74, v51
	v_max_u32_e32 v74, v50, v58
	v_min_u32_e32 v50, v50, v58
	v_max_u32_e32 v58, v53, v59
	v_min_u32_e32 v53, v53, v59
	v_max_u32_e32 v59, v60, v52
	v_min_u32_e32 v52, v60, v52
; #define CE_DESC(a, b) do { const unsigned _mx = (a) > (b) ? (a) : (b), _mn = (a) > (b) ? (b) : (a); (a) = _mx; (b) = _mn; } while (0)
; __device__ __forceinline__ void sort16_desc(unsigned (&k)[16]) {
; #pragma unroll
;     for (int size = 2; size <= 16; size <<= 1)
; #pragma unroll
;         for (int stride = size >> 1; stride > 0; stride >>= 1)
; #pragma unroll
;             for (int i = 0; i < 16; ++i) { const int j = i ^ stride;
;                 if (j > i) { if ((i & size) == 0) CE_DESC(k[i], k[j]); else CE_DESC(k[j], k[i]); } }
; }
	v_max_u32_e32 v60, v61, v47
	v_min_u32_e32 v47, v61, v47
	v_max_u32_e32 v61, v46, v62
	v_min_u32_e32 v46, v46, v62
	v_max_u32_e32 v62, v49, v63
	v_min_u32_e32 v49, v49, v63
	v_max_u32_e32 v63, v64, v48
	v_min_u32_e32 v48, v64, v48
	v_max_u32_e32 v73, v82, v55
	v_min_u32_e32 v55, v82, v55
	v_max_u32_e32 v82, v54, v66
	v_min_u32_e32 v54, v54, v66
	v_max_u32_e32 v66, v57, v67
	v_min_u32_e32 v57, v57, v67
	v_max_u32_e32 v67, v68, v56
	v_min_u32_e32 v56, v68, v56
	v_max_u32_e32 v68, v69, v1
	v_min_u32_e32 v1, v69, v1
	v_max_u32_e32 v69, v0, v70
	v_min_u32_e32 v0, v0, v70
	v_max_u32_e32 v70, v3, v71
	v_min_u32_e32 v3, v3, v71
	v_max_u32_e32 v71, v72, v2
	v_min_u32_e32 v2, v72, v2
	v_max_u32_e32 v64, v65, v74
	v_min_u32_e32 v65, v65, v74
	v_max_u32_e32 v74, v51, v50
	v_min_u32_e32 v50, v51, v50
	v_max_u32_e32 v51, v52, v53
	v_min_u32_e32 v52, v52, v53
	v_max_u32_e32 v53, v59, v58
	v_min_u32_e32 v58, v59, v58
	v_max_u32_e32 v59, v60, v61
	v_min_u32_e32 v60, v60, v61
	v_max_u32_e32 v61, v47, v46
	v_min_u32_e32 v46, v47, v46
	v_max_u32_e32 v47, v48, v49
	v_min_u32_e32 v48, v48, v49
	v_max_u32_e32 v49, v63, v62
	v_min_u32_e32 v62, v63, v62
	v_max_u32_e32 v72, v73, v82
	v_min_u32_e32 v73, v73, v82
	v_max_u32_e32 v82, v55, v54
	v_min_u32_e32 v54, v55, v54
	v_max_u32_e32 v55, v56, v57
	v_min_u32_e32 v56, v56, v57
	v_max_u32_e32 v57, v67, v66
	v_min_u32_e32 v66, v67, v66
	v_max_u32_e32 v67, v68, v69
	v_min_u32_e32 v68, v68, v69
	v_max_u32_e32 v69, v1, v0
	v_min_u32_e32 v0, v1, v0
	v_max_u32_e32 v1, v2, v3
	v_min_u32_e32 v2, v2, v3
	v_max_u32_e32 v3, v71, v70
	v_min_u32_e32 v70, v71, v70
	v_max_u32_e32 v63, v64, v52
	v_min_u32_e32 v52, v64, v52
	v_max_u32_e32 v64, v65, v51
	v_min_u32_e32 v51, v65, v51
	v_max_u32_e32 v65, v74, v58
	v_min_u32_e32 v58, v74, v58
	v_max_u32_e32 v74, v50, v53
	v_min_u32_e32 v50, v50, v53
	v_max_u32_e32 v53, v48, v59
	v_min_u32_e32 v48, v48, v59
	v_max_u32_e32 v59, v47, v60
	v_min_u32_e32 v47, v47, v60
	v_max_u32_e32 v60, v62, v61
	v_min_u32_e32 v61, v62, v61
	v_max_u32_e32 v62, v49, v46
	v_min_u32_e32 v46, v49, v46
	v_max_u32_e32 v71, v72, v56
	v_min_u32_e32 v56, v72, v56
	v_max_u32_e32 v72, v73, v55
	v_min_u32_e32 v55, v73, v55
	v_max_u32_e32 v73, v82, v66
	v_min_u32_e32 v66, v82, v66
	v_max_u32_e32 v82, v54, v57
	v_min_u32_e32 v54, v54, v57
	v_max_u32_e32 v57, v2, v67
	v_min_u32_e32 v2, v2, v67
	v_max_u32_e32 v67, v1, v68
	v_min_u32_e32 v1, v1, v68
	v_max_u32_e32 v68, v70, v69
	v_min_u32_e32 v69, v70, v69
	v_max_u32_e32 v70, v3, v0
	v_min_u32_e32 v0, v3, v0
	v_max_u32_e32 v49, v63, v65
	v_min_u32_e32 v63, v63, v65
	v_max_u32_e32 v65, v64, v74
	v_min_u32_e32 v64, v64, v74
	v_max_u32_e32 v74, v52, v58
	v_min_u32_e32 v52, v52, v58
	v_max_u32_e32 v58, v51, v50
	v_min_u32_e32 v50, v51, v50
	v_max_u32_e32 v51, v61, v48
	v_min_u32_e32 v48, v61, v48
	v_max_u32_e32 v61, v46, v47
	v_min_u32_e32 v46, v46, v47
	v_max_u32_e32 v47, v60, v53
	v_min_u32_e32 v53, v60, v53
	v_max_u32_e32 v60, v62, v59
	v_min_u32_e32 v59, v62, v59
	v_max_u32_e32 v3, v71, v73
	v_min_u32_e32 v71, v71, v73
	v_max_u32_e32 v73, v72, v82
	v_min_u32_e32 v72, v72, v82
	v_max_u32_e32 v82, v56, v66
	v_min_u32_e32 v56, v56, v66
	v_max_u32_e32 v66, v55, v54
	v_min_u32_e32 v54, v55, v54
	v_max_u32_e32 v55, v69, v2
	v_min_u32_e32 v2, v69, v2
	v_max_u32_e32 v69, v0, v1
	v_min_u32_e32 v0, v0, v1
	v_max_u32_e32 v1, v68, v57
	v_min_u32_e32 v57, v68, v57
	v_max_u32_e32 v68, v70, v67
	v_min_u32_e32 v67, v70, v67
	v_max_u32_e32 v62, v49, v65
	v_min_u32_e32 v49, v49, v65
	v_max_u32_e32 v65, v63, v64
	v_min_u32_e32 v63, v63, v64
	v_max_u32_e32 v64, v74, v58
	v_min_u32_e32 v58, v74, v58
	v_max_u32_e32 v74, v52, v50
	v_min_u32_e32 v50, v52, v50
	v_max_u32_e32 v52, v46, v48
	v_min_u32_e32 v46, v46, v48
	v_max_u32_e32 v48, v61, v51
	v_min_u32_e32 v51, v61, v51
	v_max_u32_e32 v61, v59, v53
	v_min_u32_e32 v53, v59, v53
	v_max_u32_e32 v59, v60, v47
	v_min_u32_e32 v47, v60, v47
	v_max_u32_e32 v70, v3, v73
	v_min_u32_e32 v3, v3, v73
	v_max_u32_e32 v73, v71, v72
	v_min_u32_e32 v71, v71, v72
	v_max_u32_e32 v72, v82, v66
	v_min_u32_e32 v66, v82, v66
	v_max_u32_e32 v82, v56, v54
	v_min_u32_e32 v54, v56, v54
	v_max_u32_e32 v56, v0, v2
	v_min_u32_e32 v0, v0, v2
	v_max_u32_e32 v2, v69, v55
	v_min_u32_e32 v55, v69, v55
	v_max_u32_e32 v69, v67, v57
	v_min_u32_e32 v57, v67, v57
	v_max_u32_e32 v67, v68, v1
	v_min_u32_e32 v1, v68, v1
	v_max_u32_e32 v60, v62, v46
	v_min_u32_e32 v46, v62, v46
	v_max_u32_e32 v62, v49, v52
	v_min_u32_e32 v49, v49, v52
	v_max_u32_e32 v52, v65, v51
	v_min_u32_e32 v51, v65, v51
	v_max_u32_e32 v65, v63, v48
	v_min_u32_e32 v48, v63, v48
	v_max_u32_e32 v63, v64, v53
	v_min_u32_e32 v53, v64, v53
	v_max_u32_e32 v64, v58, v61
	v_min_u32_e32 v58, v58, v61
	v_max_u32_e32 v61, v74, v47
	v_min_u32_e32 v47, v74, v47
	v_max_u32_e32 v74, v50, v59
	v_min_u32_e32 v50, v50, v59
	v_max_u32_e32 v68, v70, v0
	v_min_u32_e32 v0, v70, v0
	v_max_u32_e32 v70, v3, v56
	v_min_u32_e32 v3, v3, v56
	v_max_u32_e32 v56, v73, v55
	v_min_u32_e32 v55, v73, v55
	v_max_u32_e32 v73, v71, v2
	v_min_u32_e32 v2, v71, v2
	v_max_u32_e32 v71, v72, v57
	v_min_u32_e32 v57, v72, v57
	v_max_u32_e32 v72, v66, v69
	v_min_u32_e32 v66, v66, v69
	v_max_u32_e32 v69, v82, v1
	v_min_u32_e32 v1, v82, v1
	v_max_u32_e32 v82, v54, v67
	v_min_u32_e32 v54, v54, v67
	v_max_u32_e32 v59, v60, v63
	v_min_u32_e32 v60, v60, v63
	v_max_u32_e32 v63, v62, v64
	v_min_u32_e32 v62, v62, v64
	v_max_u32_e32 v64, v52, v61
	v_min_u32_e32 v52, v52, v61
	v_max_u32_e32 v61, v65, v74
	v_min_u32_e32 v65, v65, v74
	v_max_u32_e32 v74, v46, v53
	v_min_u32_e32 v46, v46, v53
	v_max_u32_e32 v53, v49, v58
	v_min_u32_e32 v49, v49, v58
	v_max_u32_e32 v58, v51, v47
; #define CE_DESC(a, b) do { const unsigned _mx = (a) > (b) ? (a) : (b), _mn = (a) > (b) ? (b) : (a); (a) = _mx; (b) = _mn; } while (0)
; __device__ __forceinline__ void merge16(unsigned (&a)[16], const unsigned (&b)[16]) {
; #pragma unroll
;     for (int i = 0; i < 16; ++i) a[i] = a[i] > b[15 - i] ? a[i] : b[15 - i];
; #pragma unroll
;     for (int stride = 8; stride > 0; stride >>= 1)
; #pragma unroll
;         for (int i = 0; i < 16; ++i) { const int j = i ^ stride; if (j > i) CE_DESC(a[i], a[j]); }
; }
; __device__ __forceinline__ void peer_tile(const Args& A, LAS unsigned char* lds, int tile) {
;     ...
;                 sort16_desc(k0); sort16_desc(k1); merge16(k0, k1);
; #pragma unroll
;                 for (int msk = 16; msk <= 32; msk <<= 1) {
; #pragma unroll
;                     for (int i = 0; i < 16; ++i) k1[i] = (unsigned)__shfl_xor((int)k0[i], msk);
;                     merge16(k0, k1); }
	v_min_u32_e32 v47, v51, v47
	v_max_u32_e32 v51, v48, v50
	v_min_u32_e32 v48, v48, v50
	v_max_u32_e32 v67, v68, v71
	v_min_u32_e32 v68, v68, v71
	v_max_u32_e32 v71, v70, v72
	v_min_u32_e32 v70, v70, v72
	v_max_u32_e32 v72, v56, v69
	v_min_u32_e32 v56, v56, v69
	v_max_u32_e32 v69, v73, v82
	v_min_u32_e32 v73, v73, v82
	v_max_u32_e32 v82, v0, v57
	v_min_u32_e32 v0, v0, v57
	v_max_u32_e32 v57, v3, v66
	v_min_u32_e32 v3, v3, v66
	v_max_u32_e32 v66, v55, v1
	v_min_u32_e32 v1, v55, v1
	v_max_u32_e32 v55, v2, v54
	v_min_u32_e32 v2, v2, v54
	v_max_u32_e32 v50, v59, v64
	v_min_u32_e32 v59, v59, v64
	v_max_u32_e32 v64, v63, v61
	v_min_u32_e32 v61, v63, v61
	v_max_u32_e32 v63, v60, v52
	v_min_u32_e32 v52, v60, v52
	v_max_u32_e32 v60, v62, v65
	v_min_u32_e32 v62, v62, v65
	v_max_u32_e32 v65, v74, v58
	v_min_u32_e32 v58, v74, v58
	v_max_u32_e32 v74, v53, v51
	v_min_u32_e32 v51, v53, v51
	v_max_u32_e32 v53, v46, v47
	v_min_u32_e32 v46, v46, v47
	v_max_u32_e32 v47, v49, v48
	v_min_u32_e32 v48, v49, v48
	v_max_u32_e32 v54, v67, v72
	v_min_u32_e32 v67, v67, v72
	v_max_u32_e32 v72, v71, v69
	v_min_u32_e32 v69, v71, v69
	v_max_u32_e32 v71, v68, v56
	v_min_u32_e32 v56, v68, v56
	v_max_u32_e32 v68, v70, v73
	v_min_u32_e32 v70, v70, v73
	v_max_u32_e32 v73, v82, v66
	v_min_u32_e32 v66, v82, v66
	v_max_u32_e32 v82, v57, v55
	v_min_u32_e32 v55, v57, v55
	v_max_u32_e32 v57, v0, v1
	v_min_u32_e32 v0, v0, v1
	v_max_u32_e32 v1, v3, v2
	v_min_u32_e32 v2, v3, v2
	v_min_u32_e32 v49, v50, v64
	v_min_u32_e32 v75, v59, v61
	v_min_u32_e32 v76, v63, v60
	v_min_u32_e32 v77, v52, v62
	v_min_u32_e32 v78, v65, v74
	v_min_u32_e32 v79, v58, v51
	v_min_u32_e32 v80, v53, v47
	v_min_u32_e32 v81, v46, v48
	v_min_u32_e32 v3, v54, v72
	v_min_u32_e32 v83, v67, v69
	v_min_u32_e32 v84, v71, v68
	v_min_u32_e32 v85, v56, v70
	v_min_u32_e32 v86, v73, v82
	v_min_u32_e32 v87, v66, v55
	v_min_u32_e32 v88, v57, v1
	v_min_u32_e32 v89, v0, v2
	v_max3_u32 v50, v50, v64, v89
	v_max3_u32 v0, v49, v0, v2
	v_max3_u32 v2, v59, v61, v88
	v_max3_u32 v1, v75, v57, v1
	v_max3_u32 v49, v63, v60, v87
	v_max3_u32 v55, v76, v66, v55
	v_max3_u32 v52, v52, v62, v86
	v_max3_u32 v57, v77, v73, v82
	v_max3_u32 v59, v65, v74, v85
	v_max3_u32 v56, v78, v56, v70
	v_max3_u32 v51, v58, v51, v84
	v_max3_u32 v58, v79, v71, v68
	v_max3_u32 v47, v53, v47, v83
	v_max3_u32 v53, v80, v67, v69
	v_max3_u32 v3, v46, v48, v3
	v_max3_u32 v46, v81, v54, v72
	v_max_u32_e32 v48, v50, v59
	v_min_u32_e32 v50, v50, v59
	v_max_u32_e32 v54, v0, v56
	v_min_u32_e32 v0, v0, v56
	v_max_u32_e32 v56, v2, v51
	v_min_u32_e32 v2, v2, v51
	v_max_u32_e32 v51, v1, v58
	v_min_u32_e32 v1, v1, v58
	v_max_u32_e32 v58, v49, v47
	v_min_u32_e32 v47, v49, v47
	v_max_u32_e32 v49, v55, v53
	v_min_u32_e32 v53, v55, v53
	v_max_u32_e32 v55, v52, v3
	v_min_u32_e32 v3, v52, v3
	v_max_u32_e32 v52, v57, v46
	v_min_u32_e32 v46, v57, v46
	v_max_u32_e32 v57, v48, v58
	v_min_u32_e32 v48, v48, v58
	v_max_u32_e32 v58, v54, v49
	v_min_u32_e32 v49, v54, v49
	v_max_u32_e32 v54, v56, v55
	v_min_u32_e32 v55, v56, v55
	v_max_u32_e32 v56, v51, v52
	v_min_u32_e32 v51, v51, v52
	v_max_u32_e32 v52, v50, v47
	v_min_u32_e32 v47, v50, v47
	v_max_u32_e32 v50, v0, v53
	v_min_u32_e32 v0, v0, v53
	v_max_u32_e32 v53, v2, v3
	v_min_u32_e32 v2, v2, v3
	v_max_u32_e32 v3, v1, v46
	v_min_u32_e32 v1, v1, v46
	v_max_u32_e32 v46, v57, v54
	v_min_u32_e32 v54, v57, v54
	v_max_u32_e32 v57, v58, v56
	v_min_u32_e32 v56, v58, v56
	v_max_u32_e32 v58, v48, v55
	v_min_u32_e32 v48, v48, v55
	v_max_u32_e32 v55, v49, v51
	v_min_u32_e32 v49, v49, v51
	v_max_u32_e32 v51, v52, v53
	v_min_u32_e32 v52, v52, v53
	v_max_u32_e32 v53, v50, v3
	v_min_u32_e32 v3, v50, v3
	v_max_u32_e32 v50, v47, v2
	v_min_u32_e32 v2, v47, v2
	v_max_u32_e32 v47, v0, v1
	v_min_u32_e32 v0, v0, v1
	v_max_u32_e32 v1, v46, v57
	v_min_u32_e32 v46, v46, v57
	v_max_u32_e32 v57, v54, v56
	v_min_u32_e32 v54, v54, v56
	v_max_u32_e32 v56, v58, v55
	v_min_u32_e32 v55, v58, v55
	v_max_u32_e32 v58, v48, v49
	v_min_u32_e32 v48, v48, v49
	v_max_u32_e32 v49, v51, v53
	v_min_u32_e32 v51, v51, v53
	v_max_u32_e32 v53, v52, v3
	v_min_u32_e32 v3, v52, v3
	v_max_u32_e32 v52, v50, v47
	v_min_u32_e32 v47, v50, v47
	v_max_u32_e32 v50, v2, v0
	v_min_u32_e32 v0, v2, v0
	ds_bpermute_b32 v2, v27, v1
	ds_bpermute_b32 v59, v27, v46
	ds_bpermute_b32 v60, v27, v57
	ds_bpermute_b32 v61, v27, v54
	ds_bpermute_b32 v62, v27, v56
	ds_bpermute_b32 v63, v27, v55
	ds_bpermute_b32 v64, v27, v58
	ds_bpermute_b32 v65, v27, v48
	ds_bpermute_b32 v66, v27, v49
	ds_bpermute_b32 v67, v27, v51
	ds_bpermute_b32 v68, v27, v53
	ds_bpermute_b32 v69, v27, v0
	ds_bpermute_b32 v70, v27, v50
	ds_bpermute_b32 v71, v27, v47
	ds_bpermute_b32 v72, v27, v52
	ds_bpermute_b32 v73, v27, v3
	s_waitcnt lgkmcnt(4)
	v_max_u32_e32 v1, v1, v69
	s_waitcnt lgkmcnt(3)
	v_max_u32_e32 v46, v46, v70
	s_waitcnt lgkmcnt(2)
	v_max_u32_e32 v57, v57, v71
	s_waitcnt lgkmcnt(1)
	v_max_u32_e32 v54, v54, v72
	s_waitcnt lgkmcnt(0)
; __device__ __forceinline__ void peer_tile(const Args& A, LAS unsigned char* lds, int tile) {
;     ...
;                 { const bf16_t* sp = QRY + m * 2048 + hp * 128 + 32 * g;
;                   const u32x4 s0 = *(const u32x4*)sp, s1 = *(const u32x4*)(sp + 8), s2 = *(const u32x4*)(sp + 16), s3 = *(const u32x4*)(sp + 24);
;     ...
;                 for (int msk = 16; msk <= 32; msk <<= 1) {
; #pragma unroll
;                     for (int i = 0; i < 16; ++i) k1[i] = (unsigned)__shfl_xor((int)k0[i], msk);
;                     merge16(k0, k1); }
	v_max_u32_e32 v56, v56, v73
	v_max_u32_e32 v55, v55, v68
	v_max_u32_e32 v58, v58, v67
	v_max_u32_e32 v48, v48, v66
	v_max_u32_e32 v49, v49, v65
	v_max_u32_e32 v51, v51, v64
	v_max_u32_e32 v53, v53, v63
	v_max_u32_e32 v3, v3, v62
	v_max_u32_e32 v52, v52, v61
	v_max_u32_e32 v47, v47, v60
	v_max_u32_e32 v50, v50, v59
	v_max_u32_e32 v0, v0, v2
	v_max_u32_e32 v2, v1, v49
	v_min_u32_e32 v1, v1, v49
	v_max_u32_e32 v49, v46, v51
	v_min_u32_e32 v46, v46, v51
	v_max_u32_e32 v51, v57, v53
	v_min_u32_e32 v53, v57, v53
	v_max_u32_e32 v57, v54, v3
	v_min_u32_e32 v3, v54, v3
	v_max_u32_e32 v54, v56, v52
	v_min_u32_e32 v52, v56, v52
	v_max_u32_e32 v56, v55, v47
	v_min_u32_e32 v47, v55, v47
	v_max_u32_e32 v55, v58, v50
	v_min_u32_e32 v50, v58, v50
	v_max_u32_e32 v58, v48, v0
	v_min_u32_e32 v0, v48, v0
	v_max_u32_e32 v48, v2, v54
	v_min_u32_e32 v2, v2, v54
	v_max_u32_e32 v54, v49, v56
	v_min_u32_e32 v49, v49, v56
	v_max_u32_e32 v56, v51, v55
	v_min_u32_e32 v51, v51, v55
	v_max_u32_e32 v55, v57, v58
	v_min_u32_e32 v57, v57, v58
	v_max_u32_e32 v58, v1, v52
	v_min_u32_e32 v1, v1, v52
	v_max_u32_e32 v52, v46, v47
	v_min_u32_e32 v46, v46, v47
	v_max_u32_e32 v47, v53, v50
	v_min_u32_e32 v50, v53, v50
	v_max_u32_e32 v53, v3, v0
	v_min_u32_e32 v0, v3, v0
	v_max_u32_e32 v3, v48, v56
	v_min_u32_e32 v48, v48, v56
	v_max_u32_e32 v56, v54, v55
	v_min_u32_e32 v54, v54, v55
	v_max_u32_e32 v55, v2, v51
	v_min_u32_e32 v2, v2, v51
	v_max_u32_e32 v51, v49, v57
	v_min_u32_e32 v49, v49, v57
	v_max_u32_e32 v57, v58, v47
	v_min_u32_e32 v47, v58, v47
	v_max_u32_e32 v58, v52, v53
	v_min_u32_e32 v52, v52, v53
	v_max_u32_e32 v53, v1, v50
	v_min_u32_e32 v1, v1, v50
	v_max_u32_e32 v50, v46, v0
	v_min_u32_e32 v0, v46, v0
	v_max_u32_e32 v46, v3, v56
	v_min_u32_e32 v3, v3, v56
	v_max_u32_e32 v56, v48, v54
	v_min_u32_e32 v48, v48, v54
	v_max_u32_e32 v54, v55, v51
	v_min_u32_e32 v51, v55, v51
	v_max_u32_e32 v55, v2, v49
	v_min_u32_e32 v2, v2, v49
	v_max_u32_e32 v49, v57, v58
	v_min_u32_e32 v57, v57, v58
	v_max_u32_e32 v58, v47, v52
	v_min_u32_e32 v47, v47, v52
	v_max_u32_e32 v52, v53, v50
	v_min_u32_e32 v50, v53, v50
	v_max_u32_e32 v53, v1, v0
	v_min_u32_e32 v0, v1, v0
	ds_bpermute_b32 v62, v29, v0
	ds_bpermute_b32 v1, v29, v46
	ds_bpermute_b32 v59, v29, v3
	ds_bpermute_b32 v60, v29, v56
	ds_bpermute_b32 v61, v29, v48
	s_waitcnt lgkmcnt(4)
	v_max_u32_e32 v46, v46, v62
	global_load_dwordx4 v[62:65], v[4:5], off offset:528
	global_load_dwordx4 v[66:69], v[4:5], off offset:512
	ds_bpermute_b32 v70, v29, v54
	ds_bpermute_b32 v71, v29, v51
	ds_bpermute_b32 v72, v29, v55
	ds_bpermute_b32 v73, v29, v2
	ds_bpermute_b32 v74, v29, v49
	ds_bpermute_b32 v75, v29, v57
	ds_bpermute_b32 v76, v29, v58
	ds_bpermute_b32 v77, v29, v47
	ds_bpermute_b32 v78, v29, v52
	ds_bpermute_b32 v79, v29, v53
	ds_bpermute_b32 v80, v29, v50
	s_waitcnt lgkmcnt(4)
	v_max_u32_e32 v51, v51, v76
	s_waitcnt lgkmcnt(3)
	v_max_u32_e32 v54, v54, v77
	s_waitcnt lgkmcnt(2)
	v_max_u32_e32 v48, v48, v78
	s_waitcnt lgkmcnt(1)
	v_max_u32_e32 v3, v3, v79
	s_waitcnt lgkmcnt(0)
	v_max_u32_e32 v56, v56, v80
	v_max_u32_e32 v55, v55, v75
	v_max_u32_e32 v2, v2, v74
	v_max_u32_e32 v49, v49, v73
	v_max_u32_e32 v57, v57, v72
	v_max_u32_e32 v58, v58, v71
	v_max_u32_e32 v47, v47, v70
	v_max_u32_e32 v52, v52, v61
	v_max_u32_e32 v50, v50, v60
	v_max_u32_e32 v53, v53, v59
	v_max_u32_e32 v0, v0, v1
	v_max_u32_e32 v1, v46, v49
	v_min_u32_e32 v46, v46, v49
	v_max_u32_e32 v49, v3, v57
	v_min_u32_e32 v3, v3, v57
	v_max_u32_e32 v57, v56, v58
	v_min_u32_e32 v56, v56, v58
	v_max_u32_e32 v58, v48, v47
	v_min_u32_e32 v47, v48, v47
	v_max_u32_e32 v48, v54, v52
	v_min_u32_e32 v52, v54, v52
	v_max_u32_e32 v54, v51, v50
	v_min_u32_e32 v50, v51, v50
	v_max_u32_e32 v51, v55, v53
	v_min_u32_e32 v53, v55, v53
	v_max_u32_e32 v55, v2, v0
	v_min_u32_e32 v0, v2, v0
	v_max_u32_e32 v2, v1, v48
	v_min_u32_e32 v1, v1, v48
	v_max_u32_e32 v48, v49, v54
	v_min_u32_e32 v49, v49, v54
	v_max_u32_e32 v54, v57, v51
	v_min_u32_e32 v51, v57, v51
	v_max_u32_e32 v57, v58, v55
	v_min_u32_e32 v55, v58, v55
	v_max_u32_e32 v58, v46, v52
	v_min_u32_e32 v46, v46, v52
	v_max_u32_e32 v52, v3, v50
	v_min_u32_e32 v3, v3, v50
	v_max_u32_e32 v50, v56, v53
	v_min_u32_e32 v53, v56, v53
	v_max_u32_e32 v56, v47, v0
	v_min_u32_e32 v0, v47, v0
	v_max_u32_e32 v47, v2, v54
	v_min_u32_e32 v2, v2, v54
	v_max_u32_e32 v54, v48, v57
	v_min_u32_e32 v48, v48, v57
	v_max_u32_e32 v70, v1, v51
	v_min_u32_e32 v1, v1, v51
	v_max_u32_e32 v51, v49, v55
	v_min_u32_e32 v49, v49, v55
	v_max_u32_e32 v71, v58, v50
	v_min_u32_e32 v50, v58, v50
	v_max_u32_e32 v72, v52, v56
	v_min_u32_e32 v73, v52, v56
	v_max_u32_e32 v74, v46, v53
	v_min_u32_e32 v46, v46, v53
	v_max_u32_e32 v75, v3, v0
	v_min_u32_e32 v0, v3, v0
	v_max_u32_e32 v61, v47, v54
	v_min_u32_e32 v60, v47, v54
	v_max_u32_e32 v59, v2, v48
	v_min_u32_e32 v58, v2, v48
	v_max_u32_e32 v57, v70, v51
	v_min_u32_e32 v56, v70, v51
	v_max_u32_e32 v55, v1, v49
	v_min_u32_e32 v54, v1, v49
	v_max_u32_e32 v53, v71, v72
	v_min_u32_e32 v52, v71, v72
	v_max_u32_e32 v51, v50, v73
	v_min_u32_e32 v50, v50, v73
	v_max_u32_e32 v47, v46, v0
	v_min_u32_e32 v46, v46, v0
	global_load_dwordx4 v[0:3], v[4:5], off offset:560
	global_load_dwordx4 v[70:73], v[4:5], off offset:544
	v_max_u32_e32 v49, v74, v75
	v_min_u32_e32 v48, v74, v75
	s_waitcnt vmcnt(2)
; __device__ __forceinline__ unsigned f2key(float f) { const unsigned u = __float_as_uint(f); return (u & 0x80000000u) ? ~u : (u | 0x80000000u); }
; __device__ __forceinline__ void peer_tile(const Args& A, LAS unsigned char* lds, int tile) {
;     ...
;                 { const bf16_t* sp = QRY + m * 2048 + hp * 128 + 32 * g;
;                   const u32x4 s0 = *(const u32x4*)sp, s1 = *(const u32x4*)(sp + 8), s2 = *(const u32x4*)(sp + 16), s3 = *(const u32x4*)(sp + 24);
;                   const unsigned sw[16] = {s0.x, s0.y, s0.z, s0.w, s1.x, s1.y, s1.z, s1.w, s2.x, s2.y, s2.z, s2.w, s3.x, s3.y, s3.z, s3.w};
; #pragma unroll
;                   for (int i = 0; i < 16; ++i) {
;                       const float lo = (float)__builtin_bit_cast(_Float16, (unsigned short)(sw[i] & 0xffffu)), hi = (float)__builtin_bit_cast(_Float16, (unsigned short)(sw[i] >> 16));
;                       const unsigned klo = (f2key(lo) & ~127u) | (unsigned)(127 - (32 * g + 2 * i)), khi = (f2key(hi) & ~127u) | (unsigned)(127 - (32 * g + 2 * i + 1));
;                       if (i < 8) { k0[2 * i] = klo; k0[2 * i + 1] = khi; } else { k1[2 * (i - 8)] = klo; k1[2 * (i - 8) + 1] = khi; } } }
	v_cvt_f32_f16_sdwa v74, v66 dst_sel:DWORD dst_unused:UNUSED_PAD src0_sel:WORD_1
	v_cvt_f32_f16_e32 v66, v66
	v_not_b32_e32 v75, v74
	v_or_b32_e32 v76, 0x80000000, v74
	v_cmp_gt_i32_e32 vcc, 0, v74
	s_nop 1
	v_cndmask_b32_e32 v74, v76, v75, vcc
	v_not_b32_e32 v75, v66
	v_or_b32_e32 v76, 0x80000000, v66
	v_cmp_gt_i32_e32 vcc, 0, v66
	v_and_b32_e32 v74, 0xffffff80, v74
	v_sub_u32_e32 v74, v74, v15
	v_cndmask_b32_e32 v66, v76, v75, vcc
	v_cvt_f32_f16_sdwa v75, v67 dst_sel:DWORD dst_unused:UNUSED_PAD src0_sel:WORD_1
	v_cvt_f32_f16_e32 v67, v67
	v_and_b32_e32 v66, 0xffffff80, v66
	v_sub_u32_e32 v66, v66, v15
	v_not_b32_e32 v76, v75
	v_or_b32_e32 v77, 0x80000000, v75
	v_cmp_gt_i32_e32 vcc, 0, v75
	v_add_u32_e32 v74, 0x7e, v74
	v_add_u32_e32 v66, 0x7f, v66
	v_cndmask_b32_e32 v75, v77, v76, vcc
	v_not_b32_e32 v76, v67
	v_or_b32_e32 v77, 0x80000000, v67
	v_cmp_gt_i32_e32 vcc, 0, v67
	v_and_b32_e32 v75, 0xffffff80, v75
	v_sub_u32_e32 v75, v75, v14
	v_cndmask_b32_e32 v67, v77, v76, vcc
	v_cvt_f32_f16_sdwa v76, v68 dst_sel:DWORD dst_unused:UNUSED_PAD src0_sel:WORD_1
	v_cvt_f32_f16_e32 v68, v68
	v_and_b32_e32 v67, 0xffffff80, v67
	v_sub_u32_e32 v67, v67, v14
	v_not_b32_e32 v77, v76
	v_or_b32_e32 v78, 0x80000000, v76
	v_cmp_gt_i32_e32 vcc, 0, v76
	v_add_u32_e32 v75, 0x7e, v75
	v_add_u32_e32 v67, 0x7f, v67
	v_cndmask_b32_e32 v76, v78, v77, vcc
	v_not_b32_e32 v77, v68
	v_or_b32_e32 v78, 0x80000000, v68
	v_cmp_gt_i32_e32 vcc, 0, v68
	v_and_b32_e32 v76, 0xffffff80, v76
	v_sub_u32_e32 v76, v76, v12
	v_cndmask_b32_e32 v68, v78, v77, vcc
	v_cvt_f32_f16_sdwa v77, v69 dst_sel:DWORD dst_unused:UNUSED_PAD src0_sel:WORD_1
	v_cvt_f32_f16_e32 v69, v69
	v_and_b32_e32 v68, 0xffffff80, v68
	v_sub_u32_e32 v68, v68, v12
	v_not_b32_e32 v78, v77
	v_or_b32_e32 v79, 0x80000000, v77
	v_cmp_gt_i32_e32 vcc, 0, v77
	v_add_u32_e32 v76, 0x7e, v76
	v_add_u32_e32 v68, 0x7f, v68
	v_cndmask_b32_e32 v77, v79, v78, vcc
	v_not_b32_e32 v78, v69
	v_or_b32_e32 v79, 0x80000000, v69
	v_cmp_gt_i32_e32 vcc, 0, v69
	v_and_b32_e32 v77, 0xffffff80, v77
	v_sub_u32_e32 v77, v77, v10
	v_cndmask_b32_e32 v69, v79, v78, vcc
	v_cvt_f32_f16_sdwa v78, v62 dst_sel:DWORD dst_unused:UNUSED_PAD src0_sel:WORD_1
	v_cvt_f32_f16_e32 v62, v62
	v_and_b32_e32 v69, 0xffffff80, v69
	v_sub_u32_e32 v69, v69, v10
	v_not_b32_e32 v79, v78
	v_or_b32_e32 v80, 0x80000000, v78
	v_cmp_gt_i32_e32 vcc, 0, v78
	v_add_u32_e32 v77, 0x7e, v77
	v_add_u32_e32 v69, 0x7f, v69
	v_cndmask_b32_e32 v78, v80, v79, vcc
	v_not_b32_e32 v79, v62
	v_or_b32_e32 v80, 0x80000000, v62
	v_cmp_gt_i32_e32 vcc, 0, v62
	v_and_b32_e32 v78, 0xffffff80, v78
	v_sub_u32_e32 v78, v78, v8
	v_cndmask_b32_e32 v62, v80, v79, vcc
	v_cvt_f32_f16_sdwa v79, v63 dst_sel:DWORD dst_unused:UNUSED_PAD src0_sel:WORD_1
	v_cvt_f32_f16_e32 v63, v63
	v_and_b32_e32 v62, 0xffffff80, v62
	v_sub_u32_e32 v62, v62, v8
	v_not_b32_e32 v80, v79
	v_or_b32_e32 v81, 0x80000000, v79
	v_cmp_gt_i32_e32 vcc, 0, v79
	v_add_u32_e32 v78, 0x7e, v78
	v_add_u32_e32 v62, 0x7f, v62
	v_cndmask_b32_e32 v79, v81, v80, vcc
	v_not_b32_e32 v80, v63
	v_or_b32_e32 v81, 0x80000000, v63
	v_cmp_gt_i32_e32 vcc, 0, v63
	v_and_b32_e32 v79, 0xffffff80, v79
	v_sub_u32_e32 v79, v79, v16
	v_cndmask_b32_e32 v63, v81, v80, vcc
	v_cvt_f32_f16_sdwa v80, v64 dst_sel:DWORD dst_unused:UNUSED_PAD src0_sel:WORD_1
	v_cvt_f32_f16_e32 v64, v64
	v_and_b32_e32 v63, 0xffffff80, v63
	v_sub_u32_e32 v63, v63, v16
	v_not_b32_e32 v81, v80
	v_or_b32_e32 v82, 0x80000000, v80
	v_cmp_gt_i32_e32 vcc, 0, v80
	v_add_u32_e32 v79, 0x7e, v79
	v_add_u32_e32 v63, 0x7f, v63
	v_cndmask_b32_e32 v80, v82, v81, vcc
	v_not_b32_e32 v81, v64
	v_or_b32_e32 v82, 0x80000000, v64
	v_cmp_gt_i32_e32 vcc, 0, v64
	v_and_b32_e32 v80, 0xffffff80, v80
	v_sub_u32_e32 v80, v80, v17
	v_cndmask_b32_e32 v64, v82, v81, vcc
	v_cvt_f32_f16_sdwa v81, v65 dst_sel:DWORD dst_unused:UNUSED_PAD src0_sel:WORD_1
	v_cvt_f32_f16_e32 v65, v65
	v_and_b32_e32 v64, 0xffffff80, v64
	v_sub_u32_e32 v64, v64, v17
	v_not_b32_e32 v82, v81
	v_or_b32_e32 v83, 0x80000000, v81
	v_cmp_gt_i32_e32 vcc, 0, v81
	v_add_u32_e32 v80, 0x7e, v80
	v_add_u32_e32 v64, 0x7f, v64
	v_cndmask_b32_e32 v81, v83, v82, vcc
	v_not_b32_e32 v82, v65
	v_or_b32_e32 v83, 0x80000000, v65
	v_cmp_gt_i32_e32 vcc, 0, v65
	v_and_b32_e32 v81, 0xffffff80, v81
	v_sub_u32_e32 v81, v81, v18
	v_cndmask_b32_e32 v65, v83, v82, vcc
	s_waitcnt vmcnt(0)
; __device__ __forceinline__ unsigned f2key(float f) { const unsigned u = __float_as_uint(f); return (u & 0x80000000u) ? ~u : (u | 0x80000000u); }
; #define CE_DESC(a, b) do { const unsigned _mx = (a) > (b) ? (a) : (b), _mn = (a) > (b) ? (b) : (a); (a) = _mx; (b) = _mn; } while (0)
; __device__ __forceinline__ void sort16_desc(unsigned (&k)[16]) {
; #pragma unroll
;     for (int size = 2; size <= 16; size <<= 1)
; #pragma unroll
;         for (int stride = size >> 1; stride > 0; stride >>= 1)
; #pragma unroll
;             for (int i = 0; i < 16; ++i) { const int j = i ^ stride;
;                 if (j > i) { if ((i & size) == 0) CE_DESC(k[i], k[j]); else CE_DESC(k[j], k[i]); } }
; }
; __device__ __forceinline__ void peer_tile(const Args& A, LAS unsigned char* lds, int tile) {
;     ...
;                   for (int i = 0; i < 16; ++i) {
;                       const float lo = (float)__builtin_bit_cast(_Float16, (unsigned short)(sw[i] & 0xffffu)), hi = (float)__builtin_bit_cast(_Float16, (unsigned short)(sw[i] >> 16));
;                       const unsigned klo = (f2key(lo) & ~127u) | (unsigned)(127 - (32 * g + 2 * i)), khi = (f2key(hi) & ~127u) | (unsigned)(127 - (32 * g + 2 * i + 1));
;                       if (i < 8) { k0[2 * i] = klo; k0[2 * i + 1] = khi; } else { k1[2 * (i - 8)] = klo; k1[2 * (i - 8) + 1] = khi; } } }
;                 sort16_desc(k0); sort16_desc(k1); merge16(k0, k1);
	v_cvt_f32_f16_sdwa v82, v70 dst_sel:DWORD dst_unused:UNUSED_PAD src0_sel:WORD_1
	v_cvt_f32_f16_e32 v70, v70
	v_and_b32_e32 v65, 0xffffff80, v65
	v_sub_u32_e32 v65, v65, v18
	v_not_b32_e32 v83, v82
	v_or_b32_e32 v84, 0x80000000, v82
	v_cmp_gt_i32_e32 vcc, 0, v82
	v_add_u32_e32 v81, 0x7e, v81
	v_add_u32_e32 v65, 0x7f, v65
	v_cndmask_b32_e32 v82, v84, v83, vcc
	v_not_b32_e32 v83, v70
	v_or_b32_e32 v84, 0x80000000, v70
	v_cmp_gt_i32_e32 vcc, 0, v70
	v_and_b32_e32 v82, 0xffffff80, v82
	v_sub_u32_e32 v82, v82, v20
	v_cndmask_b32_e32 v70, v84, v83, vcc
	v_cvt_f32_f16_sdwa v83, v71 dst_sel:DWORD dst_unused:UNUSED_PAD src0_sel:WORD_1
	v_cvt_f32_f16_e32 v71, v71
	v_and_b32_e32 v70, 0xffffff80, v70
	v_sub_u32_e32 v70, v70, v20
	v_not_b32_e32 v84, v83
	v_or_b32_e32 v85, 0x80000000, v83
	v_cmp_gt_i32_e32 vcc, 0, v83
	v_add_u32_e32 v82, 0x7e, v82
	v_add_u32_e32 v70, 0x7f, v70
	v_cndmask_b32_e32 v83, v85, v84, vcc
	v_not_b32_e32 v84, v71
	v_or_b32_e32 v85, 0x80000000, v71
	v_cmp_gt_i32_e32 vcc, 0, v71
	v_and_b32_e32 v83, 0xffffff80, v83
	v_sub_u32_e32 v83, v83, v21
	v_cndmask_b32_e32 v71, v85, v84, vcc
	v_cvt_f32_f16_sdwa v84, v72 dst_sel:DWORD dst_unused:UNUSED_PAD src0_sel:WORD_1
	v_cvt_f32_f16_e32 v72, v72
	v_and_b32_e32 v71, 0xffffff80, v71
	v_sub_u32_e32 v71, v71, v21
	v_not_b32_e32 v85, v84
	v_or_b32_e32 v86, 0x80000000, v84
	v_cmp_gt_i32_e32 vcc, 0, v84
	v_add_u32_e32 v83, 0x7e, v83
	v_add_u32_e32 v71, 0x7f, v71
	v_cndmask_b32_e32 v84, v86, v85, vcc
	v_not_b32_e32 v85, v72
	v_or_b32_e32 v86, 0x80000000, v72
	v_cmp_gt_i32_e32 vcc, 0, v72
	v_and_b32_e32 v84, 0xffffff80, v84
	v_sub_u32_e32 v84, v84, v22
	v_cndmask_b32_e32 v72, v86, v85, vcc
	v_cvt_f32_f16_sdwa v85, v73 dst_sel:DWORD dst_unused:UNUSED_PAD src0_sel:WORD_1
	v_cvt_f32_f16_e32 v73, v73
	v_and_b32_e32 v72, 0xffffff80, v72
	v_sub_u32_e32 v72, v72, v22
	v_not_b32_e32 v86, v85
	v_or_b32_e32 v87, 0x80000000, v85
	v_cmp_gt_i32_e32 vcc, 0, v85
	v_add_u32_e32 v84, 0x7e, v84
	v_add_u32_e32 v72, 0x7f, v72
	v_cndmask_b32_e32 v85, v87, v86, vcc
	v_not_b32_e32 v86, v73
	v_or_b32_e32 v87, 0x80000000, v73
	v_cmp_gt_i32_e32 vcc, 0, v73
	v_and_b32_e32 v85, 0xffffff80, v85
	v_sub_u32_e32 v85, v85, v23
	v_cndmask_b32_e32 v73, v87, v86, vcc
	v_cvt_f32_f16_sdwa v86, v0 dst_sel:DWORD dst_unused:UNUSED_PAD src0_sel:WORD_1
	v_cvt_f32_f16_e32 v0, v0
	v_and_b32_e32 v73, 0xffffff80, v73
	v_sub_u32_e32 v73, v73, v23
	v_not_b32_e32 v87, v86
	v_or_b32_e32 v88, 0x80000000, v86
	v_cmp_gt_i32_e32 vcc, 0, v86
	v_add_u32_e32 v85, 0x7e, v85
	v_add_u32_e32 v73, 0x7f, v73
	v_cndmask_b32_e32 v86, v88, v87, vcc
	v_not_b32_e32 v87, v0
	v_or_b32_e32 v88, 0x80000000, v0
	v_cmp_gt_i32_e32 vcc, 0, v0
	v_and_b32_e32 v86, 0xffffff80, v86
	v_sub_u32_e32 v86, v86, v24
	v_cndmask_b32_e32 v0, v88, v87, vcc
	v_cvt_f32_f16_sdwa v87, v1 dst_sel:DWORD dst_unused:UNUSED_PAD src0_sel:WORD_1
	v_cvt_f32_f16_e32 v1, v1
	v_and_b32_e32 v0, 0xffffff80, v0
	v_sub_u32_e32 v0, v0, v24
	v_not_b32_e32 v88, v87
	v_or_b32_e32 v89, 0x80000000, v87
	v_cmp_gt_i32_e32 vcc, 0, v87
	v_add_u32_e32 v86, 0x7e, v86
	v_add_u32_e32 v0, 0x7f, v0
	v_cndmask_b32_e32 v87, v89, v88, vcc
	v_not_b32_e32 v88, v1
	v_or_b32_e32 v89, 0x80000000, v1
	v_cmp_gt_i32_e32 vcc, 0, v1
	v_and_b32_e32 v87, 0xffffff80, v87
	v_sub_u32_e32 v87, v87, v25
	v_cndmask_b32_e32 v1, v89, v88, vcc
	v_cvt_f32_f16_sdwa v88, v2 dst_sel:DWORD dst_unused:UNUSED_PAD src0_sel:WORD_1
	v_cvt_f32_f16_e32 v2, v2
	v_and_b32_e32 v1, 0xffffff80, v1
	v_sub_u32_e32 v1, v1, v25
	v_not_b32_e32 v89, v88
	v_or_b32_e32 v90, 0x80000000, v88
	v_cmp_gt_i32_e32 vcc, 0, v88
	v_add_u32_e32 v87, 0x7e, v87
	v_add_u32_e32 v1, 0x7f, v1
	v_cndmask_b32_e32 v88, v90, v89, vcc
	v_not_b32_e32 v89, v2
	v_or_b32_e32 v90, 0x80000000, v2
	v_cmp_gt_i32_e32 vcc, 0, v2
	v_and_b32_e32 v88, 0xffffff80, v88
	v_sub_u32_e32 v88, v88, v26
	v_cndmask_b32_e32 v2, v90, v89, vcc
	v_cvt_f32_f16_sdwa v89, v3 dst_sel:DWORD dst_unused:UNUSED_PAD src0_sel:WORD_1
	v_cvt_f32_f16_e32 v3, v3
	v_and_b32_e32 v2, 0xffffff80, v2
	v_sub_u32_e32 v2, v2, v26
	v_not_b32_e32 v90, v89
	v_or_b32_e32 v91, 0x80000000, v89
	v_cmp_gt_i32_e32 vcc, 0, v89
	v_add_u32_e32 v88, 0x7e, v88
	v_add_u32_e32 v2, 0x7f, v2
	v_cndmask_b32_e32 v89, v91, v90, vcc
	v_not_b32_e32 v90, v3
	v_or_b32_e32 v91, 0x80000000, v3
	v_cmp_gt_i32_e32 vcc, 0, v3
	v_and_b32_e32 v89, 0xffffff80, v89
	v_sub_u32_e32 v89, v89, v28
	v_cndmask_b32_e32 v3, v91, v90, vcc
	v_and_b32_e32 v3, 0xffffff80, v3
	v_sub_u32_e32 v3, v3, v28
	v_add_u32_e32 v89, 0x7e, v89
	v_add_u32_e32 v3, 0x7f, v3
	v_max_u32_e32 v90, v66, v74
	v_min_u32_e32 v66, v66, v74
	v_max_u32_e32 v74, v75, v67
	v_min_u32_e32 v67, v75, v67
	v_max_u32_e32 v75, v68, v76
	v_min_u32_e32 v68, v68, v76
	v_max_u32_e32 v76, v77, v69
	v_min_u32_e32 v69, v77, v69
	v_max_u32_e32 v77, v62, v78
	v_min_u32_e32 v62, v62, v78
	v_max_u32_e32 v78, v79, v63
	v_min_u32_e32 v63, v79, v63
	v_max_u32_e32 v79, v64, v80
	v_min_u32_e32 v64, v64, v80
	v_max_u32_e32 v80, v81, v65
	v_min_u32_e32 v65, v81, v65
	v_max_u32_e32 v98, v70, v82
	v_min_u32_e32 v70, v70, v82
	v_max_u32_e32 v82, v83, v71
	v_min_u32_e32 v71, v83, v71
	v_max_u32_e32 v83, v72, v84
	v_min_u32_e32 v72, v72, v84
	v_max_u32_e32 v84, v85, v73
	v_min_u32_e32 v73, v85, v73
	v_max_u32_e32 v85, v0, v86
	v_min_u32_e32 v0, v0, v86
	v_max_u32_e32 v86, v87, v1
	v_min_u32_e32 v1, v87, v1
	v_max_u32_e32 v87, v2, v88
	v_min_u32_e32 v2, v2, v88
	v_max_u32_e32 v88, v89, v3
	v_min_u32_e32 v3, v89, v3
	v_max_u32_e32 v81, v90, v67
	v_min_u32_e32 v67, v90, v67
	v_max_u32_e32 v90, v66, v74
	v_min_u32_e32 v66, v66, v74
	v_max_u32_e32 v74, v69, v75
	v_min_u32_e32 v69, v69, v75
	v_max_u32_e32 v75, v76, v68
	v_min_u32_e32 v68, v76, v68
; #define CE_DESC(a, b) do { const unsigned _mx = (a) > (b) ? (a) : (b), _mn = (a) > (b) ? (b) : (a); (a) = _mx; (b) = _mn; } while (0)
; __device__ __forceinline__ void sort16_desc(unsigned (&k)[16]) {
; #pragma unroll
;     for (int size = 2; size <= 16; size <<= 1)
; #pragma unroll
;         for (int stride = size >> 1; stride > 0; stride >>= 1)
; #pragma unroll
;             for (int i = 0; i < 16; ++i) { const int j = i ^ stride;
;                 if (j > i) { if ((i & size) == 0) CE_DESC(k[i], k[j]); else CE_DESC(k[j], k[i]); } }
; }
	v_max_u32_e32 v76, v77, v63
	v_min_u32_e32 v63, v77, v63
	v_max_u32_e32 v77, v62, v78
	v_min_u32_e32 v62, v62, v78
	v_max_u32_e32 v78, v65, v79
	v_min_u32_e32 v65, v65, v79
	v_max_u32_e32 v79, v80, v64
	v_min_u32_e32 v64, v80, v64
	v_max_u32_e32 v89, v98, v71
	v_min_u32_e32 v71, v98, v71
	v_max_u32_e32 v98, v70, v82
	v_min_u32_e32 v70, v70, v82
	v_max_u32_e32 v82, v73, v83
	v_min_u32_e32 v73, v73, v83
	v_max_u32_e32 v83, v84, v72
	v_min_u32_e32 v72, v84, v72
	v_max_u32_e32 v84, v85, v1
	v_min_u32_e32 v1, v85, v1
	v_max_u32_e32 v85, v0, v86
	v_min_u32_e32 v0, v0, v86
	v_max_u32_e32 v86, v3, v87
	v_min_u32_e32 v3, v3, v87
	v_max_u32_e32 v87, v88, v2
	v_min_u32_e32 v2, v88, v2
	v_max_u32_e32 v80, v81, v90
	v_min_u32_e32 v81, v81, v90
	v_max_u32_e32 v90, v67, v66
	v_min_u32_e32 v66, v67, v66
	v_max_u32_e32 v67, v68, v69
	v_min_u32_e32 v68, v68, v69
	v_max_u32_e32 v69, v75, v74
	v_min_u32_e32 v74, v75, v74
	v_max_u32_e32 v75, v76, v77
	v_min_u32_e32 v76, v76, v77
	v_max_u32_e32 v77, v63, v62
	v_min_u32_e32 v62, v63, v62
	v_max_u32_e32 v63, v64, v65
	v_min_u32_e32 v64, v64, v65
	v_max_u32_e32 v65, v79, v78
	v_min_u32_e32 v78, v79, v78
	v_max_u32_e32 v88, v89, v98
	v_min_u32_e32 v89, v89, v98
	v_max_u32_e32 v98, v71, v70
	v_min_u32_e32 v70, v71, v70
	v_max_u32_e32 v71, v72, v73
	v_min_u32_e32 v72, v72, v73
	v_max_u32_e32 v73, v83, v82
	v_min_u32_e32 v82, v83, v82
	v_max_u32_e32 v83, v84, v85
	v_min_u32_e32 v84, v84, v85
	v_max_u32_e32 v85, v1, v0
	v_min_u32_e32 v0, v1, v0
	v_max_u32_e32 v1, v2, v3
	v_min_u32_e32 v2, v2, v3
	v_max_u32_e32 v3, v87, v86
	v_min_u32_e32 v86, v87, v86
	v_max_u32_e32 v79, v80, v68
	v_min_u32_e32 v68, v80, v68
	v_max_u32_e32 v80, v81, v67
	v_min_u32_e32 v67, v81, v67
	v_max_u32_e32 v81, v90, v74
	v_min_u32_e32 v74, v90, v74
	v_max_u32_e32 v90, v66, v69
	v_min_u32_e32 v66, v66, v69
	v_max_u32_e32 v69, v64, v75
	v_min_u32_e32 v64, v64, v75
	v_max_u32_e32 v75, v63, v76
	v_min_u32_e32 v63, v63, v76
	v_max_u32_e32 v76, v78, v77
	v_min_u32_e32 v77, v78, v77
	v_max_u32_e32 v78, v65, v62
	v_min_u32_e32 v62, v65, v62
	v_max_u32_e32 v87, v88, v72
	v_min_u32_e32 v72, v88, v72
	v_max_u32_e32 v88, v89, v71
	v_min_u32_e32 v71, v89, v71
	v_max_u32_e32 v89, v98, v82
	v_min_u32_e32 v82, v98, v82
	v_max_u32_e32 v98, v70, v73
	v_min_u32_e32 v70, v70, v73
	v_max_u32_e32 v73, v2, v83
	v_min_u32_e32 v2, v2, v83
	v_max_u32_e32 v83, v1, v84
	v_min_u32_e32 v1, v1, v84
	v_max_u32_e32 v84, v86, v85
	v_min_u32_e32 v85, v86, v85
	v_max_u32_e32 v86, v3, v0
	v_min_u32_e32 v0, v3, v0
	v_max_u32_e32 v65, v79, v81
	v_min_u32_e32 v79, v79, v81
	v_max_u32_e32 v81, v80, v90
	v_min_u32_e32 v80, v80, v90
	v_max_u32_e32 v90, v68, v74
	v_min_u32_e32 v68, v68, v74
	v_max_u32_e32 v74, v67, v66
	v_min_u32_e32 v66, v67, v66
	v_max_u32_e32 v67, v77, v64
	v_min_u32_e32 v64, v77, v64
	v_max_u32_e32 v77, v62, v63
	v_min_u32_e32 v62, v62, v63
	v_max_u32_e32 v63, v76, v69
	v_min_u32_e32 v69, v76, v69
	v_max_u32_e32 v76, v78, v75
	v_min_u32_e32 v75, v78, v75
	v_max_u32_e32 v3, v87, v89
	v_min_u32_e32 v87, v87, v89
	v_max_u32_e32 v89, v88, v98
	v_min_u32_e32 v88, v88, v98
	v_max_u32_e32 v98, v72, v82
	v_min_u32_e32 v72, v72, v82
	v_max_u32_e32 v82, v71, v70
	v_min_u32_e32 v70, v71, v70
	v_max_u32_e32 v71, v85, v2
	v_min_u32_e32 v2, v85, v2
	v_max_u32_e32 v85, v0, v1
	v_min_u32_e32 v0, v0, v1
	v_max_u32_e32 v1, v84, v73
	v_min_u32_e32 v73, v84, v73
	v_max_u32_e32 v84, v86, v83
	v_min_u32_e32 v83, v86, v83
	v_max_u32_e32 v78, v65, v81
	v_min_u32_e32 v65, v65, v81
	v_max_u32_e32 v81, v79, v80
	v_min_u32_e32 v79, v79, v80
	v_max_u32_e32 v80, v90, v74
	v_min_u32_e32 v74, v90, v74
	v_max_u32_e32 v90, v68, v66
	v_min_u32_e32 v66, v68, v66
	v_max_u32_e32 v68, v62, v64
	v_min_u32_e32 v62, v62, v64
	v_max_u32_e32 v64, v77, v67
	v_min_u32_e32 v67, v77, v67
	v_max_u32_e32 v77, v75, v69
	v_min_u32_e32 v69, v75, v69
	v_max_u32_e32 v75, v76, v63
	v_min_u32_e32 v63, v76, v63
	v_max_u32_e32 v86, v3, v89
	v_min_u32_e32 v3, v3, v89
	v_max_u32_e32 v89, v87, v88
	v_min_u32_e32 v87, v87, v88
	v_max_u32_e32 v88, v98, v82
	v_min_u32_e32 v82, v98, v82
	v_max_u32_e32 v98, v72, v70
	v_min_u32_e32 v70, v72, v70
	v_max_u32_e32 v72, v0, v2
	v_min_u32_e32 v0, v0, v2
	v_max_u32_e32 v2, v85, v71
	v_min_u32_e32 v71, v85, v71
	v_max_u32_e32 v85, v83, v73
	v_min_u32_e32 v73, v83, v73
	v_max_u32_e32 v83, v84, v1
	v_min_u32_e32 v1, v84, v1
	v_max_u32_e32 v76, v78, v62
	v_min_u32_e32 v62, v78, v62
	v_max_u32_e32 v78, v65, v68
	v_min_u32_e32 v65, v65, v68
	v_max_u32_e32 v68, v81, v67
	v_min_u32_e32 v67, v81, v67
	v_max_u32_e32 v81, v79, v64
	v_min_u32_e32 v64, v79, v64
	v_max_u32_e32 v79, v80, v69
	v_min_u32_e32 v69, v80, v69
	v_max_u32_e32 v80, v74, v77
	v_min_u32_e32 v74, v74, v77
	v_max_u32_e32 v77, v90, v63
	v_min_u32_e32 v63, v90, v63
	v_max_u32_e32 v90, v66, v75
	v_min_u32_e32 v66, v66, v75
	v_max_u32_e32 v84, v86, v0
	v_min_u32_e32 v0, v86, v0
	v_max_u32_e32 v86, v3, v72
	v_min_u32_e32 v3, v3, v72
	v_max_u32_e32 v72, v89, v71
	v_min_u32_e32 v71, v89, v71
	v_max_u32_e32 v89, v87, v2
	v_min_u32_e32 v2, v87, v2
	v_max_u32_e32 v87, v88, v73
	v_min_u32_e32 v73, v88, v73
	v_max_u32_e32 v88, v82, v85
	v_min_u32_e32 v82, v82, v85
	v_max_u32_e32 v85, v98, v1
	v_min_u32_e32 v1, v98, v1
	v_max_u32_e32 v98, v70, v83
	v_min_u32_e32 v70, v70, v83
	v_max_u32_e32 v75, v76, v79
	v_min_u32_e32 v76, v76, v79
	v_max_u32_e32 v79, v78, v80
	v_min_u32_e32 v78, v78, v80
	v_max_u32_e32 v80, v68, v77
	v_min_u32_e32 v68, v68, v77
	v_max_u32_e32 v77, v81, v90
	v_min_u32_e32 v81, v81, v90
	v_max_u32_e32 v90, v62, v69
	v_min_u32_e32 v62, v62, v69
	v_max_u32_e32 v69, v65, v74
	v_min_u32_e32 v65, v65, v74
	v_max_u32_e32 v74, v67, v63
; #define CE_DESC(a, b) do { const unsigned _mx = (a) > (b) ? (a) : (b), _mn = (a) > (b) ? (b) : (a); (a) = _mx; (b) = _mn; } while (0)
; __device__ __forceinline__ void merge16(unsigned (&a)[16], const unsigned (&b)[16]) {
; #pragma unroll
;     for (int i = 0; i < 16; ++i) a[i] = a[i] > b[15 - i] ? a[i] : b[15 - i];
; #pragma unroll
;     for (int stride = 8; stride > 0; stride >>= 1)
; #pragma unroll
;         for (int i = 0; i < 16; ++i) { const int j = i ^ stride; if (j > i) CE_DESC(a[i], a[j]); }
; }
; __device__ __forceinline__ void peer_tile(const Args& A, LAS unsigned char* lds, int tile) {
;     ...
;                 sort16_desc(k0); sort16_desc(k1); merge16(k0, k1);
; #pragma unroll
;                 for (int msk = 16; msk <= 32; msk <<= 1) {
; #pragma unroll
;                     for (int i = 0; i < 16; ++i) k1[i] = (unsigned)__shfl_xor((int)k0[i], msk);
;                     merge16(k0, k1); }
	v_min_u32_e32 v63, v67, v63
	v_max_u32_e32 v67, v64, v66
	v_min_u32_e32 v64, v64, v66
	v_max_u32_e32 v83, v84, v87
	v_min_u32_e32 v84, v84, v87
	v_max_u32_e32 v87, v86, v88
	v_min_u32_e32 v86, v86, v88
	v_max_u32_e32 v88, v72, v85
	v_min_u32_e32 v72, v72, v85
	v_max_u32_e32 v85, v89, v98
	v_min_u32_e32 v89, v89, v98
	v_max_u32_e32 v98, v0, v73
	v_min_u32_e32 v0, v0, v73
	v_max_u32_e32 v73, v3, v82
	v_min_u32_e32 v3, v3, v82
	v_max_u32_e32 v82, v71, v1
	v_min_u32_e32 v1, v71, v1
	v_max_u32_e32 v71, v2, v70
	v_min_u32_e32 v2, v2, v70
	v_max_u32_e32 v66, v75, v80
	v_min_u32_e32 v75, v75, v80
	v_max_u32_e32 v80, v79, v77
	v_min_u32_e32 v77, v79, v77
	v_max_u32_e32 v79, v76, v68
	v_min_u32_e32 v68, v76, v68
	v_max_u32_e32 v76, v78, v81
	v_min_u32_e32 v78, v78, v81
	v_max_u32_e32 v81, v90, v74
	v_min_u32_e32 v74, v90, v74
	v_max_u32_e32 v90, v69, v67
	v_min_u32_e32 v67, v69, v67
	v_max_u32_e32 v69, v62, v63
	v_min_u32_e32 v62, v62, v63
	v_max_u32_e32 v63, v65, v64
	v_min_u32_e32 v64, v65, v64
	v_max_u32_e32 v70, v83, v88
	v_min_u32_e32 v83, v83, v88
	v_max_u32_e32 v88, v87, v85
	v_min_u32_e32 v85, v87, v85
	v_max_u32_e32 v87, v84, v72
	v_min_u32_e32 v72, v84, v72
	v_max_u32_e32 v84, v86, v89
	v_min_u32_e32 v86, v86, v89
	v_max_u32_e32 v89, v98, v82
	v_min_u32_e32 v82, v98, v82
	v_max_u32_e32 v98, v73, v71
	v_min_u32_e32 v71, v73, v71
	v_max_u32_e32 v73, v0, v1
	v_min_u32_e32 v0, v0, v1
	v_max_u32_e32 v1, v3, v2
	v_min_u32_e32 v2, v3, v2
	v_min_u32_e32 v65, v66, v80
	v_min_u32_e32 v91, v75, v77
	v_min_u32_e32 v92, v79, v76
	v_min_u32_e32 v93, v68, v78
	v_min_u32_e32 v94, v81, v90
	v_min_u32_e32 v95, v74, v67
	v_min_u32_e32 v96, v69, v63
	v_min_u32_e32 v97, v62, v64
	v_min_u32_e32 v3, v70, v88
	v_min_u32_e32 v99, v83, v85
	v_min_u32_e32 v100, v87, v84
	v_min_u32_e32 v101, v72, v86
	v_min_u32_e32 v102, v89, v98
	v_min_u32_e32 v103, v82, v71
	v_min_u32_e32 v104, v73, v1
	v_min_u32_e32 v105, v0, v2
	v_max3_u32 v66, v66, v80, v105
	v_max3_u32 v0, v65, v0, v2
	v_max3_u32 v2, v75, v77, v104
	v_max3_u32 v1, v91, v73, v1
	v_max3_u32 v65, v79, v76, v103
	v_max3_u32 v71, v92, v82, v71
	v_max3_u32 v68, v68, v78, v102
	v_max3_u32 v73, v93, v89, v98
	v_max3_u32 v75, v81, v90, v101
	v_max3_u32 v72, v94, v72, v86
	v_max3_u32 v67, v74, v67, v100
	v_max3_u32 v74, v95, v87, v84
	v_max3_u32 v63, v69, v63, v99
	v_max3_u32 v69, v96, v83, v85
	v_max3_u32 v3, v62, v64, v3
	v_max3_u32 v62, v97, v70, v88
	v_max_u32_e32 v64, v66, v75
	v_min_u32_e32 v66, v66, v75
	v_max_u32_e32 v70, v0, v72
	v_min_u32_e32 v0, v0, v72
	v_max_u32_e32 v72, v2, v67
	v_min_u32_e32 v2, v2, v67
	v_max_u32_e32 v67, v1, v74
	v_min_u32_e32 v1, v1, v74
	v_max_u32_e32 v74, v65, v63
	v_min_u32_e32 v63, v65, v63
	v_max_u32_e32 v65, v71, v69
	v_min_u32_e32 v69, v71, v69
	v_max_u32_e32 v71, v68, v3
	v_min_u32_e32 v3, v68, v3
	v_max_u32_e32 v68, v73, v62
	v_min_u32_e32 v62, v73, v62
	v_max_u32_e32 v73, v64, v74
	v_min_u32_e32 v64, v64, v74
	v_max_u32_e32 v74, v70, v65
	v_min_u32_e32 v65, v70, v65
	v_max_u32_e32 v70, v72, v71
	v_min_u32_e32 v71, v72, v71
	v_max_u32_e32 v72, v67, v68
	v_min_u32_e32 v67, v67, v68
	v_max_u32_e32 v68, v66, v63
	v_min_u32_e32 v63, v66, v63
	v_max_u32_e32 v66, v0, v69
	v_min_u32_e32 v0, v0, v69
	v_max_u32_e32 v69, v2, v3
	v_min_u32_e32 v2, v2, v3
	v_max_u32_e32 v3, v1, v62
	v_min_u32_e32 v1, v1, v62
	v_max_u32_e32 v62, v73, v70
	v_min_u32_e32 v70, v73, v70
	v_max_u32_e32 v73, v74, v72
	v_min_u32_e32 v72, v74, v72
	v_max_u32_e32 v74, v64, v71
	v_min_u32_e32 v64, v64, v71
	v_max_u32_e32 v71, v65, v67
	v_min_u32_e32 v65, v65, v67
	v_max_u32_e32 v67, v68, v69
	v_min_u32_e32 v68, v68, v69
	v_max_u32_e32 v69, v66, v3
	v_min_u32_e32 v3, v66, v3
	v_max_u32_e32 v66, v63, v2
	v_min_u32_e32 v2, v63, v2
	v_max_u32_e32 v63, v0, v1
	v_min_u32_e32 v0, v0, v1
	v_max_u32_e32 v1, v62, v73
	v_min_u32_e32 v62, v62, v73
	v_max_u32_e32 v73, v70, v72
	v_min_u32_e32 v70, v70, v72
	v_max_u32_e32 v72, v74, v71
	v_min_u32_e32 v71, v74, v71
	v_max_u32_e32 v74, v64, v65
	v_min_u32_e32 v64, v64, v65
	v_max_u32_e32 v65, v67, v69
	v_min_u32_e32 v67, v67, v69
	v_max_u32_e32 v69, v68, v3
	v_min_u32_e32 v3, v68, v3
	v_max_u32_e32 v68, v66, v63
	v_min_u32_e32 v63, v66, v63
	v_max_u32_e32 v66, v2, v0
	v_min_u32_e32 v0, v2, v0
	ds_bpermute_b32 v2, v27, v1
	ds_bpermute_b32 v75, v27, v62
	ds_bpermute_b32 v76, v27, v73
	ds_bpermute_b32 v77, v27, v70
	ds_bpermute_b32 v78, v27, v72
	ds_bpermute_b32 v79, v27, v71
	ds_bpermute_b32 v80, v27, v74
	ds_bpermute_b32 v81, v27, v64
	ds_bpermute_b32 v82, v27, v65
	ds_bpermute_b32 v83, v27, v67
	ds_bpermute_b32 v84, v27, v69
	ds_bpermute_b32 v85, v27, v0
	ds_bpermute_b32 v86, v27, v66
	ds_bpermute_b32 v87, v27, v63
	ds_bpermute_b32 v88, v27, v68
	ds_bpermute_b32 v89, v27, v3
	s_waitcnt lgkmcnt(4)
	v_max_u32_e32 v1, v1, v85
	s_waitcnt lgkmcnt(3)
	v_max_u32_e32 v62, v62, v86
	s_waitcnt lgkmcnt(2)
	v_max_u32_e32 v73, v73, v87
	s_waitcnt lgkmcnt(1)
	v_max_u32_e32 v70, v70, v88
	s_waitcnt lgkmcnt(0)
; __device__ __forceinline__ void peer_tile(const Args& A, LAS unsigned char* lds, int tile) {
;     ...
;                 { const bf16_t* sp = QRY + m * 2048 + hp * 128 + 32 * g;
;                   const u32x4 s0 = *(const u32x4*)sp, s1 = *(const u32x4*)(sp + 8), s2 = *(const u32x4*)(sp + 16), s3 = *(const u32x4*)(sp + 24);
;     ...
;                 for (int msk = 16; msk <= 32; msk <<= 1) {
; #pragma unroll
;                     for (int i = 0; i < 16; ++i) k1[i] = (unsigned)__shfl_xor((int)k0[i], msk);
;                     merge16(k0, k1); }
	v_max_u32_e32 v72, v72, v89
	v_max_u32_e32 v71, v71, v84
	v_max_u32_e32 v74, v74, v83
	v_max_u32_e32 v64, v64, v82
	v_max_u32_e32 v65, v65, v81
	v_max_u32_e32 v67, v67, v80
	v_max_u32_e32 v69, v69, v79
	v_max_u32_e32 v3, v3, v78
	v_max_u32_e32 v68, v68, v77
	v_max_u32_e32 v63, v63, v76
	v_max_u32_e32 v66, v66, v75
	v_max_u32_e32 v0, v0, v2
	v_max_u32_e32 v2, v1, v65
	v_min_u32_e32 v1, v1, v65
	v_max_u32_e32 v65, v62, v67
	v_min_u32_e32 v62, v62, v67
	v_max_u32_e32 v67, v73, v69
	v_min_u32_e32 v69, v73, v69
	v_max_u32_e32 v73, v70, v3
	v_min_u32_e32 v3, v70, v3
	v_max_u32_e32 v70, v72, v68
	v_min_u32_e32 v68, v72, v68
	v_max_u32_e32 v72, v71, v63
	v_min_u32_e32 v63, v71, v63
	v_max_u32_e32 v71, v74, v66
	v_min_u32_e32 v66, v74, v66
	v_max_u32_e32 v74, v64, v0
	v_min_u32_e32 v0, v64, v0
	v_max_u32_e32 v64, v2, v70
	v_min_u32_e32 v2, v2, v70
	v_max_u32_e32 v70, v65, v72
	v_min_u32_e32 v65, v65, v72
	v_max_u32_e32 v72, v67, v71
	v_min_u32_e32 v67, v67, v71
	v_max_u32_e32 v71, v73, v74
	v_min_u32_e32 v73, v73, v74
	v_max_u32_e32 v74, v1, v68
	v_min_u32_e32 v1, v1, v68
	v_max_u32_e32 v68, v62, v63
	v_min_u32_e32 v62, v62, v63
	v_max_u32_e32 v63, v69, v66
	v_min_u32_e32 v66, v69, v66
	v_max_u32_e32 v69, v3, v0
	v_min_u32_e32 v0, v3, v0
	v_max_u32_e32 v3, v64, v72
	v_min_u32_e32 v64, v64, v72
	v_max_u32_e32 v72, v70, v71
	v_min_u32_e32 v70, v70, v71
	v_max_u32_e32 v71, v2, v67
	v_min_u32_e32 v2, v2, v67
	v_max_u32_e32 v67, v65, v73
	v_min_u32_e32 v65, v65, v73
	v_max_u32_e32 v73, v74, v63
	v_min_u32_e32 v63, v74, v63
	v_max_u32_e32 v74, v68, v69
	v_min_u32_e32 v68, v68, v69
	v_max_u32_e32 v69, v1, v66
	v_min_u32_e32 v1, v1, v66
	v_max_u32_e32 v66, v62, v0
	v_min_u32_e32 v0, v62, v0
	v_max_u32_e32 v62, v3, v72
	v_min_u32_e32 v3, v3, v72
	v_max_u32_e32 v72, v64, v70
	v_min_u32_e32 v64, v64, v70
	v_max_u32_e32 v70, v71, v67
	v_min_u32_e32 v67, v71, v67
	v_max_u32_e32 v71, v2, v65
	v_min_u32_e32 v2, v2, v65
	v_max_u32_e32 v65, v73, v74
	v_min_u32_e32 v73, v73, v74
	v_max_u32_e32 v74, v63, v68
	v_min_u32_e32 v63, v63, v68
	v_max_u32_e32 v68, v69, v66
	v_min_u32_e32 v66, v69, v66
	v_max_u32_e32 v69, v1, v0
	v_min_u32_e32 v0, v1, v0
	ds_bpermute_b32 v78, v29, v0
	ds_bpermute_b32 v1, v29, v62
	ds_bpermute_b32 v75, v29, v3
	ds_bpermute_b32 v76, v29, v72
	ds_bpermute_b32 v77, v29, v64
	s_waitcnt lgkmcnt(4)
	v_max_u32_e32 v62, v62, v78
	global_load_dwordx4 v[78:81], v[4:5], off offset:784
	global_load_dwordx4 v[82:85], v[4:5], off offset:768
	ds_bpermute_b32 v86, v29, v70
	ds_bpermute_b32 v87, v29, v67
	ds_bpermute_b32 v88, v29, v71
	ds_bpermute_b32 v89, v29, v2
	ds_bpermute_b32 v90, v29, v65
	ds_bpermute_b32 v91, v29, v73
	ds_bpermute_b32 v92, v29, v74
	ds_bpermute_b32 v93, v29, v63
	ds_bpermute_b32 v94, v29, v68
	ds_bpermute_b32 v95, v29, v69
	ds_bpermute_b32 v96, v29, v66
	s_waitcnt lgkmcnt(4)
	v_max_u32_e32 v67, v67, v92
	s_waitcnt lgkmcnt(3)
	v_max_u32_e32 v70, v70, v93
	s_waitcnt lgkmcnt(2)
	v_max_u32_e32 v64, v64, v94
	s_waitcnt lgkmcnt(1)
	v_max_u32_e32 v3, v3, v95
	s_waitcnt lgkmcnt(0)
	v_max_u32_e32 v72, v72, v96
	v_max_u32_e32 v71, v71, v91
	v_max_u32_e32 v2, v2, v90
	v_max_u32_e32 v65, v65, v89
	v_max_u32_e32 v73, v73, v88
	v_max_u32_e32 v74, v74, v87
	v_max_u32_e32 v63, v63, v86
	v_max_u32_e32 v68, v68, v77
	v_max_u32_e32 v66, v66, v76
	v_max_u32_e32 v69, v69, v75
	v_max_u32_e32 v0, v0, v1
	v_max_u32_e32 v1, v62, v65
	v_min_u32_e32 v62, v62, v65
	v_max_u32_e32 v65, v3, v73
	v_min_u32_e32 v3, v3, v73
	v_max_u32_e32 v73, v72, v74
	v_min_u32_e32 v72, v72, v74
	v_max_u32_e32 v74, v64, v63
	v_min_u32_e32 v63, v64, v63
	v_max_u32_e32 v64, v70, v68
	v_min_u32_e32 v68, v70, v68
	v_max_u32_e32 v70, v67, v66
	v_min_u32_e32 v66, v67, v66
	v_max_u32_e32 v67, v71, v69
	v_min_u32_e32 v69, v71, v69
	v_max_u32_e32 v71, v2, v0
	v_min_u32_e32 v0, v2, v0
	v_max_u32_e32 v2, v1, v64
	v_min_u32_e32 v1, v1, v64
	v_max_u32_e32 v64, v65, v70
	v_min_u32_e32 v65, v65, v70
	v_max_u32_e32 v70, v73, v67
	v_min_u32_e32 v67, v73, v67
	v_max_u32_e32 v73, v74, v71
	v_min_u32_e32 v71, v74, v71
	v_max_u32_e32 v74, v62, v68
	v_min_u32_e32 v62, v62, v68
	v_max_u32_e32 v68, v3, v66
	v_min_u32_e32 v3, v3, v66
	v_max_u32_e32 v66, v72, v69
	v_min_u32_e32 v69, v72, v69
	v_max_u32_e32 v72, v63, v0
	v_min_u32_e32 v0, v63, v0
	v_max_u32_e32 v63, v2, v70
	v_min_u32_e32 v2, v2, v70
	v_max_u32_e32 v70, v64, v73
	v_min_u32_e32 v64, v64, v73
	v_max_u32_e32 v86, v1, v67
	v_min_u32_e32 v1, v1, v67
	v_max_u32_e32 v67, v65, v71
	v_min_u32_e32 v65, v65, v71
	v_max_u32_e32 v87, v74, v66
	v_min_u32_e32 v66, v74, v66
	v_max_u32_e32 v88, v68, v72
	v_min_u32_e32 v89, v68, v72
	v_max_u32_e32 v90, v62, v69
	v_min_u32_e32 v62, v62, v69
	v_max_u32_e32 v91, v3, v0
	v_min_u32_e32 v0, v3, v0
	v_max_u32_e32 v77, v63, v70
	v_min_u32_e32 v76, v63, v70
	v_max_u32_e32 v75, v2, v64
	v_min_u32_e32 v74, v2, v64
	v_max_u32_e32 v73, v86, v67
	v_min_u32_e32 v72, v86, v67
	v_max_u32_e32 v71, v1, v65
	v_min_u32_e32 v70, v1, v65
	v_max_u32_e32 v69, v87, v88
	v_min_u32_e32 v68, v87, v88
	v_max_u32_e32 v67, v66, v89
	v_min_u32_e32 v66, v66, v89
	v_max_u32_e32 v63, v62, v0
	v_min_u32_e32 v62, v62, v0
	global_load_dwordx4 v[0:3], v[4:5], off offset:816
	global_load_dwordx4 v[86:89], v[4:5], off offset:800
	v_max_u32_e32 v65, v90, v91
	v_min_u32_e32 v64, v90, v91
	s_waitcnt vmcnt(2)
; __device__ __forceinline__ unsigned f2key(float f) { const unsigned u = __float_as_uint(f); return (u & 0x80000000u) ? ~u : (u | 0x80000000u); }
; __device__ __forceinline__ void peer_tile(const Args& A, LAS unsigned char* lds, int tile) {
;     ...
;                 { const bf16_t* sp = QRY + m * 2048 + hp * 128 + 32 * g;
;                   const u32x4 s0 = *(const u32x4*)sp, s1 = *(const u32x4*)(sp + 8), s2 = *(const u32x4*)(sp + 16), s3 = *(const u32x4*)(sp + 24);
;                   const unsigned sw[16] = {s0.x, s0.y, s0.z, s0.w, s1.x, s1.y, s1.z, s1.w, s2.x, s2.y, s2.z, s2.w, s3.x, s3.y, s3.z, s3.w};
; #pragma unroll
;                   for (int i = 0; i < 16; ++i) {
;                       const float lo = (float)__builtin_bit_cast(_Float16, (unsigned short)(sw[i] & 0xffffu)), hi = (float)__builtin_bit_cast(_Float16, (unsigned short)(sw[i] >> 16));
;                       const unsigned klo = (f2key(lo) & ~127u) | (unsigned)(127 - (32 * g + 2 * i)), khi = (f2key(hi) & ~127u) | (unsigned)(127 - (32 * g + 2 * i + 1));
;                       if (i < 8) { k0[2 * i] = klo; k0[2 * i + 1] = khi; } else { k1[2 * (i - 8)] = klo; k1[2 * (i - 8) + 1] = khi; } } }
;     ...
;                 for (int i = 0; i < 16; ++i) L2[p][i] = (g & 2) ? ((g & 1) ? LA[3][p][i] : LA[2][p][i]) : ((g & 1) ? LA[1][p][i] : LA[0][p][i]);
	v_cvt_f32_f16_sdwa v90, v82 dst_sel:DWORD dst_unused:UNUSED_PAD src0_sel:WORD_1
	v_cvt_f32_f16_e32 v82, v82
	v_cndmask_b32_e64 v38, v70, v38, s[0:1]
	v_cndmask_b32_e64 v37, v69, v37, s[0:1]
	v_not_b32_e32 v91, v90
	v_or_b32_e32 v92, 0x80000000, v90
	v_cmp_gt_i32_e32 vcc, 0, v90
	v_cndmask_b32_e64 v36, v68, v36, s[0:1]
	v_cndmask_b32_e64 v35, v67, v35, s[0:1]
	v_cndmask_b32_e32 v90, v92, v91, vcc
	v_not_b32_e32 v91, v82
	v_or_b32_e32 v92, 0x80000000, v82
	v_cmp_gt_i32_e32 vcc, 0, v82
	v_and_b32_e32 v90, 0xffffff80, v90
	v_sub_u32_e32 v90, v90, v15
	v_cndmask_b32_e32 v82, v92, v91, vcc
	v_cvt_f32_f16_sdwa v91, v83 dst_sel:DWORD dst_unused:UNUSED_PAD src0_sel:WORD_1
	v_cvt_f32_f16_e32 v83, v83
	v_and_b32_e32 v82, 0xffffff80, v82
	v_sub_u32_e32 v82, v82, v15
	v_not_b32_e32 v92, v91
	v_or_b32_e32 v93, 0x80000000, v91
	v_cmp_gt_i32_e32 vcc, 0, v91
	v_add_u32_e32 v90, 0x7e, v90
	v_add_u32_e32 v82, 0x7f, v82
	v_cndmask_b32_e32 v91, v93, v92, vcc
	v_not_b32_e32 v92, v83
	v_or_b32_e32 v93, 0x80000000, v83
	v_cmp_gt_i32_e32 vcc, 0, v83
	v_and_b32_e32 v91, 0xffffff80, v91
	v_sub_u32_e32 v91, v91, v14
	v_cndmask_b32_e32 v83, v93, v92, vcc
	v_cvt_f32_f16_sdwa v92, v84 dst_sel:DWORD dst_unused:UNUSED_PAD src0_sel:WORD_1
	v_cvt_f32_f16_e32 v84, v84
	v_and_b32_e32 v83, 0xffffff80, v83
	v_sub_u32_e32 v83, v83, v14
	v_not_b32_e32 v93, v92
	v_or_b32_e32 v94, 0x80000000, v92
	v_cmp_gt_i32_e32 vcc, 0, v92
	v_add_u32_e32 v91, 0x7e, v91
	v_add_u32_e32 v83, 0x7f, v83
	v_cndmask_b32_e32 v92, v94, v93, vcc
	v_not_b32_e32 v93, v84
	v_or_b32_e32 v94, 0x80000000, v84
	v_cmp_gt_i32_e32 vcc, 0, v84
	v_and_b32_e32 v92, 0xffffff80, v92
	v_sub_u32_e32 v92, v92, v12
	v_cndmask_b32_e32 v84, v94, v93, vcc
	v_cvt_f32_f16_sdwa v93, v85 dst_sel:DWORD dst_unused:UNUSED_PAD src0_sel:WORD_1
	v_cvt_f32_f16_e32 v85, v85
	v_and_b32_e32 v84, 0xffffff80, v84
	v_sub_u32_e32 v84, v84, v12
	v_not_b32_e32 v94, v93
	v_or_b32_e32 v95, 0x80000000, v93
	v_cmp_gt_i32_e32 vcc, 0, v93
	v_add_u32_e32 v92, 0x7e, v92
	v_add_u32_e32 v84, 0x7f, v84
	v_cndmask_b32_e32 v93, v95, v94, vcc
	v_not_b32_e32 v94, v85
	v_or_b32_e32 v95, 0x80000000, v85
	v_cmp_gt_i32_e32 vcc, 0, v85
	v_and_b32_e32 v93, 0xffffff80, v93
	v_sub_u32_e32 v93, v93, v10
	v_cndmask_b32_e32 v85, v95, v94, vcc
	v_cvt_f32_f16_sdwa v94, v78 dst_sel:DWORD dst_unused:UNUSED_PAD src0_sel:WORD_1
	v_cvt_f32_f16_e32 v78, v78
	v_and_b32_e32 v85, 0xffffff80, v85
	v_sub_u32_e32 v85, v85, v10
	v_not_b32_e32 v95, v94
	v_or_b32_e32 v96, 0x80000000, v94
	v_cmp_gt_i32_e32 vcc, 0, v94
	v_add_u32_e32 v93, 0x7e, v93
	v_add_u32_e32 v85, 0x7f, v85
	v_cndmask_b32_e32 v94, v96, v95, vcc
	v_not_b32_e32 v95, v78
	v_or_b32_e32 v96, 0x80000000, v78
	v_cmp_gt_i32_e32 vcc, 0, v78
	v_and_b32_e32 v94, 0xffffff80, v94
	v_sub_u32_e32 v94, v94, v8
	v_cndmask_b32_e32 v78, v96, v95, vcc
	v_cvt_f32_f16_sdwa v95, v79 dst_sel:DWORD dst_unused:UNUSED_PAD src0_sel:WORD_1
	v_cvt_f32_f16_e32 v79, v79
	v_and_b32_e32 v78, 0xffffff80, v78
	v_sub_u32_e32 v78, v78, v8
	v_not_b32_e32 v96, v95
	v_or_b32_e32 v97, 0x80000000, v95
	v_cmp_gt_i32_e32 vcc, 0, v95
	v_add_u32_e32 v94, 0x7e, v94
	v_add_u32_e32 v78, 0x7f, v78
	v_cndmask_b32_e32 v95, v97, v96, vcc
	v_not_b32_e32 v96, v79
	v_or_b32_e32 v97, 0x80000000, v79
	v_cmp_gt_i32_e32 vcc, 0, v79
	v_and_b32_e32 v95, 0xffffff80, v95
	v_sub_u32_e32 v95, v95, v16
	v_cndmask_b32_e32 v79, v97, v96, vcc
	v_cvt_f32_f16_sdwa v96, v80 dst_sel:DWORD dst_unused:UNUSED_PAD src0_sel:WORD_1
	v_cvt_f32_f16_e32 v80, v80
	v_and_b32_e32 v79, 0xffffff80, v79
	v_sub_u32_e32 v79, v79, v16
	v_not_b32_e32 v97, v96
	v_or_b32_e32 v98, 0x80000000, v96
	v_cmp_gt_i32_e32 vcc, 0, v96
	v_add_u32_e32 v95, 0x7e, v95
	v_add_u32_e32 v79, 0x7f, v79
	v_cndmask_b32_e32 v96, v98, v97, vcc
	v_not_b32_e32 v97, v80
	v_or_b32_e32 v98, 0x80000000, v80
	v_cmp_gt_i32_e32 vcc, 0, v80
	v_and_b32_e32 v96, 0xffffff80, v96
	v_sub_u32_e32 v96, v96, v17
	v_cndmask_b32_e32 v80, v98, v97, vcc
	v_cvt_f32_f16_sdwa v97, v81 dst_sel:DWORD dst_unused:UNUSED_PAD src0_sel:WORD_1
	v_cvt_f32_f16_e32 v81, v81
	v_and_b32_e32 v80, 0xffffff80, v80
	v_sub_u32_e32 v80, v80, v17
	v_not_b32_e32 v98, v97
	v_or_b32_e32 v99, 0x80000000, v97
	v_cmp_gt_i32_e32 vcc, 0, v97
	v_add_u32_e32 v96, 0x7e, v96
	v_add_u32_e32 v80, 0x7f, v80
	v_cndmask_b32_e32 v97, v99, v98, vcc
	v_not_b32_e32 v98, v81
	v_or_b32_e32 v99, 0x80000000, v81
	v_cmp_gt_i32_e32 vcc, 0, v81
	v_and_b32_e32 v97, 0xffffff80, v97
	v_sub_u32_e32 v97, v97, v18
	v_cndmask_b32_e32 v81, v99, v98, vcc
	s_waitcnt vmcnt(0)
; __device__ __forceinline__ unsigned f2key(float f) { const unsigned u = __float_as_uint(f); return (u & 0x80000000u) ? ~u : (u | 0x80000000u); }
; #define CE_DESC(a, b) do { const unsigned _mx = (a) > (b) ? (a) : (b), _mn = (a) > (b) ? (b) : (a); (a) = _mx; (b) = _mn; } while (0)
; __device__ __forceinline__ void sort16_desc(unsigned (&k)[16]) {
; #pragma unroll
;     for (int size = 2; size <= 16; size <<= 1)
; #pragma unroll
;         for (int stride = size >> 1; stride > 0; stride >>= 1)
; #pragma unroll
;             for (int i = 0; i < 16; ++i) { const int j = i ^ stride;
;                 if (j > i) { if ((i & size) == 0) CE_DESC(k[i], k[j]); else CE_DESC(k[j], k[i]); } }
; }
; __device__ __forceinline__ void peer_tile(const Args& A, LAS unsigned char* lds, int tile) {
;     ...
;                   for (int i = 0; i < 16; ++i) {
;                       const float lo = (float)__builtin_bit_cast(_Float16, (unsigned short)(sw[i] & 0xffffu)), hi = (float)__builtin_bit_cast(_Float16, (unsigned short)(sw[i] >> 16));
;                       const unsigned klo = (f2key(lo) & ~127u) | (unsigned)(127 - (32 * g + 2 * i)), khi = (f2key(hi) & ~127u) | (unsigned)(127 - (32 * g + 2 * i + 1));
;                       if (i < 8) { k0[2 * i] = klo; k0[2 * i + 1] = khi; } else { k1[2 * (i - 8)] = klo; k1[2 * (i - 8) + 1] = khi; } } }
;                 sort16_desc(k0); sort16_desc(k1); merge16(k0, k1);
	v_cvt_f32_f16_sdwa v98, v86 dst_sel:DWORD dst_unused:UNUSED_PAD src0_sel:WORD_1
	v_cvt_f32_f16_e32 v86, v86
	v_and_b32_e32 v81, 0xffffff80, v81
	v_sub_u32_e32 v81, v81, v18
	v_not_b32_e32 v99, v98
	v_or_b32_e32 v100, 0x80000000, v98
	v_cmp_gt_i32_e32 vcc, 0, v98
	v_add_u32_e32 v97, 0x7e, v97
	v_add_u32_e32 v81, 0x7f, v81
	v_cndmask_b32_e32 v98, v100, v99, vcc
	v_not_b32_e32 v99, v86
	v_or_b32_e32 v100, 0x80000000, v86
	v_cmp_gt_i32_e32 vcc, 0, v86
	v_and_b32_e32 v98, 0xffffff80, v98
	v_sub_u32_e32 v98, v98, v20
	v_cndmask_b32_e32 v86, v100, v99, vcc
	v_cvt_f32_f16_sdwa v99, v87 dst_sel:DWORD dst_unused:UNUSED_PAD src0_sel:WORD_1
	v_cvt_f32_f16_e32 v87, v87
	v_and_b32_e32 v86, 0xffffff80, v86
	v_sub_u32_e32 v86, v86, v20
	v_not_b32_e32 v100, v99
	v_or_b32_e32 v101, 0x80000000, v99
	v_cmp_gt_i32_e32 vcc, 0, v99
	v_add_u32_e32 v98, 0x7e, v98
	v_add_u32_e32 v86, 0x7f, v86
	v_cndmask_b32_e32 v99, v101, v100, vcc
	v_not_b32_e32 v100, v87
	v_or_b32_e32 v101, 0x80000000, v87
	v_cmp_gt_i32_e32 vcc, 0, v87
	v_and_b32_e32 v99, 0xffffff80, v99
	v_sub_u32_e32 v99, v99, v21
	v_cndmask_b32_e32 v87, v101, v100, vcc
	v_cvt_f32_f16_sdwa v100, v88 dst_sel:DWORD dst_unused:UNUSED_PAD src0_sel:WORD_1
	v_cvt_f32_f16_e32 v88, v88
	v_and_b32_e32 v87, 0xffffff80, v87
	v_sub_u32_e32 v87, v87, v21
	v_not_b32_e32 v101, v100
	v_or_b32_e32 v102, 0x80000000, v100
	v_cmp_gt_i32_e32 vcc, 0, v100
	v_add_u32_e32 v99, 0x7e, v99
	v_add_u32_e32 v87, 0x7f, v87
	v_cndmask_b32_e32 v100, v102, v101, vcc
	v_not_b32_e32 v101, v88
	v_or_b32_e32 v102, 0x80000000, v88
	v_cmp_gt_i32_e32 vcc, 0, v88
	v_and_b32_e32 v100, 0xffffff80, v100
	v_sub_u32_e32 v100, v100, v22
	v_cndmask_b32_e32 v88, v102, v101, vcc
	v_cvt_f32_f16_sdwa v101, v89 dst_sel:DWORD dst_unused:UNUSED_PAD src0_sel:WORD_1
	v_cvt_f32_f16_e32 v89, v89
	v_and_b32_e32 v88, 0xffffff80, v88
	v_sub_u32_e32 v88, v88, v22
	v_not_b32_e32 v102, v101
	v_or_b32_e32 v103, 0x80000000, v101
	v_cmp_gt_i32_e32 vcc, 0, v101
	v_add_u32_e32 v100, 0x7e, v100
	v_add_u32_e32 v88, 0x7f, v88
	v_cndmask_b32_e32 v101, v103, v102, vcc
	v_not_b32_e32 v102, v89
	v_or_b32_e32 v103, 0x80000000, v89
	v_cmp_gt_i32_e32 vcc, 0, v89
	v_and_b32_e32 v101, 0xffffff80, v101
	v_sub_u32_e32 v101, v101, v23
	v_cndmask_b32_e32 v89, v103, v102, vcc
	v_cvt_f32_f16_sdwa v102, v0 dst_sel:DWORD dst_unused:UNUSED_PAD src0_sel:WORD_1
	v_cvt_f32_f16_e32 v0, v0
	v_and_b32_e32 v89, 0xffffff80, v89
	v_sub_u32_e32 v89, v89, v23
	v_not_b32_e32 v103, v102
	v_or_b32_e32 v104, 0x80000000, v102
	v_cmp_gt_i32_e32 vcc, 0, v102
	v_add_u32_e32 v101, 0x7e, v101
	v_add_u32_e32 v89, 0x7f, v89
	v_cndmask_b32_e32 v102, v104, v103, vcc
	v_not_b32_e32 v103, v0
	v_or_b32_e32 v104, 0x80000000, v0
	v_cmp_gt_i32_e32 vcc, 0, v0
	v_and_b32_e32 v102, 0xffffff80, v102
	v_sub_u32_e32 v102, v102, v24
	v_cndmask_b32_e32 v0, v104, v103, vcc
	v_cvt_f32_f16_sdwa v103, v1 dst_sel:DWORD dst_unused:UNUSED_PAD src0_sel:WORD_1
	v_cvt_f32_f16_e32 v1, v1
	v_and_b32_e32 v0, 0xffffff80, v0
	v_sub_u32_e32 v0, v0, v24
	v_not_b32_e32 v104, v103
	v_or_b32_e32 v105, 0x80000000, v103
	v_cmp_gt_i32_e32 vcc, 0, v103
	v_add_u32_e32 v102, 0x7e, v102
	v_add_u32_e32 v0, 0x7f, v0
	v_cndmask_b32_e32 v103, v105, v104, vcc
	v_not_b32_e32 v104, v1
	v_or_b32_e32 v105, 0x80000000, v1
	v_cmp_gt_i32_e32 vcc, 0, v1
	v_and_b32_e32 v103, 0xffffff80, v103
	v_sub_u32_e32 v103, v103, v25
	v_cndmask_b32_e32 v1, v105, v104, vcc
	v_cvt_f32_f16_sdwa v104, v2 dst_sel:DWORD dst_unused:UNUSED_PAD src0_sel:WORD_1
	v_cvt_f32_f16_e32 v2, v2
	v_and_b32_e32 v1, 0xffffff80, v1
	v_sub_u32_e32 v1, v1, v25
	v_not_b32_e32 v105, v104
	v_or_b32_e32 v106, 0x80000000, v104
	v_cmp_gt_i32_e32 vcc, 0, v104
	v_add_u32_e32 v103, 0x7e, v103
	v_add_u32_e32 v1, 0x7f, v1
	v_cndmask_b32_e32 v104, v106, v105, vcc
	v_not_b32_e32 v105, v2
	v_or_b32_e32 v106, 0x80000000, v2
	v_cmp_gt_i32_e32 vcc, 0, v2
	v_and_b32_e32 v104, 0xffffff80, v104
	v_sub_u32_e32 v104, v104, v26
	v_cndmask_b32_e32 v2, v106, v105, vcc
	v_cvt_f32_f16_sdwa v105, v3 dst_sel:DWORD dst_unused:UNUSED_PAD src0_sel:WORD_1
	v_cvt_f32_f16_e32 v3, v3
	v_and_b32_e32 v2, 0xffffff80, v2
	v_sub_u32_e32 v2, v2, v26
	v_not_b32_e32 v106, v105
	v_or_b32_e32 v107, 0x80000000, v105
	v_cmp_gt_i32_e32 vcc, 0, v105
	v_add_u32_e32 v104, 0x7e, v104
	v_add_u32_e32 v2, 0x7f, v2
	v_cndmask_b32_e32 v105, v107, v106, vcc
	v_not_b32_e32 v106, v3
	v_or_b32_e32 v107, 0x80000000, v3
	v_cmp_gt_i32_e32 vcc, 0, v3
	v_and_b32_e32 v105, 0xffffff80, v105
	v_sub_u32_e32 v105, v105, v28
	v_cndmask_b32_e32 v3, v107, v106, vcc
	v_and_b32_e32 v3, 0xffffff80, v3
	v_sub_u32_e32 v3, v3, v28
	v_add_u32_e32 v105, 0x7e, v105
	v_add_u32_e32 v3, 0x7f, v3
	v_max_u32_e32 v106, v82, v90
	v_min_u32_e32 v82, v82, v90
	v_max_u32_e32 v90, v91, v83
	v_min_u32_e32 v83, v91, v83
	v_max_u32_e32 v91, v84, v92
	v_min_u32_e32 v84, v84, v92
	v_max_u32_e32 v92, v93, v85
	v_min_u32_e32 v85, v93, v85
	v_max_u32_e32 v93, v78, v94
	v_min_u32_e32 v78, v78, v94
	v_max_u32_e32 v94, v95, v79
	v_min_u32_e32 v79, v95, v79
	v_max_u32_e32 v95, v80, v96
	v_min_u32_e32 v80, v80, v96
	v_max_u32_e32 v96, v97, v81
	v_min_u32_e32 v81, v97, v81
	v_max_u32_e32 v115, v86, v98
	v_min_u32_e32 v86, v86, v98
	v_max_u32_e32 v98, v99, v87
	v_min_u32_e32 v87, v99, v87
	v_max_u32_e32 v99, v88, v100
	v_min_u32_e32 v88, v88, v100
	v_max_u32_e32 v100, v101, v89
	v_min_u32_e32 v89, v101, v89
	v_max_u32_e32 v101, v0, v102
	v_min_u32_e32 v0, v0, v102
	v_max_u32_e32 v102, v103, v1
	v_min_u32_e32 v1, v103, v1
	v_max_u32_e32 v103, v2, v104
	v_min_u32_e32 v2, v2, v104
	v_max_u32_e32 v104, v105, v3
	v_min_u32_e32 v3, v105, v3
	v_max_u32_e32 v97, v106, v83
	v_min_u32_e32 v83, v106, v83
	v_max_u32_e32 v106, v82, v90
; #define CE_DESC(a, b) do { const unsigned _mx = (a) > (b) ? (a) : (b), _mn = (a) > (b) ? (b) : (a); (a) = _mx; (b) = _mn; } while (0)
; __device__ __forceinline__ void sort16_desc(unsigned (&k)[16]) {
; #pragma unroll
;     for (int size = 2; size <= 16; size <<= 1)
; #pragma unroll
;         for (int stride = size >> 1; stride > 0; stride >>= 1)
; #pragma unroll
;             for (int i = 0; i < 16; ++i) { const int j = i ^ stride;
;                 if (j > i) { if ((i & size) == 0) CE_DESC(k[i], k[j]); else CE_DESC(k[j], k[i]); } }
; }
	v_min_u32_e32 v82, v82, v90
	v_max_u32_e32 v90, v85, v91
	v_min_u32_e32 v85, v85, v91
	v_max_u32_e32 v91, v92, v84
	v_min_u32_e32 v84, v92, v84
	v_max_u32_e32 v92, v93, v79
	v_min_u32_e32 v79, v93, v79
	v_max_u32_e32 v93, v78, v94
	v_min_u32_e32 v78, v78, v94
	v_max_u32_e32 v94, v81, v95
	v_min_u32_e32 v81, v81, v95
	v_max_u32_e32 v95, v96, v80
	v_min_u32_e32 v80, v96, v80
	v_max_u32_e32 v105, v115, v87
	v_min_u32_e32 v87, v115, v87
	v_max_u32_e32 v115, v86, v98
	v_min_u32_e32 v86, v86, v98
	v_max_u32_e32 v98, v89, v99
	v_min_u32_e32 v89, v89, v99
	v_max_u32_e32 v99, v100, v88
	v_min_u32_e32 v88, v100, v88
	v_max_u32_e32 v100, v101, v1
	v_min_u32_e32 v1, v101, v1
	v_max_u32_e32 v101, v0, v102
	v_min_u32_e32 v0, v0, v102
	v_max_u32_e32 v102, v3, v103
	v_min_u32_e32 v3, v3, v103
	v_max_u32_e32 v103, v104, v2
	v_min_u32_e32 v2, v104, v2
	v_max_u32_e32 v96, v97, v106
	v_min_u32_e32 v97, v97, v106
	v_max_u32_e32 v106, v83, v82
	v_min_u32_e32 v82, v83, v82
	v_max_u32_e32 v83, v84, v85
	v_min_u32_e32 v84, v84, v85
	v_max_u32_e32 v85, v91, v90
	v_min_u32_e32 v90, v91, v90
	v_max_u32_e32 v91, v92, v93
	v_min_u32_e32 v92, v92, v93
	v_max_u32_e32 v93, v79, v78
	v_min_u32_e32 v78, v79, v78
	v_max_u32_e32 v79, v80, v81
	v_min_u32_e32 v80, v80, v81
	v_max_u32_e32 v81, v95, v94
	v_min_u32_e32 v94, v95, v94
	v_max_u32_e32 v104, v105, v115
	v_min_u32_e32 v105, v105, v115
	v_max_u32_e32 v115, v87, v86
	v_min_u32_e32 v86, v87, v86
	v_max_u32_e32 v87, v88, v89
	v_min_u32_e32 v88, v88, v89
	v_max_u32_e32 v89, v99, v98
	v_min_u32_e32 v98, v99, v98
	v_max_u32_e32 v99, v100, v101
	v_min_u32_e32 v100, v100, v101
	v_max_u32_e32 v101, v1, v0
	v_min_u32_e32 v0, v1, v0
	v_max_u32_e32 v1, v2, v3
	v_min_u32_e32 v2, v2, v3
	v_max_u32_e32 v3, v103, v102
	v_min_u32_e32 v102, v103, v102
	v_max_u32_e32 v95, v96, v84
	v_min_u32_e32 v84, v96, v84
	v_max_u32_e32 v96, v97, v83
	v_min_u32_e32 v83, v97, v83
	v_max_u32_e32 v97, v106, v90
	v_min_u32_e32 v90, v106, v90
	v_max_u32_e32 v106, v82, v85
	v_min_u32_e32 v82, v82, v85
	v_max_u32_e32 v85, v80, v91
	v_min_u32_e32 v80, v80, v91
	v_max_u32_e32 v91, v79, v92
	v_min_u32_e32 v79, v79, v92
	v_max_u32_e32 v92, v94, v93
	v_min_u32_e32 v93, v94, v93
	v_max_u32_e32 v94, v81, v78
	v_min_u32_e32 v78, v81, v78
	v_max_u32_e32 v103, v104, v88
	v_min_u32_e32 v88, v104, v88
	v_max_u32_e32 v104, v105, v87
	v_min_u32_e32 v87, v105, v87
	v_max_u32_e32 v105, v115, v98
	v_min_u32_e32 v98, v115, v98
	v_max_u32_e32 v115, v86, v89
	v_min_u32_e32 v86, v86, v89
	v_max_u32_e32 v89, v2, v99
	v_min_u32_e32 v2, v2, v99
	v_max_u32_e32 v99, v1, v100
	v_min_u32_e32 v1, v1, v100
	v_max_u32_e32 v100, v102, v101
	v_min_u32_e32 v101, v102, v101
	v_max_u32_e32 v102, v3, v0
	v_min_u32_e32 v0, v3, v0
	v_max_u32_e32 v81, v95, v97
	v_min_u32_e32 v95, v95, v97
	v_max_u32_e32 v97, v96, v106
	v_min_u32_e32 v96, v96, v106
	v_max_u32_e32 v106, v84, v90
	v_min_u32_e32 v84, v84, v90
	v_max_u32_e32 v90, v83, v82
	v_min_u32_e32 v82, v83, v82
	v_max_u32_e32 v83, v93, v80
	v_min_u32_e32 v80, v93, v80
	v_max_u32_e32 v93, v78, v79
	v_min_u32_e32 v78, v78, v79
	v_max_u32_e32 v79, v92, v85
	v_min_u32_e32 v85, v92, v85
	v_max_u32_e32 v92, v94, v91
	v_min_u32_e32 v91, v94, v91
	v_max_u32_e32 v3, v103, v105
	v_min_u32_e32 v103, v103, v105
	v_max_u32_e32 v105, v104, v115
	v_min_u32_e32 v104, v104, v115
	v_max_u32_e32 v115, v88, v98
	v_min_u32_e32 v88, v88, v98
	v_max_u32_e32 v98, v87, v86
	v_min_u32_e32 v86, v87, v86
	v_max_u32_e32 v87, v101, v2
	v_min_u32_e32 v2, v101, v2
	v_max_u32_e32 v101, v0, v1
	v_min_u32_e32 v0, v0, v1
	v_max_u32_e32 v1, v100, v89
	v_min_u32_e32 v89, v100, v89
	v_max_u32_e32 v100, v102, v99
	v_min_u32_e32 v99, v102, v99
	v_max_u32_e32 v94, v81, v97
	v_min_u32_e32 v81, v81, v97
	v_max_u32_e32 v97, v95, v96
	v_min_u32_e32 v95, v95, v96
	v_max_u32_e32 v96, v106, v90
	v_min_u32_e32 v90, v106, v90
	v_max_u32_e32 v106, v84, v82
	v_min_u32_e32 v82, v84, v82
	v_max_u32_e32 v84, v78, v80
	v_min_u32_e32 v78, v78, v80
	v_max_u32_e32 v80, v93, v83
	v_min_u32_e32 v83, v93, v83
	v_max_u32_e32 v93, v91, v85
	v_min_u32_e32 v85, v91, v85
	v_max_u32_e32 v91, v92, v79
	v_min_u32_e32 v79, v92, v79
	v_max_u32_e32 v102, v3, v105
	v_min_u32_e32 v3, v3, v105
	v_max_u32_e32 v105, v103, v104
	v_min_u32_e32 v103, v103, v104
	v_max_u32_e32 v104, v115, v98
	v_min_u32_e32 v98, v115, v98
	v_max_u32_e32 v115, v88, v86
	v_min_u32_e32 v86, v88, v86
	v_max_u32_e32 v88, v0, v2
	v_min_u32_e32 v0, v0, v2
	v_max_u32_e32 v2, v101, v87
	v_min_u32_e32 v87, v101, v87
	v_max_u32_e32 v101, v99, v89
	v_min_u32_e32 v89, v99, v89
	v_max_u32_e32 v99, v100, v1
	v_min_u32_e32 v1, v100, v1
	v_max_u32_e32 v92, v94, v78
	v_min_u32_e32 v78, v94, v78
	v_max_u32_e32 v94, v81, v84
	v_min_u32_e32 v81, v81, v84
	v_max_u32_e32 v84, v97, v83
	v_min_u32_e32 v83, v97, v83
	v_max_u32_e32 v97, v95, v80
	v_min_u32_e32 v80, v95, v80
	v_max_u32_e32 v95, v96, v85
	v_min_u32_e32 v85, v96, v85
	v_max_u32_e32 v96, v90, v93
	v_min_u32_e32 v90, v90, v93
	v_max_u32_e32 v93, v106, v79
	v_min_u32_e32 v79, v106, v79
	v_max_u32_e32 v106, v82, v91
	v_min_u32_e32 v82, v82, v91
	v_max_u32_e32 v100, v102, v0
	v_min_u32_e32 v0, v102, v0
	v_max_u32_e32 v102, v3, v88
	v_min_u32_e32 v3, v3, v88
	v_max_u32_e32 v88, v105, v87
	v_min_u32_e32 v87, v105, v87
	v_max_u32_e32 v105, v103, v2
	v_min_u32_e32 v2, v103, v2
	v_max_u32_e32 v103, v104, v89
	v_min_u32_e32 v89, v104, v89
	v_max_u32_e32 v104, v98, v101
	v_min_u32_e32 v98, v98, v101
	v_max_u32_e32 v101, v115, v1
	v_min_u32_e32 v1, v115, v1
	v_max_u32_e32 v115, v86, v99
	v_min_u32_e32 v86, v86, v99
	v_max_u32_e32 v91, v92, v95
	v_min_u32_e32 v92, v92, v95
	v_max_u32_e32 v95, v94, v96
; #define CE_DESC(a, b) do { const unsigned _mx = (a) > (b) ? (a) : (b), _mn = (a) > (b) ? (b) : (a); (a) = _mx; (b) = _mn; } while (0)
; __device__ __forceinline__ void merge16(unsigned (&a)[16], const unsigned (&b)[16]) {
; #pragma unroll
;     for (int i = 0; i < 16; ++i) a[i] = a[i] > b[15 - i] ? a[i] : b[15 - i];
; #pragma unroll
;     for (int stride = 8; stride > 0; stride >>= 1)
; #pragma unroll
;         for (int i = 0; i < 16; ++i) { const int j = i ^ stride; if (j > i) CE_DESC(a[i], a[j]); }
; }
; __device__ __forceinline__ void peer_tile(const Args& A, LAS unsigned char* lds, int tile) {
;     ...
;                 sort16_desc(k0); sort16_desc(k1); merge16(k0, k1);
; #pragma unroll
;                 for (int msk = 16; msk <= 32; msk <<= 1) {
; #pragma unroll
;                     for (int i = 0; i < 16; ++i) k1[i] = (unsigned)__shfl_xor((int)k0[i], msk);
;                     merge16(k0, k1); }
	v_min_u32_e32 v94, v94, v96
	v_max_u32_e32 v96, v84, v93
	v_min_u32_e32 v84, v84, v93
	v_max_u32_e32 v93, v97, v106
	v_min_u32_e32 v97, v97, v106
	v_max_u32_e32 v106, v78, v85
	v_min_u32_e32 v78, v78, v85
	v_max_u32_e32 v85, v81, v90
	v_min_u32_e32 v81, v81, v90
	v_max_u32_e32 v90, v83, v79
	v_min_u32_e32 v79, v83, v79
	v_max_u32_e32 v83, v80, v82
	v_min_u32_e32 v80, v80, v82
	v_max_u32_e32 v99, v100, v103
	v_min_u32_e32 v100, v100, v103
	v_max_u32_e32 v103, v102, v104
	v_min_u32_e32 v102, v102, v104
	v_max_u32_e32 v104, v88, v101
	v_min_u32_e32 v88, v88, v101
	v_max_u32_e32 v101, v105, v115
	v_min_u32_e32 v105, v105, v115
	v_max_u32_e32 v115, v0, v89
	v_min_u32_e32 v0, v0, v89
	v_max_u32_e32 v89, v3, v98
	v_min_u32_e32 v3, v3, v98
	v_max_u32_e32 v98, v87, v1
	v_min_u32_e32 v1, v87, v1
	v_max_u32_e32 v87, v2, v86
	v_min_u32_e32 v2, v2, v86
	v_max_u32_e32 v82, v91, v96
	v_min_u32_e32 v91, v91, v96
	v_max_u32_e32 v96, v95, v93
	v_min_u32_e32 v93, v95, v93
	v_max_u32_e32 v95, v92, v84
	v_min_u32_e32 v84, v92, v84
	v_max_u32_e32 v92, v94, v97
	v_min_u32_e32 v94, v94, v97
	v_max_u32_e32 v97, v106, v90
	v_min_u32_e32 v90, v106, v90
	v_max_u32_e32 v106, v85, v83
	v_min_u32_e32 v83, v85, v83
	v_max_u32_e32 v85, v78, v79
	v_min_u32_e32 v78, v78, v79
	v_max_u32_e32 v79, v81, v80
	v_min_u32_e32 v80, v81, v80
	v_max_u32_e32 v86, v99, v104
	v_min_u32_e32 v99, v99, v104
	v_max_u32_e32 v104, v103, v101
	v_min_u32_e32 v101, v103, v101
	v_max_u32_e32 v103, v100, v88
	v_min_u32_e32 v88, v100, v88
	v_max_u32_e32 v100, v102, v105
	v_min_u32_e32 v102, v102, v105
	v_max_u32_e32 v105, v115, v98
	v_min_u32_e32 v98, v115, v98
	v_max_u32_e32 v115, v89, v87
	v_min_u32_e32 v87, v89, v87
	v_max_u32_e32 v89, v0, v1
	v_min_u32_e32 v0, v0, v1
	v_max_u32_e32 v1, v3, v2
	v_min_u32_e32 v2, v3, v2
	v_min_u32_e32 v81, v82, v96
	v_min_u32_e32 v107, v91, v93
	v_min_u32_e32 v108, v95, v92
	v_min_u32_e32 v109, v84, v94
	v_min_u32_e32 v110, v97, v106
	v_min_u32_e32 v111, v90, v83
	v_min_u32_e32 v112, v85, v79
	v_min_u32_e32 v114, v78, v80
	v_min_u32_e32 v3, v86, v104
	v_min_u32_e32 v116, v99, v101
	v_min_u32_e32 v117, v103, v100
	v_min_u32_e32 v118, v88, v102
	v_min_u32_e32 v119, v105, v115
	v_min_u32_e32 v120, v98, v87
	v_min_u32_e32 v121, v89, v1
	v_min_u32_e32 v122, v0, v2
	v_max3_u32 v82, v82, v96, v122
	v_max3_u32 v0, v81, v0, v2
	v_max3_u32 v2, v91, v93, v121
	v_max3_u32 v1, v107, v89, v1
	v_max3_u32 v81, v95, v92, v120
	v_max3_u32 v87, v108, v98, v87
	v_max3_u32 v84, v84, v94, v119
	v_max3_u32 v89, v109, v105, v115
	v_max3_u32 v91, v97, v106, v118
	v_max3_u32 v88, v110, v88, v102
	v_max3_u32 v83, v90, v83, v117
	v_max3_u32 v90, v111, v103, v100
	v_max3_u32 v79, v85, v79, v116
	v_max3_u32 v85, v112, v99, v101
	v_max3_u32 v3, v78, v80, v3
	v_max3_u32 v78, v114, v86, v104
	v_max_u32_e32 v80, v82, v91
	v_min_u32_e32 v82, v82, v91
	v_max_u32_e32 v86, v0, v88
	v_min_u32_e32 v0, v0, v88
	v_max_u32_e32 v88, v2, v83
	v_min_u32_e32 v2, v2, v83
	v_max_u32_e32 v83, v1, v90
	v_min_u32_e32 v1, v1, v90
	v_max_u32_e32 v90, v81, v79
	v_min_u32_e32 v79, v81, v79
	v_max_u32_e32 v81, v87, v85
	v_min_u32_e32 v85, v87, v85
	v_max_u32_e32 v87, v84, v3
	v_min_u32_e32 v3, v84, v3
	v_max_u32_e32 v84, v89, v78
	v_min_u32_e32 v78, v89, v78
	v_max_u32_e32 v89, v80, v90
	v_min_u32_e32 v80, v80, v90
	v_max_u32_e32 v90, v86, v81
	v_min_u32_e32 v81, v86, v81
	v_max_u32_e32 v86, v88, v87
	v_min_u32_e32 v87, v88, v87
	v_max_u32_e32 v88, v83, v84
	v_min_u32_e32 v83, v83, v84
	v_max_u32_e32 v84, v82, v79
	v_min_u32_e32 v79, v82, v79
	v_max_u32_e32 v82, v0, v85
	v_min_u32_e32 v0, v0, v85
	v_max_u32_e32 v85, v2, v3
	v_min_u32_e32 v2, v2, v3
	v_max_u32_e32 v3, v1, v78
	v_min_u32_e32 v1, v1, v78
	v_max_u32_e32 v78, v89, v86
	v_min_u32_e32 v86, v89, v86
	v_max_u32_e32 v89, v90, v88
	v_min_u32_e32 v88, v90, v88
	v_max_u32_e32 v90, v80, v87
	v_min_u32_e32 v80, v80, v87
	v_max_u32_e32 v87, v81, v83
	v_min_u32_e32 v81, v81, v83
	v_max_u32_e32 v83, v84, v85
	v_min_u32_e32 v84, v84, v85
	v_max_u32_e32 v85, v82, v3
	v_min_u32_e32 v3, v82, v3
	v_max_u32_e32 v82, v79, v2
	v_min_u32_e32 v2, v79, v2
	v_max_u32_e32 v79, v0, v1
	v_min_u32_e32 v0, v0, v1
	v_max_u32_e32 v1, v78, v89
	v_min_u32_e32 v78, v78, v89
	v_max_u32_e32 v89, v86, v88
	v_min_u32_e32 v86, v86, v88
	v_max_u32_e32 v88, v90, v87
	v_min_u32_e32 v87, v90, v87
	v_max_u32_e32 v90, v80, v81
	v_min_u32_e32 v80, v80, v81
	v_max_u32_e32 v81, v83, v85
	v_min_u32_e32 v83, v83, v85
	v_max_u32_e32 v85, v84, v3
	v_min_u32_e32 v3, v84, v3
	v_max_u32_e32 v84, v82, v79
	v_min_u32_e32 v79, v82, v79
	v_max_u32_e32 v82, v2, v0
	v_min_u32_e32 v0, v2, v0
	ds_bpermute_b32 v2, v27, v1
	ds_bpermute_b32 v91, v27, v78
	ds_bpermute_b32 v92, v27, v89
	ds_bpermute_b32 v93, v27, v86
	ds_bpermute_b32 v94, v27, v88
	ds_bpermute_b32 v95, v27, v87
	ds_bpermute_b32 v96, v27, v90
	ds_bpermute_b32 v97, v27, v80
	ds_bpermute_b32 v98, v27, v81
	ds_bpermute_b32 v99, v27, v83
	ds_bpermute_b32 v100, v27, v85
	ds_bpermute_b32 v101, v27, v0
	ds_bpermute_b32 v102, v27, v82
	ds_bpermute_b32 v103, v27, v79
	ds_bpermute_b32 v104, v27, v84
	ds_bpermute_b32 v105, v27, v3
	s_waitcnt lgkmcnt(4)
	v_max_u32_e32 v1, v1, v101
	s_waitcnt lgkmcnt(3)
	v_max_u32_e32 v78, v78, v102
	s_waitcnt lgkmcnt(2)
	v_max_u32_e32 v89, v89, v103
	s_waitcnt lgkmcnt(1)
	v_max_u32_e32 v86, v86, v104
	s_waitcnt lgkmcnt(0)
; __device__ __forceinline__ void peer_tile(const Args& A, LAS unsigned char* lds, int tile) {
;     ...
;                 { const bf16_t* sp = QRY + m * 2048 + hp * 128 + 32 * g;
;                   const u32x4 s0 = *(const u32x4*)sp, s1 = *(const u32x4*)(sp + 8), s2 = *(const u32x4*)(sp + 16), s3 = *(const u32x4*)(sp + 24);
;     ...
;                 for (int msk = 16; msk <= 32; msk <<= 1) {
; #pragma unroll
;                     for (int i = 0; i < 16; ++i) k1[i] = (unsigned)__shfl_xor((int)k0[i], msk);
;                     merge16(k0, k1); }
	v_max_u32_e32 v88, v88, v105
	v_max_u32_e32 v87, v87, v100
	v_max_u32_e32 v90, v90, v99
	v_max_u32_e32 v80, v80, v98
	v_max_u32_e32 v81, v81, v97
	v_max_u32_e32 v83, v83, v96
	v_max_u32_e32 v85, v85, v95
	v_max_u32_e32 v3, v3, v94
	v_max_u32_e32 v84, v84, v93
	v_max_u32_e32 v79, v79, v92
	v_max_u32_e32 v82, v82, v91
	v_max_u32_e32 v0, v0, v2
	v_max_u32_e32 v2, v1, v81
	v_min_u32_e32 v1, v1, v81
	v_max_u32_e32 v81, v78, v83
	v_min_u32_e32 v78, v78, v83
	v_max_u32_e32 v83, v89, v85
	v_min_u32_e32 v85, v89, v85
	v_max_u32_e32 v89, v86, v3
	v_min_u32_e32 v3, v86, v3
	v_max_u32_e32 v86, v88, v84
	v_min_u32_e32 v84, v88, v84
	v_max_u32_e32 v88, v87, v79
	v_min_u32_e32 v79, v87, v79
	v_max_u32_e32 v87, v90, v82
	v_min_u32_e32 v82, v90, v82
	v_max_u32_e32 v90, v80, v0
	v_min_u32_e32 v0, v80, v0
	v_max_u32_e32 v80, v2, v86
	v_min_u32_e32 v2, v2, v86
	v_max_u32_e32 v86, v81, v88
	v_min_u32_e32 v81, v81, v88
	v_max_u32_e32 v88, v83, v87
	v_min_u32_e32 v83, v83, v87
	v_max_u32_e32 v87, v89, v90
	v_min_u32_e32 v89, v89, v90
	v_max_u32_e32 v90, v1, v84
	v_min_u32_e32 v1, v1, v84
	v_max_u32_e32 v84, v78, v79
	v_min_u32_e32 v78, v78, v79
	v_max_u32_e32 v79, v85, v82
	v_min_u32_e32 v82, v85, v82
	v_max_u32_e32 v85, v3, v0
	v_min_u32_e32 v0, v3, v0
	v_max_u32_e32 v3, v80, v88
	v_min_u32_e32 v80, v80, v88
	v_max_u32_e32 v88, v86, v87
	v_min_u32_e32 v86, v86, v87
	v_max_u32_e32 v87, v2, v83
	v_min_u32_e32 v2, v2, v83
	v_max_u32_e32 v83, v81, v89
	v_min_u32_e32 v81, v81, v89
	v_max_u32_e32 v89, v90, v79
	v_min_u32_e32 v79, v90, v79
	v_max_u32_e32 v90, v84, v85
	v_min_u32_e32 v84, v84, v85
	v_max_u32_e32 v85, v1, v82
	v_min_u32_e32 v1, v1, v82
	v_max_u32_e32 v82, v78, v0
	v_min_u32_e32 v0, v78, v0
	v_max_u32_e32 v78, v3, v88
	v_min_u32_e32 v3, v3, v88
	v_max_u32_e32 v88, v80, v86
	v_min_u32_e32 v80, v80, v86
	v_max_u32_e32 v86, v87, v83
	v_min_u32_e32 v83, v87, v83
	v_max_u32_e32 v87, v2, v81
	v_min_u32_e32 v2, v2, v81
	v_max_u32_e32 v81, v89, v90
	v_min_u32_e32 v89, v89, v90
	v_max_u32_e32 v90, v79, v84
	v_min_u32_e32 v79, v79, v84
	v_max_u32_e32 v84, v85, v82
	v_min_u32_e32 v82, v85, v82
	v_max_u32_e32 v85, v1, v0
	v_min_u32_e32 v0, v1, v0
	ds_bpermute_b32 v94, v29, v0
	ds_bpermute_b32 v1, v29, v78
	ds_bpermute_b32 v91, v29, v3
	ds_bpermute_b32 v92, v29, v88
	ds_bpermute_b32 v93, v29, v80
	s_waitcnt lgkmcnt(4)
	v_max_u32_e32 v78, v78, v94
	global_load_dwordx4 v[94:97], v[4:5], off offset:1040
	global_load_dwordx4 v[98:101], v[4:5], off offset:1024
	ds_bpermute_b32 v102, v29, v86
	ds_bpermute_b32 v103, v29, v83
	ds_bpermute_b32 v104, v29, v87
	ds_bpermute_b32 v105, v29, v2
	ds_bpermute_b32 v106, v29, v81
	ds_bpermute_b32 v107, v29, v89
	ds_bpermute_b32 v108, v29, v90
	ds_bpermute_b32 v109, v29, v79
	ds_bpermute_b32 v110, v29, v84
	ds_bpermute_b32 v111, v29, v85
	ds_bpermute_b32 v112, v29, v82
	s_waitcnt lgkmcnt(4)
	v_max_u32_e32 v83, v83, v108
	s_waitcnt lgkmcnt(3)
	v_max_u32_e32 v86, v86, v109
	s_waitcnt lgkmcnt(2)
	v_max_u32_e32 v80, v80, v110
	s_waitcnt lgkmcnt(1)
	v_max_u32_e32 v3, v3, v111
	s_waitcnt lgkmcnt(0)
	v_max_u32_e32 v88, v88, v112
	v_max_u32_e32 v87, v87, v107
	v_max_u32_e32 v2, v2, v106
	v_max_u32_e32 v81, v81, v105
	v_max_u32_e32 v89, v89, v104
	v_max_u32_e32 v90, v90, v103
	v_max_u32_e32 v79, v79, v102
	v_max_u32_e32 v84, v84, v93
	v_max_u32_e32 v82, v82, v92
	v_max_u32_e32 v85, v85, v91
	v_max_u32_e32 v0, v0, v1
	v_max_u32_e32 v1, v78, v81
	v_min_u32_e32 v78, v78, v81
	v_max_u32_e32 v81, v3, v89
	v_min_u32_e32 v3, v3, v89
	v_max_u32_e32 v89, v88, v90
	v_min_u32_e32 v88, v88, v90
	v_max_u32_e32 v90, v80, v79
	v_min_u32_e32 v79, v80, v79
	v_max_u32_e32 v80, v86, v84
	v_min_u32_e32 v84, v86, v84
	v_max_u32_e32 v86, v83, v82
	v_min_u32_e32 v82, v83, v82
	v_max_u32_e32 v83, v87, v85
	v_min_u32_e32 v85, v87, v85
	v_max_u32_e32 v87, v2, v0
	v_min_u32_e32 v0, v2, v0
	v_max_u32_e32 v2, v1, v80
	v_min_u32_e32 v1, v1, v80
	v_max_u32_e32 v80, v81, v86
	v_min_u32_e32 v81, v81, v86
	v_max_u32_e32 v86, v89, v83
	v_min_u32_e32 v83, v89, v83
	v_max_u32_e32 v89, v90, v87
	v_min_u32_e32 v87, v90, v87
	v_max_u32_e32 v90, v78, v84
	v_min_u32_e32 v78, v78, v84
	v_max_u32_e32 v84, v3, v82
	v_min_u32_e32 v3, v3, v82
	v_max_u32_e32 v82, v88, v85
	v_min_u32_e32 v85, v88, v85
	v_max_u32_e32 v88, v79, v0
	v_min_u32_e32 v0, v79, v0
	v_max_u32_e32 v79, v2, v86
	v_min_u32_e32 v2, v2, v86
	v_max_u32_e32 v86, v80, v89
	v_min_u32_e32 v80, v80, v89
	v_max_u32_e32 v102, v1, v83
	v_min_u32_e32 v1, v1, v83
	v_max_u32_e32 v83, v81, v87
	v_min_u32_e32 v81, v81, v87
	v_max_u32_e32 v103, v90, v82
	v_min_u32_e32 v82, v90, v82
	v_max_u32_e32 v104, v84, v88
	v_min_u32_e32 v105, v84, v88
	v_max_u32_e32 v106, v78, v85
	v_min_u32_e32 v78, v78, v85
	v_max_u32_e32 v107, v3, v0
	v_min_u32_e32 v0, v3, v0
	v_max_u32_e32 v93, v79, v86
	v_min_u32_e32 v92, v79, v86
	v_max_u32_e32 v91, v2, v80
	v_min_u32_e32 v90, v2, v80
	v_max_u32_e32 v89, v102, v83
	v_min_u32_e32 v88, v102, v83
	v_max_u32_e32 v87, v1, v81
	v_min_u32_e32 v86, v1, v81
	v_max_u32_e32 v85, v103, v104
	v_min_u32_e32 v84, v103, v104
	v_max_u32_e32 v83, v82, v105
	v_min_u32_e32 v82, v82, v105
	v_max_u32_e32 v79, v78, v0
	v_min_u32_e32 v78, v78, v0
	global_load_dwordx4 v[0:3], v[4:5], off offset:1072
	global_load_dwordx4 v[102:105], v[4:5], off offset:1056
	v_max_u32_e32 v81, v106, v107
	v_min_u32_e32 v80, v106, v107
	s_waitcnt vmcnt(2)
; __device__ __forceinline__ unsigned f2key(float f) { const unsigned u = __float_as_uint(f); return (u & 0x80000000u) ? ~u : (u | 0x80000000u); }
; __device__ __forceinline__ void peer_tile(const Args& A, LAS unsigned char* lds, int tile) {
;     ...
;                 { const bf16_t* sp = QRY + m * 2048 + hp * 128 + 32 * g;
;                   const u32x4 s0 = *(const u32x4*)sp, s1 = *(const u32x4*)(sp + 8), s2 = *(const u32x4*)(sp + 16), s3 = *(const u32x4*)(sp + 24);
;                   const unsigned sw[16] = {s0.x, s0.y, s0.z, s0.w, s1.x, s1.y, s1.z, s1.w, s2.x, s2.y, s2.z, s2.w, s3.x, s3.y, s3.z, s3.w};
; #pragma unroll
;                   for (int i = 0; i < 16; ++i) {
;                       const float lo = (float)__builtin_bit_cast(_Float16, (unsigned short)(sw[i] & 0xffffu)), hi = (float)__builtin_bit_cast(_Float16, (unsigned short)(sw[i] >> 16));
;                       const unsigned klo = (f2key(lo) & ~127u) | (unsigned)(127 - (32 * g + 2 * i)), khi = (f2key(hi) & ~127u) | (unsigned)(127 - (32 * g + 2 * i + 1));
;                       if (i < 8) { k0[2 * i] = klo; k0[2 * i + 1] = khi; } else { k1[2 * (i - 8)] = klo; k1[2 * (i - 8) + 1] = khi; } } }
	v_cvt_f32_f16_sdwa v106, v98 dst_sel:DWORD dst_unused:UNUSED_PAD src0_sel:WORD_1
	v_cvt_f32_f16_e32 v98, v98
	v_cndmask_b32_e64 v34, v66, v34, s[0:1]
	v_cndmask_b32_e64 v33, v65, v33, s[0:1]
	v_not_b32_e32 v107, v106
	v_or_b32_e32 v108, 0x80000000, v106
	v_cmp_gt_i32_e32 vcc, 0, v106
	v_cndmask_b32_e64 v32, v64, v32, s[0:1]
	v_cndmask_b32_e64 v31, v63, v31, s[0:1]
	v_cndmask_b32_e32 v106, v108, v107, vcc
	v_not_b32_e32 v107, v98
	v_or_b32_e32 v108, 0x80000000, v98
	v_cmp_gt_i32_e32 vcc, 0, v98
	v_and_b32_e32 v106, 0xffffff80, v106
	v_sub_u32_e32 v106, v106, v15
	v_cndmask_b32_e32 v98, v108, v107, vcc
	v_cvt_f32_f16_sdwa v107, v99 dst_sel:DWORD dst_unused:UNUSED_PAD src0_sel:WORD_1
	v_cvt_f32_f16_e32 v99, v99
	v_and_b32_e32 v98, 0xffffff80, v98
	v_sub_u32_e32 v98, v98, v15
	v_not_b32_e32 v108, v107
	v_or_b32_e32 v109, 0x80000000, v107
	v_cmp_gt_i32_e32 vcc, 0, v107
	v_add_u32_e32 v106, 0x7e, v106
	v_add_u32_e32 v98, 0x7f, v98
	v_cndmask_b32_e32 v107, v109, v108, vcc
	v_not_b32_e32 v108, v99
	v_or_b32_e32 v109, 0x80000000, v99
	v_cmp_gt_i32_e32 vcc, 0, v99
	v_and_b32_e32 v107, 0xffffff80, v107
	v_sub_u32_e32 v107, v107, v14
	v_cndmask_b32_e32 v99, v109, v108, vcc
	v_cvt_f32_f16_sdwa v108, v100 dst_sel:DWORD dst_unused:UNUSED_PAD src0_sel:WORD_1
	v_cvt_f32_f16_e32 v100, v100
	v_and_b32_e32 v99, 0xffffff80, v99
	v_sub_u32_e32 v99, v99, v14
	v_not_b32_e32 v109, v108
	v_or_b32_e32 v110, 0x80000000, v108
	v_cmp_gt_i32_e32 vcc, 0, v108
	v_add_u32_e32 v107, 0x7e, v107
	v_add_u32_e32 v99, 0x7f, v99
	v_cndmask_b32_e32 v108, v110, v109, vcc
	v_not_b32_e32 v109, v100
	v_or_b32_e32 v110, 0x80000000, v100
	v_cmp_gt_i32_e32 vcc, 0, v100
	v_and_b32_e32 v108, 0xffffff80, v108
	v_sub_u32_e32 v108, v108, v12
	v_cndmask_b32_e32 v100, v110, v109, vcc
	v_cvt_f32_f16_sdwa v109, v101 dst_sel:DWORD dst_unused:UNUSED_PAD src0_sel:WORD_1
	v_cvt_f32_f16_e32 v101, v101
	v_and_b32_e32 v100, 0xffffff80, v100
	v_sub_u32_e32 v100, v100, v12
	v_not_b32_e32 v110, v109
	v_or_b32_e32 v111, 0x80000000, v109
	v_cmp_gt_i32_e32 vcc, 0, v109
	v_add_u32_e32 v108, 0x7e, v108
	v_add_u32_e32 v100, 0x7f, v100
	v_cndmask_b32_e32 v109, v111, v110, vcc
	v_not_b32_e32 v110, v101
	v_or_b32_e32 v111, 0x80000000, v101
	v_cmp_gt_i32_e32 vcc, 0, v101
	v_and_b32_e32 v109, 0xffffff80, v109
	v_sub_u32_e32 v109, v109, v10
	v_cndmask_b32_e32 v101, v111, v110, vcc
	v_cvt_f32_f16_sdwa v110, v94 dst_sel:DWORD dst_unused:UNUSED_PAD src0_sel:WORD_1
	v_cvt_f32_f16_e32 v94, v94
	v_and_b32_e32 v101, 0xffffff80, v101
	v_sub_u32_e32 v101, v101, v10
	v_not_b32_e32 v111, v110
	v_or_b32_e32 v112, 0x80000000, v110
	v_cmp_gt_i32_e32 vcc, 0, v110
	v_add_u32_e32 v109, 0x7e, v109
	v_add_u32_e32 v101, 0x7f, v101
	v_cndmask_b32_e32 v110, v112, v111, vcc
	v_not_b32_e32 v111, v94
	v_or_b32_e32 v112, 0x80000000, v94
	v_cmp_gt_i32_e32 vcc, 0, v94
	v_and_b32_e32 v110, 0xffffff80, v110
	v_sub_u32_e32 v110, v110, v8
	v_cndmask_b32_e32 v94, v112, v111, vcc
	v_cvt_f32_f16_sdwa v111, v95 dst_sel:DWORD dst_unused:UNUSED_PAD src0_sel:WORD_1
	v_cvt_f32_f16_e32 v95, v95
	v_and_b32_e32 v94, 0xffffff80, v94
	v_sub_u32_e32 v94, v94, v8
	v_not_b32_e32 v112, v111
	v_or_b32_e32 v114, 0x80000000, v111
	v_cmp_gt_i32_e32 vcc, 0, v111
	v_add_u32_e32 v110, 0x7e, v110
	v_add_u32_e32 v94, 0x7f, v94
	v_cndmask_b32_e32 v111, v114, v112, vcc
	v_not_b32_e32 v112, v95
	v_or_b32_e32 v114, 0x80000000, v95
	v_cmp_gt_i32_e32 vcc, 0, v95
	v_and_b32_e32 v111, 0xffffff80, v111
	v_sub_u32_e32 v111, v111, v16
	v_cndmask_b32_e32 v95, v114, v112, vcc
	v_cvt_f32_f16_sdwa v112, v96 dst_sel:DWORD dst_unused:UNUSED_PAD src0_sel:WORD_1
	v_cvt_f32_f16_e32 v96, v96
	v_and_b32_e32 v95, 0xffffff80, v95
	v_sub_u32_e32 v95, v95, v16
	v_not_b32_e32 v114, v112
	v_or_b32_e32 v115, 0x80000000, v112
	v_cmp_gt_i32_e32 vcc, 0, v112
	v_add_u32_e32 v111, 0x7e, v111
	v_add_u32_e32 v95, 0x7f, v95
	v_cndmask_b32_e32 v112, v115, v114, vcc
	v_not_b32_e32 v114, v96
	v_or_b32_e32 v115, 0x80000000, v96
	v_cmp_gt_i32_e32 vcc, 0, v96
	v_and_b32_e32 v112, 0xffffff80, v112
	v_sub_u32_e32 v112, v112, v17
	v_cndmask_b32_e32 v96, v115, v114, vcc
	v_cvt_f32_f16_sdwa v114, v97 dst_sel:DWORD dst_unused:UNUSED_PAD src0_sel:WORD_1
	v_cvt_f32_f16_e32 v97, v97
	v_and_b32_e32 v96, 0xffffff80, v96
	v_sub_u32_e32 v96, v96, v17
	v_not_b32_e32 v115, v114
	v_or_b32_e32 v116, 0x80000000, v114
	v_cmp_gt_i32_e32 vcc, 0, v114
	v_add_u32_e32 v112, 0x7e, v112
	v_add_u32_e32 v96, 0x7f, v96
	v_cndmask_b32_e32 v114, v116, v115, vcc
	v_not_b32_e32 v115, v97
	v_or_b32_e32 v116, 0x80000000, v97
	v_cmp_gt_i32_e32 vcc, 0, v97
	v_and_b32_e32 v114, 0xffffff80, v114
	v_sub_u32_e32 v114, v114, v18
	v_cndmask_b32_e32 v97, v116, v115, vcc
	s_waitcnt vmcnt(0)
; __device__ __forceinline__ unsigned f2key(float f) { const unsigned u = __float_as_uint(f); return (u & 0x80000000u) ? ~u : (u | 0x80000000u); }
; #define CE_DESC(a, b) do { const unsigned _mx = (a) > (b) ? (a) : (b), _mn = (a) > (b) ? (b) : (a); (a) = _mx; (b) = _mn; } while (0)
; __device__ __forceinline__ void sort16_desc(unsigned (&k)[16]) {
; #pragma unroll
;     for (int size = 2; size <= 16; size <<= 1)
; #pragma unroll
;         for (int stride = size >> 1; stride > 0; stride >>= 1)
; #pragma unroll
;             for (int i = 0; i < 16; ++i) { const int j = i ^ stride;
;                 if (j > i) { if ((i & size) == 0) CE_DESC(k[i], k[j]); else CE_DESC(k[j], k[i]); } }
; __device__ __forceinline__ void peer_tile(const Args& A, LAS unsigned char* lds, int tile) {
;     ...
;                   for (int i = 0; i < 16; ++i) {
;                       const float lo = (float)__builtin_bit_cast(_Float16, (unsigned short)(sw[i] & 0xffffu)), hi = (float)__builtin_bit_cast(_Float16, (unsigned short)(sw[i] >> 16));
;                       const unsigned klo = (f2key(lo) & ~127u) | (unsigned)(127 - (32 * g + 2 * i)), khi = (f2key(hi) & ~127u) | (unsigned)(127 - (32 * g + 2 * i + 1));
;                       if (i < 8) { k0[2 * i] = klo; k0[2 * i + 1] = khi; } else { k1[2 * (i - 8)] = klo; k1[2 * (i - 8) + 1] = khi; } } }
;                 sort16_desc(k0); sort16_desc(k1); merge16(k0, k1);
	v_cvt_f32_f16_sdwa v115, v102 dst_sel:DWORD dst_unused:UNUSED_PAD src0_sel:WORD_1
	v_cvt_f32_f16_e32 v102, v102
	v_and_b32_e32 v97, 0xffffff80, v97
	v_sub_u32_e32 v97, v97, v18
	v_not_b32_e32 v116, v115
	v_or_b32_e32 v117, 0x80000000, v115
	v_cmp_gt_i32_e32 vcc, 0, v115
	v_add_u32_e32 v114, 0x7e, v114
	v_add_u32_e32 v97, 0x7f, v97
	v_cndmask_b32_e32 v115, v117, v116, vcc
	v_not_b32_e32 v116, v102
	v_or_b32_e32 v117, 0x80000000, v102
	v_cmp_gt_i32_e32 vcc, 0, v102
	v_and_b32_e32 v115, 0xffffff80, v115
	v_sub_u32_e32 v115, v115, v20
	v_cndmask_b32_e32 v102, v117, v116, vcc
	v_cvt_f32_f16_sdwa v116, v103 dst_sel:DWORD dst_unused:UNUSED_PAD src0_sel:WORD_1
	v_cvt_f32_f16_e32 v103, v103
	v_and_b32_e32 v102, 0xffffff80, v102
	v_sub_u32_e32 v102, v102, v20
	v_not_b32_e32 v117, v116
	v_or_b32_e32 v118, 0x80000000, v116
	v_cmp_gt_i32_e32 vcc, 0, v116
	v_add_u32_e32 v115, 0x7e, v115
	v_add_u32_e32 v102, 0x7f, v102
	v_cndmask_b32_e32 v116, v118, v117, vcc
	v_not_b32_e32 v117, v103
	v_or_b32_e32 v118, 0x80000000, v103
	v_cmp_gt_i32_e32 vcc, 0, v103
	v_and_b32_e32 v116, 0xffffff80, v116
	v_sub_u32_e32 v116, v116, v21
	v_cndmask_b32_e32 v103, v118, v117, vcc
	v_cvt_f32_f16_sdwa v117, v104 dst_sel:DWORD dst_unused:UNUSED_PAD src0_sel:WORD_1
	v_cvt_f32_f16_e32 v104, v104
	v_and_b32_e32 v103, 0xffffff80, v103
	v_sub_u32_e32 v103, v103, v21
	v_not_b32_e32 v118, v117
	v_or_b32_e32 v119, 0x80000000, v117
	v_cmp_gt_i32_e32 vcc, 0, v117
	v_add_u32_e32 v116, 0x7e, v116
	v_add_u32_e32 v103, 0x7f, v103
	v_cndmask_b32_e32 v117, v119, v118, vcc
	v_not_b32_e32 v118, v104
	v_or_b32_e32 v119, 0x80000000, v104
	v_cmp_gt_i32_e32 vcc, 0, v104
	v_and_b32_e32 v117, 0xffffff80, v117
	v_sub_u32_e32 v117, v117, v22
	v_cndmask_b32_e32 v104, v119, v118, vcc
	v_cvt_f32_f16_sdwa v118, v105 dst_sel:DWORD dst_unused:UNUSED_PAD src0_sel:WORD_1
	v_cvt_f32_f16_e32 v105, v105
	v_and_b32_e32 v104, 0xffffff80, v104
	v_sub_u32_e32 v104, v104, v22
	v_not_b32_e32 v119, v118
	v_or_b32_e32 v120, 0x80000000, v118
	v_cmp_gt_i32_e32 vcc, 0, v118
	v_add_u32_e32 v117, 0x7e, v117
	v_add_u32_e32 v104, 0x7f, v104
	v_cndmask_b32_e32 v118, v120, v119, vcc
	v_not_b32_e32 v119, v105
	v_or_b32_e32 v120, 0x80000000, v105
	v_cmp_gt_i32_e32 vcc, 0, v105
	v_and_b32_e32 v118, 0xffffff80, v118
	v_sub_u32_e32 v118, v118, v23
	v_cndmask_b32_e32 v105, v120, v119, vcc
	v_cvt_f32_f16_sdwa v119, v0 dst_sel:DWORD dst_unused:UNUSED_PAD src0_sel:WORD_1
	v_cvt_f32_f16_e32 v0, v0
	v_and_b32_e32 v105, 0xffffff80, v105
	v_sub_u32_e32 v105, v105, v23
	v_not_b32_e32 v120, v119
	v_or_b32_e32 v121, 0x80000000, v119
	v_cmp_gt_i32_e32 vcc, 0, v119
	v_add_u32_e32 v118, 0x7e, v118
	v_add_u32_e32 v105, 0x7f, v105
	v_cndmask_b32_e32 v119, v121, v120, vcc
	v_not_b32_e32 v120, v0
	v_or_b32_e32 v121, 0x80000000, v0
	v_cmp_gt_i32_e32 vcc, 0, v0
	v_and_b32_e32 v119, 0xffffff80, v119
	v_sub_u32_e32 v119, v119, v24
	v_cndmask_b32_e32 v0, v121, v120, vcc
	v_cvt_f32_f16_sdwa v120, v1 dst_sel:DWORD dst_unused:UNUSED_PAD src0_sel:WORD_1
	v_cvt_f32_f16_e32 v1, v1
	v_and_b32_e32 v0, 0xffffff80, v0
	v_sub_u32_e32 v0, v0, v24
	v_not_b32_e32 v121, v120
	v_or_b32_e32 v122, 0x80000000, v120
	v_cmp_gt_i32_e32 vcc, 0, v120
	v_add_u32_e32 v119, 0x7e, v119
	v_add_u32_e32 v0, 0x7f, v0
	v_cndmask_b32_e32 v120, v122, v121, vcc
	v_not_b32_e32 v121, v1
	v_or_b32_e32 v122, 0x80000000, v1
	v_cmp_gt_i32_e32 vcc, 0, v1
	v_and_b32_e32 v120, 0xffffff80, v120
	v_sub_u32_e32 v120, v120, v25
	v_cndmask_b32_e32 v1, v122, v121, vcc
	v_cvt_f32_f16_sdwa v121, v2 dst_sel:DWORD dst_unused:UNUSED_PAD src0_sel:WORD_1
	v_cvt_f32_f16_e32 v2, v2
	v_and_b32_e32 v1, 0xffffff80, v1
	v_sub_u32_e32 v1, v1, v25
	v_not_b32_e32 v122, v121
	v_or_b32_e32 v123, 0x80000000, v121
	v_cmp_gt_i32_e32 vcc, 0, v121
	v_add_u32_e32 v120, 0x7e, v120
	v_add_u32_e32 v1, 0x7f, v1
	v_cndmask_b32_e32 v121, v123, v122, vcc
	v_not_b32_e32 v122, v2
	v_or_b32_e32 v123, 0x80000000, v2
	v_cmp_gt_i32_e32 vcc, 0, v2
	v_and_b32_e32 v121, 0xffffff80, v121
	v_sub_u32_e32 v121, v121, v26
	v_cndmask_b32_e32 v2, v123, v122, vcc
	v_cvt_f32_f16_sdwa v122, v3 dst_sel:DWORD dst_unused:UNUSED_PAD src0_sel:WORD_1
	v_cvt_f32_f16_e32 v3, v3
	v_and_b32_e32 v2, 0xffffff80, v2
	v_sub_u32_e32 v2, v2, v26
	v_not_b32_e32 v123, v122
	v_or_b32_e32 v124, 0x80000000, v122
	v_cmp_gt_i32_e32 vcc, 0, v122
	v_add_u32_e32 v121, 0x7e, v121
	v_add_u32_e32 v2, 0x7f, v2
	v_cndmask_b32_e32 v122, v124, v123, vcc
	v_not_b32_e32 v123, v3
	v_or_b32_e32 v124, 0x80000000, v3
	v_cmp_gt_i32_e32 vcc, 0, v3
	v_and_b32_e32 v122, 0xffffff80, v122
	v_sub_u32_e32 v122, v122, v28
	v_cndmask_b32_e32 v3, v124, v123, vcc
	v_and_b32_e32 v3, 0xffffff80, v3
	v_sub_u32_e32 v3, v3, v28
	v_add_u32_e32 v122, 0x7e, v122
	v_add_u32_e32 v3, 0x7f, v3
	v_max_u32_e32 v123, v98, v106
	v_min_u32_e32 v98, v98, v106
	v_max_u32_e32 v106, v107, v99
	v_min_u32_e32 v99, v107, v99
	v_max_u32_e32 v107, v100, v108
	v_min_u32_e32 v100, v100, v108
	v_max_u32_e32 v108, v109, v101
	v_min_u32_e32 v101, v109, v101
	v_max_u32_e32 v109, v94, v110
	v_min_u32_e32 v94, v94, v110
	v_max_u32_e32 v110, v111, v95
	v_min_u32_e32 v95, v111, v95
	v_max_u32_e32 v111, v96, v112
	v_min_u32_e32 v96, v96, v112
	v_max_u32_e32 v112, v114, v97
	v_min_u32_e32 v97, v114, v97
	v_max_u32_e32 v131, v102, v115
	v_min_u32_e32 v102, v102, v115
	v_max_u32_e32 v115, v116, v103
	v_min_u32_e32 v103, v116, v103
	v_max_u32_e32 v116, v104, v117
	v_min_u32_e32 v104, v104, v117
	v_max_u32_e32 v117, v118, v105
	v_min_u32_e32 v105, v118, v105
	v_max_u32_e32 v118, v0, v119
	v_min_u32_e32 v0, v0, v119
	v_max_u32_e32 v119, v120, v1
	v_min_u32_e32 v1, v120, v1
	v_max_u32_e32 v120, v2, v121
	v_min_u32_e32 v2, v2, v121
; #define CE_DESC(a, b) do { const unsigned _mx = (a) > (b) ? (a) : (b), _mn = (a) > (b) ? (b) : (a); (a) = _mx; (b) = _mn; } while (0)
; __device__ __forceinline__ void sort16_desc(unsigned (&k)[16]) {
; #pragma unroll
;     for (int size = 2; size <= 16; size <<= 1)
; #pragma unroll
;         for (int stride = size >> 1; stride > 0; stride >>= 1)
; #pragma unroll
;             for (int i = 0; i < 16; ++i) { const int j = i ^ stride;
;                 if (j > i) { if ((i & size) == 0) CE_DESC(k[i], k[j]); else CE_DESC(k[j], k[i]); } }
	v_max_u32_e32 v121, v122, v3
	v_min_u32_e32 v3, v122, v3
	v_max_u32_e32 v114, v123, v99
	v_min_u32_e32 v99, v123, v99
	v_max_u32_e32 v123, v98, v106
	v_min_u32_e32 v98, v98, v106
	v_max_u32_e32 v106, v101, v107
	v_min_u32_e32 v101, v101, v107
	v_max_u32_e32 v107, v108, v100
	v_min_u32_e32 v100, v108, v100
	v_max_u32_e32 v108, v109, v95
	v_min_u32_e32 v95, v109, v95
	v_max_u32_e32 v109, v94, v110
	v_min_u32_e32 v94, v94, v110
	v_max_u32_e32 v110, v97, v111
	v_min_u32_e32 v97, v97, v111
	v_max_u32_e32 v111, v112, v96
	v_min_u32_e32 v96, v112, v96
	v_max_u32_e32 v122, v131, v103
	v_min_u32_e32 v103, v131, v103
	v_max_u32_e32 v131, v102, v115
	v_min_u32_e32 v102, v102, v115
	v_max_u32_e32 v115, v105, v116
	v_min_u32_e32 v105, v105, v116
	v_max_u32_e32 v116, v117, v104
	v_min_u32_e32 v104, v117, v104
	v_max_u32_e32 v117, v118, v1
	v_min_u32_e32 v1, v118, v1
	v_max_u32_e32 v118, v0, v119
	v_min_u32_e32 v0, v0, v119
	v_max_u32_e32 v119, v3, v120
	v_min_u32_e32 v3, v3, v120
	v_max_u32_e32 v120, v121, v2
	v_min_u32_e32 v2, v121, v2
	v_max_u32_e32 v112, v114, v123
	v_min_u32_e32 v114, v114, v123
	v_max_u32_e32 v123, v99, v98
	v_min_u32_e32 v98, v99, v98
	v_max_u32_e32 v99, v100, v101
	v_min_u32_e32 v100, v100, v101
	v_max_u32_e32 v101, v107, v106
	v_min_u32_e32 v106, v107, v106
	v_max_u32_e32 v107, v108, v109
	v_min_u32_e32 v108, v108, v109
	v_max_u32_e32 v109, v95, v94
	v_min_u32_e32 v94, v95, v94
	v_max_u32_e32 v95, v96, v97
	v_min_u32_e32 v96, v96, v97
	v_max_u32_e32 v97, v111, v110
	v_min_u32_e32 v110, v111, v110
	v_max_u32_e32 v121, v122, v131
	v_min_u32_e32 v122, v122, v131
	v_max_u32_e32 v131, v103, v102
	v_min_u32_e32 v102, v103, v102
	v_max_u32_e32 v103, v104, v105
	v_min_u32_e32 v104, v104, v105
	v_max_u32_e32 v105, v116, v115
	v_min_u32_e32 v115, v116, v115
	v_max_u32_e32 v116, v117, v118
	v_min_u32_e32 v117, v117, v118
	v_max_u32_e32 v118, v1, v0
	v_min_u32_e32 v0, v1, v0
	v_max_u32_e32 v1, v2, v3
	v_min_u32_e32 v2, v2, v3
	v_max_u32_e32 v3, v120, v119
	v_min_u32_e32 v119, v120, v119
	v_max_u32_e32 v111, v112, v100
	v_min_u32_e32 v100, v112, v100
	v_max_u32_e32 v112, v114, v99
	v_min_u32_e32 v99, v114, v99
	v_max_u32_e32 v114, v123, v106
	v_min_u32_e32 v106, v123, v106
	v_max_u32_e32 v123, v98, v101
	v_min_u32_e32 v98, v98, v101
	v_max_u32_e32 v101, v96, v107
	v_min_u32_e32 v96, v96, v107
	v_max_u32_e32 v107, v95, v108
	v_min_u32_e32 v95, v95, v108
	v_max_u32_e32 v108, v110, v109
	v_min_u32_e32 v109, v110, v109
	v_max_u32_e32 v110, v97, v94
	v_min_u32_e32 v94, v97, v94
	v_max_u32_e32 v120, v121, v104
	v_min_u32_e32 v104, v121, v104
	v_max_u32_e32 v121, v122, v103
	v_min_u32_e32 v103, v122, v103
	v_max_u32_e32 v122, v131, v115
	v_min_u32_e32 v115, v131, v115
	v_max_u32_e32 v131, v102, v105
	v_min_u32_e32 v102, v102, v105
	v_max_u32_e32 v105, v2, v116
	v_min_u32_e32 v2, v2, v116
	v_max_u32_e32 v116, v1, v117
	v_min_u32_e32 v1, v1, v117
	v_max_u32_e32 v117, v119, v118
	v_min_u32_e32 v118, v119, v118
	v_max_u32_e32 v119, v3, v0
	v_min_u32_e32 v0, v3, v0
	v_max_u32_e32 v97, v111, v114
	v_min_u32_e32 v111, v111, v114
	v_max_u32_e32 v114, v112, v123
	v_min_u32_e32 v112, v112, v123
	v_max_u32_e32 v123, v100, v106
	v_min_u32_e32 v100, v100, v106
	v_max_u32_e32 v106, v99, v98
	v_min_u32_e32 v98, v99, v98
	v_max_u32_e32 v99, v109, v96
	v_min_u32_e32 v96, v109, v96
	v_max_u32_e32 v109, v94, v95
	v_min_u32_e32 v94, v94, v95
	v_max_u32_e32 v95, v108, v101
	v_min_u32_e32 v101, v108, v101
	v_max_u32_e32 v108, v110, v107
	v_min_u32_e32 v107, v110, v107
	v_max_u32_e32 v3, v120, v122
	v_min_u32_e32 v120, v120, v122
	v_max_u32_e32 v122, v121, v131
	v_min_u32_e32 v121, v121, v131
	v_max_u32_e32 v131, v104, v115
	v_min_u32_e32 v104, v104, v115
	v_max_u32_e32 v115, v103, v102
	v_min_u32_e32 v102, v103, v102
	v_max_u32_e32 v103, v118, v2
	v_min_u32_e32 v2, v118, v2
	v_max_u32_e32 v118, v0, v1
	v_min_u32_e32 v0, v0, v1
	v_max_u32_e32 v1, v117, v105
	v_min_u32_e32 v105, v117, v105
	v_max_u32_e32 v117, v119, v116
	v_min_u32_e32 v116, v119, v116
	v_max_u32_e32 v110, v97, v114
	v_min_u32_e32 v97, v97, v114
	v_max_u32_e32 v114, v111, v112
	v_min_u32_e32 v111, v111, v112
	v_max_u32_e32 v112, v123, v106
	v_min_u32_e32 v106, v123, v106
	v_max_u32_e32 v123, v100, v98
	v_min_u32_e32 v98, v100, v98
	v_max_u32_e32 v100, v94, v96
	v_min_u32_e32 v94, v94, v96
	v_max_u32_e32 v96, v109, v99
	v_min_u32_e32 v99, v109, v99
	v_max_u32_e32 v109, v107, v101
	v_min_u32_e32 v101, v107, v101
	v_max_u32_e32 v107, v108, v95
	v_min_u32_e32 v95, v108, v95
	v_max_u32_e32 v119, v3, v122
	v_min_u32_e32 v3, v3, v122
	v_max_u32_e32 v122, v120, v121
	v_min_u32_e32 v120, v120, v121
	v_max_u32_e32 v121, v131, v115
	v_min_u32_e32 v115, v131, v115
	v_max_u32_e32 v131, v104, v102
	v_min_u32_e32 v102, v104, v102
	v_max_u32_e32 v104, v0, v2
	v_min_u32_e32 v0, v0, v2
	v_max_u32_e32 v2, v118, v103
	v_min_u32_e32 v103, v118, v103
	v_max_u32_e32 v118, v116, v105
	v_min_u32_e32 v105, v116, v105
	v_max_u32_e32 v116, v117, v1
	v_min_u32_e32 v1, v117, v1
	v_max_u32_e32 v108, v110, v94
	v_min_u32_e32 v94, v110, v94
	v_max_u32_e32 v110, v97, v100
	v_min_u32_e32 v97, v97, v100
	v_max_u32_e32 v100, v114, v99
	v_min_u32_e32 v99, v114, v99
	v_max_u32_e32 v114, v111, v96
	v_min_u32_e32 v96, v111, v96
	v_max_u32_e32 v111, v112, v101
	v_min_u32_e32 v101, v112, v101
	v_max_u32_e32 v112, v106, v109
	v_min_u32_e32 v106, v106, v109
	v_max_u32_e32 v109, v123, v95
	v_min_u32_e32 v95, v123, v95
	v_max_u32_e32 v123, v98, v107
	v_min_u32_e32 v98, v98, v107
	v_max_u32_e32 v117, v119, v0
	v_min_u32_e32 v0, v119, v0
	v_max_u32_e32 v119, v3, v104
	v_min_u32_e32 v3, v3, v104
	v_max_u32_e32 v104, v122, v103
	v_min_u32_e32 v103, v122, v103
; #define CE_DESC(a, b) do { const unsigned _mx = (a) > (b) ? (a) : (b), _mn = (a) > (b) ? (b) : (a); (a) = _mx; (b) = _mn; } while (0)
; __device__ __forceinline__ void sort16_desc(unsigned (&k)[16]) {
; #pragma unroll
;     for (int size = 2; size <= 16; size <<= 1)
; #pragma unroll
;         for (int stride = size >> 1; stride > 0; stride >>= 1)
; #pragma unroll
;             for (int i = 0; i < 16; ++i) { const int j = i ^ stride;
;                 if (j > i) { if ((i & size) == 0) CE_DESC(k[i], k[j]); else CE_DESC(k[j], k[i]); } }
; }
; __device__ __forceinline__ void merge16(unsigned (&a)[16], const unsigned (&b)[16]) {
; #pragma unroll
;     for (int i = 0; i < 16; ++i) a[i] = a[i] > b[15 - i] ? a[i] : b[15 - i];
; #pragma unroll
;     for (int stride = 8; stride > 0; stride >>= 1)
; #pragma unroll
;         for (int i = 0; i < 16; ++i) { const int j = i ^ stride; if (j > i) CE_DESC(a[i], a[j]); }
; }
; __device__ __forceinline__ void peer_tile(const Args& A, LAS unsigned char* lds, int tile) {
;     ...
;                 sort16_desc(k0); sort16_desc(k1); merge16(k0, k1);
; #pragma unroll
;                 for (int msk = 16; msk <= 32; msk <<= 1) {
; #pragma unroll
;                     for (int i = 0; i < 16; ++i) k1[i] = (unsigned)__shfl_xor((int)k0[i], msk);
	v_max_u32_e32 v122, v120, v2
	v_min_u32_e32 v2, v120, v2
	v_max_u32_e32 v120, v121, v105
	v_min_u32_e32 v105, v121, v105
	v_max_u32_e32 v121, v115, v118
	v_min_u32_e32 v115, v115, v118
	v_max_u32_e32 v118, v131, v1
	v_min_u32_e32 v1, v131, v1
	v_max_u32_e32 v131, v102, v116
	v_min_u32_e32 v102, v102, v116
	v_max_u32_e32 v107, v108, v111
	v_min_u32_e32 v108, v108, v111
	v_max_u32_e32 v111, v110, v112
	v_min_u32_e32 v110, v110, v112
	v_max_u32_e32 v112, v100, v109
	v_min_u32_e32 v100, v100, v109
	v_max_u32_e32 v109, v114, v123
	v_min_u32_e32 v114, v114, v123
	v_max_u32_e32 v123, v94, v101
	v_min_u32_e32 v94, v94, v101
	v_max_u32_e32 v101, v97, v106
	v_min_u32_e32 v97, v97, v106
	v_max_u32_e32 v106, v99, v95
	v_min_u32_e32 v95, v99, v95
	v_max_u32_e32 v99, v96, v98
	v_min_u32_e32 v96, v96, v98
	v_max_u32_e32 v116, v117, v120
	v_min_u32_e32 v117, v117, v120
	v_max_u32_e32 v120, v119, v121
	v_min_u32_e32 v119, v119, v121
	v_max_u32_e32 v121, v104, v118
	v_min_u32_e32 v104, v104, v118
	v_max_u32_e32 v118, v122, v131
	v_min_u32_e32 v122, v122, v131
	v_max_u32_e32 v131, v0, v105
	v_min_u32_e32 v0, v0, v105
	v_max_u32_e32 v105, v3, v115
	v_min_u32_e32 v3, v3, v115
	v_max_u32_e32 v115, v103, v1
	v_min_u32_e32 v1, v103, v1
	v_max_u32_e32 v103, v2, v102
	v_min_u32_e32 v2, v2, v102
	v_max_u32_e32 v98, v107, v112
	v_min_u32_e32 v107, v107, v112
	v_max_u32_e32 v112, v111, v109
	v_min_u32_e32 v109, v111, v109
	v_max_u32_e32 v111, v108, v100
	v_min_u32_e32 v100, v108, v100
	v_max_u32_e32 v108, v110, v114
	v_min_u32_e32 v110, v110, v114
	v_max_u32_e32 v114, v123, v106
	v_min_u32_e32 v106, v123, v106
	v_max_u32_e32 v123, v101, v99
	v_min_u32_e32 v99, v101, v99
	v_max_u32_e32 v101, v94, v95
	v_min_u32_e32 v94, v94, v95
	v_max_u32_e32 v95, v97, v96
	v_min_u32_e32 v96, v97, v96
	v_max_u32_e32 v102, v116, v121
	v_min_u32_e32 v116, v116, v121
	v_max_u32_e32 v121, v120, v118
	v_min_u32_e32 v118, v120, v118
	v_max_u32_e32 v120, v117, v104
	v_min_u32_e32 v104, v117, v104
	v_max_u32_e32 v117, v119, v122
	v_min_u32_e32 v119, v119, v122
	v_max_u32_e32 v122, v131, v115
	v_min_u32_e32 v115, v131, v115
	v_max_u32_e32 v131, v105, v103
	v_min_u32_e32 v103, v105, v103
	v_max_u32_e32 v105, v0, v1
	v_min_u32_e32 v0, v0, v1
	v_max_u32_e32 v1, v3, v2
	v_min_u32_e32 v2, v3, v2
	v_min_u32_e32 v97, v98, v112
	v_min_u32_e32 v124, v107, v109
	v_min_u32_e32 v125, v111, v108
	v_min_u32_e32 v126, v100, v110
	v_min_u32_e32 v127, v114, v123
	v_min_u32_e32 v128, v106, v99
	v_min_u32_e32 v129, v101, v95
	v_min_u32_e32 v130, v94, v96
	v_min_u32_e32 v3, v102, v121
	v_min_u32_e32 v132, v116, v118
	v_min_u32_e32 v133, v120, v117
	v_min_u32_e32 v134, v104, v119
	v_min_u32_e32 v135, v122, v131
	v_min_u32_e32 v136, v115, v103
	v_min_u32_e32 v137, v105, v1
	v_min_u32_e32 v138, v0, v2
	v_max3_u32 v98, v98, v112, v138
	v_max3_u32 v0, v97, v0, v2
	v_max3_u32 v2, v107, v109, v137
	v_max3_u32 v1, v124, v105, v1
	v_max3_u32 v97, v111, v108, v136
	v_max3_u32 v103, v125, v115, v103
	v_max3_u32 v100, v100, v110, v135
	v_max3_u32 v105, v126, v122, v131
	v_max3_u32 v107, v114, v123, v134
	v_max3_u32 v104, v127, v104, v119
	v_max3_u32 v99, v106, v99, v133
	v_max3_u32 v106, v128, v120, v117
	v_max3_u32 v95, v101, v95, v132
	v_max3_u32 v101, v129, v116, v118
	v_max3_u32 v3, v94, v96, v3
	v_max3_u32 v94, v130, v102, v121
	v_max_u32_e32 v96, v98, v107
	v_min_u32_e32 v98, v98, v107
	v_max_u32_e32 v102, v0, v104
	v_min_u32_e32 v0, v0, v104
	v_max_u32_e32 v104, v2, v99
	v_min_u32_e32 v2, v2, v99
	v_max_u32_e32 v99, v1, v106
	v_min_u32_e32 v1, v1, v106
	v_max_u32_e32 v106, v97, v95
	v_min_u32_e32 v95, v97, v95
	v_max_u32_e32 v97, v103, v101
	v_min_u32_e32 v101, v103, v101
	v_max_u32_e32 v103, v100, v3
	v_min_u32_e32 v3, v100, v3
	v_max_u32_e32 v100, v105, v94
	v_min_u32_e32 v94, v105, v94
	v_max_u32_e32 v105, v96, v106
	v_min_u32_e32 v96, v96, v106
	v_max_u32_e32 v106, v102, v97
	v_min_u32_e32 v97, v102, v97
	v_max_u32_e32 v102, v104, v103
	v_min_u32_e32 v103, v104, v103
	v_max_u32_e32 v104, v99, v100
	v_min_u32_e32 v99, v99, v100
	v_max_u32_e32 v100, v98, v95
	v_min_u32_e32 v95, v98, v95
	v_max_u32_e32 v98, v0, v101
	v_min_u32_e32 v0, v0, v101
	v_max_u32_e32 v101, v2, v3
	v_min_u32_e32 v2, v2, v3
	v_max_u32_e32 v3, v1, v94
	v_min_u32_e32 v1, v1, v94
	v_max_u32_e32 v94, v105, v102
	v_min_u32_e32 v102, v105, v102
	v_max_u32_e32 v105, v106, v104
	v_min_u32_e32 v104, v106, v104
	v_max_u32_e32 v106, v96, v103
	v_min_u32_e32 v96, v96, v103
	v_max_u32_e32 v103, v97, v99
	v_min_u32_e32 v97, v97, v99
	v_max_u32_e32 v99, v100, v101
	v_min_u32_e32 v100, v100, v101
	v_max_u32_e32 v101, v98, v3
	v_min_u32_e32 v3, v98, v3
	v_max_u32_e32 v98, v95, v2
	v_min_u32_e32 v2, v95, v2
	v_max_u32_e32 v95, v0, v1
	v_min_u32_e32 v0, v0, v1
	v_max_u32_e32 v1, v94, v105
	v_min_u32_e32 v94, v94, v105
	v_max_u32_e32 v105, v102, v104
	v_min_u32_e32 v102, v102, v104
	v_max_u32_e32 v104, v106, v103
	v_min_u32_e32 v103, v106, v103
	v_max_u32_e32 v106, v96, v97
	v_min_u32_e32 v96, v96, v97
	v_max_u32_e32 v97, v99, v101
	v_min_u32_e32 v99, v99, v101
	v_max_u32_e32 v101, v100, v3
	v_min_u32_e32 v3, v100, v3
	v_max_u32_e32 v100, v98, v95
	v_min_u32_e32 v95, v98, v95
	v_max_u32_e32 v98, v2, v0
	v_min_u32_e32 v0, v2, v0
	ds_bpermute_b32 v2, v27, v1
	ds_bpermute_b32 v107, v27, v94
	ds_bpermute_b32 v108, v27, v105
	ds_bpermute_b32 v109, v27, v102
	ds_bpermute_b32 v110, v27, v104
	ds_bpermute_b32 v111, v27, v103
	ds_bpermute_b32 v112, v27, v106
	ds_bpermute_b32 v114, v27, v96
	ds_bpermute_b32 v115, v27, v97
	ds_bpermute_b32 v116, v27, v99
	ds_bpermute_b32 v117, v27, v101
	ds_bpermute_b32 v118, v27, v0
	ds_bpermute_b32 v119, v27, v98
	ds_bpermute_b32 v120, v27, v95
	ds_bpermute_b32 v121, v27, v100
	ds_bpermute_b32 v122, v27, v3
	s_waitcnt lgkmcnt(4)
; __device__ __forceinline__ void peer_tile(const Args& A, LAS unsigned char* lds, int tile) {
;     ...
;                 for (int msk = 16; msk <= 32; msk <<= 1) {
; #pragma unroll
;                     for (int i = 0; i < 16; ++i) k1[i] = (unsigned)__shfl_xor((int)k0[i], msk);
;                     merge16(k0, k1); }
; #pragma unroll
;                 for (int i = 0; i < 16; ++i) LA[hh][p][i] = k0[i];
	v_max_u32_e32 v1, v1, v118
	s_waitcnt lgkmcnt(3)
	v_max_u32_e32 v94, v94, v119
	s_waitcnt lgkmcnt(2)
	v_max_u32_e32 v105, v105, v120
	s_waitcnt lgkmcnt(1)
	v_max_u32_e32 v102, v102, v121
	s_waitcnt lgkmcnt(0)
	v_max_u32_e32 v104, v104, v122
	v_max_u32_e32 v103, v103, v117
	v_max_u32_e32 v106, v106, v116
	v_max_u32_e32 v96, v96, v115
	v_max_u32_e32 v97, v97, v114
	v_max_u32_e32 v99, v99, v112
	v_max_u32_e32 v101, v101, v111
	v_max_u32_e32 v3, v3, v110
	v_max_u32_e32 v100, v100, v109
	v_max_u32_e32 v95, v95, v108
	v_max_u32_e32 v98, v98, v107
	v_max_u32_e32 v0, v0, v2
	v_max_u32_e32 v2, v1, v97
	v_min_u32_e32 v1, v1, v97
	v_max_u32_e32 v97, v94, v99
	v_min_u32_e32 v94, v94, v99
	v_max_u32_e32 v99, v105, v101
	v_min_u32_e32 v101, v105, v101
	v_max_u32_e32 v105, v102, v3
	v_min_u32_e32 v3, v102, v3
	v_max_u32_e32 v102, v104, v100
	v_min_u32_e32 v100, v104, v100
	v_max_u32_e32 v104, v103, v95
	v_min_u32_e32 v95, v103, v95
	v_max_u32_e32 v103, v106, v98
	v_min_u32_e32 v98, v106, v98
	v_max_u32_e32 v106, v96, v0
	v_min_u32_e32 v0, v96, v0
	v_max_u32_e32 v96, v2, v102
	v_min_u32_e32 v2, v2, v102
	v_max_u32_e32 v102, v97, v104
	v_min_u32_e32 v97, v97, v104
	v_max_u32_e32 v104, v99, v103
	v_min_u32_e32 v99, v99, v103
	v_max_u32_e32 v103, v105, v106
	v_min_u32_e32 v105, v105, v106
	v_max_u32_e32 v106, v1, v100
	v_min_u32_e32 v1, v1, v100
	v_max_u32_e32 v100, v94, v95
	v_min_u32_e32 v94, v94, v95
	v_max_u32_e32 v95, v101, v98
	v_min_u32_e32 v98, v101, v98
	v_max_u32_e32 v101, v3, v0
	v_min_u32_e32 v0, v3, v0
	v_max_u32_e32 v3, v96, v104
	v_min_u32_e32 v96, v96, v104
	v_max_u32_e32 v104, v102, v103
	v_min_u32_e32 v102, v102, v103
	v_max_u32_e32 v103, v2, v99
	v_min_u32_e32 v2, v2, v99
	v_max_u32_e32 v99, v97, v105
	v_min_u32_e32 v97, v97, v105
	v_max_u32_e32 v105, v106, v95
	v_min_u32_e32 v95, v106, v95
	v_max_u32_e32 v106, v100, v101
	v_min_u32_e32 v100, v100, v101
	v_max_u32_e32 v101, v1, v98
	v_min_u32_e32 v1, v1, v98
	v_max_u32_e32 v98, v94, v0
	v_min_u32_e32 v0, v94, v0
	v_max_u32_e32 v94, v3, v104
	v_min_u32_e32 v3, v3, v104
	v_max_u32_e32 v104, v96, v102
	v_min_u32_e32 v96, v96, v102
	v_max_u32_e32 v102, v103, v99
	v_min_u32_e32 v99, v103, v99
	v_max_u32_e32 v103, v2, v97
	v_min_u32_e32 v2, v2, v97
	v_max_u32_e32 v97, v105, v106
	v_min_u32_e32 v105, v105, v106
	v_max_u32_e32 v106, v95, v100
	v_min_u32_e32 v95, v95, v100
	v_max_u32_e32 v100, v101, v98
	v_min_u32_e32 v98, v101, v98
	v_max_u32_e32 v101, v1, v0
	v_min_u32_e32 v0, v1, v0
	ds_bpermute_b32 v114, v29, v0
	ds_bpermute_b32 v1, v29, v94
	ds_bpermute_b32 v107, v29, v3
	ds_bpermute_b32 v108, v29, v104
	ds_bpermute_b32 v109, v29, v96
	s_waitcnt lgkmcnt(4)
	v_max_u32_e32 v94, v94, v114
	global_load_dwordx4 v[114:117], v[4:5], off offset:1296
	global_load_dwordx4 v[118:121], v[4:5], off offset:1280
	ds_bpermute_b32 v110, v29, v102
	ds_bpermute_b32 v111, v29, v99
	ds_bpermute_b32 v112, v29, v103
	ds_bpermute_b32 v122, v29, v2
	ds_bpermute_b32 v123, v29, v97
	ds_bpermute_b32 v124, v29, v105
	ds_bpermute_b32 v125, v29, v106
	ds_bpermute_b32 v126, v29, v95
	ds_bpermute_b32 v127, v29, v100
	ds_bpermute_b32 v128, v29, v101
	ds_bpermute_b32 v129, v29, v98
	s_waitcnt lgkmcnt(4)
	v_max_u32_e32 v99, v99, v125
	s_waitcnt lgkmcnt(3)
	v_max_u32_e32 v102, v102, v126
	s_waitcnt lgkmcnt(2)
	v_max_u32_e32 v96, v96, v127
	s_waitcnt lgkmcnt(1)
	v_max_u32_e32 v3, v3, v128
	s_waitcnt lgkmcnt(0)
	v_max_u32_e32 v104, v104, v129
	v_max_u32_e32 v103, v103, v124
	v_max_u32_e32 v2, v2, v123
	v_max_u32_e32 v97, v97, v122
	v_max_u32_e32 v105, v105, v112
	v_max_u32_e32 v106, v106, v111
	v_max_u32_e32 v95, v95, v110
	v_max_u32_e32 v100, v100, v109
	v_max_u32_e32 v98, v98, v108
	v_max_u32_e32 v101, v101, v107
	v_max_u32_e32 v0, v0, v1
	v_max_u32_e32 v1, v94, v97
	v_min_u32_e32 v94, v94, v97
	v_max_u32_e32 v97, v3, v105
	v_min_u32_e32 v3, v3, v105
	v_max_u32_e32 v105, v104, v106
	v_min_u32_e32 v104, v104, v106
	v_max_u32_e32 v106, v96, v95
	v_min_u32_e32 v95, v96, v95
	v_max_u32_e32 v96, v102, v100
	v_min_u32_e32 v100, v102, v100
	v_max_u32_e32 v102, v99, v98
	v_min_u32_e32 v98, v99, v98
	v_max_u32_e32 v99, v103, v101
	v_min_u32_e32 v101, v103, v101
	v_max_u32_e32 v103, v2, v0
	v_min_u32_e32 v0, v2, v0
	v_max_u32_e32 v2, v1, v96
	v_min_u32_e32 v1, v1, v96
	v_max_u32_e32 v96, v97, v102
	v_min_u32_e32 v97, v97, v102
	v_max_u32_e32 v102, v105, v99
	v_min_u32_e32 v99, v105, v99
	v_max_u32_e32 v105, v106, v103
	v_min_u32_e32 v103, v106, v103
	v_max_u32_e32 v106, v94, v100
	v_min_u32_e32 v94, v94, v100
	v_max_u32_e32 v100, v3, v98
	v_min_u32_e32 v3, v3, v98
	v_max_u32_e32 v98, v104, v101
	v_min_u32_e32 v101, v104, v101
	v_max_u32_e32 v104, v95, v0
	v_min_u32_e32 v0, v95, v0
	v_max_u32_e32 v95, v2, v102
	v_min_u32_e32 v2, v2, v102
	v_max_u32_e32 v102, v96, v105
	v_min_u32_e32 v96, v96, v105
	v_max_u32_e32 v110, v1, v99
	v_min_u32_e32 v1, v1, v99
	v_max_u32_e32 v99, v97, v103
	v_min_u32_e32 v97, v97, v103
	v_max_u32_e32 v111, v106, v98
	v_min_u32_e32 v98, v106, v98
	v_min_u32_e32 v122, v100, v104
	v_max_u32_e32 v123, v94, v101
	v_min_u32_e32 v94, v94, v101
	v_max_u32_e32 v124, v3, v0
	v_min_u32_e32 v0, v3, v0
	v_max_u32_e32 v112, v100, v104
	v_max_u32_e32 v109, v95, v102
	v_min_u32_e32 v108, v95, v102
	v_max_u32_e32 v107, v2, v96
	v_min_u32_e32 v106, v2, v96
	v_max_u32_e32 v105, v110, v99
	v_min_u32_e32 v104, v110, v99
	v_max_u32_e32 v103, v1, v97
	v_min_u32_e32 v102, v1, v97
	v_max_u32_e32 v99, v98, v122
	v_min_u32_e32 v98, v98, v122
	v_max_u32_e32 v97, v123, v124
	v_min_u32_e32 v96, v123, v124
	v_max_u32_e32 v95, v94, v0
	v_min_u32_e32 v94, v94, v0
	global_load_dwordx4 v[0:3], v[4:5], off offset:1328
	global_load_dwordx4 v[122:125], v[4:5], off offset:1312
	s_waitcnt vmcnt(2)
; __device__ __forceinline__ unsigned f2key(float f) { const unsigned u = __float_as_uint(f); return (u & 0x80000000u) ? ~u : (u | 0x80000000u); }
; __device__ __forceinline__ void peer_tile(const Args& A, LAS unsigned char* lds, int tile) {
;     ...
;                 { const bf16_t* sp = QRY + m * 2048 + hp * 128 + 32 * g;
;                   const u32x4 s0 = *(const u32x4*)sp, s1 = *(const u32x4*)(sp + 8), s2 = *(const u32x4*)(sp + 16), s3 = *(const u32x4*)(sp + 24);
;                   const unsigned sw[16] = {s0.x, s0.y, s0.z, s0.w, s1.x, s1.y, s1.z, s1.w, s2.x, s2.y, s2.z, s2.w, s3.x, s3.y, s3.z, s3.w};
; #pragma unroll
;                   for (int i = 0; i < 16; ++i) {
;                       const float lo = (float)__builtin_bit_cast(_Float16, (unsigned short)(sw[i] & 0xffffu)), hi = (float)__builtin_bit_cast(_Float16, (unsigned short)(sw[i] >> 16));
;                       const unsigned klo = (f2key(lo) & ~127u) | (unsigned)(127 - (32 * g + 2 * i)), khi = (f2key(hi) & ~127u) | (unsigned)(127 - (32 * g + 2 * i + 1));
;                       if (i < 8) { k0[2 * i] = klo; k0[2 * i + 1] = khi; } else { k1[2 * (i - 8)] = klo; k1[2 * (i - 8) + 1] = khi; } } }
	v_cvt_f32_f16_sdwa v110, v118 dst_sel:DWORD dst_unused:UNUSED_PAD src0_sel:WORD_1
	v_max_u32_e32 v101, v111, v112
	v_min_u32_e32 v100, v111, v112
	v_cvt_f32_f16_e32 v111, v118
	v_not_b32_e32 v112, v110
	v_or_b32_e32 v118, 0x80000000, v110
	v_cmp_gt_i32_e32 vcc, 0, v110
	v_cndmask_b32_e64 v30, v62, v30, s[0:1]
	s_nop 0
	v_cndmask_b32_e32 v110, v118, v112, vcc
	v_not_b32_e32 v112, v111
	v_or_b32_e32 v118, 0x80000000, v111
	v_cmp_gt_i32_e32 vcc, 0, v111
	v_and_b32_e32 v110, 0xffffff80, v110
	v_sub_u32_e32 v110, v110, v15
	v_cndmask_b32_e32 v111, v118, v112, vcc
	v_cvt_f32_f16_sdwa v112, v119 dst_sel:DWORD dst_unused:UNUSED_PAD src0_sel:WORD_1
	v_cvt_f32_f16_e32 v118, v119
	v_and_b32_e32 v111, 0xffffff80, v111
	v_sub_u32_e32 v111, v111, v15
	v_not_b32_e32 v119, v112
	v_or_b32_e32 v126, 0x80000000, v112
	v_cmp_gt_i32_e32 vcc, 0, v112
	v_add_u32_e32 v110, 0x7e, v110
	v_add_u32_e32 v111, 0x7f, v111
	v_cndmask_b32_e32 v112, v126, v119, vcc
	v_not_b32_e32 v119, v118
	v_or_b32_e32 v126, 0x80000000, v118
	v_cmp_gt_i32_e32 vcc, 0, v118
	v_and_b32_e32 v112, 0xffffff80, v112
	v_sub_u32_e32 v112, v112, v14
	v_cndmask_b32_e32 v118, v126, v119, vcc
	v_cvt_f32_f16_sdwa v119, v120 dst_sel:DWORD dst_unused:UNUSED_PAD src0_sel:WORD_1
	v_cvt_f32_f16_e32 v120, v120
	v_and_b32_e32 v118, 0xffffff80, v118
	v_sub_u32_e32 v118, v118, v14
	v_not_b32_e32 v126, v119
	v_or_b32_e32 v127, 0x80000000, v119
	v_cmp_gt_i32_e32 vcc, 0, v119
	v_add_u32_e32 v112, 0x7e, v112
	v_add_u32_e32 v118, 0x7f, v118
	v_cndmask_b32_e32 v119, v127, v126, vcc
	v_not_b32_e32 v126, v120
	v_or_b32_e32 v127, 0x80000000, v120
	v_cmp_gt_i32_e32 vcc, 0, v120
	v_and_b32_e32 v119, 0xffffff80, v119
	v_sub_u32_e32 v119, v119, v12
	v_cndmask_b32_e32 v120, v127, v126, vcc
	v_cvt_f32_f16_sdwa v126, v121 dst_sel:DWORD dst_unused:UNUSED_PAD src0_sel:WORD_1
	v_cvt_f32_f16_e32 v121, v121
	v_and_b32_e32 v120, 0xffffff80, v120
	v_sub_u32_e32 v120, v120, v12
	v_not_b32_e32 v127, v126
	v_or_b32_e32 v128, 0x80000000, v126
	v_cmp_gt_i32_e32 vcc, 0, v126
	v_add_u32_e32 v119, 0x7e, v119
	v_add_u32_e32 v120, 0x7f, v120
	v_cndmask_b32_e32 v126, v128, v127, vcc
	v_not_b32_e32 v127, v121
	v_or_b32_e32 v128, 0x80000000, v121
	v_cmp_gt_i32_e32 vcc, 0, v121
	v_and_b32_e32 v126, 0xffffff80, v126
	v_sub_u32_e32 v126, v126, v10
	v_cndmask_b32_e32 v121, v128, v127, vcc
	v_cvt_f32_f16_sdwa v127, v114 dst_sel:DWORD dst_unused:UNUSED_PAD src0_sel:WORD_1
	v_cvt_f32_f16_e32 v114, v114
	v_and_b32_e32 v121, 0xffffff80, v121
	v_sub_u32_e32 v121, v121, v10
	v_not_b32_e32 v128, v127
	v_or_b32_e32 v129, 0x80000000, v127
	v_cmp_gt_i32_e32 vcc, 0, v127
	v_add_u32_e32 v126, 0x7e, v126
	v_add_u32_e32 v121, 0x7f, v121
	v_cndmask_b32_e32 v127, v129, v128, vcc
	v_not_b32_e32 v128, v114
	v_or_b32_e32 v129, 0x80000000, v114
	v_cmp_gt_i32_e32 vcc, 0, v114
	v_and_b32_e32 v127, 0xffffff80, v127
	v_sub_u32_e32 v127, v127, v8
	v_cndmask_b32_e32 v114, v129, v128, vcc
	v_cvt_f32_f16_sdwa v128, v115 dst_sel:DWORD dst_unused:UNUSED_PAD src0_sel:WORD_1
	v_cvt_f32_f16_e32 v115, v115
	v_and_b32_e32 v114, 0xffffff80, v114
	v_sub_u32_e32 v114, v114, v8
	v_not_b32_e32 v129, v128
	v_or_b32_e32 v130, 0x80000000, v128
	v_cmp_gt_i32_e32 vcc, 0, v128
	v_add_u32_e32 v127, 0x7e, v127
	v_add_u32_e32 v114, 0x7f, v114
	v_cndmask_b32_e32 v128, v130, v129, vcc
	v_not_b32_e32 v129, v115
	v_or_b32_e32 v130, 0x80000000, v115
	v_cmp_gt_i32_e32 vcc, 0, v115
	v_and_b32_e32 v128, 0xffffff80, v128
	v_sub_u32_e32 v128, v128, v16
	v_cndmask_b32_e32 v115, v130, v129, vcc
	v_cvt_f32_f16_sdwa v129, v116 dst_sel:DWORD dst_unused:UNUSED_PAD src0_sel:WORD_1
	v_cvt_f32_f16_e32 v116, v116
	v_and_b32_e32 v115, 0xffffff80, v115
	v_sub_u32_e32 v115, v115, v16
	v_not_b32_e32 v130, v129
	v_or_b32_e32 v131, 0x80000000, v129
	v_cmp_gt_i32_e32 vcc, 0, v129
	v_add_u32_e32 v128, 0x7e, v128
	v_add_u32_e32 v115, 0x7f, v115
	v_cndmask_b32_e32 v129, v131, v130, vcc
	v_not_b32_e32 v130, v116
	v_or_b32_e32 v131, 0x80000000, v116
	v_cmp_gt_i32_e32 vcc, 0, v116
	v_and_b32_e32 v129, 0xffffff80, v129
	v_sub_u32_e32 v129, v129, v17
	v_cndmask_b32_e32 v116, v131, v130, vcc
	v_cvt_f32_f16_sdwa v130, v117 dst_sel:DWORD dst_unused:UNUSED_PAD src0_sel:WORD_1
	v_cvt_f32_f16_e32 v117, v117
	v_and_b32_e32 v116, 0xffffff80, v116
	v_sub_u32_e32 v116, v116, v17
	v_not_b32_e32 v131, v130
	v_or_b32_e32 v132, 0x80000000, v130
	v_cmp_gt_i32_e32 vcc, 0, v130
	v_add_u32_e32 v129, 0x7e, v129
	v_add_u32_e32 v116, 0x7f, v116
	v_cndmask_b32_e32 v130, v132, v131, vcc
	v_not_b32_e32 v131, v117
	v_or_b32_e32 v132, 0x80000000, v117
	v_cmp_gt_i32_e32 vcc, 0, v117
	v_and_b32_e32 v130, 0xffffff80, v130
	v_sub_u32_e32 v130, v130, v18
	v_cndmask_b32_e32 v117, v132, v131, vcc
	s_waitcnt vmcnt(0)
; __device__ __forceinline__ unsigned f2key(float f) { const unsigned u = __float_as_uint(f); return (u & 0x80000000u) ? ~u : (u | 0x80000000u); }
; #define CE_DESC(a, b) do { const unsigned _mx = (a) > (b) ? (a) : (b), _mn = (a) > (b) ? (b) : (a); (a) = _mx; (b) = _mn; } while (0)
; __device__ __forceinline__ void sort16_desc(unsigned (&k)[16]) {
; #pragma unroll
;     for (int size = 2; size <= 16; size <<= 1)
; #pragma unroll
;         for (int stride = size >> 1; stride > 0; stride >>= 1)
; #pragma unroll
;             for (int i = 0; i < 16; ++i) { const int j = i ^ stride;
;                 if (j > i) { if ((i & size) == 0) CE_DESC(k[i], k[j]); else CE_DESC(k[j], k[i]); } }
; __device__ __forceinline__ void peer_tile(const Args& A, LAS unsigned char* lds, int tile) {
;     ...
;                   for (int i = 0; i < 16; ++i) {
;                       const float lo = (float)__builtin_bit_cast(_Float16, (unsigned short)(sw[i] & 0xffffu)), hi = (float)__builtin_bit_cast(_Float16, (unsigned short)(sw[i] >> 16));
;                       const unsigned klo = (f2key(lo) & ~127u) | (unsigned)(127 - (32 * g + 2 * i)), khi = (f2key(hi) & ~127u) | (unsigned)(127 - (32 * g + 2 * i + 1));
;                       if (i < 8) { k0[2 * i] = klo; k0[2 * i + 1] = khi; } else { k1[2 * (i - 8)] = klo; k1[2 * (i - 8) + 1] = khi; } } }
;                 sort16_desc(k0); sort16_desc(k1); merge16(k0, k1);
	v_cvt_f32_f16_sdwa v131, v122 dst_sel:DWORD dst_unused:UNUSED_PAD src0_sel:WORD_1
	v_cvt_f32_f16_e32 v122, v122
	v_and_b32_e32 v117, 0xffffff80, v117
	v_sub_u32_e32 v117, v117, v18
	v_not_b32_e32 v132, v131
	v_or_b32_e32 v133, 0x80000000, v131
	v_cmp_gt_i32_e32 vcc, 0, v131
	v_add_u32_e32 v130, 0x7e, v130
	v_add_u32_e32 v117, 0x7f, v117
	v_cndmask_b32_e32 v131, v133, v132, vcc
	v_not_b32_e32 v132, v122
	v_or_b32_e32 v133, 0x80000000, v122
	v_cmp_gt_i32_e32 vcc, 0, v122
	v_and_b32_e32 v131, 0xffffff80, v131
	v_sub_u32_e32 v131, v131, v20
	v_cndmask_b32_e32 v122, v133, v132, vcc
	v_cvt_f32_f16_sdwa v132, v123 dst_sel:DWORD dst_unused:UNUSED_PAD src0_sel:WORD_1
	v_cvt_f32_f16_e32 v123, v123
	v_and_b32_e32 v122, 0xffffff80, v122
	v_sub_u32_e32 v122, v122, v20
	v_not_b32_e32 v133, v132
	v_or_b32_e32 v134, 0x80000000, v132
	v_cmp_gt_i32_e32 vcc, 0, v132
	v_add_u32_e32 v131, 0x7e, v131
	v_add_u32_e32 v122, 0x7f, v122
	v_cndmask_b32_e32 v132, v134, v133, vcc
	v_not_b32_e32 v133, v123
	v_or_b32_e32 v134, 0x80000000, v123
	v_cmp_gt_i32_e32 vcc, 0, v123
	v_and_b32_e32 v132, 0xffffff80, v132
	v_sub_u32_e32 v132, v132, v21
	v_cndmask_b32_e32 v123, v134, v133, vcc
	v_cvt_f32_f16_sdwa v133, v124 dst_sel:DWORD dst_unused:UNUSED_PAD src0_sel:WORD_1
	v_cvt_f32_f16_e32 v124, v124
	v_and_b32_e32 v123, 0xffffff80, v123
	v_sub_u32_e32 v123, v123, v21
	v_not_b32_e32 v134, v133
	v_or_b32_e32 v135, 0x80000000, v133
	v_cmp_gt_i32_e32 vcc, 0, v133
	v_add_u32_e32 v132, 0x7e, v132
	v_add_u32_e32 v123, 0x7f, v123
	v_cndmask_b32_e32 v133, v135, v134, vcc
	v_not_b32_e32 v134, v124
	v_or_b32_e32 v135, 0x80000000, v124
	v_cmp_gt_i32_e32 vcc, 0, v124
	v_and_b32_e32 v133, 0xffffff80, v133
	v_sub_u32_e32 v133, v133, v22
	v_cndmask_b32_e32 v124, v135, v134, vcc
	v_cvt_f32_f16_sdwa v134, v125 dst_sel:DWORD dst_unused:UNUSED_PAD src0_sel:WORD_1
	v_cvt_f32_f16_e32 v125, v125
	v_and_b32_e32 v124, 0xffffff80, v124
	v_sub_u32_e32 v124, v124, v22
	v_not_b32_e32 v135, v134
	v_or_b32_e32 v136, 0x80000000, v134
	v_cmp_gt_i32_e32 vcc, 0, v134
	v_add_u32_e32 v133, 0x7e, v133
	v_add_u32_e32 v124, 0x7f, v124
	v_cndmask_b32_e32 v134, v136, v135, vcc
	v_not_b32_e32 v135, v125
	v_or_b32_e32 v136, 0x80000000, v125
	v_cmp_gt_i32_e32 vcc, 0, v125
	v_and_b32_e32 v134, 0xffffff80, v134
	v_sub_u32_e32 v134, v134, v23
	v_cndmask_b32_e32 v125, v136, v135, vcc
	v_cvt_f32_f16_sdwa v135, v0 dst_sel:DWORD dst_unused:UNUSED_PAD src0_sel:WORD_1
	v_cvt_f32_f16_e32 v0, v0
	v_and_b32_e32 v125, 0xffffff80, v125
	v_sub_u32_e32 v125, v125, v23
	v_not_b32_e32 v136, v135
	v_or_b32_e32 v137, 0x80000000, v135
	v_cmp_gt_i32_e32 vcc, 0, v135
	v_add_u32_e32 v134, 0x7e, v134
	v_add_u32_e32 v125, 0x7f, v125
	v_cndmask_b32_e32 v135, v137, v136, vcc
	v_not_b32_e32 v136, v0
	v_or_b32_e32 v137, 0x80000000, v0
	v_cmp_gt_i32_e32 vcc, 0, v0
	v_and_b32_e32 v135, 0xffffff80, v135
	v_sub_u32_e32 v135, v135, v24
	v_cndmask_b32_e32 v0, v137, v136, vcc
	v_cvt_f32_f16_sdwa v136, v1 dst_sel:DWORD dst_unused:UNUSED_PAD src0_sel:WORD_1
	v_cvt_f32_f16_e32 v1, v1
	v_and_b32_e32 v0, 0xffffff80, v0
	v_sub_u32_e32 v0, v0, v24
	v_not_b32_e32 v137, v136
	v_or_b32_e32 v138, 0x80000000, v136
	v_cmp_gt_i32_e32 vcc, 0, v136
	v_add_u32_e32 v135, 0x7e, v135
	v_add_u32_e32 v0, 0x7f, v0
	v_cndmask_b32_e32 v136, v138, v137, vcc
	v_not_b32_e32 v137, v1
	v_or_b32_e32 v138, 0x80000000, v1
	v_cmp_gt_i32_e32 vcc, 0, v1
	v_and_b32_e32 v136, 0xffffff80, v136
	v_sub_u32_e32 v136, v136, v25
	v_cndmask_b32_e32 v1, v138, v137, vcc
	v_cvt_f32_f16_sdwa v137, v2 dst_sel:DWORD dst_unused:UNUSED_PAD src0_sel:WORD_1
	v_cvt_f32_f16_e32 v2, v2
	v_and_b32_e32 v1, 0xffffff80, v1
	v_sub_u32_e32 v1, v1, v25
	v_not_b32_e32 v138, v137
	v_or_b32_e32 v139, 0x80000000, v137
	v_cmp_gt_i32_e32 vcc, 0, v137
	v_add_u32_e32 v136, 0x7e, v136
	v_add_u32_e32 v1, 0x7f, v1
	v_cndmask_b32_e32 v137, v139, v138, vcc
	v_not_b32_e32 v138, v2
	v_or_b32_e32 v139, 0x80000000, v2
	v_cmp_gt_i32_e32 vcc, 0, v2
	v_and_b32_e32 v137, 0xffffff80, v137
	v_sub_u32_e32 v137, v137, v26
	v_cndmask_b32_e32 v2, v139, v138, vcc
	v_cvt_f32_f16_sdwa v138, v3 dst_sel:DWORD dst_unused:UNUSED_PAD src0_sel:WORD_1
	v_cvt_f32_f16_e32 v3, v3
	v_and_b32_e32 v2, 0xffffff80, v2
	v_sub_u32_e32 v2, v2, v26
	v_not_b32_e32 v139, v138
	v_or_b32_e32 v140, 0x80000000, v138
	v_cmp_gt_i32_e32 vcc, 0, v138
	v_add_u32_e32 v137, 0x7e, v137
	v_add_u32_e32 v2, 0x7f, v2
	v_cndmask_b32_e32 v138, v140, v139, vcc
	v_not_b32_e32 v139, v3
	v_or_b32_e32 v140, 0x80000000, v3
	v_cmp_gt_i32_e32 vcc, 0, v3
	v_and_b32_e32 v138, 0xffffff80, v138
	v_sub_u32_e32 v138, v138, v28
	v_cndmask_b32_e32 v3, v140, v139, vcc
	v_and_b32_e32 v3, 0xffffff80, v3
	v_sub_u32_e32 v3, v3, v28
	v_add_u32_e32 v138, 0x7e, v138
	v_add_u32_e32 v3, 0x7f, v3
	v_max_u32_e32 v139, v111, v110
	v_min_u32_e32 v110, v111, v110
	v_max_u32_e32 v111, v112, v118
	v_min_u32_e32 v112, v112, v118
	v_max_u32_e32 v118, v120, v119
	v_min_u32_e32 v119, v120, v119
	v_max_u32_e32 v120, v126, v121
	v_min_u32_e32 v121, v126, v121
	v_max_u32_e32 v126, v114, v127
	v_min_u32_e32 v114, v114, v127
	v_max_u32_e32 v127, v128, v115
	v_min_u32_e32 v115, v128, v115
	v_max_u32_e32 v128, v116, v129
	v_min_u32_e32 v116, v116, v129
	v_max_u32_e32 v129, v130, v117
	v_min_u32_e32 v117, v130, v117
	v_max_u32_e32 v147, v122, v131
	v_min_u32_e32 v122, v122, v131
	v_max_u32_e32 v131, v132, v123
	v_min_u32_e32 v123, v132, v123
	v_max_u32_e32 v132, v124, v133
	v_min_u32_e32 v124, v124, v133
	v_max_u32_e32 v133, v134, v125
	v_min_u32_e32 v125, v134, v125
	v_max_u32_e32 v134, v0, v135
	v_min_u32_e32 v0, v0, v135
	v_max_u32_e32 v135, v136, v1
	v_min_u32_e32 v1, v136, v1
	v_max_u32_e32 v136, v2, v137
	v_min_u32_e32 v2, v2, v137
; #define CE_DESC(a, b) do { const unsigned _mx = (a) > (b) ? (a) : (b), _mn = (a) > (b) ? (b) : (a); (a) = _mx; (b) = _mn; } while (0)
; __device__ __forceinline__ void sort16_desc(unsigned (&k)[16]) {
; #pragma unroll
;     for (int size = 2; size <= 16; size <<= 1)
; #pragma unroll
;         for (int stride = size >> 1; stride > 0; stride >>= 1)
; #pragma unroll
;             for (int i = 0; i < 16; ++i) { const int j = i ^ stride;
;                 if (j > i) { if ((i & size) == 0) CE_DESC(k[i], k[j]); else CE_DESC(k[j], k[i]); } }
	v_max_u32_e32 v137, v138, v3
	v_min_u32_e32 v3, v138, v3
	v_max_u32_e32 v130, v139, v112
	v_min_u32_e32 v112, v139, v112
	v_max_u32_e32 v139, v110, v111
	v_min_u32_e32 v110, v110, v111
	v_max_u32_e32 v111, v121, v118
	v_min_u32_e32 v118, v121, v118
	v_max_u32_e32 v121, v120, v119
	v_min_u32_e32 v119, v120, v119
	v_max_u32_e32 v120, v126, v115
	v_min_u32_e32 v115, v126, v115
	v_max_u32_e32 v126, v114, v127
	v_min_u32_e32 v114, v114, v127
	v_max_u32_e32 v127, v117, v128
	v_min_u32_e32 v117, v117, v128
	v_max_u32_e32 v128, v129, v116
	v_min_u32_e32 v116, v129, v116
	v_max_u32_e32 v138, v147, v123
	v_min_u32_e32 v123, v147, v123
	v_max_u32_e32 v147, v122, v131
	v_min_u32_e32 v122, v122, v131
	v_max_u32_e32 v131, v125, v132
	v_min_u32_e32 v125, v125, v132
	v_max_u32_e32 v132, v133, v124
	v_min_u32_e32 v124, v133, v124
	v_max_u32_e32 v133, v134, v1
	v_min_u32_e32 v1, v134, v1
	v_max_u32_e32 v134, v0, v135
	v_min_u32_e32 v0, v0, v135
	v_max_u32_e32 v135, v3, v136
	v_min_u32_e32 v3, v3, v136
	v_max_u32_e32 v136, v137, v2
	v_min_u32_e32 v2, v137, v2
	v_max_u32_e32 v129, v130, v139
	v_min_u32_e32 v130, v130, v139
	v_max_u32_e32 v139, v112, v110
	v_min_u32_e32 v110, v112, v110
	v_max_u32_e32 v112, v119, v118
	v_min_u32_e32 v118, v119, v118
	v_max_u32_e32 v119, v121, v111
	v_min_u32_e32 v111, v121, v111
	v_max_u32_e32 v121, v120, v126
	v_min_u32_e32 v120, v120, v126
	v_max_u32_e32 v126, v115, v114
	v_min_u32_e32 v114, v115, v114
	v_max_u32_e32 v115, v116, v117
	v_min_u32_e32 v116, v116, v117
	v_max_u32_e32 v117, v128, v127
	v_min_u32_e32 v127, v128, v127
	v_max_u32_e32 v137, v138, v147
	v_min_u32_e32 v138, v138, v147
	v_max_u32_e32 v147, v123, v122
	v_min_u32_e32 v122, v123, v122
	v_max_u32_e32 v123, v124, v125
	v_min_u32_e32 v124, v124, v125
	v_max_u32_e32 v125, v132, v131
	v_min_u32_e32 v131, v132, v131
	v_max_u32_e32 v132, v133, v134
	v_min_u32_e32 v133, v133, v134
	v_max_u32_e32 v134, v1, v0
	v_min_u32_e32 v0, v1, v0
	v_max_u32_e32 v1, v2, v3
	v_min_u32_e32 v2, v2, v3
	v_max_u32_e32 v3, v136, v135
	v_min_u32_e32 v135, v136, v135
	v_max_u32_e32 v128, v129, v118
	v_min_u32_e32 v118, v129, v118
	v_max_u32_e32 v129, v130, v112
	v_min_u32_e32 v112, v130, v112
	v_max_u32_e32 v130, v139, v111
	v_min_u32_e32 v111, v139, v111
	v_max_u32_e32 v139, v110, v119
	v_min_u32_e32 v110, v110, v119
	v_max_u32_e32 v119, v116, v121
	v_min_u32_e32 v116, v116, v121
	v_max_u32_e32 v121, v115, v120
	v_min_u32_e32 v115, v115, v120
	v_max_u32_e32 v120, v127, v126
	v_min_u32_e32 v126, v127, v126
	v_max_u32_e32 v127, v117, v114
	v_min_u32_e32 v114, v117, v114
	v_max_u32_e32 v136, v137, v124
	v_min_u32_e32 v124, v137, v124
	v_max_u32_e32 v137, v138, v123
	v_min_u32_e32 v123, v138, v123
	v_max_u32_e32 v138, v147, v131
	v_min_u32_e32 v131, v147, v131
	v_max_u32_e32 v147, v122, v125
	v_min_u32_e32 v122, v122, v125
	v_max_u32_e32 v125, v2, v132
	v_min_u32_e32 v2, v2, v132
	v_max_u32_e32 v132, v1, v133
	v_min_u32_e32 v1, v1, v133
	v_max_u32_e32 v133, v135, v134
	v_min_u32_e32 v134, v135, v134
	v_max_u32_e32 v135, v3, v0
	v_min_u32_e32 v0, v3, v0
	v_max_u32_e32 v117, v128, v130
	v_min_u32_e32 v128, v128, v130
	v_max_u32_e32 v130, v129, v139
	v_min_u32_e32 v129, v129, v139
	v_max_u32_e32 v139, v118, v111
	v_min_u32_e32 v111, v118, v111
	v_max_u32_e32 v118, v112, v110
	v_min_u32_e32 v110, v112, v110
	v_max_u32_e32 v112, v126, v116
	v_min_u32_e32 v116, v126, v116
	v_max_u32_e32 v126, v114, v115
	v_min_u32_e32 v114, v114, v115
	v_max_u32_e32 v115, v120, v119
	v_min_u32_e32 v119, v120, v119
	v_max_u32_e32 v120, v127, v121
	v_min_u32_e32 v121, v127, v121
	v_max_u32_e32 v3, v136, v138
	v_min_u32_e32 v136, v136, v138
	v_max_u32_e32 v138, v137, v147
	v_min_u32_e32 v137, v137, v147
	v_max_u32_e32 v147, v124, v131
	v_min_u32_e32 v124, v124, v131
	v_max_u32_e32 v131, v123, v122
	v_min_u32_e32 v122, v123, v122
	v_max_u32_e32 v123, v134, v2
	v_min_u32_e32 v2, v134, v2
	v_max_u32_e32 v134, v0, v1
	v_min_u32_e32 v0, v0, v1
	v_max_u32_e32 v1, v133, v125
	v_min_u32_e32 v125, v133, v125
	v_max_u32_e32 v133, v135, v132
	v_min_u32_e32 v132, v135, v132
	v_max_u32_e32 v127, v117, v130
	v_min_u32_e32 v117, v117, v130
	v_max_u32_e32 v130, v128, v129
	v_min_u32_e32 v128, v128, v129
	v_max_u32_e32 v129, v139, v118
	v_min_u32_e32 v118, v139, v118
	v_max_u32_e32 v139, v111, v110
	v_min_u32_e32 v110, v111, v110
	v_max_u32_e32 v111, v114, v116
	v_min_u32_e32 v114, v114, v116
	v_max_u32_e32 v116, v126, v112
	v_min_u32_e32 v112, v126, v112
	v_max_u32_e32 v126, v121, v119
	v_min_u32_e32 v119, v121, v119
	v_max_u32_e32 v121, v120, v115
	v_min_u32_e32 v115, v120, v115
	v_max_u32_e32 v135, v3, v138
	v_min_u32_e32 v3, v3, v138
	v_max_u32_e32 v138, v136, v137
	v_min_u32_e32 v136, v136, v137
	v_max_u32_e32 v137, v147, v131
	v_min_u32_e32 v131, v147, v131
	v_max_u32_e32 v147, v124, v122
	v_min_u32_e32 v122, v124, v122
	v_max_u32_e32 v124, v0, v2
	v_min_u32_e32 v0, v0, v2
	v_max_u32_e32 v2, v134, v123
	v_min_u32_e32 v123, v134, v123
	v_max_u32_e32 v134, v132, v125
	v_min_u32_e32 v125, v132, v125
	v_max_u32_e32 v132, v133, v1
	v_min_u32_e32 v1, v133, v1
	v_max_u32_e32 v120, v127, v114
	v_min_u32_e32 v114, v127, v114
	v_max_u32_e32 v127, v117, v111
	v_min_u32_e32 v111, v117, v111
	v_max_u32_e32 v117, v130, v112
	v_min_u32_e32 v112, v130, v112
	v_max_u32_e32 v130, v128, v116
	v_min_u32_e32 v116, v128, v116
	v_max_u32_e32 v128, v129, v119
	v_min_u32_e32 v119, v129, v119
	v_max_u32_e32 v129, v118, v126
	v_min_u32_e32 v118, v118, v126
	v_max_u32_e32 v126, v139, v115
	v_min_u32_e32 v115, v139, v115
	v_max_u32_e32 v139, v110, v121
	v_min_u32_e32 v110, v110, v121
	v_max_u32_e32 v133, v135, v0
	v_min_u32_e32 v0, v135, v0
; #define CE_DESC(a, b) do { const unsigned _mx = (a) > (b) ? (a) : (b), _mn = (a) > (b) ? (b) : (a); (a) = _mx; (b) = _mn; } while (0)
; __device__ __forceinline__ void sort16_desc(unsigned (&k)[16]) {
; #pragma unroll
;     for (int size = 2; size <= 16; size <<= 1)
; #pragma unroll
;         for (int stride = size >> 1; stride > 0; stride >>= 1)
; #pragma unroll
;             for (int i = 0; i < 16; ++i) { const int j = i ^ stride;
;                 if (j > i) { if ((i & size) == 0) CE_DESC(k[i], k[j]); else CE_DESC(k[j], k[i]); } }
; }
; __device__ __forceinline__ void merge16(unsigned (&a)[16], const unsigned (&b)[16]) {
; #pragma unroll
;     for (int i = 0; i < 16; ++i) a[i] = a[i] > b[15 - i] ? a[i] : b[15 - i];
; #pragma unroll
;     for (int stride = 8; stride > 0; stride >>= 1)
; #pragma unroll
;         for (int i = 0; i < 16; ++i) { const int j = i ^ stride; if (j > i) CE_DESC(a[i], a[j]); }
; }
; __device__ __forceinline__ void peer_tile(const Args& A, LAS unsigned char* lds, int tile) {
;     ...
;                 sort16_desc(k0); sort16_desc(k1); merge16(k0, k1);
; #pragma unroll
;                 for (int msk = 16; msk <= 32; msk <<= 1) {
; #pragma unroll
;                     for (int i = 0; i < 16; ++i) k1[i] = (unsigned)__shfl_xor((int)k0[i], msk);
	v_max_u32_e32 v135, v3, v124
	v_min_u32_e32 v3, v3, v124
	v_max_u32_e32 v124, v138, v123
	v_min_u32_e32 v123, v138, v123
	v_max_u32_e32 v138, v136, v2
	v_min_u32_e32 v2, v136, v2
	v_max_u32_e32 v136, v137, v125
	v_min_u32_e32 v125, v137, v125
	v_max_u32_e32 v137, v131, v134
	v_min_u32_e32 v131, v131, v134
	v_max_u32_e32 v134, v147, v1
	v_min_u32_e32 v1, v147, v1
	v_max_u32_e32 v147, v122, v132
	v_min_u32_e32 v122, v122, v132
	v_max_u32_e32 v121, v120, v128
	v_min_u32_e32 v120, v120, v128
	v_max_u32_e32 v128, v127, v129
	v_min_u32_e32 v127, v127, v129
	v_max_u32_e32 v129, v117, v126
	v_min_u32_e32 v117, v117, v126
	v_max_u32_e32 v126, v130, v139
	v_min_u32_e32 v130, v130, v139
	v_max_u32_e32 v139, v114, v119
	v_min_u32_e32 v114, v114, v119
	v_max_u32_e32 v119, v111, v118
	v_min_u32_e32 v111, v111, v118
	v_max_u32_e32 v118, v112, v115
	v_min_u32_e32 v112, v112, v115
	v_max_u32_e32 v115, v116, v110
	v_min_u32_e32 v110, v116, v110
	v_max_u32_e32 v132, v133, v136
	v_min_u32_e32 v133, v133, v136
	v_max_u32_e32 v136, v135, v137
	v_min_u32_e32 v135, v135, v137
	v_max_u32_e32 v137, v124, v134
	v_min_u32_e32 v124, v124, v134
	v_max_u32_e32 v134, v138, v147
	v_min_u32_e32 v138, v138, v147
	v_max_u32_e32 v147, v0, v125
	v_min_u32_e32 v0, v0, v125
	v_max_u32_e32 v125, v3, v131
	v_min_u32_e32 v3, v3, v131
	v_max_u32_e32 v131, v123, v1
	v_min_u32_e32 v1, v123, v1
	v_max_u32_e32 v123, v2, v122
	v_min_u32_e32 v2, v2, v122
	v_max_u32_e32 v116, v121, v129
	v_min_u32_e32 v121, v121, v129
	v_max_u32_e32 v129, v128, v126
	v_min_u32_e32 v126, v128, v126
	v_max_u32_e32 v128, v120, v117
	v_min_u32_e32 v117, v120, v117
	v_max_u32_e32 v120, v127, v130
	v_min_u32_e32 v127, v127, v130
	v_max_u32_e32 v130, v139, v118
	v_min_u32_e32 v118, v139, v118
	v_max_u32_e32 v139, v119, v115
	v_min_u32_e32 v115, v119, v115
	v_max_u32_e32 v119, v114, v112
	v_min_u32_e32 v112, v114, v112
	v_max_u32_e32 v114, v111, v110
	v_min_u32_e32 v110, v111, v110
	v_max_u32_e32 v122, v132, v137
	v_min_u32_e32 v132, v132, v137
	v_max_u32_e32 v137, v136, v134
	v_min_u32_e32 v134, v136, v134
	v_max_u32_e32 v136, v133, v124
	v_min_u32_e32 v124, v133, v124
	v_max_u32_e32 v133, v135, v138
	v_min_u32_e32 v135, v135, v138
	v_max_u32_e32 v138, v147, v131
	v_min_u32_e32 v131, v147, v131
	v_max_u32_e32 v147, v125, v123
	v_min_u32_e32 v123, v125, v123
	v_max_u32_e32 v125, v0, v1
	v_min_u32_e32 v0, v0, v1
	v_max_u32_e32 v1, v3, v2
	v_min_u32_e32 v2, v3, v2
	v_min_u32_e32 v111, v116, v129
	v_min_u32_e32 v140, v121, v126
	v_min_u32_e32 v141, v128, v120
	v_min_u32_e32 v142, v117, v127
	v_min_u32_e32 v143, v130, v139
	v_min_u32_e32 v144, v118, v115
	v_min_u32_e32 v145, v119, v114
	v_min_u32_e32 v146, v112, v110
	v_min_u32_e32 v3, v122, v137
	v_min_u32_e32 v148, v132, v134
	v_min_u32_e32 v149, v136, v133
	v_min_u32_e32 v150, v124, v135
	v_min_u32_e32 v151, v138, v147
	v_min_u32_e32 v152, v131, v123
	v_min_u32_e32 v153, v125, v1
	v_min_u32_e32 v154, v0, v2
	v_max3_u32 v116, v116, v129, v154
	v_max3_u32 v0, v111, v0, v2
	v_max3_u32 v2, v121, v126, v153
	v_max3_u32 v1, v140, v125, v1
	v_max3_u32 v111, v128, v120, v152
	v_max3_u32 v120, v141, v131, v123
	v_max3_u32 v117, v117, v127, v151
	v_max3_u32 v121, v142, v138, v147
	v_max3_u32 v123, v130, v139, v150
	v_max3_u32 v124, v143, v124, v135
	v_max3_u32 v115, v118, v115, v149
	v_max3_u32 v118, v144, v136, v133
	v_max3_u32 v114, v119, v114, v148
	v_max3_u32 v119, v145, v132, v134
	v_max3_u32 v3, v112, v110, v3
	v_max3_u32 v110, v146, v122, v137
	v_max_u32_e32 v112, v116, v123
	v_min_u32_e32 v116, v116, v123
	v_max_u32_e32 v122, v0, v124
	v_min_u32_e32 v0, v0, v124
	v_max_u32_e32 v123, v2, v115
	v_min_u32_e32 v2, v2, v115
	v_max_u32_e32 v115, v1, v118
	v_min_u32_e32 v1, v1, v118
	v_max_u32_e32 v118, v111, v114
	v_min_u32_e32 v111, v111, v114
	v_max_u32_e32 v114, v120, v119
	v_min_u32_e32 v119, v120, v119
	v_max_u32_e32 v120, v117, v3
	v_min_u32_e32 v3, v117, v3
	v_max_u32_e32 v117, v121, v110
	v_min_u32_e32 v110, v121, v110
	v_max_u32_e32 v121, v112, v118
	v_min_u32_e32 v112, v112, v118
	v_max_u32_e32 v118, v122, v114
	v_min_u32_e32 v114, v122, v114
	v_max_u32_e32 v122, v123, v120
	v_min_u32_e32 v120, v123, v120
	v_max_u32_e32 v123, v115, v117
	v_min_u32_e32 v115, v115, v117
	v_max_u32_e32 v117, v116, v111
	v_min_u32_e32 v111, v116, v111
	v_max_u32_e32 v116, v0, v119
	v_min_u32_e32 v0, v0, v119
	v_max_u32_e32 v119, v2, v3
	v_min_u32_e32 v2, v2, v3
	v_max_u32_e32 v3, v1, v110
	v_min_u32_e32 v1, v1, v110
	v_max_u32_e32 v110, v121, v122
	v_min_u32_e32 v121, v121, v122
	v_max_u32_e32 v122, v118, v123
	v_min_u32_e32 v118, v118, v123
	v_max_u32_e32 v123, v112, v120
	v_min_u32_e32 v112, v112, v120
	v_max_u32_e32 v120, v114, v115
	v_min_u32_e32 v114, v114, v115
	v_max_u32_e32 v115, v117, v119
	v_min_u32_e32 v117, v117, v119
	v_max_u32_e32 v119, v116, v3
	v_min_u32_e32 v3, v116, v3
	v_max_u32_e32 v116, v111, v2
	v_min_u32_e32 v2, v111, v2
	v_max_u32_e32 v111, v0, v1
	v_min_u32_e32 v0, v0, v1
	v_max_u32_e32 v1, v110, v122
	v_min_u32_e32 v110, v110, v122
	v_max_u32_e32 v122, v121, v118
	v_min_u32_e32 v118, v121, v118
	v_max_u32_e32 v121, v123, v120
	v_min_u32_e32 v120, v123, v120
	v_max_u32_e32 v123, v112, v114
	v_min_u32_e32 v112, v112, v114
	v_max_u32_e32 v114, v115, v119
	v_min_u32_e32 v115, v115, v119
	v_max_u32_e32 v119, v117, v3
	v_min_u32_e32 v3, v117, v3
	v_max_u32_e32 v117, v116, v111
	v_min_u32_e32 v111, v116, v111
	v_max_u32_e32 v116, v2, v0
	v_min_u32_e32 v0, v2, v0
	ds_bpermute_b32 v2, v27, v1
	ds_bpermute_b32 v124, v27, v110
	ds_bpermute_b32 v125, v27, v122
	ds_bpermute_b32 v126, v27, v118
	ds_bpermute_b32 v127, v27, v121
	ds_bpermute_b32 v128, v27, v120
	ds_bpermute_b32 v129, v27, v123
	ds_bpermute_b32 v130, v27, v112
	ds_bpermute_b32 v131, v27, v114
	ds_bpermute_b32 v132, v27, v115
	ds_bpermute_b32 v133, v27, v119
	ds_bpermute_b32 v134, v27, v0
	ds_bpermute_b32 v135, v27, v116
	ds_bpermute_b32 v136, v27, v111
	ds_bpermute_b32 v137, v27, v117
	ds_bpermute_b32 v138, v27, v3
	s_waitcnt lgkmcnt(4)
; __device__ __forceinline__ void peer_tile(const Args& A, LAS unsigned char* lds, int tile) {
;     ...
;                 for (int msk = 16; msk <= 32; msk <<= 1) {
; #pragma unroll
;                     for (int i = 0; i < 16; ++i) k1[i] = (unsigned)__shfl_xor((int)k0[i], msk);
;                     merge16(k0, k1); }
; #pragma unroll
;                 for (int i = 0; i < 16; ++i) LA[hh][p][i] = k0[i];
	v_max_u32_e32 v1, v1, v134
	s_waitcnt lgkmcnt(3)
	v_max_u32_e32 v110, v110, v135
	s_waitcnt lgkmcnt(2)
	v_max_u32_e32 v122, v122, v136
	s_waitcnt lgkmcnt(1)
	v_max_u32_e32 v118, v118, v137
	s_waitcnt lgkmcnt(0)
	v_max_u32_e32 v121, v121, v138
	v_max_u32_e32 v120, v120, v133
	v_max_u32_e32 v123, v123, v132
	v_max_u32_e32 v112, v112, v131
	v_max_u32_e32 v114, v114, v130
	v_max_u32_e32 v115, v115, v129
	v_max_u32_e32 v119, v119, v128
	v_max_u32_e32 v3, v3, v127
	v_max_u32_e32 v117, v117, v126
	v_max_u32_e32 v111, v111, v125
	v_max_u32_e32 v116, v116, v124
	v_max_u32_e32 v0, v0, v2
	v_max_u32_e32 v2, v1, v114
	v_min_u32_e32 v1, v1, v114
	v_max_u32_e32 v114, v110, v115
	v_min_u32_e32 v110, v110, v115
	v_max_u32_e32 v115, v122, v119
	v_min_u32_e32 v119, v122, v119
	v_max_u32_e32 v122, v118, v3
	v_min_u32_e32 v3, v118, v3
	v_max_u32_e32 v118, v121, v117
	v_min_u32_e32 v117, v121, v117
	v_max_u32_e32 v121, v120, v111
	v_min_u32_e32 v111, v120, v111
	v_max_u32_e32 v120, v123, v116
	v_min_u32_e32 v116, v123, v116
	v_max_u32_e32 v123, v112, v0
	v_min_u32_e32 v0, v112, v0
	v_max_u32_e32 v112, v2, v118
	v_min_u32_e32 v2, v2, v118
	v_max_u32_e32 v118, v114, v121
	v_min_u32_e32 v114, v114, v121
	v_max_u32_e32 v121, v115, v120
	v_min_u32_e32 v115, v115, v120
	v_max_u32_e32 v120, v122, v123
	v_min_u32_e32 v122, v122, v123
	v_max_u32_e32 v123, v1, v117
	v_min_u32_e32 v1, v1, v117
	v_max_u32_e32 v117, v110, v111
	v_min_u32_e32 v110, v110, v111
	v_max_u32_e32 v111, v119, v116
	v_min_u32_e32 v116, v119, v116
	v_max_u32_e32 v119, v3, v0
	v_min_u32_e32 v0, v3, v0
	v_max_u32_e32 v3, v112, v121
	v_min_u32_e32 v112, v112, v121
	v_max_u32_e32 v121, v118, v120
	v_min_u32_e32 v118, v118, v120
	v_max_u32_e32 v120, v2, v115
	v_min_u32_e32 v2, v2, v115
	v_max_u32_e32 v115, v114, v122
	v_min_u32_e32 v114, v114, v122
	v_max_u32_e32 v122, v123, v111
	v_min_u32_e32 v111, v123, v111
	v_max_u32_e32 v123, v117, v119
	v_min_u32_e32 v117, v117, v119
	v_max_u32_e32 v119, v1, v116
	v_min_u32_e32 v1, v1, v116
	v_max_u32_e32 v116, v110, v0
	v_min_u32_e32 v0, v110, v0
	v_max_u32_e32 v110, v3, v121
	v_min_u32_e32 v3, v3, v121
	v_max_u32_e32 v121, v112, v118
	v_min_u32_e32 v112, v112, v118
	v_max_u32_e32 v118, v120, v115
	v_min_u32_e32 v115, v120, v115
	v_max_u32_e32 v120, v2, v114
	v_min_u32_e32 v2, v2, v114
	v_max_u32_e32 v114, v122, v123
	v_min_u32_e32 v122, v122, v123
	v_max_u32_e32 v123, v111, v117
	v_min_u32_e32 v111, v111, v117
	v_max_u32_e32 v117, v119, v116
	v_min_u32_e32 v116, v119, v116
	v_max_u32_e32 v119, v1, v0
	v_min_u32_e32 v0, v1, v0
	ds_bpermute_b32 v128, v29, v0
	ds_bpermute_b32 v1, v29, v110
	ds_bpermute_b32 v124, v29, v3
	ds_bpermute_b32 v125, v29, v121
	ds_bpermute_b32 v126, v29, v112
	s_waitcnt lgkmcnt(4)
	v_max_u32_e32 v110, v110, v128
	global_load_dwordx4 v[128:131], v[4:5], off offset:1552
	global_load_dwordx4 v[132:135], v[4:5], off offset:1536
	ds_bpermute_b32 v127, v29, v118
	ds_bpermute_b32 v136, v29, v115
	ds_bpermute_b32 v137, v29, v120
	ds_bpermute_b32 v138, v29, v2
	ds_bpermute_b32 v139, v29, v114
	ds_bpermute_b32 v140, v29, v122
	ds_bpermute_b32 v141, v29, v123
	ds_bpermute_b32 v142, v29, v111
	ds_bpermute_b32 v143, v29, v117
	ds_bpermute_b32 v144, v29, v119
	ds_bpermute_b32 v145, v29, v116
	s_waitcnt lgkmcnt(4)
	v_max_u32_e32 v115, v115, v141
	s_waitcnt lgkmcnt(3)
	v_max_u32_e32 v118, v118, v142
	s_waitcnt lgkmcnt(2)
	v_max_u32_e32 v112, v112, v143
	s_waitcnt lgkmcnt(1)
	v_max_u32_e32 v3, v3, v144
	s_waitcnt lgkmcnt(0)
	v_max_u32_e32 v121, v121, v145
	v_max_u32_e32 v120, v120, v140
	v_max_u32_e32 v2, v2, v139
	v_max_u32_e32 v114, v114, v138
	v_max_u32_e32 v122, v122, v137
	v_max_u32_e32 v123, v123, v136
	v_max_u32_e32 v111, v111, v127
	v_max_u32_e32 v117, v117, v126
	v_max_u32_e32 v116, v116, v125
	v_max_u32_e32 v119, v119, v124
	v_max_u32_e32 v0, v0, v1
	v_max_u32_e32 v1, v110, v114
	v_min_u32_e32 v110, v110, v114
	v_max_u32_e32 v114, v3, v122
	v_min_u32_e32 v3, v3, v122
	v_max_u32_e32 v122, v121, v123
	v_min_u32_e32 v121, v121, v123
	v_max_u32_e32 v123, v112, v111
	v_min_u32_e32 v111, v112, v111
	v_max_u32_e32 v112, v118, v117
	v_min_u32_e32 v117, v118, v117
	v_max_u32_e32 v118, v115, v116
	v_min_u32_e32 v115, v115, v116
	v_max_u32_e32 v116, v120, v119
	v_min_u32_e32 v119, v120, v119
	v_max_u32_e32 v120, v2, v0
	v_min_u32_e32 v0, v2, v0
	v_max_u32_e32 v2, v1, v112
	v_min_u32_e32 v1, v1, v112
	v_max_u32_e32 v112, v114, v118
	v_min_u32_e32 v114, v114, v118
	v_max_u32_e32 v118, v122, v116
	v_min_u32_e32 v116, v122, v116
	v_max_u32_e32 v122, v123, v120
	v_min_u32_e32 v120, v123, v120
	v_max_u32_e32 v123, v110, v117
	v_min_u32_e32 v110, v110, v117
	v_max_u32_e32 v117, v3, v115
	v_min_u32_e32 v3, v3, v115
	v_max_u32_e32 v115, v121, v119
	v_min_u32_e32 v119, v121, v119
	v_max_u32_e32 v121, v111, v0
	v_min_u32_e32 v0, v111, v0
	v_max_u32_e32 v111, v2, v118
	v_min_u32_e32 v2, v2, v118
	v_max_u32_e32 v118, v112, v122
	v_min_u32_e32 v112, v112, v122
	v_max_u32_e32 v127, v1, v116
	v_min_u32_e32 v1, v1, v116
	v_max_u32_e32 v116, v114, v120
	v_min_u32_e32 v114, v114, v120
	v_max_u32_e32 v136, v123, v115
	v_min_u32_e32 v115, v123, v115
	v_max_u32_e32 v137, v117, v121
	v_min_u32_e32 v138, v117, v121
	v_max_u32_e32 v139, v110, v119
	v_min_u32_e32 v110, v110, v119
	v_max_u32_e32 v140, v3, v0
	v_min_u32_e32 v0, v3, v0
	v_max_u32_e32 v126, v111, v118
	v_min_u32_e32 v125, v111, v118
	v_max_u32_e32 v124, v2, v112
	v_min_u32_e32 v123, v2, v112
	v_max_u32_e32 v122, v127, v116
	v_min_u32_e32 v121, v127, v116
	v_max_u32_e32 v120, v1, v114
	v_min_u32_e32 v119, v1, v114
	v_max_u32_e32 v118, v136, v137
	v_min_u32_e32 v117, v136, v137
	v_max_u32_e32 v116, v115, v138
	v_min_u32_e32 v115, v115, v138
	v_max_u32_e32 v114, v139, v140
	v_min_u32_e32 v112, v139, v140
	v_max_u32_e32 v111, v110, v0
	v_min_u32_e32 v110, v110, v0
	global_load_dwordx4 v[0:3], v[4:5], off offset:1584
	global_load_dwordx4 v[136:139], v[4:5], off offset:1568
	s_waitcnt vmcnt(2)
; __device__ __forceinline__ unsigned f2key(float f) { const unsigned u = __float_as_uint(f); return (u & 0x80000000u) ? ~u : (u | 0x80000000u); }
; __device__ __forceinline__ void peer_tile(const Args& A, LAS unsigned char* lds, int tile) {
;     ...
;                 { const bf16_t* sp = QRY + m * 2048 + hp * 128 + 32 * g;
;                   const u32x4 s0 = *(const u32x4*)sp, s1 = *(const u32x4*)(sp + 8), s2 = *(const u32x4*)(sp + 16), s3 = *(const u32x4*)(sp + 24);
;                   const unsigned sw[16] = {s0.x, s0.y, s0.z, s0.w, s1.x, s1.y, s1.z, s1.w, s2.x, s2.y, s2.z, s2.w, s3.x, s3.y, s3.z, s3.w};
; #pragma unroll
;                   for (int i = 0; i < 16; ++i) {
;                       const float lo = (float)__builtin_bit_cast(_Float16, (unsigned short)(sw[i] & 0xffffu)), hi = (float)__builtin_bit_cast(_Float16, (unsigned short)(sw[i] >> 16));
;                       const unsigned klo = (f2key(lo) & ~127u) | (unsigned)(127 - (32 * g + 2 * i)), khi = (f2key(hi) & ~127u) | (unsigned)(127 - (32 * g + 2 * i + 1));
;                       if (i < 8) { k0[2 * i] = klo; k0[2 * i + 1] = khi; } else { k1[2 * (i - 8)] = klo; k1[2 * (i - 8) + 1] = khi; } } }
	v_cvt_f32_f16_sdwa v127, v132 dst_sel:DWORD dst_unused:UNUSED_PAD src0_sel:WORD_1
	v_cvt_f32_f16_e32 v132, v132
	v_not_b32_e32 v140, v127
	v_or_b32_e32 v141, 0x80000000, v127
	v_cmp_gt_i32_e32 vcc, 0, v127
	s_nop 1
	v_cndmask_b32_e32 v127, v141, v140, vcc
	v_not_b32_e32 v140, v132
	v_or_b32_e32 v141, 0x80000000, v132
	v_cmp_gt_i32_e32 vcc, 0, v132
	v_and_b32_e32 v127, 0xffffff80, v127
	v_sub_u32_e32 v127, v127, v15
	v_cndmask_b32_e32 v132, v141, v140, vcc
	v_cvt_f32_f16_sdwa v140, v133 dst_sel:DWORD dst_unused:UNUSED_PAD src0_sel:WORD_1
	v_cvt_f32_f16_e32 v133, v133
	v_and_b32_e32 v132, 0xffffff80, v132
	v_sub_u32_e32 v132, v132, v15
	v_not_b32_e32 v141, v140
	v_or_b32_e32 v142, 0x80000000, v140
	v_cmp_gt_i32_e32 vcc, 0, v140
	v_add_u32_e32 v127, 0x7e, v127
	v_add_u32_e32 v132, 0x7f, v132
	v_cndmask_b32_e32 v140, v142, v141, vcc
	v_not_b32_e32 v141, v133
	v_or_b32_e32 v142, 0x80000000, v133
	v_cmp_gt_i32_e32 vcc, 0, v133
	v_and_b32_e32 v140, 0xffffff80, v140
	v_sub_u32_e32 v140, v140, v14
	v_cndmask_b32_e32 v133, v142, v141, vcc
	v_cvt_f32_f16_sdwa v141, v134 dst_sel:DWORD dst_unused:UNUSED_PAD src0_sel:WORD_1
	v_cvt_f32_f16_e32 v134, v134
	v_and_b32_e32 v133, 0xffffff80, v133
	v_sub_u32_e32 v133, v133, v14
	v_not_b32_e32 v142, v141
	v_or_b32_e32 v143, 0x80000000, v141
	v_cmp_gt_i32_e32 vcc, 0, v141
	v_add_u32_e32 v140, 0x7e, v140
	v_add_u32_e32 v133, 0x7f, v133
	v_cndmask_b32_e32 v141, v143, v142, vcc
	v_not_b32_e32 v142, v134
	v_or_b32_e32 v143, 0x80000000, v134
	v_cmp_gt_i32_e32 vcc, 0, v134
	v_and_b32_e32 v141, 0xffffff80, v141
	v_sub_u32_e32 v141, v141, v12
	v_cndmask_b32_e32 v134, v143, v142, vcc
	v_cvt_f32_f16_sdwa v142, v135 dst_sel:DWORD dst_unused:UNUSED_PAD src0_sel:WORD_1
	v_cvt_f32_f16_e32 v135, v135
	v_and_b32_e32 v134, 0xffffff80, v134
	v_sub_u32_e32 v134, v134, v12
	v_not_b32_e32 v143, v142
	v_or_b32_e32 v144, 0x80000000, v142
	v_cmp_gt_i32_e32 vcc, 0, v142
	v_add_u32_e32 v141, 0x7e, v141
	v_add_u32_e32 v134, 0x7f, v134
	v_cndmask_b32_e32 v142, v144, v143, vcc
	v_not_b32_e32 v143, v135
	v_or_b32_e32 v144, 0x80000000, v135
	v_cmp_gt_i32_e32 vcc, 0, v135
	v_and_b32_e32 v142, 0xffffff80, v142
	v_sub_u32_e32 v142, v142, v10
	v_cndmask_b32_e32 v135, v144, v143, vcc
	v_cvt_f32_f16_sdwa v143, v128 dst_sel:DWORD dst_unused:UNUSED_PAD src0_sel:WORD_1
	v_cvt_f32_f16_e32 v128, v128
	v_and_b32_e32 v135, 0xffffff80, v135
	v_sub_u32_e32 v135, v135, v10
	v_not_b32_e32 v144, v143
	v_or_b32_e32 v145, 0x80000000, v143
	v_cmp_gt_i32_e32 vcc, 0, v143
	v_add_u32_e32 v142, 0x7e, v142
	v_add_u32_e32 v135, 0x7f, v135
	v_cndmask_b32_e32 v143, v145, v144, vcc
	v_not_b32_e32 v144, v128
	v_or_b32_e32 v145, 0x80000000, v128
	v_cmp_gt_i32_e32 vcc, 0, v128
	v_and_b32_e32 v143, 0xffffff80, v143
	v_sub_u32_e32 v143, v143, v8
	v_cndmask_b32_e32 v128, v145, v144, vcc
	v_cvt_f32_f16_sdwa v144, v129 dst_sel:DWORD dst_unused:UNUSED_PAD src0_sel:WORD_1
	v_cvt_f32_f16_e32 v129, v129
	v_and_b32_e32 v128, 0xffffff80, v128
	v_sub_u32_e32 v128, v128, v8
	v_not_b32_e32 v145, v144
	v_or_b32_e32 v146, 0x80000000, v144
	v_cmp_gt_i32_e32 vcc, 0, v144
	v_add_u32_e32 v143, 0x7e, v143
	v_add_u32_e32 v128, 0x7f, v128
	v_cndmask_b32_e32 v144, v146, v145, vcc
	v_not_b32_e32 v145, v129
	v_or_b32_e32 v146, 0x80000000, v129
	v_cmp_gt_i32_e32 vcc, 0, v129
	v_and_b32_e32 v144, 0xffffff80, v144
	v_sub_u32_e32 v144, v144, v16
	v_cndmask_b32_e32 v129, v146, v145, vcc
	v_cvt_f32_f16_sdwa v145, v130 dst_sel:DWORD dst_unused:UNUSED_PAD src0_sel:WORD_1
	v_cvt_f32_f16_e32 v130, v130
	v_and_b32_e32 v129, 0xffffff80, v129
	v_sub_u32_e32 v129, v129, v16
	v_not_b32_e32 v146, v145
	v_or_b32_e32 v147, 0x80000000, v145
	v_cmp_gt_i32_e32 vcc, 0, v145
	v_add_u32_e32 v144, 0x7e, v144
	v_add_u32_e32 v129, 0x7f, v129
	v_cndmask_b32_e32 v145, v147, v146, vcc
	v_not_b32_e32 v146, v130
	v_or_b32_e32 v147, 0x80000000, v130
	v_cmp_gt_i32_e32 vcc, 0, v130
	v_and_b32_e32 v145, 0xffffff80, v145
	v_sub_u32_e32 v145, v145, v17
	v_cndmask_b32_e32 v130, v147, v146, vcc
	v_cvt_f32_f16_sdwa v146, v131 dst_sel:DWORD dst_unused:UNUSED_PAD src0_sel:WORD_1
	v_cvt_f32_f16_e32 v131, v131
	v_and_b32_e32 v130, 0xffffff80, v130
	v_sub_u32_e32 v130, v130, v17
	v_not_b32_e32 v147, v146
	v_or_b32_e32 v148, 0x80000000, v146
	v_cmp_gt_i32_e32 vcc, 0, v146
	v_add_u32_e32 v145, 0x7e, v145
	v_add_u32_e32 v130, 0x7f, v130
	v_cndmask_b32_e32 v146, v148, v147, vcc
	v_not_b32_e32 v147, v131
	v_or_b32_e32 v148, 0x80000000, v131
	v_cmp_gt_i32_e32 vcc, 0, v131
	v_and_b32_e32 v146, 0xffffff80, v146
	v_sub_u32_e32 v146, v146, v18
	v_cndmask_b32_e32 v131, v148, v147, vcc
	s_waitcnt vmcnt(0)
; __device__ __forceinline__ unsigned f2key(float f) { const unsigned u = __float_as_uint(f); return (u & 0x80000000u) ? ~u : (u | 0x80000000u); }
; #define CE_DESC(a, b) do { const unsigned _mx = (a) > (b) ? (a) : (b), _mn = (a) > (b) ? (b) : (a); (a) = _mx; (b) = _mn; } while (0)
; __device__ __forceinline__ void sort16_desc(unsigned (&k)[16]) {
; #pragma unroll
;     for (int size = 2; size <= 16; size <<= 1)
; #pragma unroll
;         for (int stride = size >> 1; stride > 0; stride >>= 1)
; #pragma unroll
;             for (int i = 0; i < 16; ++i) { const int j = i ^ stride;
;                 if (j > i) { if ((i & size) == 0) CE_DESC(k[i], k[j]); else CE_DESC(k[j], k[i]); } }
; __device__ __forceinline__ void peer_tile(const Args& A, LAS unsigned char* lds, int tile) {
;     ...
;                   for (int i = 0; i < 16; ++i) {
;                       const float lo = (float)__builtin_bit_cast(_Float16, (unsigned short)(sw[i] & 0xffffu)), hi = (float)__builtin_bit_cast(_Float16, (unsigned short)(sw[i] >> 16));
;                       const unsigned klo = (f2key(lo) & ~127u) | (unsigned)(127 - (32 * g + 2 * i)), khi = (f2key(hi) & ~127u) | (unsigned)(127 - (32 * g + 2 * i + 1));
;                       if (i < 8) { k0[2 * i] = klo; k0[2 * i + 1] = khi; } else { k1[2 * (i - 8)] = klo; k1[2 * (i - 8) + 1] = khi; } } }
;                 sort16_desc(k0); sort16_desc(k1); merge16(k0, k1);
	v_cvt_f32_f16_sdwa v147, v136 dst_sel:DWORD dst_unused:UNUSED_PAD src0_sel:WORD_1
	v_cvt_f32_f16_e32 v136, v136
	v_and_b32_e32 v131, 0xffffff80, v131
	v_sub_u32_e32 v131, v131, v18
	v_not_b32_e32 v148, v147
	v_or_b32_e32 v149, 0x80000000, v147
	v_cmp_gt_i32_e32 vcc, 0, v147
	v_add_u32_e32 v146, 0x7e, v146
	v_add_u32_e32 v131, 0x7f, v131
	v_cndmask_b32_e32 v147, v149, v148, vcc
	v_not_b32_e32 v148, v136
	v_or_b32_e32 v149, 0x80000000, v136
	v_cmp_gt_i32_e32 vcc, 0, v136
	v_and_b32_e32 v147, 0xffffff80, v147
	v_sub_u32_e32 v147, v147, v20
	v_cndmask_b32_e32 v136, v149, v148, vcc
	v_cvt_f32_f16_sdwa v148, v137 dst_sel:DWORD dst_unused:UNUSED_PAD src0_sel:WORD_1
	v_cvt_f32_f16_e32 v137, v137
	v_and_b32_e32 v136, 0xffffff80, v136
	v_sub_u32_e32 v136, v136, v20
	v_not_b32_e32 v149, v148
	v_or_b32_e32 v150, 0x80000000, v148
	v_cmp_gt_i32_e32 vcc, 0, v148
	v_add_u32_e32 v147, 0x7e, v147
	v_add_u32_e32 v136, 0x7f, v136
	v_cndmask_b32_e32 v148, v150, v149, vcc
	v_not_b32_e32 v149, v137
	v_or_b32_e32 v150, 0x80000000, v137
	v_cmp_gt_i32_e32 vcc, 0, v137
	v_and_b32_e32 v148, 0xffffff80, v148
	v_sub_u32_e32 v148, v148, v21
	v_cndmask_b32_e32 v137, v150, v149, vcc
	v_cvt_f32_f16_sdwa v149, v138 dst_sel:DWORD dst_unused:UNUSED_PAD src0_sel:WORD_1
	v_cvt_f32_f16_e32 v138, v138
	v_and_b32_e32 v137, 0xffffff80, v137
	v_sub_u32_e32 v137, v137, v21
	v_not_b32_e32 v150, v149
	v_or_b32_e32 v151, 0x80000000, v149
	v_cmp_gt_i32_e32 vcc, 0, v149
	v_add_u32_e32 v148, 0x7e, v148
	v_add_u32_e32 v137, 0x7f, v137
	v_cndmask_b32_e32 v149, v151, v150, vcc
	v_not_b32_e32 v150, v138
	v_or_b32_e32 v151, 0x80000000, v138
	v_cmp_gt_i32_e32 vcc, 0, v138
	v_and_b32_e32 v149, 0xffffff80, v149
	v_sub_u32_e32 v149, v149, v22
	v_cndmask_b32_e32 v138, v151, v150, vcc
	v_cvt_f32_f16_sdwa v150, v139 dst_sel:DWORD dst_unused:UNUSED_PAD src0_sel:WORD_1
	v_cvt_f32_f16_e32 v139, v139
	v_and_b32_e32 v138, 0xffffff80, v138
	v_sub_u32_e32 v138, v138, v22
	v_not_b32_e32 v151, v150
	v_or_b32_e32 v152, 0x80000000, v150
	v_cmp_gt_i32_e32 vcc, 0, v150
	v_add_u32_e32 v149, 0x7e, v149
	v_add_u32_e32 v138, 0x7f, v138
	v_cndmask_b32_e32 v150, v152, v151, vcc
	v_not_b32_e32 v151, v139
	v_or_b32_e32 v152, 0x80000000, v139
	v_cmp_gt_i32_e32 vcc, 0, v139
	v_and_b32_e32 v150, 0xffffff80, v150
	v_sub_u32_e32 v150, v150, v23
	v_cndmask_b32_e32 v139, v152, v151, vcc
	v_cvt_f32_f16_sdwa v151, v0 dst_sel:DWORD dst_unused:UNUSED_PAD src0_sel:WORD_1
	v_cvt_f32_f16_e32 v0, v0
	v_and_b32_e32 v139, 0xffffff80, v139
	v_sub_u32_e32 v139, v139, v23
	v_not_b32_e32 v152, v151
	v_or_b32_e32 v153, 0x80000000, v151
	v_cmp_gt_i32_e32 vcc, 0, v151
	v_add_u32_e32 v150, 0x7e, v150
	v_add_u32_e32 v139, 0x7f, v139
	v_cndmask_b32_e32 v151, v153, v152, vcc
	v_not_b32_e32 v152, v0
	v_or_b32_e32 v153, 0x80000000, v0
	v_cmp_gt_i32_e32 vcc, 0, v0
	v_and_b32_e32 v151, 0xffffff80, v151
	v_sub_u32_e32 v151, v151, v24
	v_cndmask_b32_e32 v0, v153, v152, vcc
	v_cvt_f32_f16_sdwa v152, v1 dst_sel:DWORD dst_unused:UNUSED_PAD src0_sel:WORD_1
	v_cvt_f32_f16_e32 v1, v1
	v_and_b32_e32 v0, 0xffffff80, v0
	v_sub_u32_e32 v0, v0, v24
	v_not_b32_e32 v153, v152
	v_or_b32_e32 v154, 0x80000000, v152
	v_cmp_gt_i32_e32 vcc, 0, v152
	v_add_u32_e32 v151, 0x7e, v151
	v_add_u32_e32 v0, 0x7f, v0
	v_cndmask_b32_e32 v152, v154, v153, vcc
	v_not_b32_e32 v153, v1
	v_or_b32_e32 v154, 0x80000000, v1
	v_cmp_gt_i32_e32 vcc, 0, v1
	v_and_b32_e32 v152, 0xffffff80, v152
	v_sub_u32_e32 v152, v152, v25
	v_cndmask_b32_e32 v1, v154, v153, vcc
	v_cvt_f32_f16_sdwa v153, v2 dst_sel:DWORD dst_unused:UNUSED_PAD src0_sel:WORD_1
	v_cvt_f32_f16_e32 v2, v2
	v_and_b32_e32 v1, 0xffffff80, v1
	v_sub_u32_e32 v1, v1, v25
	v_not_b32_e32 v154, v153
	v_or_b32_e32 v155, 0x80000000, v153
	v_cmp_gt_i32_e32 vcc, 0, v153
	v_add_u32_e32 v152, 0x7e, v152
	v_add_u32_e32 v1, 0x7f, v1
	v_cndmask_b32_e32 v153, v155, v154, vcc
	v_not_b32_e32 v154, v2
	v_or_b32_e32 v155, 0x80000000, v2
	v_cmp_gt_i32_e32 vcc, 0, v2
	v_and_b32_e32 v153, 0xffffff80, v153
	v_sub_u32_e32 v153, v153, v26
	v_cndmask_b32_e32 v2, v155, v154, vcc
	v_cvt_f32_f16_sdwa v154, v3 dst_sel:DWORD dst_unused:UNUSED_PAD src0_sel:WORD_1
	v_cvt_f32_f16_e32 v3, v3
	v_and_b32_e32 v2, 0xffffff80, v2
	v_sub_u32_e32 v2, v2, v26
	v_not_b32_e32 v155, v154
	v_or_b32_e32 v156, 0x80000000, v154
	v_cmp_gt_i32_e32 vcc, 0, v154
	v_add_u32_e32 v153, 0x7e, v153
	v_add_u32_e32 v2, 0x7f, v2
	v_cndmask_b32_e32 v154, v156, v155, vcc
	v_not_b32_e32 v155, v3
	v_or_b32_e32 v156, 0x80000000, v3
	v_cmp_gt_i32_e32 vcc, 0, v3
	v_and_b32_e32 v154, 0xffffff80, v154
	v_sub_u32_e32 v154, v154, v28
	v_cndmask_b32_e32 v3, v156, v155, vcc
	v_and_b32_e32 v3, 0xffffff80, v3
	v_sub_u32_e32 v3, v3, v28
	v_add_u32_e32 v154, 0x7e, v154
	v_add_u32_e32 v3, 0x7f, v3
	v_max_u32_e32 v155, v132, v127
	v_min_u32_e32 v127, v132, v127
	v_max_u32_e32 v132, v140, v133
	v_min_u32_e32 v133, v140, v133
	v_max_u32_e32 v140, v134, v141
	v_min_u32_e32 v134, v134, v141
	v_max_u32_e32 v141, v142, v135
	v_min_u32_e32 v135, v142, v135
	v_max_u32_e32 v142, v128, v143
	v_min_u32_e32 v128, v128, v143
	v_max_u32_e32 v143, v144, v129
	v_min_u32_e32 v129, v144, v129
	v_max_u32_e32 v144, v130, v145
	v_min_u32_e32 v130, v130, v145
	v_max_u32_e32 v145, v146, v131
	v_min_u32_e32 v131, v146, v131
	v_max_u32_e32 v163, v136, v147
	v_min_u32_e32 v136, v136, v147
	v_max_u32_e32 v147, v148, v137
	v_min_u32_e32 v137, v148, v137
	v_max_u32_e32 v148, v138, v149
	v_min_u32_e32 v138, v138, v149
	v_max_u32_e32 v149, v150, v139
	v_min_u32_e32 v139, v150, v139
	v_max_u32_e32 v150, v0, v151
	v_min_u32_e32 v0, v0, v151
	v_max_u32_e32 v151, v152, v1
	v_min_u32_e32 v1, v152, v1
	v_max_u32_e32 v152, v2, v153
	v_min_u32_e32 v2, v2, v153
; #define CE_DESC(a, b) do { const unsigned _mx = (a) > (b) ? (a) : (b), _mn = (a) > (b) ? (b) : (a); (a) = _mx; (b) = _mn; } while (0)
; __device__ __forceinline__ void sort16_desc(unsigned (&k)[16]) {
; #pragma unroll
;     for (int size = 2; size <= 16; size <<= 1)
; #pragma unroll
;         for (int stride = size >> 1; stride > 0; stride >>= 1)
; #pragma unroll
;             for (int i = 0; i < 16; ++i) { const int j = i ^ stride;
;                 if (j > i) { if ((i & size) == 0) CE_DESC(k[i], k[j]); else CE_DESC(k[j], k[i]); } }
	v_max_u32_e32 v153, v154, v3
	v_min_u32_e32 v3, v154, v3
	v_max_u32_e32 v146, v155, v133
	v_min_u32_e32 v133, v155, v133
	v_max_u32_e32 v155, v127, v132
	v_min_u32_e32 v127, v127, v132
	v_max_u32_e32 v132, v135, v140
	v_min_u32_e32 v135, v135, v140
	v_max_u32_e32 v140, v141, v134
	v_min_u32_e32 v134, v141, v134
	v_max_u32_e32 v141, v142, v129
	v_min_u32_e32 v129, v142, v129
	v_max_u32_e32 v142, v128, v143
	v_min_u32_e32 v128, v128, v143
	v_max_u32_e32 v143, v131, v144
	v_min_u32_e32 v131, v131, v144
	v_max_u32_e32 v144, v145, v130
	v_min_u32_e32 v130, v145, v130
	v_max_u32_e32 v154, v163, v137
	v_min_u32_e32 v137, v163, v137
	v_max_u32_e32 v163, v136, v147
	v_min_u32_e32 v136, v136, v147
	v_max_u32_e32 v147, v139, v148
	v_min_u32_e32 v139, v139, v148
	v_max_u32_e32 v148, v149, v138
	v_min_u32_e32 v138, v149, v138
	v_max_u32_e32 v149, v150, v1
	v_min_u32_e32 v1, v150, v1
	v_max_u32_e32 v150, v0, v151
	v_min_u32_e32 v0, v0, v151
	v_max_u32_e32 v151, v3, v152
	v_min_u32_e32 v3, v3, v152
	v_max_u32_e32 v152, v153, v2
	v_min_u32_e32 v2, v153, v2
	v_max_u32_e32 v145, v146, v155
	v_min_u32_e32 v146, v146, v155
	v_max_u32_e32 v155, v133, v127
	v_min_u32_e32 v127, v133, v127
	v_max_u32_e32 v133, v134, v135
	v_min_u32_e32 v134, v134, v135
	v_max_u32_e32 v135, v140, v132
	v_min_u32_e32 v132, v140, v132
	v_max_u32_e32 v140, v141, v142
	v_min_u32_e32 v141, v141, v142
	v_max_u32_e32 v142, v129, v128
	v_min_u32_e32 v128, v129, v128
	v_max_u32_e32 v129, v130, v131
	v_min_u32_e32 v130, v130, v131
	v_max_u32_e32 v131, v144, v143
	v_min_u32_e32 v143, v144, v143
	v_max_u32_e32 v153, v154, v163
	v_min_u32_e32 v154, v154, v163
	v_max_u32_e32 v163, v137, v136
	v_min_u32_e32 v136, v137, v136
	v_max_u32_e32 v137, v138, v139
	v_min_u32_e32 v138, v138, v139
	v_max_u32_e32 v139, v148, v147
	v_min_u32_e32 v147, v148, v147
	v_max_u32_e32 v148, v149, v150
	v_min_u32_e32 v149, v149, v150
	v_max_u32_e32 v150, v1, v0
	v_min_u32_e32 v0, v1, v0
	v_max_u32_e32 v1, v2, v3
	v_min_u32_e32 v2, v2, v3
	v_max_u32_e32 v3, v152, v151
	v_min_u32_e32 v151, v152, v151
	v_max_u32_e32 v144, v145, v134
	v_min_u32_e32 v134, v145, v134
	v_max_u32_e32 v145, v146, v133
	v_min_u32_e32 v133, v146, v133
	v_max_u32_e32 v146, v155, v132
	v_min_u32_e32 v132, v155, v132
	v_max_u32_e32 v155, v127, v135
	v_min_u32_e32 v127, v127, v135
	v_max_u32_e32 v135, v130, v140
	v_min_u32_e32 v130, v130, v140
	v_max_u32_e32 v140, v129, v141
	v_min_u32_e32 v129, v129, v141
	v_max_u32_e32 v141, v143, v142
	v_min_u32_e32 v142, v143, v142
	v_max_u32_e32 v143, v131, v128
	v_min_u32_e32 v128, v131, v128
	v_max_u32_e32 v152, v153, v138
	v_min_u32_e32 v138, v153, v138
	v_max_u32_e32 v153, v154, v137
	v_min_u32_e32 v137, v154, v137
	v_max_u32_e32 v154, v163, v147
	v_min_u32_e32 v147, v163, v147
	v_max_u32_e32 v163, v136, v139
	v_min_u32_e32 v136, v136, v139
	v_max_u32_e32 v139, v2, v148
	v_min_u32_e32 v2, v2, v148
	v_max_u32_e32 v148, v1, v149
	v_min_u32_e32 v1, v1, v149
	v_max_u32_e32 v149, v151, v150
	v_min_u32_e32 v150, v151, v150
	v_max_u32_e32 v151, v3, v0
	v_min_u32_e32 v0, v3, v0
	v_max_u32_e32 v131, v144, v146
	v_min_u32_e32 v144, v144, v146
	v_max_u32_e32 v146, v145, v155
	v_min_u32_e32 v145, v145, v155
	v_max_u32_e32 v155, v134, v132
	v_min_u32_e32 v132, v134, v132
	v_max_u32_e32 v134, v133, v127
	v_min_u32_e32 v127, v133, v127
	v_max_u32_e32 v133, v142, v130
	v_min_u32_e32 v130, v142, v130
	v_max_u32_e32 v142, v128, v129
	v_min_u32_e32 v128, v128, v129
	v_max_u32_e32 v129, v141, v135
	v_min_u32_e32 v135, v141, v135
	v_max_u32_e32 v141, v143, v140
	v_min_u32_e32 v140, v143, v140
	v_max_u32_e32 v3, v152, v154
	v_min_u32_e32 v152, v152, v154
	v_max_u32_e32 v154, v153, v163
	v_min_u32_e32 v153, v153, v163
	v_max_u32_e32 v163, v138, v147
	v_min_u32_e32 v138, v138, v147
	v_max_u32_e32 v147, v137, v136
	v_min_u32_e32 v136, v137, v136
	v_max_u32_e32 v137, v150, v2
	v_min_u32_e32 v2, v150, v2
	v_max_u32_e32 v150, v0, v1
	v_min_u32_e32 v0, v0, v1
	v_max_u32_e32 v1, v149, v139
	v_min_u32_e32 v139, v149, v139
	v_max_u32_e32 v149, v151, v148
	v_min_u32_e32 v148, v151, v148
	v_max_u32_e32 v143, v131, v146
	v_min_u32_e32 v131, v131, v146
	v_max_u32_e32 v146, v144, v145
	v_min_u32_e32 v144, v144, v145
	v_max_u32_e32 v145, v155, v134
	v_min_u32_e32 v134, v155, v134
	v_max_u32_e32 v155, v132, v127
	v_min_u32_e32 v127, v132, v127
	v_max_u32_e32 v132, v128, v130
	v_min_u32_e32 v128, v128, v130
	v_max_u32_e32 v130, v142, v133
	v_min_u32_e32 v133, v142, v133
	v_max_u32_e32 v142, v140, v135
	v_min_u32_e32 v135, v140, v135
	v_max_u32_e32 v140, v141, v129
	v_min_u32_e32 v129, v141, v129
	v_max_u32_e32 v151, v3, v154
	v_min_u32_e32 v3, v3, v154
	v_max_u32_e32 v154, v152, v153
	v_min_u32_e32 v152, v152, v153
	v_max_u32_e32 v153, v163, v147
	v_min_u32_e32 v147, v163, v147
	v_max_u32_e32 v163, v138, v136
	v_min_u32_e32 v136, v138, v136
	v_max_u32_e32 v138, v0, v2
	v_min_u32_e32 v0, v0, v2
	v_max_u32_e32 v2, v150, v137
	v_min_u32_e32 v137, v150, v137
	v_max_u32_e32 v150, v148, v139
	v_min_u32_e32 v139, v148, v139
	v_max_u32_e32 v148, v149, v1
	v_min_u32_e32 v1, v149, v1
	v_max_u32_e32 v141, v143, v128
	v_min_u32_e32 v128, v143, v128
	v_max_u32_e32 v143, v131, v132
	v_min_u32_e32 v131, v131, v132
	v_max_u32_e32 v132, v146, v133
	v_min_u32_e32 v133, v146, v133
	v_max_u32_e32 v146, v144, v130
	v_min_u32_e32 v130, v144, v130
	v_max_u32_e32 v144, v145, v135
	v_min_u32_e32 v135, v145, v135
	v_max_u32_e32 v145, v134, v142
	v_min_u32_e32 v134, v134, v142
	v_max_u32_e32 v142, v155, v129
	v_min_u32_e32 v129, v155, v129
	v_max_u32_e32 v155, v127, v140
	v_min_u32_e32 v127, v127, v140
	v_max_u32_e32 v149, v151, v0
	v_min_u32_e32 v0, v151, v0
; #define CE_DESC(a, b) do { const unsigned _mx = (a) > (b) ? (a) : (b), _mn = (a) > (b) ? (b) : (a); (a) = _mx; (b) = _mn; } while (0)
; __device__ __forceinline__ void sort16_desc(unsigned (&k)[16]) {
; #pragma unroll
;     for (int size = 2; size <= 16; size <<= 1)
; #pragma unroll
;         for (int stride = size >> 1; stride > 0; stride >>= 1)
; #pragma unroll
;             for (int i = 0; i < 16; ++i) { const int j = i ^ stride;
;                 if (j > i) { if ((i & size) == 0) CE_DESC(k[i], k[j]); else CE_DESC(k[j], k[i]); } }
; }
; __device__ __forceinline__ void merge16(unsigned (&a)[16], const unsigned (&b)[16]) {
; #pragma unroll
;     for (int i = 0; i < 16; ++i) a[i] = a[i] > b[15 - i] ? a[i] : b[15 - i];
; #pragma unroll
;     for (int stride = 8; stride > 0; stride >>= 1)
; #pragma unroll
;         for (int i = 0; i < 16; ++i) { const int j = i ^ stride; if (j > i) CE_DESC(a[i], a[j]); }
; }
; __device__ __forceinline__ void peer_tile(const Args& A, LAS unsigned char* lds, int tile) {
;     ...
;                 sort16_desc(k0); sort16_desc(k1); merge16(k0, k1);
; #pragma unroll
;                 for (int msk = 16; msk <= 32; msk <<= 1) {
; #pragma unroll
;                     for (int i = 0; i < 16; ++i) k1[i] = (unsigned)__shfl_xor((int)k0[i], msk);
	v_max_u32_e32 v151, v3, v138
	v_min_u32_e32 v3, v3, v138
	v_max_u32_e32 v138, v154, v137
	v_min_u32_e32 v137, v154, v137
	v_max_u32_e32 v154, v152, v2
	v_min_u32_e32 v2, v152, v2
	v_max_u32_e32 v152, v153, v139
	v_min_u32_e32 v139, v153, v139
	v_max_u32_e32 v153, v147, v150
	v_min_u32_e32 v147, v147, v150
	v_max_u32_e32 v150, v163, v1
	v_min_u32_e32 v1, v163, v1
	v_max_u32_e32 v163, v136, v148
	v_min_u32_e32 v136, v136, v148
	v_max_u32_e32 v140, v141, v144
	v_min_u32_e32 v141, v141, v144
	v_max_u32_e32 v144, v143, v145
	v_min_u32_e32 v143, v143, v145
	v_max_u32_e32 v145, v132, v142
	v_min_u32_e32 v132, v132, v142
	v_max_u32_e32 v142, v146, v155
	v_min_u32_e32 v146, v146, v155
	v_max_u32_e32 v155, v128, v135
	v_min_u32_e32 v128, v128, v135
	v_max_u32_e32 v135, v131, v134
	v_min_u32_e32 v131, v131, v134
	v_max_u32_e32 v134, v133, v129
	v_min_u32_e32 v129, v133, v129
	v_max_u32_e32 v133, v130, v127
	v_min_u32_e32 v127, v130, v127
	v_max_u32_e32 v148, v149, v152
	v_min_u32_e32 v149, v149, v152
	v_max_u32_e32 v152, v151, v153
	v_min_u32_e32 v151, v151, v153
	v_max_u32_e32 v153, v138, v150
	v_min_u32_e32 v138, v138, v150
	v_max_u32_e32 v150, v154, v163
	v_min_u32_e32 v154, v154, v163
	v_max_u32_e32 v163, v0, v139
	v_min_u32_e32 v0, v0, v139
	v_max_u32_e32 v139, v3, v147
	v_min_u32_e32 v3, v3, v147
	v_max_u32_e32 v147, v137, v1
	v_min_u32_e32 v1, v137, v1
	v_max_u32_e32 v137, v2, v136
	v_min_u32_e32 v2, v2, v136
	v_max_u32_e32 v130, v140, v145
	v_min_u32_e32 v140, v140, v145
	v_max_u32_e32 v145, v144, v142
	v_min_u32_e32 v142, v144, v142
	v_max_u32_e32 v144, v141, v132
	v_min_u32_e32 v132, v141, v132
	v_max_u32_e32 v141, v143, v146
	v_min_u32_e32 v143, v143, v146
	v_max_u32_e32 v146, v155, v134
	v_min_u32_e32 v134, v155, v134
	v_max_u32_e32 v155, v135, v133
	v_min_u32_e32 v133, v135, v133
	v_max_u32_e32 v135, v128, v129
	v_min_u32_e32 v128, v128, v129
	v_max_u32_e32 v129, v131, v127
	v_min_u32_e32 v127, v131, v127
	v_max_u32_e32 v136, v148, v153
	v_min_u32_e32 v148, v148, v153
	v_max_u32_e32 v153, v152, v150
	v_min_u32_e32 v150, v152, v150
	v_max_u32_e32 v152, v149, v138
	v_min_u32_e32 v138, v149, v138
	v_max_u32_e32 v149, v151, v154
	v_min_u32_e32 v151, v151, v154
	v_max_u32_e32 v154, v163, v147
	v_min_u32_e32 v147, v163, v147
	v_max_u32_e32 v163, v139, v137
	v_min_u32_e32 v137, v139, v137
	v_max_u32_e32 v139, v0, v1
	v_min_u32_e32 v0, v0, v1
	v_max_u32_e32 v1, v3, v2
	v_min_u32_e32 v2, v3, v2
	v_min_u32_e32 v131, v130, v145
	v_min_u32_e32 v156, v140, v142
	v_min_u32_e32 v157, v144, v141
	v_min_u32_e32 v158, v132, v143
	v_min_u32_e32 v159, v146, v155
	v_min_u32_e32 v160, v134, v133
	v_min_u32_e32 v161, v135, v129
	v_min_u32_e32 v162, v128, v127
	v_min_u32_e32 v3, v136, v153
	v_min_u32_e32 v164, v148, v150
	v_min_u32_e32 v165, v152, v149
	v_min_u32_e32 v166, v138, v151
	v_min_u32_e32 v167, v154, v163
	v_min_u32_e32 v168, v147, v137
	v_min_u32_e32 v169, v139, v1
	v_min_u32_e32 v170, v0, v2
	v_max3_u32 v130, v130, v145, v170
	v_max3_u32 v0, v131, v0, v2
	v_max3_u32 v2, v140, v142, v169
	v_max3_u32 v1, v156, v139, v1
	v_max3_u32 v131, v144, v141, v168
	v_max3_u32 v137, v157, v147, v137
	v_max3_u32 v132, v132, v143, v167
	v_max3_u32 v139, v158, v154, v163
	v_max3_u32 v140, v146, v155, v166
	v_max3_u32 v138, v159, v138, v151
	v_max3_u32 v133, v134, v133, v165
	v_max3_u32 v134, v160, v152, v149
	v_max3_u32 v129, v135, v129, v164
	v_max3_u32 v135, v161, v148, v150
	v_max3_u32 v3, v128, v127, v3
	v_max3_u32 v127, v162, v136, v153
	v_max_u32_e32 v128, v130, v140
	v_min_u32_e32 v130, v130, v140
	v_max_u32_e32 v136, v0, v138
	v_min_u32_e32 v0, v0, v138
	v_max_u32_e32 v138, v2, v133
	v_min_u32_e32 v2, v2, v133
	v_max_u32_e32 v133, v1, v134
	v_min_u32_e32 v1, v1, v134
	v_max_u32_e32 v134, v131, v129
	v_min_u32_e32 v129, v131, v129
	v_max_u32_e32 v131, v137, v135
	v_min_u32_e32 v135, v137, v135
	v_max_u32_e32 v137, v132, v3
	v_min_u32_e32 v3, v132, v3
	v_max_u32_e32 v132, v139, v127
	v_min_u32_e32 v127, v139, v127
	v_max_u32_e32 v139, v128, v134
	v_min_u32_e32 v128, v128, v134
	v_max_u32_e32 v134, v136, v131
	v_min_u32_e32 v131, v136, v131
	v_max_u32_e32 v136, v138, v137
	v_min_u32_e32 v137, v138, v137
	v_max_u32_e32 v138, v133, v132
	v_min_u32_e32 v132, v133, v132
	v_max_u32_e32 v133, v130, v129
	v_min_u32_e32 v129, v130, v129
	v_max_u32_e32 v130, v0, v135
	v_min_u32_e32 v0, v0, v135
	v_max_u32_e32 v135, v2, v3
	v_min_u32_e32 v2, v2, v3
	v_max_u32_e32 v3, v1, v127
	v_min_u32_e32 v1, v1, v127
	v_max_u32_e32 v127, v139, v136
	v_min_u32_e32 v136, v139, v136
	v_max_u32_e32 v139, v134, v138
	v_min_u32_e32 v134, v134, v138
	v_max_u32_e32 v138, v128, v137
	v_min_u32_e32 v128, v128, v137
	v_max_u32_e32 v137, v131, v132
	v_min_u32_e32 v131, v131, v132
	v_max_u32_e32 v132, v133, v135
	v_min_u32_e32 v133, v133, v135
	v_max_u32_e32 v135, v130, v3
	v_min_u32_e32 v3, v130, v3
	v_max_u32_e32 v130, v129, v2
	v_min_u32_e32 v2, v129, v2
	v_max_u32_e32 v129, v0, v1
	v_min_u32_e32 v0, v0, v1
	v_max_u32_e32 v1, v127, v139
	v_min_u32_e32 v127, v127, v139
	v_max_u32_e32 v139, v136, v134
	v_min_u32_e32 v134, v136, v134
	v_max_u32_e32 v136, v138, v137
	v_min_u32_e32 v137, v138, v137
	v_max_u32_e32 v138, v128, v131
	v_min_u32_e32 v128, v128, v131
	v_max_u32_e32 v131, v132, v135
	v_min_u32_e32 v132, v132, v135
	v_max_u32_e32 v135, v133, v3
	v_min_u32_e32 v3, v133, v3
	v_max_u32_e32 v133, v130, v129
	v_min_u32_e32 v129, v130, v129
	v_max_u32_e32 v130, v2, v0
	v_min_u32_e32 v0, v2, v0
	ds_bpermute_b32 v2, v27, v1
	ds_bpermute_b32 v140, v27, v127
	ds_bpermute_b32 v141, v27, v139
	ds_bpermute_b32 v142, v27, v134
	ds_bpermute_b32 v143, v27, v136
	ds_bpermute_b32 v144, v27, v137
	ds_bpermute_b32 v145, v27, v138
	ds_bpermute_b32 v146, v27, v128
	ds_bpermute_b32 v147, v27, v131
	ds_bpermute_b32 v148, v27, v132
	ds_bpermute_b32 v149, v27, v135
	ds_bpermute_b32 v150, v27, v0
	ds_bpermute_b32 v151, v27, v130
	ds_bpermute_b32 v152, v27, v129
	ds_bpermute_b32 v153, v27, v133
	ds_bpermute_b32 v154, v27, v3
	s_waitcnt lgkmcnt(4)
; __device__ __forceinline__ void peer_tile(const Args& A, LAS unsigned char* lds, int tile) {
;     ...
;                 for (int msk = 16; msk <= 32; msk <<= 1) {
; #pragma unroll
;                     for (int i = 0; i < 16; ++i) k1[i] = (unsigned)__shfl_xor((int)k0[i], msk);
;                     merge16(k0, k1); }
; #pragma unroll
;                 for (int i = 0; i < 16; ++i) LA[hh][p][i] = k0[i];
	v_max_u32_e32 v1, v1, v150
	s_waitcnt lgkmcnt(3)
	v_max_u32_e32 v127, v127, v151
	s_waitcnt lgkmcnt(2)
	v_max_u32_e32 v139, v139, v152
	s_waitcnt lgkmcnt(1)
	v_max_u32_e32 v134, v134, v153
	s_waitcnt lgkmcnt(0)
	v_max_u32_e32 v136, v136, v154
	v_max_u32_e32 v137, v137, v149
	v_max_u32_e32 v138, v138, v148
	v_max_u32_e32 v128, v128, v147
	v_max_u32_e32 v131, v131, v146
	v_max_u32_e32 v132, v132, v145
	v_max_u32_e32 v135, v135, v144
	v_max_u32_e32 v3, v3, v143
	v_max_u32_e32 v133, v133, v142
	v_max_u32_e32 v129, v129, v141
	v_max_u32_e32 v130, v130, v140
	v_max_u32_e32 v0, v0, v2
	v_max_u32_e32 v2, v1, v131
	v_min_u32_e32 v1, v1, v131
	v_max_u32_e32 v131, v127, v132
	v_min_u32_e32 v127, v127, v132
	v_max_u32_e32 v132, v139, v135
	v_min_u32_e32 v135, v139, v135
	v_max_u32_e32 v139, v134, v3
	v_min_u32_e32 v3, v134, v3
	v_max_u32_e32 v134, v136, v133
	v_min_u32_e32 v133, v136, v133
	v_max_u32_e32 v136, v137, v129
	v_min_u32_e32 v129, v137, v129
	v_max_u32_e32 v137, v138, v130
	v_min_u32_e32 v130, v138, v130
	v_max_u32_e32 v138, v128, v0
	v_min_u32_e32 v0, v128, v0
	v_max_u32_e32 v128, v2, v134
	v_min_u32_e32 v2, v2, v134
	v_max_u32_e32 v134, v131, v136
	v_min_u32_e32 v131, v131, v136
	v_max_u32_e32 v136, v132, v137
	v_min_u32_e32 v132, v132, v137
	v_max_u32_e32 v137, v139, v138
	v_min_u32_e32 v138, v139, v138
	v_max_u32_e32 v139, v1, v133
	v_min_u32_e32 v1, v1, v133
	v_max_u32_e32 v133, v127, v129
	v_min_u32_e32 v127, v127, v129
	v_max_u32_e32 v129, v135, v130
	v_min_u32_e32 v130, v135, v130
	v_max_u32_e32 v135, v3, v0
	v_min_u32_e32 v0, v3, v0
	v_max_u32_e32 v3, v128, v136
	v_min_u32_e32 v128, v128, v136
	v_max_u32_e32 v136, v134, v137
	v_min_u32_e32 v134, v134, v137
	v_max_u32_e32 v137, v2, v132
	v_min_u32_e32 v2, v2, v132
	v_max_u32_e32 v132, v131, v138
	v_min_u32_e32 v131, v131, v138
	v_max_u32_e32 v138, v139, v129
	v_min_u32_e32 v129, v139, v129
	v_max_u32_e32 v139, v133, v135
	v_min_u32_e32 v133, v133, v135
	v_max_u32_e32 v135, v1, v130
	v_min_u32_e32 v1, v1, v130
	v_max_u32_e32 v130, v127, v0
	v_min_u32_e32 v0, v127, v0
	v_max_u32_e32 v127, v3, v136
	v_min_u32_e32 v3, v3, v136
	v_max_u32_e32 v136, v128, v134
	v_min_u32_e32 v128, v128, v134
	v_max_u32_e32 v134, v137, v132
	v_min_u32_e32 v132, v137, v132
	v_max_u32_e32 v137, v2, v131
	v_min_u32_e32 v2, v2, v131
	v_max_u32_e32 v131, v138, v139
	v_min_u32_e32 v138, v138, v139
	v_max_u32_e32 v139, v129, v133
	v_min_u32_e32 v129, v129, v133
	v_max_u32_e32 v133, v135, v130
	v_min_u32_e32 v130, v135, v130
	v_max_u32_e32 v135, v1, v0
	v_min_u32_e32 v0, v1, v0
	ds_bpermute_b32 v144, v29, v0
	ds_bpermute_b32 v1, v29, v127
	ds_bpermute_b32 v140, v29, v3
	ds_bpermute_b32 v141, v29, v136
	ds_bpermute_b32 v142, v29, v128
	s_waitcnt lgkmcnt(4)
	v_max_u32_e32 v127, v127, v144
	global_load_dwordx4 v[144:147], v[4:5], off offset:1808
	global_load_dwordx4 v[148:151], v[4:5], off offset:1792
	ds_bpermute_b32 v143, v29, v134
	ds_bpermute_b32 v152, v29, v132
	ds_bpermute_b32 v153, v29, v137
	ds_bpermute_b32 v154, v29, v2
	ds_bpermute_b32 v155, v29, v131
	ds_bpermute_b32 v156, v29, v138
	ds_bpermute_b32 v157, v29, v139
	ds_bpermute_b32 v158, v29, v129
	ds_bpermute_b32 v159, v29, v133
	ds_bpermute_b32 v160, v29, v135
	ds_bpermute_b32 v161, v29, v130
	s_waitcnt lgkmcnt(4)
	v_max_u32_e32 v132, v132, v157
	s_waitcnt lgkmcnt(3)
	v_max_u32_e32 v134, v134, v158
	s_waitcnt lgkmcnt(2)
	v_max_u32_e32 v128, v128, v159
	s_waitcnt lgkmcnt(1)
	v_max_u32_e32 v3, v3, v160
	s_waitcnt lgkmcnt(0)
	v_max_u32_e32 v136, v136, v161
	v_max_u32_e32 v137, v137, v156
	v_max_u32_e32 v2, v2, v155
	v_max_u32_e32 v131, v131, v154
	v_max_u32_e32 v138, v138, v153
	v_max_u32_e32 v139, v139, v152
	v_max_u32_e32 v129, v129, v143
	v_max_u32_e32 v133, v133, v142
	v_max_u32_e32 v130, v130, v141
	v_max_u32_e32 v135, v135, v140
	v_max_u32_e32 v0, v0, v1
	v_max_u32_e32 v1, v127, v131
	v_min_u32_e32 v127, v127, v131
	v_max_u32_e32 v131, v3, v138
	v_min_u32_e32 v3, v3, v138
	v_max_u32_e32 v138, v136, v139
	v_min_u32_e32 v136, v136, v139
	v_max_u32_e32 v139, v128, v129
	v_min_u32_e32 v128, v128, v129
	v_max_u32_e32 v129, v134, v133
	v_min_u32_e32 v133, v134, v133
	v_max_u32_e32 v134, v132, v130
	v_min_u32_e32 v130, v132, v130
	v_max_u32_e32 v132, v137, v135
	v_min_u32_e32 v135, v137, v135
	v_max_u32_e32 v137, v2, v0
	v_min_u32_e32 v0, v2, v0
	v_max_u32_e32 v2, v1, v129
	v_min_u32_e32 v1, v1, v129
	v_max_u32_e32 v129, v131, v134
	v_min_u32_e32 v131, v131, v134
	v_max_u32_e32 v134, v138, v132
	v_min_u32_e32 v132, v138, v132
	v_max_u32_e32 v138, v139, v137
	v_min_u32_e32 v137, v139, v137
	v_max_u32_e32 v139, v127, v133
	v_min_u32_e32 v127, v127, v133
	v_max_u32_e32 v133, v3, v130
	v_min_u32_e32 v3, v3, v130
	v_max_u32_e32 v130, v136, v135
	v_min_u32_e32 v135, v136, v135
	v_max_u32_e32 v136, v128, v0
	v_min_u32_e32 v0, v128, v0
	v_max_u32_e32 v128, v2, v134
	v_min_u32_e32 v2, v2, v134
	v_max_u32_e32 v134, v129, v138
	v_min_u32_e32 v129, v129, v138
	v_max_u32_e32 v143, v1, v132
	v_min_u32_e32 v1, v1, v132
	v_max_u32_e32 v132, v131, v137
	v_min_u32_e32 v131, v131, v137
	v_max_u32_e32 v152, v139, v130
	v_min_u32_e32 v130, v139, v130
	v_max_u32_e32 v153, v133, v136
	v_min_u32_e32 v154, v133, v136
	v_max_u32_e32 v155, v127, v135
	v_min_u32_e32 v127, v127, v135
	v_max_u32_e32 v156, v3, v0
	v_min_u32_e32 v0, v3, v0
	v_max_u32_e32 v142, v128, v134
	v_min_u32_e32 v141, v128, v134
	v_max_u32_e32 v140, v2, v129
	v_min_u32_e32 v139, v2, v129
	v_max_u32_e32 v138, v143, v132
	v_min_u32_e32 v137, v143, v132
	v_max_u32_e32 v136, v1, v131
	v_min_u32_e32 v135, v1, v131
	v_max_u32_e32 v134, v152, v153
	v_min_u32_e32 v133, v152, v153
	v_max_u32_e32 v132, v130, v154
	v_min_u32_e32 v131, v130, v154
	v_max_u32_e32 v130, v155, v156
	v_min_u32_e32 v129, v155, v156
	v_max_u32_e32 v128, v127, v0
	v_min_u32_e32 v127, v127, v0
	global_load_dwordx4 v[0:3], v[4:5], off offset:1840
	global_load_dwordx4 v[152:155], v[4:5], off offset:1824
	s_waitcnt vmcnt(2)
; __device__ __forceinline__ unsigned f2key(float f) { const unsigned u = __float_as_uint(f); return (u & 0x80000000u) ? ~u : (u | 0x80000000u); }
; __device__ __forceinline__ void peer_tile(const Args& A, LAS unsigned char* lds, int tile) {
;     ...
;                 { const bf16_t* sp = QRY + m * 2048 + hp * 128 + 32 * g;
;                   const u32x4 s0 = *(const u32x4*)sp, s1 = *(const u32x4*)(sp + 8), s2 = *(const u32x4*)(sp + 16), s3 = *(const u32x4*)(sp + 24);
;                   const unsigned sw[16] = {s0.x, s0.y, s0.z, s0.w, s1.x, s1.y, s1.z, s1.w, s2.x, s2.y, s2.z, s2.w, s3.x, s3.y, s3.z, s3.w};
; #pragma unroll
;                   for (int i = 0; i < 16; ++i) {
;                       const float lo = (float)__builtin_bit_cast(_Float16, (unsigned short)(sw[i] & 0xffffu)), hi = (float)__builtin_bit_cast(_Float16, (unsigned short)(sw[i] >> 16));
;                       const unsigned klo = (f2key(lo) & ~127u) | (unsigned)(127 - (32 * g + 2 * i)), khi = (f2key(hi) & ~127u) | (unsigned)(127 - (32 * g + 2 * i + 1));
;                       if (i < 8) { k0[2 * i] = klo; k0[2 * i + 1] = khi; } else { k1[2 * (i - 8)] = klo; k1[2 * (i - 8) + 1] = khi; } } }
	v_cvt_f32_f16_sdwa v143, v148 dst_sel:DWORD dst_unused:UNUSED_PAD src0_sel:WORD_1
	v_cvt_f32_f16_e32 v4, v148
	v_not_b32_e32 v5, v143
	v_or_b32_e32 v148, 0x80000000, v143
	v_cmp_gt_i32_e32 vcc, 0, v143
	v_not_b32_e32 v143, v4
	s_nop 0
	v_cndmask_b32_e32 v5, v148, v5, vcc
	v_or_b32_e32 v148, 0x80000000, v4
	v_cmp_gt_i32_e32 vcc, 0, v4
	v_and_b32_e32 v5, 0xffffff80, v5
	v_sub_u32_e32 v5, v5, v15
	v_cndmask_b32_e32 v4, v148, v143, vcc
	v_and_b32_e32 v4, 0xffffff80, v4
	v_cvt_f32_f16_sdwa v143, v149 dst_sel:DWORD dst_unused:UNUSED_PAD src0_sel:WORD_1
	v_sub_u32_e32 v4, v4, v15
	v_cvt_f32_f16_e32 v15, v149
	v_add_u32_e32 v5, 0x7e, v5
	v_not_b32_e32 v148, v143
	v_or_b32_e32 v149, 0x80000000, v143
	v_cmp_gt_i32_e32 vcc, 0, v143
	v_add_u32_e32 v4, 0x7f, v4
	s_nop 0
	v_cndmask_b32_e32 v143, v149, v148, vcc
	v_not_b32_e32 v148, v15
	v_or_b32_e32 v149, 0x80000000, v15
	v_cmp_gt_i32_e32 vcc, 0, v15
	v_and_b32_e32 v143, 0xffffff80, v143
	v_sub_u32_e32 v143, v143, v14
	v_cndmask_b32_e32 v15, v149, v148, vcc
	v_and_b32_e32 v15, 0xffffff80, v15
	v_cvt_f32_f16_sdwa v148, v150 dst_sel:DWORD dst_unused:UNUSED_PAD src0_sel:WORD_1
	v_sub_u32_e32 v14, v15, v14
	v_cvt_f32_f16_e32 v15, v150
	v_add_u32_e32 v143, 0x7e, v143
	v_not_b32_e32 v149, v148
	v_or_b32_e32 v150, 0x80000000, v148
	v_cmp_gt_i32_e32 vcc, 0, v148
	v_add_u32_e32 v14, 0x7f, v14
	s_nop 0
	v_cndmask_b32_e32 v148, v150, v149, vcc
	v_not_b32_e32 v149, v15
	v_or_b32_e32 v150, 0x80000000, v15
	v_cmp_gt_i32_e32 vcc, 0, v15
	v_and_b32_e32 v148, 0xffffff80, v148
	v_sub_u32_e32 v148, v148, v12
	v_cndmask_b32_e32 v15, v150, v149, vcc
	v_and_b32_e32 v15, 0xffffff80, v15
	v_cvt_f32_f16_sdwa v149, v151 dst_sel:DWORD dst_unused:UNUSED_PAD src0_sel:WORD_1
	v_sub_u32_e32 v12, v15, v12
	v_cvt_f32_f16_e32 v15, v151
	v_add_u32_e32 v148, 0x7e, v148
	v_not_b32_e32 v150, v149
	v_or_b32_e32 v151, 0x80000000, v149
	v_cmp_gt_i32_e32 vcc, 0, v149
	v_add_u32_e32 v12, 0x7f, v12
	s_nop 0
	v_cndmask_b32_e32 v149, v151, v150, vcc
	v_not_b32_e32 v150, v15
	v_or_b32_e32 v151, 0x80000000, v15
	v_cmp_gt_i32_e32 vcc, 0, v15
	v_and_b32_e32 v149, 0xffffff80, v149
	v_sub_u32_e32 v149, v149, v10
	v_cndmask_b32_e32 v15, v151, v150, vcc
	v_and_b32_e32 v15, 0xffffff80, v15
	v_cvt_f32_f16_sdwa v150, v144 dst_sel:DWORD dst_unused:UNUSED_PAD src0_sel:WORD_1
	v_sub_u32_e32 v10, v15, v10
	v_cvt_f32_f16_e32 v15, v144
	v_add_u32_e32 v149, 0x7e, v149
	v_not_b32_e32 v144, v150
	v_or_b32_e32 v151, 0x80000000, v150
	v_cmp_gt_i32_e32 vcc, 0, v150
	v_not_b32_e32 v150, v15
	v_add_u32_e32 v10, 0x7f, v10
	v_cndmask_b32_e32 v144, v151, v144, vcc
	v_or_b32_e32 v151, 0x80000000, v15
	v_cmp_gt_i32_e32 vcc, 0, v15
	v_and_b32_e32 v144, 0xffffff80, v144
	v_sub_u32_e32 v144, v144, v8
	v_cndmask_b32_e32 v15, v151, v150, vcc
	v_and_b32_e32 v15, 0xffffff80, v15
	v_cvt_f32_f16_sdwa v150, v145 dst_sel:DWORD dst_unused:UNUSED_PAD src0_sel:WORD_1
	v_sub_u32_e32 v8, v15, v8
	v_cvt_f32_f16_e32 v15, v145
	v_add_u32_e32 v144, 0x7e, v144
	v_not_b32_e32 v145, v150
	v_or_b32_e32 v151, 0x80000000, v150
	v_cmp_gt_i32_e32 vcc, 0, v150
	v_not_b32_e32 v150, v15
	v_add_u32_e32 v8, 0x7f, v8
	v_cndmask_b32_e32 v145, v151, v145, vcc
	v_or_b32_e32 v151, 0x80000000, v15
	v_cmp_gt_i32_e32 vcc, 0, v15
	v_and_b32_e32 v145, 0xffffff80, v145
	v_sub_u32_e32 v145, v145, v16
	v_cndmask_b32_e32 v15, v151, v150, vcc
	v_and_b32_e32 v15, 0xffffff80, v15
	v_cvt_f32_f16_sdwa v150, v146 dst_sel:DWORD dst_unused:UNUSED_PAD src0_sel:WORD_1
	v_sub_u32_e32 v15, v15, v16
	v_cvt_f32_f16_e32 v16, v146
	v_add_u32_e32 v145, 0x7e, v145
	v_not_b32_e32 v146, v150
	v_or_b32_e32 v151, 0x80000000, v150
	v_cmp_gt_i32_e32 vcc, 0, v150
	v_not_b32_e32 v150, v16
	v_add_u32_e32 v15, 0x7f, v15
	v_cndmask_b32_e32 v146, v151, v146, vcc
	v_or_b32_e32 v151, 0x80000000, v16
	v_cmp_gt_i32_e32 vcc, 0, v16
	v_and_b32_e32 v146, 0xffffff80, v146
	v_sub_u32_e32 v146, v146, v17
	v_cndmask_b32_e32 v16, v151, v150, vcc
	v_and_b32_e32 v16, 0xffffff80, v16
	v_cvt_f32_f16_sdwa v150, v147 dst_sel:DWORD dst_unused:UNUSED_PAD src0_sel:WORD_1
	v_sub_u32_e32 v16, v16, v17
	v_cvt_f32_f16_e32 v17, v147
	v_add_u32_e32 v146, 0x7e, v146
	v_not_b32_e32 v147, v150
	v_or_b32_e32 v151, 0x80000000, v150
	v_cmp_gt_i32_e32 vcc, 0, v150
	v_not_b32_e32 v150, v17
	v_add_u32_e32 v16, 0x7f, v16
	v_cndmask_b32_e32 v147, v151, v147, vcc
	v_or_b32_e32 v151, 0x80000000, v17
	v_cmp_gt_i32_e32 vcc, 0, v17
	v_and_b32_e32 v147, 0xffffff80, v147
	v_sub_u32_e32 v147, v147, v18
	v_cndmask_b32_e32 v17, v151, v150, vcc
	v_and_b32_e32 v17, 0xffffff80, v17
	s_waitcnt vmcnt(0)
; __device__ __forceinline__ unsigned f2key(float f) { const unsigned u = __float_as_uint(f); return (u & 0x80000000u) ? ~u : (u | 0x80000000u); }
; #define CE_DESC(a, b) do { const unsigned _mx = (a) > (b) ? (a) : (b), _mn = (a) > (b) ? (b) : (a); (a) = _mx; (b) = _mn; } while (0)
; __device__ __forceinline__ void sort16_desc(unsigned (&k)[16]) {
; #pragma unroll
;     for (int size = 2; size <= 16; size <<= 1)
; #pragma unroll
;         for (int stride = size >> 1; stride > 0; stride >>= 1)
; #pragma unroll
;             for (int i = 0; i < 16; ++i) { const int j = i ^ stride;
;                 if (j > i) { if ((i & size) == 0) CE_DESC(k[i], k[j]); else CE_DESC(k[j], k[i]); } }
; __device__ __forceinline__ void peer_tile(const Args& A, LAS unsigned char* lds, int tile) {
;     ...
;                   for (int i = 0; i < 16; ++i) {
;                       const float lo = (float)__builtin_bit_cast(_Float16, (unsigned short)(sw[i] & 0xffffu)), hi = (float)__builtin_bit_cast(_Float16, (unsigned short)(sw[i] >> 16));
;                       const unsigned klo = (f2key(lo) & ~127u) | (unsigned)(127 - (32 * g + 2 * i)), khi = (f2key(hi) & ~127u) | (unsigned)(127 - (32 * g + 2 * i + 1));
;                       if (i < 8) { k0[2 * i] = klo; k0[2 * i + 1] = khi; } else { k1[2 * (i - 8)] = klo; k1[2 * (i - 8) + 1] = khi; } } }
;                 sort16_desc(k0); sort16_desc(k1); merge16(k0, k1);
	v_cvt_f32_f16_sdwa v150, v152 dst_sel:DWORD dst_unused:UNUSED_PAD src0_sel:WORD_1
	v_sub_u32_e32 v17, v17, v18
	v_cvt_f32_f16_e32 v18, v152
	v_add_u32_e32 v147, 0x7e, v147
	v_not_b32_e32 v151, v150
	v_or_b32_e32 v152, 0x80000000, v150
	v_cmp_gt_i32_e32 vcc, 0, v150
	v_add_u32_e32 v17, 0x7f, v17
	s_nop 0
	v_cndmask_b32_e32 v150, v152, v151, vcc
	v_not_b32_e32 v151, v18
	v_or_b32_e32 v152, 0x80000000, v18
	v_cmp_gt_i32_e32 vcc, 0, v18
	v_and_b32_e32 v150, 0xffffff80, v150
	v_sub_u32_e32 v150, v150, v20
	v_cndmask_b32_e32 v18, v152, v151, vcc
	v_and_b32_e32 v18, 0xffffff80, v18
	v_cvt_f32_f16_sdwa v151, v153 dst_sel:DWORD dst_unused:UNUSED_PAD src0_sel:WORD_1
	v_sub_u32_e32 v18, v18, v20
	v_cvt_f32_f16_e32 v20, v153
	v_add_u32_e32 v150, 0x7e, v150
	v_not_b32_e32 v152, v151
	v_or_b32_e32 v153, 0x80000000, v151
	v_cmp_gt_i32_e32 vcc, 0, v151
	v_add_u32_e32 v18, 0x7f, v18
	v_max_u32_e32 v161, v18, v150
	v_cndmask_b32_e32 v151, v153, v152, vcc
	v_not_b32_e32 v152, v20
	v_or_b32_e32 v153, 0x80000000, v20
	v_cmp_gt_i32_e32 vcc, 0, v20
	v_and_b32_e32 v151, 0xffffff80, v151
	v_sub_u32_e32 v151, v151, v21
	v_cndmask_b32_e32 v20, v153, v152, vcc
	v_and_b32_e32 v20, 0xffffff80, v20
	v_cvt_f32_f16_sdwa v152, v154 dst_sel:DWORD dst_unused:UNUSED_PAD src0_sel:WORD_1
	v_sub_u32_e32 v20, v20, v21
	v_cvt_f32_f16_e32 v21, v154
	v_add_u32_e32 v151, 0x7e, v151
	v_not_b32_e32 v153, v152
	v_or_b32_e32 v154, 0x80000000, v152
	v_cmp_gt_i32_e32 vcc, 0, v152
	v_add_u32_e32 v20, 0x7f, v20
	v_min_u32_e32 v18, v18, v150
	v_cndmask_b32_e32 v152, v154, v153, vcc
	v_not_b32_e32 v153, v21
	v_or_b32_e32 v154, 0x80000000, v21
	v_cmp_gt_i32_e32 vcc, 0, v21
	v_and_b32_e32 v152, 0xffffff80, v152
	v_sub_u32_e32 v152, v152, v22
	v_cndmask_b32_e32 v21, v154, v153, vcc
	v_and_b32_e32 v21, 0xffffff80, v21
	v_cvt_f32_f16_sdwa v153, v155 dst_sel:DWORD dst_unused:UNUSED_PAD src0_sel:WORD_1
	v_sub_u32_e32 v21, v21, v22
	v_cvt_f32_f16_e32 v22, v155
	v_add_u32_e32 v152, 0x7e, v152
	v_not_b32_e32 v154, v153
	v_or_b32_e32 v155, 0x80000000, v153
	v_cmp_gt_i32_e32 vcc, 0, v153
	v_add_u32_e32 v21, 0x7f, v21
	v_max_u32_e32 v150, v151, v20
	v_cndmask_b32_e32 v153, v155, v154, vcc
	v_not_b32_e32 v154, v22
	v_or_b32_e32 v155, 0x80000000, v22
	v_cmp_gt_i32_e32 vcc, 0, v22
	v_and_b32_e32 v153, 0xffffff80, v153
	v_sub_u32_e32 v153, v153, v23
	v_cndmask_b32_e32 v22, v155, v154, vcc
	v_cvt_f32_f16_sdwa v154, v0 dst_sel:DWORD dst_unused:UNUSED_PAD src0_sel:WORD_1
	v_cvt_f32_f16_e32 v0, v0
	v_and_b32_e32 v22, 0xffffff80, v22
	v_sub_u32_e32 v22, v22, v23
	v_not_b32_e32 v23, v154
	v_or_b32_e32 v155, 0x80000000, v154
	v_cmp_gt_i32_e32 vcc, 0, v154
	v_not_b32_e32 v154, v0
	v_add_u32_e32 v153, 0x7e, v153
	v_cndmask_b32_e32 v23, v155, v23, vcc
	v_or_b32_e32 v155, 0x80000000, v0
	v_cmp_gt_i32_e32 vcc, 0, v0
	v_and_b32_e32 v23, 0xffffff80, v23
	v_sub_u32_e32 v23, v23, v24
	v_cndmask_b32_e32 v0, v155, v154, vcc
	v_cvt_f32_f16_sdwa v154, v1 dst_sel:DWORD dst_unused:UNUSED_PAD src0_sel:WORD_1
	v_cvt_f32_f16_e32 v1, v1
	v_and_b32_e32 v0, 0xffffff80, v0
	v_sub_u32_e32 v0, v0, v24
	v_not_b32_e32 v24, v154
	v_or_b32_e32 v155, 0x80000000, v154
	v_cmp_gt_i32_e32 vcc, 0, v154
	v_not_b32_e32 v154, v1
	v_add_u32_e32 v22, 0x7f, v22
	v_cndmask_b32_e32 v24, v155, v24, vcc
	v_or_b32_e32 v155, 0x80000000, v1
	v_cmp_gt_i32_e32 vcc, 0, v1
	v_and_b32_e32 v24, 0xffffff80, v24
	v_sub_u32_e32 v24, v24, v25
	v_cndmask_b32_e32 v1, v155, v154, vcc
	v_cvt_f32_f16_sdwa v154, v2 dst_sel:DWORD dst_unused:UNUSED_PAD src0_sel:WORD_1
	v_cvt_f32_f16_e32 v2, v2
	v_and_b32_e32 v1, 0xffffff80, v1
	v_sub_u32_e32 v1, v1, v25
	v_not_b32_e32 v25, v154
	v_or_b32_e32 v155, 0x80000000, v154
	v_cmp_gt_i32_e32 vcc, 0, v154
	v_not_b32_e32 v154, v2
	v_add_u32_e32 v23, 0x7e, v23
	v_cndmask_b32_e32 v25, v155, v25, vcc
	v_or_b32_e32 v155, 0x80000000, v2
	v_cmp_gt_i32_e32 vcc, 0, v2
	v_and_b32_e32 v25, 0xffffff80, v25
	v_sub_u32_e32 v25, v25, v26
	v_cndmask_b32_e32 v2, v155, v154, vcc
	v_cvt_f32_f16_sdwa v154, v3 dst_sel:DWORD dst_unused:UNUSED_PAD src0_sel:WORD_1
	v_cvt_f32_f16_e32 v3, v3
	v_and_b32_e32 v2, 0xffffff80, v2
	v_sub_u32_e32 v2, v2, v26
	v_not_b32_e32 v26, v154
	v_or_b32_e32 v155, 0x80000000, v154
	v_cmp_gt_i32_e32 vcc, 0, v154
	v_not_b32_e32 v154, v3
	v_add_u32_e32 v0, 0x7f, v0
	v_cndmask_b32_e32 v26, v155, v26, vcc
	v_or_b32_e32 v155, 0x80000000, v3
	v_cmp_gt_i32_e32 vcc, 0, v3
	v_and_b32_e32 v26, 0xffffff80, v26
	v_sub_u32_e32 v26, v26, v28
	v_cndmask_b32_e32 v3, v155, v154, vcc
	v_and_b32_e32 v3, 0xffffff80, v3
	v_sub_u32_e32 v3, v3, v28
	v_add_u32_e32 v24, 0x7e, v24
	v_add_u32_e32 v1, 0x7f, v1
	v_add_u32_e32 v25, 0x7e, v25
	v_add_u32_e32 v2, 0x7f, v2
	v_add_u32_e32 v26, 0x7e, v26
	v_add_u32_e32 v3, 0x7f, v3
	v_max_u32_e32 v28, v4, v5
	v_min_u32_e32 v4, v4, v5
	v_max_u32_e32 v5, v143, v14
	v_min_u32_e32 v14, v143, v14
	v_max_u32_e32 v143, v12, v148
	v_min_u32_e32 v12, v12, v148
	v_max_u32_e32 v148, v149, v10
	v_min_u32_e32 v10, v149, v10
	v_max_u32_e32 v149, v8, v144
	v_min_u32_e32 v8, v8, v144
	v_max_u32_e32 v144, v145, v15
	v_min_u32_e32 v15, v145, v15
	v_max_u32_e32 v145, v16, v146
	v_min_u32_e32 v16, v16, v146
	v_max_u32_e32 v146, v147, v17
	v_min_u32_e32 v17, v147, v17
	v_min_u32_e32 v20, v151, v20
	v_max_u32_e32 v151, v21, v152
	v_min_u32_e32 v21, v21, v152
	v_max_u32_e32 v152, v153, v22
	v_min_u32_e32 v22, v153, v22
	v_max_u32_e32 v153, v0, v23
	v_min_u32_e32 v0, v0, v23
	v_max_u32_e32 v23, v24, v1
	v_min_u32_e32 v1, v24, v1
	v_max_u32_e32 v24, v2, v25
	v_min_u32_e32 v2, v2, v25
	v_max_u32_e32 v25, v26, v3
	v_min_u32_e32 v3, v26, v3
	v_max_u32_e32 v147, v28, v14
	v_min_u32_e32 v14, v28, v14
	v_max_u32_e32 v28, v4, v5
	v_min_u32_e32 v4, v4, v5
; #define CE_DESC(a, b) do { const unsigned _mx = (a) > (b) ? (a) : (b), _mn = (a) > (b) ? (b) : (a); (a) = _mx; (b) = _mn; } while (0)
; __device__ __forceinline__ void sort16_desc(unsigned (&k)[16]) {
; #pragma unroll
;     for (int size = 2; size <= 16; size <<= 1)
; #pragma unroll
;         for (int stride = size >> 1; stride > 0; stride >>= 1)
; #pragma unroll
;             for (int i = 0; i < 16; ++i) { const int j = i ^ stride;
;                 if (j > i) { if ((i & size) == 0) CE_DESC(k[i], k[j]); else CE_DESC(k[j], k[i]); } }
	v_max_u32_e32 v5, v10, v143
	v_min_u32_e32 v10, v10, v143
	v_max_u32_e32 v143, v148, v12
	v_min_u32_e32 v12, v148, v12
	v_max_u32_e32 v148, v149, v15
	v_min_u32_e32 v15, v149, v15
	v_max_u32_e32 v149, v8, v144
	v_min_u32_e32 v8, v8, v144
	v_max_u32_e32 v144, v17, v145
	v_min_u32_e32 v17, v17, v145
	v_max_u32_e32 v145, v146, v16
	v_min_u32_e32 v16, v146, v16
	v_max_u32_e32 v26, v161, v20
	v_min_u32_e32 v20, v161, v20
	v_max_u32_e32 v161, v18, v150
	v_min_u32_e32 v18, v18, v150
	v_max_u32_e32 v150, v22, v151
	v_min_u32_e32 v22, v22, v151
	v_max_u32_e32 v151, v152, v21
	v_min_u32_e32 v21, v152, v21
	v_max_u32_e32 v152, v153, v1
	v_min_u32_e32 v1, v153, v1
	v_max_u32_e32 v153, v0, v23
	v_min_u32_e32 v0, v0, v23
	v_max_u32_e32 v23, v3, v24
	v_min_u32_e32 v3, v3, v24
	v_max_u32_e32 v24, v25, v2
	v_min_u32_e32 v2, v25, v2
	v_max_u32_e32 v146, v147, v28
	v_min_u32_e32 v28, v147, v28
	v_max_u32_e32 v147, v14, v4
	v_min_u32_e32 v4, v14, v4
	v_max_u32_e32 v14, v12, v10
	v_min_u32_e32 v10, v12, v10
	v_max_u32_e32 v12, v143, v5
	v_min_u32_e32 v5, v143, v5
	v_max_u32_e32 v143, v148, v149
	v_min_u32_e32 v148, v148, v149
	v_max_u32_e32 v149, v15, v8
	v_min_u32_e32 v8, v15, v8
	v_max_u32_e32 v15, v16, v17
	v_min_u32_e32 v16, v16, v17
	v_max_u32_e32 v17, v145, v144
	v_min_u32_e32 v144, v145, v144
	v_max_u32_e32 v25, v26, v161
	v_min_u32_e32 v26, v26, v161
	v_max_u32_e32 v161, v20, v18
	v_min_u32_e32 v18, v20, v18
	v_max_u32_e32 v20, v21, v22
	v_min_u32_e32 v21, v21, v22
	v_max_u32_e32 v22, v151, v150
	v_min_u32_e32 v150, v151, v150
	v_max_u32_e32 v151, v152, v153
	v_min_u32_e32 v152, v152, v153
	v_max_u32_e32 v153, v1, v0
	v_min_u32_e32 v0, v1, v0
	v_max_u32_e32 v1, v2, v3
	v_min_u32_e32 v2, v2, v3
	v_max_u32_e32 v3, v24, v23
	v_min_u32_e32 v23, v24, v23
	v_max_u32_e32 v145, v146, v10
	v_min_u32_e32 v10, v146, v10
	v_max_u32_e32 v146, v28, v14
	v_min_u32_e32 v14, v28, v14
	v_max_u32_e32 v28, v147, v5
	v_min_u32_e32 v5, v147, v5
	v_max_u32_e32 v147, v4, v12
	v_min_u32_e32 v4, v4, v12
	v_max_u32_e32 v12, v16, v143
	v_min_u32_e32 v16, v16, v143
	v_max_u32_e32 v143, v15, v148
	v_min_u32_e32 v15, v15, v148
	v_max_u32_e32 v148, v144, v149
	v_min_u32_e32 v144, v144, v149
	v_max_u32_e32 v149, v17, v8
	v_min_u32_e32 v8, v17, v8
	v_max_u32_e32 v24, v25, v21
	v_min_u32_e32 v21, v25, v21
	v_max_u32_e32 v25, v26, v20
	v_min_u32_e32 v20, v26, v20
	v_max_u32_e32 v26, v161, v150
	v_min_u32_e32 v150, v161, v150
	v_max_u32_e32 v161, v18, v22
	v_min_u32_e32 v18, v18, v22
	v_max_u32_e32 v22, v2, v151
	v_min_u32_e32 v2, v2, v151
	v_max_u32_e32 v151, v1, v152
	v_min_u32_e32 v1, v1, v152
	v_max_u32_e32 v152, v23, v153
	v_min_u32_e32 v23, v23, v153
	v_max_u32_e32 v153, v3, v0
	v_min_u32_e32 v0, v3, v0
	v_max_u32_e32 v17, v145, v28
	v_min_u32_e32 v28, v145, v28
	v_max_u32_e32 v145, v146, v147
	v_min_u32_e32 v146, v146, v147
	v_max_u32_e32 v147, v10, v5
	v_min_u32_e32 v5, v10, v5
	v_max_u32_e32 v10, v14, v4
	v_min_u32_e32 v4, v14, v4
	v_max_u32_e32 v14, v144, v16
	v_min_u32_e32 v16, v144, v16
	v_max_u32_e32 v144, v8, v15
	v_min_u32_e32 v8, v8, v15
	v_max_u32_e32 v15, v148, v12
	v_min_u32_e32 v12, v148, v12
	v_max_u32_e32 v148, v149, v143
	v_min_u32_e32 v143, v149, v143
	v_max_u32_e32 v3, v24, v26
	v_min_u32_e32 v24, v24, v26
	v_max_u32_e32 v26, v25, v161
	v_min_u32_e32 v25, v25, v161
	v_max_u32_e32 v161, v21, v150
	v_min_u32_e32 v21, v21, v150
	v_max_u32_e32 v150, v20, v18
	v_min_u32_e32 v18, v20, v18
	v_max_u32_e32 v20, v23, v2
	v_min_u32_e32 v2, v23, v2
	v_max_u32_e32 v23, v0, v1
	v_min_u32_e32 v0, v0, v1
	v_max_u32_e32 v1, v152, v22
	v_min_u32_e32 v22, v152, v22
	v_max_u32_e32 v152, v153, v151
	v_min_u32_e32 v151, v153, v151
	v_max_u32_e32 v149, v17, v145
	v_min_u32_e32 v17, v17, v145
	v_max_u32_e32 v145, v28, v146
	v_min_u32_e32 v28, v28, v146
	v_max_u32_e32 v146, v147, v10
	v_min_u32_e32 v10, v147, v10
	v_max_u32_e32 v147, v5, v4
	v_min_u32_e32 v4, v5, v4
	v_max_u32_e32 v5, v8, v16
	v_min_u32_e32 v8, v8, v16
	v_max_u32_e32 v16, v144, v14
	v_min_u32_e32 v14, v144, v14
	v_max_u32_e32 v144, v143, v12
	v_min_u32_e32 v12, v143, v12
	v_max_u32_e32 v143, v148, v15
	v_min_u32_e32 v15, v148, v15
	v_max_u32_e32 v153, v3, v26
	v_min_u32_e32 v3, v3, v26
	v_max_u32_e32 v26, v24, v25
	v_min_u32_e32 v24, v24, v25
	v_max_u32_e32 v25, v161, v150
	v_min_u32_e32 v150, v161, v150
	v_max_u32_e32 v161, v21, v18
	v_min_u32_e32 v18, v21, v18
	v_max_u32_e32 v21, v0, v2
	v_min_u32_e32 v0, v0, v2
	v_max_u32_e32 v2, v23, v20
	v_min_u32_e32 v20, v23, v20
	v_max_u32_e32 v23, v151, v22
	v_min_u32_e32 v22, v151, v22
	v_max_u32_e32 v151, v152, v1
	v_min_u32_e32 v1, v152, v1
	v_max_u32_e32 v148, v149, v8
	v_min_u32_e32 v8, v149, v8
	v_max_u32_e32 v149, v17, v5
	v_min_u32_e32 v5, v17, v5
	v_max_u32_e32 v17, v145, v14
	v_min_u32_e32 v14, v145, v14
	v_max_u32_e32 v145, v28, v16
	v_min_u32_e32 v16, v28, v16
	v_max_u32_e32 v28, v146, v12
	v_min_u32_e32 v12, v146, v12
	v_max_u32_e32 v146, v10, v144
	v_min_u32_e32 v10, v10, v144
	v_max_u32_e32 v144, v147, v15
	v_min_u32_e32 v15, v147, v15
	v_max_u32_e32 v147, v4, v143
	v_min_u32_e32 v4, v4, v143
	v_max_u32_e32 v152, v153, v0
	v_min_u32_e32 v0, v153, v0
	v_max_u32_e32 v153, v3, v21
	v_min_u32_e32 v3, v3, v21
	v_max_u32_e32 v21, v26, v20
	v_min_u32_e32 v20, v26, v20
	v_max_u32_e32 v26, v24, v2
	v_min_u32_e32 v2, v24, v2
	v_max_u32_e32 v24, v25, v22
	v_min_u32_e32 v22, v25, v22
	v_max_u32_e32 v25, v150, v23
	v_min_u32_e32 v23, v150, v23
	v_max_u32_e32 v150, v161, v1
	v_min_u32_e32 v1, v161, v1
	v_max_u32_e32 v161, v18, v151
	v_min_u32_e32 v18, v18, v151
	v_max_u32_e32 v143, v148, v28
	v_min_u32_e32 v28, v148, v28
	v_max_u32_e32 v148, v149, v146
	v_min_u32_e32 v146, v149, v146
; #define CE_DESC(a, b) do { const unsigned _mx = (a) > (b) ? (a) : (b), _mn = (a) > (b) ? (b) : (a); (a) = _mx; (b) = _mn; } while (0)
; __device__ __forceinline__ void sort16_desc(unsigned (&k)[16]) {
; #pragma unroll
;     for (int size = 2; size <= 16; size <<= 1)
; #pragma unroll
;         for (int stride = size >> 1; stride > 0; stride >>= 1)
; #pragma unroll
;             for (int i = 0; i < 16; ++i) { const int j = i ^ stride;
;                 if (j > i) { if ((i & size) == 0) CE_DESC(k[i], k[j]); else CE_DESC(k[j], k[i]); } }
; }
; __device__ __forceinline__ void merge16(unsigned (&a)[16], const unsigned (&b)[16]) {
; #pragma unroll
;     for (int i = 0; i < 16; ++i) a[i] = a[i] > b[15 - i] ? a[i] : b[15 - i];
; #pragma unroll
;     for (int stride = 8; stride > 0; stride >>= 1)
; #pragma unroll
;         for (int i = 0; i < 16; ++i) { const int j = i ^ stride; if (j > i) CE_DESC(a[i], a[j]); }
; }
; __device__ __forceinline__ void peer_tile(const Args& A, LAS unsigned char* lds, int tile) {
;     ...
;                 sort16_desc(k0); sort16_desc(k1); merge16(k0, k1);
; #pragma unroll
;                 for (int msk = 16; msk <= 32; msk <<= 1) {
; #pragma unroll
;                     for (int i = 0; i < 16; ++i) k1[i] = (unsigned)__shfl_xor((int)k0[i], msk);
	v_max_u32_e32 v149, v17, v144
	v_min_u32_e32 v17, v17, v144
	v_max_u32_e32 v144, v145, v147
	v_min_u32_e32 v145, v145, v147
	v_max_u32_e32 v147, v8, v12
	v_min_u32_e32 v8, v8, v12
	v_max_u32_e32 v12, v5, v10
	v_min_u32_e32 v5, v5, v10
	v_max_u32_e32 v10, v14, v15
	v_min_u32_e32 v14, v14, v15
	v_max_u32_e32 v15, v16, v4
	v_min_u32_e32 v4, v16, v4
	v_max_u32_e32 v151, v152, v24
	v_min_u32_e32 v24, v152, v24
	v_max_u32_e32 v152, v153, v25
	v_min_u32_e32 v25, v153, v25
	v_max_u32_e32 v153, v21, v150
	v_min_u32_e32 v21, v21, v150
	v_max_u32_e32 v150, v26, v161
	v_min_u32_e32 v26, v26, v161
	v_max_u32_e32 v161, v0, v22
	v_min_u32_e32 v0, v0, v22
	v_max_u32_e32 v22, v3, v23
	v_min_u32_e32 v3, v3, v23
	v_max_u32_e32 v23, v20, v1
	v_min_u32_e32 v1, v20, v1
	v_max_u32_e32 v20, v2, v18
	v_min_u32_e32 v2, v2, v18
	v_max_u32_e32 v16, v143, v149
	v_min_u32_e32 v143, v143, v149
	v_max_u32_e32 v149, v148, v144
	v_min_u32_e32 v144, v148, v144
	v_max_u32_e32 v148, v28, v17
	v_min_u32_e32 v17, v28, v17
	v_max_u32_e32 v28, v146, v145
	v_min_u32_e32 v145, v146, v145
	v_max_u32_e32 v146, v147, v10
	v_min_u32_e32 v10, v147, v10
	v_max_u32_e32 v147, v12, v15
	v_min_u32_e32 v12, v12, v15
	v_max_u32_e32 v15, v8, v14
	v_min_u32_e32 v8, v8, v14
	v_max_u32_e32 v14, v5, v4
	v_min_u32_e32 v4, v5, v4
	v_max_u32_e32 v18, v151, v153
	v_min_u32_e32 v151, v151, v153
	v_max_u32_e32 v153, v152, v150
	v_min_u32_e32 v150, v152, v150
	v_max_u32_e32 v152, v24, v21
	v_min_u32_e32 v21, v24, v21
	v_max_u32_e32 v24, v25, v26
	v_min_u32_e32 v25, v25, v26
	v_max_u32_e32 v26, v161, v23
	v_min_u32_e32 v23, v161, v23
	v_max_u32_e32 v161, v22, v20
	v_min_u32_e32 v20, v22, v20
	v_max_u32_e32 v22, v0, v1
	v_min_u32_e32 v0, v0, v1
	v_max_u32_e32 v1, v3, v2
	v_min_u32_e32 v2, v3, v2
	v_min_u32_e32 v5, v16, v149
	v_min_u32_e32 v154, v143, v144
	v_min_u32_e32 v155, v148, v28
	v_min_u32_e32 v156, v17, v145
	v_min_u32_e32 v157, v146, v147
	v_min_u32_e32 v158, v10, v12
	v_min_u32_e32 v159, v15, v14
	v_min_u32_e32 v160, v8, v4
	v_min_u32_e32 v3, v18, v153
	v_min_u32_e32 v162, v151, v150
	v_min_u32_e32 v163, v152, v24
	v_min_u32_e32 v164, v21, v25
	v_min_u32_e32 v165, v26, v161
	v_min_u32_e32 v166, v23, v20
	v_min_u32_e32 v167, v22, v1
	v_min_u32_e32 v168, v0, v2
	v_max3_u32 v16, v16, v149, v168
	v_max3_u32 v0, v5, v0, v2
	v_max3_u32 v2, v143, v144, v167
	v_max3_u32 v1, v154, v22, v1
	v_max3_u32 v5, v148, v28, v166
	v_max3_u32 v20, v155, v23, v20
	v_max3_u32 v17, v17, v145, v165
	v_max3_u32 v22, v156, v26, v161
	v_max3_u32 v23, v146, v147, v164
	v_max3_u32 v21, v157, v21, v25
	v_max3_u32 v10, v10, v12, v163
	v_max3_u32 v12, v158, v152, v24
	v_max3_u32 v14, v15, v14, v162
	v_max3_u32 v15, v159, v151, v150
	v_max3_u32 v3, v8, v4, v3
	v_max3_u32 v4, v160, v18, v153
	v_max_u32_e32 v8, v16, v23
	v_min_u32_e32 v16, v16, v23
	v_max_u32_e32 v18, v0, v21
	v_min_u32_e32 v0, v0, v21
	v_max_u32_e32 v21, v2, v10
	v_min_u32_e32 v2, v2, v10
	v_max_u32_e32 v10, v1, v12
	v_min_u32_e32 v1, v1, v12
	v_max_u32_e32 v12, v5, v14
	v_min_u32_e32 v5, v5, v14
	v_max_u32_e32 v14, v20, v15
	v_min_u32_e32 v15, v20, v15
	v_max_u32_e32 v20, v17, v3
	v_min_u32_e32 v3, v17, v3
	v_max_u32_e32 v17, v22, v4
	v_min_u32_e32 v4, v22, v4
	v_max_u32_e32 v22, v8, v12
	v_min_u32_e32 v8, v8, v12
	v_max_u32_e32 v12, v18, v14
	v_min_u32_e32 v14, v18, v14
	v_max_u32_e32 v18, v21, v20
	v_min_u32_e32 v20, v21, v20
	v_max_u32_e32 v21, v10, v17
	v_min_u32_e32 v10, v10, v17
	v_max_u32_e32 v17, v16, v5
	v_min_u32_e32 v5, v16, v5
	v_max_u32_e32 v16, v0, v15
	v_min_u32_e32 v0, v0, v15
	v_max_u32_e32 v15, v2, v3
	v_min_u32_e32 v2, v2, v3
	v_max_u32_e32 v3, v1, v4
	v_min_u32_e32 v1, v1, v4
	v_max_u32_e32 v4, v22, v18
	v_min_u32_e32 v18, v22, v18
	v_max_u32_e32 v22, v12, v21
	v_min_u32_e32 v12, v12, v21
	v_max_u32_e32 v21, v8, v20
	v_min_u32_e32 v8, v8, v20
	v_max_u32_e32 v20, v14, v10
	v_min_u32_e32 v10, v14, v10
	v_max_u32_e32 v14, v17, v15
	v_min_u32_e32 v15, v17, v15
	v_max_u32_e32 v17, v16, v3
	v_min_u32_e32 v3, v16, v3
	v_max_u32_e32 v16, v5, v2
	v_min_u32_e32 v2, v5, v2
	v_max_u32_e32 v5, v0, v1
	v_min_u32_e32 v0, v0, v1
	v_max_u32_e32 v1, v4, v22
	v_min_u32_e32 v4, v4, v22
	v_max_u32_e32 v22, v18, v12
	v_min_u32_e32 v12, v18, v12
	v_max_u32_e32 v18, v21, v20
	v_min_u32_e32 v20, v21, v20
	v_max_u32_e32 v21, v8, v10
	v_min_u32_e32 v8, v8, v10
	v_max_u32_e32 v10, v14, v17
	v_min_u32_e32 v14, v14, v17
	v_max_u32_e32 v17, v15, v3
	v_min_u32_e32 v3, v15, v3
	v_max_u32_e32 v15, v16, v5
	v_min_u32_e32 v5, v16, v5
	v_max_u32_e32 v16, v2, v0
	v_min_u32_e32 v0, v2, v0
	ds_bpermute_b32 v2, v27, v1
	ds_bpermute_b32 v23, v27, v4
	ds_bpermute_b32 v24, v27, v22
	ds_bpermute_b32 v25, v27, v12
	ds_bpermute_b32 v26, v27, v18
	ds_bpermute_b32 v28, v27, v20
	ds_bpermute_b32 v143, v27, v21
	ds_bpermute_b32 v144, v27, v8
	ds_bpermute_b32 v145, v27, v10
	ds_bpermute_b32 v146, v27, v14
	ds_bpermute_b32 v147, v27, v17
	ds_bpermute_b32 v148, v27, v0
	ds_bpermute_b32 v149, v27, v16
	ds_bpermute_b32 v150, v27, v5
	ds_bpermute_b32 v151, v27, v15
	ds_bpermute_b32 v27, v27, v3
	s_waitcnt lgkmcnt(4)
	v_max_u32_e32 v1, v1, v148
	s_waitcnt lgkmcnt(3)
	v_max_u32_e32 v4, v4, v149
	s_waitcnt lgkmcnt(2)
	v_max_u32_e32 v22, v22, v150
	s_waitcnt lgkmcnt(1)
	v_max_u32_e32 v12, v12, v151
	s_waitcnt lgkmcnt(0)
; __device__ __forceinline__ void peer_tile(const Args& A, LAS unsigned char* lds, int tile) {
;     ...
;                 for (int msk = 16; msk <= 32; msk <<= 1) {
; #pragma unroll
;                     for (int i = 0; i < 16; ++i) k1[i] = (unsigned)__shfl_xor((int)k0[i], msk);
;                     merge16(k0, k1); }
; #pragma unroll
;                 for (int i = 0; i < 16; ++i) LA[hh][p][i] = k0[i];
;     ...
;             const int h = 4 * hg + g;
;             unsigned L2[2][16];
; #pragma unroll
;             for (int p = 0; p < 2; ++p)
; #pragma unroll
;                 for (int i = 0; i < 16; ++i) L2[p][i] = (g & 2) ? ((g & 1) ? LA[3][p][i] : LA[2][p][i]) : ((g & 1) ? LA[1][p][i] : LA[0][p][i]);
	v_max_u32_e32 v18, v18, v27
	v_max_u32_e32 v20, v20, v147
	v_max_u32_e32 v21, v21, v146
	v_max_u32_e32 v8, v8, v145
	v_max_u32_e32 v10, v10, v144
	v_max_u32_e32 v14, v14, v143
	v_max_u32_e32 v17, v17, v28
	v_max_u32_e32 v3, v3, v26
	v_max_u32_e32 v15, v15, v25
	v_max_u32_e32 v5, v5, v24
	v_max_u32_e32 v16, v16, v23
	v_max_u32_e32 v0, v0, v2
	v_max_u32_e32 v2, v1, v10
	v_min_u32_e32 v1, v1, v10
	v_max_u32_e32 v10, v4, v14
	v_min_u32_e32 v4, v4, v14
	v_max_u32_e32 v14, v22, v17
	v_min_u32_e32 v17, v22, v17
	v_max_u32_e32 v22, v12, v3
	v_min_u32_e32 v3, v12, v3
	v_max_u32_e32 v12, v18, v15
	v_min_u32_e32 v15, v18, v15
	v_max_u32_e32 v18, v20, v5
	v_min_u32_e32 v5, v20, v5
	v_max_u32_e32 v20, v21, v16
	v_min_u32_e32 v16, v21, v16
	v_max_u32_e32 v21, v8, v0
	v_min_u32_e32 v0, v8, v0
	v_max_u32_e32 v8, v2, v12
	v_min_u32_e32 v2, v2, v12
	v_max_u32_e32 v12, v10, v18
	v_min_u32_e32 v10, v10, v18
	v_max_u32_e32 v18, v14, v20
	v_min_u32_e32 v14, v14, v20
	v_max_u32_e32 v20, v22, v21
	v_min_u32_e32 v21, v22, v21
	v_max_u32_e32 v22, v1, v15
	v_min_u32_e32 v1, v1, v15
	v_max_u32_e32 v15, v4, v5
	v_min_u32_e32 v4, v4, v5
	v_max_u32_e32 v5, v17, v16
	v_min_u32_e32 v16, v17, v16
	v_max_u32_e32 v17, v3, v0
	v_min_u32_e32 v0, v3, v0
	v_max_u32_e32 v3, v8, v18
	v_min_u32_e32 v8, v8, v18
	v_max_u32_e32 v18, v12, v20
	v_min_u32_e32 v12, v12, v20
	v_max_u32_e32 v20, v2, v14
	v_min_u32_e32 v2, v2, v14
	v_max_u32_e32 v14, v10, v21
	v_min_u32_e32 v10, v10, v21
	v_max_u32_e32 v21, v22, v5
	v_min_u32_e32 v5, v22, v5
	v_max_u32_e32 v22, v15, v17
	v_min_u32_e32 v15, v15, v17
	v_max_u32_e32 v17, v1, v16
	v_min_u32_e32 v1, v1, v16
	v_max_u32_e32 v16, v4, v0
	v_min_u32_e32 v0, v4, v0
	v_max_u32_e32 v4, v3, v18
	v_min_u32_e32 v3, v3, v18
	v_max_u32_e32 v18, v8, v12
	v_min_u32_e32 v8, v8, v12
	v_max_u32_e32 v12, v20, v14
	v_min_u32_e32 v14, v20, v14
	v_max_u32_e32 v20, v2, v10
	v_min_u32_e32 v2, v2, v10
	v_max_u32_e32 v10, v21, v22
	v_min_u32_e32 v21, v21, v22
	v_max_u32_e32 v22, v5, v15
	v_min_u32_e32 v5, v5, v15
	v_max_u32_e32 v15, v17, v16
	v_min_u32_e32 v16, v17, v16
	v_max_u32_e32 v17, v1, v0
	v_min_u32_e32 v0, v1, v0
	ds_bpermute_b32 v1, v29, v4
	ds_bpermute_b32 v23, v29, v3
	ds_bpermute_b32 v24, v29, v18
	ds_bpermute_b32 v25, v29, v8
	ds_bpermute_b32 v26, v29, v12
	ds_bpermute_b32 v27, v29, v14
	ds_bpermute_b32 v28, v29, v20
	ds_bpermute_b32 v143, v29, v2
	ds_bpermute_b32 v144, v29, v10
	ds_bpermute_b32 v145, v29, v21
	ds_bpermute_b32 v146, v29, v22
	ds_bpermute_b32 v147, v29, v0
	ds_bpermute_b32 v148, v29, v17
	ds_bpermute_b32 v149, v29, v16
	ds_bpermute_b32 v150, v29, v15
	ds_bpermute_b32 v29, v29, v5
	s_waitcnt lgkmcnt(4)
	v_max_u32_e32 v4, v4, v147
	s_waitcnt lgkmcnt(3)
	v_max_u32_e32 v3, v3, v148
	s_waitcnt lgkmcnt(2)
	v_max_u32_e32 v18, v18, v149
	s_waitcnt lgkmcnt(1)
	v_max_u32_e32 v8, v8, v150
	s_waitcnt lgkmcnt(0)
	v_max_u32_e32 v12, v12, v29
	v_max_u32_e32 v14, v14, v146
	v_max_u32_e32 v20, v20, v145
	v_max_u32_e32 v2, v2, v144
	v_max_u32_e32 v10, v10, v143
	v_max_u32_e32 v21, v21, v28
	v_max_u32_e32 v22, v22, v27
	v_max_u32_e32 v5, v5, v26
	v_max_u32_e32 v15, v15, v25
	v_max_u32_e32 v16, v16, v24
	v_max_u32_e32 v17, v17, v23
	v_max_u32_e32 v0, v0, v1
	v_max_u32_e32 v1, v4, v10
	v_min_u32_e32 v4, v4, v10
	v_max_u32_e32 v10, v3, v21
	v_min_u32_e32 v3, v3, v21
	v_max_u32_e32 v21, v18, v22
	v_min_u32_e32 v18, v18, v22
	v_max_u32_e32 v22, v8, v5
	v_min_u32_e32 v5, v8, v5
	v_max_u32_e32 v8, v12, v15
	v_min_u32_e32 v12, v12, v15
	v_max_u32_e32 v15, v14, v16
	v_min_u32_e32 v14, v14, v16
	v_max_u32_e32 v16, v20, v17
	v_min_u32_e32 v17, v20, v17
	v_max_u32_e32 v20, v2, v0
	v_min_u32_e32 v0, v2, v0
	v_max_u32_e32 v2, v1, v8
	v_min_u32_e32 v1, v1, v8
	v_max_u32_e32 v8, v10, v15
	v_min_u32_e32 v10, v10, v15
	v_max_u32_e32 v15, v21, v16
	v_min_u32_e32 v16, v21, v16
	v_max_u32_e32 v21, v22, v20
	v_min_u32_e32 v20, v22, v20
	v_max_u32_e32 v22, v4, v12
	v_min_u32_e32 v4, v4, v12
	v_max_u32_e32 v12, v3, v14
	v_min_u32_e32 v3, v3, v14
	v_max_u32_e32 v14, v18, v17
	v_min_u32_e32 v17, v18, v17
	v_max_u32_e32 v18, v5, v0
	v_min_u32_e32 v0, v5, v0
	v_max_u32_e32 v5, v2, v15
	v_min_u32_e32 v2, v2, v15
	v_max_u32_e32 v15, v8, v21
	v_min_u32_e32 v8, v8, v21
	v_max_u32_e32 v21, v1, v16
	v_min_u32_e32 v1, v1, v16
	v_max_u32_e32 v16, v10, v20
	v_min_u32_e32 v10, v10, v20
	v_max_u32_e32 v20, v22, v14
	v_min_u32_e32 v14, v22, v14
	v_max_u32_e32 v22, v12, v18
	v_min_u32_e32 v12, v12, v18
	v_max_u32_e32 v18, v4, v17
	v_min_u32_e32 v4, v4, v17
	v_max_u32_e32 v17, v3, v0
	v_min_u32_e32 v0, v3, v0
	v_max_u32_e32 v3, v5, v15
	v_min_u32_e32 v5, v5, v15
	v_max_u32_e32 v15, v2, v8
	v_min_u32_e32 v2, v2, v8
	v_max_u32_e32 v8, v21, v16
	v_min_u32_e32 v16, v21, v16
	v_max_u32_e32 v21, v1, v10
	v_min_u32_e32 v1, v1, v10
	v_max_u32_e32 v10, v20, v22
	v_min_u32_e32 v20, v20, v22
	v_max_u32_e32 v22, v14, v12
	v_min_u32_e32 v12, v14, v12
	v_max_u32_e32 v14, v18, v17
	v_min_u32_e32 v17, v18, v17
	v_max_u32_e32 v18, v4, v0
	v_min_u32_e32 v0, v4, v0
	v_and_b32_e32 v4, 16, v19
	v_cmp_eq_u32_e32 vcc, 0, v4
	v_cndmask_b32_e64 v23, v77, v45, s[0:1]
	v_cndmask_b32_e64 v24, v76, v44, s[0:1]
	v_cndmask_b32_e32 v4, v142, v109, vcc
	v_cndmask_b32_e64 v4, v4, v23, s[4:5]
	v_cndmask_b32_e32 v23, v141, v108, vcc
	v_cndmask_b32_e64 v23, v23, v24, s[4:5]
	v_cndmask_b32_e32 v24, v140, v107, vcc
	v_cndmask_b32_e64 v25, v75, v43, s[0:1]
	v_cndmask_b32_e64 v24, v24, v25, s[4:5]
	v_cndmask_b32_e32 v25, v139, v106, vcc
	v_cndmask_b32_e64 v26, v74, v42, s[0:1]
	v_cndmask_b32_e64 v25, v25, v26, s[4:5]
	v_cndmask_b32_e32 v26, v138, v105, vcc
	v_cndmask_b32_e64 v27, v73, v41, s[0:1]
	v_cndmask_b32_e64 v26, v26, v27, s[4:5]
; __device__ __forceinline__ float key2f(unsigned k) { const unsigned u = (k & 0x80000000u) ? (k & 0x7fffffffu) : ~k; return __uint_as_float(u); }
; __device__ __forceinline__ void peer_tile(const Args& A, LAS unsigned char* lds, int tile) {
;     ...
;                 for (int i = 0; i < 16; ++i) L2[p][i] = (g & 2) ? ((g & 1) ? LA[3][p][i] : LA[2][p][i]) : ((g & 1) ? LA[1][p][i] : LA[0][p][i]);
;             float va[16], vb[16];
; #pragma unroll
;             for (int i = 0; i < 16; ++i) { va[i] = key2f(L2[0][i] & ~127u); vb[i] = key2f(L2[1][i] & ~127u); idx[i] = 127u - (L2[0][i] & 127u); idx[16 + i] = 127u - (L2[1][i] & 127u); }
	v_cndmask_b32_e32 v27, v137, v104, vcc
	v_cndmask_b32_e64 v28, v72, v40, s[0:1]
	v_cndmask_b32_e64 v27, v27, v28, s[4:5]
	v_cndmask_b32_e32 v28, v136, v103, vcc
	v_cndmask_b32_e64 v29, v71, v39, s[0:1]
	v_cndmask_b32_e64 v28, v28, v29, s[4:5]
	v_cndmask_b32_e32 v29, v135, v102, vcc
	v_cndmask_b32_e64 v29, v29, v38, s[4:5]
	v_cndmask_b32_e32 v38, v134, v101, vcc
	v_cndmask_b32_e64 v37, v38, v37, s[4:5]
	v_cndmask_b32_e32 v38, v133, v100, vcc
	v_cndmask_b32_e64 v36, v38, v36, s[4:5]
	v_cndmask_b32_e32 v38, v132, v99, vcc
	v_cndmask_b32_e64 v38, v38, v35, s[4:5]
	v_cndmask_b32_e32 v35, v131, v98, vcc
	v_cndmask_b32_e64 v39, v35, v34, s[4:5]
	v_cndmask_b32_e32 v34, v130, v97, vcc
	v_cndmask_b32_e64 v33, v34, v33, s[4:5]
	v_cndmask_b32_e32 v34, v129, v96, vcc
	v_cndmask_b32_e64 v40, v34, v32, s[4:5]
	v_cndmask_b32_e32 v32, v128, v95, vcc
	v_cndmask_b32_e64 v42, v32, v31, s[4:5]
	v_cndmask_b32_e32 v31, v127, v94, vcc
	v_cndmask_b32_e64 v43, v31, v30, s[4:5]
	v_cndmask_b32_e32 v3, v3, v126, vcc
	v_cndmask_b32_e64 v30, v93, v61, s[0:1]
	v_cndmask_b32_e64 v3, v3, v30, s[4:5]
	v_cndmask_b32_e32 v5, v5, v125, vcc
	v_cndmask_b32_e64 v30, v92, v60, s[0:1]
	v_cndmask_b32_e64 v30, v5, v30, s[4:5]
	v_cndmask_b32_e32 v5, v15, v124, vcc
	v_cndmask_b32_e64 v15, v91, v59, s[0:1]
	v_cndmask_b32_e64 v15, v5, v15, s[4:5]
	v_cndmask_b32_e32 v2, v2, v123, vcc
	v_cndmask_b32_e64 v5, v90, v58, s[0:1]
	v_cndmask_b32_e64 v31, v2, v5, s[4:5]
	v_cndmask_b32_e32 v2, v8, v122, vcc
	v_cndmask_b32_e64 v5, v89, v57, s[0:1]
	v_cndmask_b32_e64 v8, v2, v5, s[4:5]
	v_cndmask_b32_e32 v2, v16, v121, vcc
	v_cndmask_b32_e64 v5, v88, v56, s[0:1]
	v_cndmask_b32_e64 v32, v2, v5, s[4:5]
	v_cndmask_b32_e32 v2, v21, v120, vcc
	v_cndmask_b32_e64 v5, v87, v55, s[0:1]
	v_cndmask_b32_e64 v21, v2, v5, s[4:5]
	v_cndmask_b32_e32 v1, v1, v119, vcc
	v_cndmask_b32_e64 v2, v86, v54, s[0:1]
	v_cndmask_b32_e64 v34, v1, v2, s[4:5]
	v_cndmask_b32_e32 v1, v10, v118, vcc
	v_cndmask_b32_e64 v2, v85, v53, s[0:1]
	v_cndmask_b32_e64 v41, v1, v2, s[4:5]
	v_cndmask_b32_e32 v1, v20, v117, vcc
	v_cndmask_b32_e64 v2, v84, v52, s[0:1]
	v_cndmask_b32_e64 v44, v1, v2, s[4:5]
	v_cndmask_b32_e32 v1, v22, v116, vcc
	v_cndmask_b32_e64 v2, v83, v51, s[0:1]
	v_cndmask_b32_e64 v45, v1, v2, s[4:5]
	v_cndmask_b32_e32 v1, v12, v115, vcc
	v_cndmask_b32_e64 v2, v82, v50, s[0:1]
	v_cndmask_b32_e64 v50, v1, v2, s[4:5]
	v_cndmask_b32_e32 v1, v14, v114, vcc
	v_cndmask_b32_e64 v2, v81, v49, s[0:1]
	v_cndmask_b32_e64 v49, v1, v2, s[4:5]
	v_cndmask_b32_e32 v1, v17, v112, vcc
	v_cndmask_b32_e64 v2, v80, v48, s[0:1]
	v_cndmask_b32_e64 v48, v1, v2, s[4:5]
	v_cndmask_b32_e32 v1, v18, v111, vcc
	v_cndmask_b32_e64 v2, v79, v47, s[0:1]
	v_cndmask_b32_e64 v47, v1, v2, s[4:5]
	v_cndmask_b32_e32 v0, v0, v110, vcc
	v_cndmask_b32_e64 v1, v78, v46, s[0:1]
	v_cndmask_b32_e64 v46, v0, v1, s[4:5]
	v_and_b32_e32 v0, 0x7fffff80, v4
	v_bitop3_b32 v1, v4, s19, v4 bitop3:0xcf
	v_cmp_gt_i32_e32 vcc, 0, v4
	v_bitop3_b32 v2, v4, s19, v4 bitop3:0xc
	v_bitop3_b32 v4, v23, s19, v23 bitop3:0xcf
	v_cndmask_b32_e32 v20, v1, v0, vcc
	v_and_b32_e32 v0, 0x7fffff80, v3
	v_bitop3_b32 v1, v3, s19, v3 bitop3:0xcf
	v_cmp_gt_i32_e32 vcc, 0, v3
	v_add_u32_e32 v5, 0, v6
	v_bitop3_b32 v3, v3, s19, v3 bitop3:0xc
	v_cndmask_b32_e32 v1, v1, v0, vcc
	v_and_b32_e32 v0, 0x7fffff80, v23
	v_cmp_gt_i32_e32 vcc, 0, v23
	v_bitop3_b32 v14, v31, s19, v31 bitop3:0xcf
	v_bitop3_b32 v6, v24, s19, v24 bitop3:0xc
	v_cndmask_b32_e32 v18, v4, v0, vcc
	v_and_b32_e32 v0, 0x7fffff80, v30
	v_bitop3_b32 v4, v30, s19, v30 bitop3:0xcf
	v_cmp_gt_i32_e32 vcc, 0, v30
	v_bitop3_b32 v10, v15, s19, v15 bitop3:0xc
	v_bitop3_b32 v16, v32, s19, v32 bitop3:0xcf
	v_cndmask_b32_e32 v0, v4, v0, vcc
	v_bitop3_b32 v4, v23, s19, v23 bitop3:0xc
	ds_write2_b32 v5, v2, v4 offset1:1
	v_bitop3_b32 v2, v30, s19, v30 bitop3:0xc
	ds_write2_b32 v5, v3, v2 offset0:16 offset1:17
	v_and_b32_e32 v2, 0x7fffff80, v24
	v_bitop3_b32 v3, v24, s19, v24 bitop3:0xcf
	v_cmp_gt_i32_e32 vcc, 0, v24
	v_bitop3_b32 v4, v25, s19, v25 bitop3:0xcf
	v_bitop3_b32 v22, v29, s19, v29 bitop3:0xcf
	v_cndmask_b32_e32 v12, v3, v2, vcc
	v_and_b32_e32 v2, 0x7fffff80, v15
	v_bitop3_b32 v3, v15, s19, v15 bitop3:0xcf
	v_cmp_gt_i32_e32 vcc, 0, v15
	v_bitop3_b32 v15, v27, s19, v27 bitop3:0xcf
	v_bitop3_b32 v24, v34, s19, v34 bitop3:0xcf
	v_cndmask_b32_e32 v3, v3, v2, vcc
	v_and_b32_e32 v2, 0x7fffff80, v25
	v_cmp_gt_i32_e32 vcc, 0, v25
	s_nop 1
	v_cndmask_b32_e32 v4, v4, v2, vcc
	v_and_b32_e32 v2, 0x7fffff80, v31
	v_cmp_gt_i32_e32 vcc, 0, v31
	s_nop 1
	v_cndmask_b32_e32 v2, v14, v2, vcc
	v_bitop3_b32 v14, v25, s19, v25 bitop3:0xc
	ds_write2_b32 v5, v6, v14 offset0:2 offset1:3
	v_bitop3_b32 v6, v31, s19, v31 bitop3:0xc
	ds_write2_b32 v5, v10, v6 offset0:18 offset1:19
	v_and_b32_e32 v6, 0x7fffff80, v26
	v_bitop3_b32 v10, v26, s19, v26 bitop3:0xcf
	v_cmp_gt_i32_e32 vcc, 0, v26
	v_bitop3_b32 v25, v36, s19, v36 bitop3:0xcf
	s_nop 0
	v_cndmask_b32_e32 v14, v10, v6, vcc
	v_and_b32_e32 v6, 0x7fffff80, v8
	v_bitop3_b32 v10, v8, s19, v8 bitop3:0xcf
	v_cmp_gt_i32_e32 vcc, 0, v8
	v_bitop3_b32 v8, v8, s19, v8 bitop3:0xc
	s_nop 0
	v_cndmask_b32_e32 v17, v10, v6, vcc
	v_and_b32_e32 v10, 0x7fffff80, v27
	v_cmp_gt_i32_e32 vcc, 0, v27
	v_bitop3_b32 v6, v26, s19, v26 bitop3:0xc
	v_bitop3_b32 v26, v43, s19, v43 bitop3:0xcf
	v_cndmask_b32_e32 v10, v15, v10, vcc
	v_and_b32_e32 v15, 0x7fffff80, v32
	v_cmp_gt_i32_e32 vcc, 0, v32
	s_nop 1
	v_cndmask_b32_e32 v16, v16, v15, vcc
	v_bitop3_b32 v15, v27, s19, v27 bitop3:0xc
	ds_write2_b32 v5, v6, v15 offset0:4 offset1:5
	v_bitop3_b32 v6, v32, s19, v32 bitop3:0xc
	ds_write2_b32 v5, v8, v6 offset0:20 offset1:21
	v_and_b32_e32 v6, 0x7fffff80, v28
; __device__ __forceinline__ float key2f(unsigned k) { const unsigned u = (k & 0x80000000u) ? (k & 0x7fffffffu) : ~k; return __uint_as_float(u); }
; #define CK(i, j) ((f2key(va[i] + vb[j]) & ~255u) | (unsigned)(255 - (16 * (i) + (j))))
; __device__ __forceinline__ void peer_tile(const Args& A, LAS unsigned char* lds, int tile) {
;     ...
;             float va[16], vb[16];
; #pragma unroll
;             for (int i = 0; i < 16; ++i) { va[i] = key2f(L2[0][i] & ~127u); vb[i] = key2f(L2[1][i] & ~127u); idx[i] = 127u - (L2[0][i] & 127u); idx[16 + i] = 127u - (L2[1][i] & 127u); }
;     ...
;             unsigned Lf[16], Bt[16];
; #pragma unroll
;             for (int j = 0; j < 16; ++j) Lf[j] = CK(0, j);
	v_bitop3_b32 v8, v28, s19, v28 bitop3:0xcf
	v_cmp_gt_i32_e32 vcc, 0, v28
	v_bitop3_b32 v15, v21, s19, v21 bitop3:0xcf
	s_nop 0
	v_cndmask_b32_e32 v8, v8, v6, vcc
	v_and_b32_e32 v6, 0x7fffff80, v21
	v_cmp_gt_i32_e32 vcc, 0, v21
	v_bitop3_b32 v21, v21, s19, v21 bitop3:0xc
	s_nop 0
	v_cndmask_b32_e32 v23, v15, v6, vcc
	v_and_b32_e32 v6, 0x7fffff80, v29
	v_cmp_gt_i32_e32 vcc, 0, v29
	v_bitop3_b32 v15, v28, s19, v28 bitop3:0xc
	s_nop 0
	v_cndmask_b32_e32 v6, v22, v6, vcc
	v_and_b32_e32 v22, 0x7fffff80, v34
	v_cmp_gt_i32_e32 vcc, 0, v34
	s_nop 1
	v_cndmask_b32_e32 v22, v24, v22, vcc
	v_bitop3_b32 v24, v29, s19, v29 bitop3:0xc
	ds_write2_b32 v5, v15, v24 offset0:6 offset1:7
	v_bitop3_b32 v15, v34, s19, v34 bitop3:0xc
	ds_write2_b32 v5, v21, v15 offset0:22 offset1:23
	v_and_b32_e32 v15, 0x7fffff80, v37
	v_bitop3_b32 v21, v37, s19, v37 bitop3:0xcf
	v_cmp_gt_i32_e32 vcc, 0, v37
	v_and_b32_e32 v24, 0x7fffff80, v36
	s_nop 0
	v_cndmask_b32_e32 v27, v21, v15, vcc
	v_and_b32_e32 v15, 0x7fffff80, v41
	v_bitop3_b32 v21, v41, s19, v41 bitop3:0xcf
	v_cmp_gt_i32_e32 vcc, 0, v41
	s_nop 1
	v_cndmask_b32_e32 v35, v21, v15, vcc
	v_cmp_gt_i32_e32 vcc, 0, v36
	v_bitop3_b32 v15, v37, s19, v37 bitop3:0xc
	v_bitop3_b32 v21, v41, s19, v41 bitop3:0xc
	v_cndmask_b32_e32 v28, v25, v24, vcc
	v_and_b32_e32 v24, 0x7fffff80, v44
	v_bitop3_b32 v25, v44, s19, v44 bitop3:0xcf
	v_cmp_gt_i32_e32 vcc, 0, v44
	s_nop 1
	v_cndmask_b32_e32 v34, v25, v24, vcc
	v_bitop3_b32 v24, v36, s19, v36 bitop3:0xc
	ds_write2_b32 v5, v15, v24 offset0:8 offset1:9
	v_bitop3_b32 v15, v44, s19, v44 bitop3:0xc
	ds_write2_b32 v5, v21, v15 offset0:24 offset1:25
	v_and_b32_e32 v15, 0x7fffff80, v38
	v_bitop3_b32 v21, v38, s19, v38 bitop3:0xcf
	v_cmp_gt_i32_e32 vcc, 0, v38
	v_and_b32_e32 v24, 0x7fffff80, v39
	v_bitop3_b32 v25, v39, s19, v39 bitop3:0xcf
	v_cndmask_b32_e32 v29, v21, v15, vcc
	v_and_b32_e32 v15, 0x7fffff80, v45
	v_bitop3_b32 v21, v45, s19, v45 bitop3:0xcf
	v_cmp_gt_i32_e32 vcc, 0, v45
	s_nop 1
	v_cndmask_b32_e32 v37, v21, v15, vcc
	v_cmp_gt_i32_e32 vcc, 0, v39
	v_bitop3_b32 v15, v38, s19, v38 bitop3:0xc
	v_bitop3_b32 v21, v45, s19, v45 bitop3:0xc
	v_cndmask_b32_e32 v30, v25, v24, vcc
	v_and_b32_e32 v24, 0x7fffff80, v50
	v_bitop3_b32 v25, v50, s19, v50 bitop3:0xcf
	v_cmp_gt_i32_e32 vcc, 0, v50
	s_nop 1
	v_cndmask_b32_e32 v36, v25, v24, vcc
	v_bitop3_b32 v24, v39, s19, v39 bitop3:0xc
	ds_write2_b32 v5, v15, v24 offset0:10 offset1:11
	v_bitop3_b32 v15, v50, s19, v50 bitop3:0xc
	ds_write2_b32 v5, v21, v15 offset0:26 offset1:27
	v_and_b32_e32 v15, 0x7fffff80, v33
	v_bitop3_b32 v21, v33, s19, v33 bitop3:0xcf
	v_cmp_gt_i32_e32 vcc, 0, v33
	v_and_b32_e32 v24, 0x7fffff80, v40
	v_bitop3_b32 v25, v40, s19, v40 bitop3:0xcf
	v_cndmask_b32_e32 v31, v21, v15, vcc
	v_and_b32_e32 v15, 0x7fffff80, v49
	v_bitop3_b32 v21, v49, s19, v49 bitop3:0xcf
	v_cmp_gt_i32_e32 vcc, 0, v49
	s_nop 1
	v_cndmask_b32_e32 v39, v21, v15, vcc
	v_cmp_gt_i32_e32 vcc, 0, v40
	v_bitop3_b32 v15, v33, s19, v33 bitop3:0xc
	v_bitop3_b32 v21, v49, s19, v49 bitop3:0xc
	v_cndmask_b32_e32 v32, v25, v24, vcc
	v_and_b32_e32 v24, 0x7fffff80, v48
	v_bitop3_b32 v25, v48, s19, v48 bitop3:0xcf
	v_cmp_gt_i32_e32 vcc, 0, v48
	v_bitop3_b32 v33, v46, s19, v46 bitop3:0xcf
	s_nop 0
	v_cndmask_b32_e32 v38, v25, v24, vcc
	v_bitop3_b32 v24, v40, s19, v40 bitop3:0xc
	ds_write2_b32 v5, v15, v24 offset0:12 offset1:13
	v_bitop3_b32 v15, v48, s19, v48 bitop3:0xc
	ds_write2_b32 v5, v21, v15 offset0:28 offset1:29
	v_and_b32_e32 v15, 0x7fffff80, v42
	v_bitop3_b32 v21, v42, s19, v42 bitop3:0xcf
	v_cmp_gt_i32_e32 vcc, 0, v42
	v_and_b32_e32 v24, 0x7fffff80, v43
	s_nop 0
	v_cndmask_b32_e32 v25, v21, v15, vcc
	v_and_b32_e32 v15, 0x7fffff80, v47
	v_bitop3_b32 v21, v47, s19, v47 bitop3:0xcf
	v_cmp_gt_i32_e32 vcc, 0, v47
	s_nop 1
	v_cndmask_b32_e32 v41, v21, v15, vcc
	v_cmp_gt_i32_e32 vcc, 0, v43
	v_bitop3_b32 v21, v47, s19, v47 bitop3:0xc
	v_bitop3_b32 v15, v42, s19, v42 bitop3:0xc
	v_cndmask_b32_e32 v26, v26, v24, vcc
	v_and_b32_e32 v24, 0x7fffff80, v46
	v_cmp_gt_i32_e32 vcc, 0, v46
	v_pk_add_f32 v[34:35], v[20:21], v[34:35] op_sel_hi:[0,1]
	s_nop 0
	v_cndmask_b32_e32 v40, v33, v24, vcc
	v_bitop3_b32 v24, v43, s19, v43 bitop3:0xc
	v_pk_add_f32 v[42:43], v[20:21], v[0:1] op_sel_hi:[0,1]
	ds_write2_b32 v5, v15, v24 offset0:14 offset1:15
	v_not_b32_e32 v15, v43
	v_or_b32_e32 v33, 0x80000000, v43
	v_cmp_gt_i32_e32 vcc, 0, v43
	v_or_b32_e32 v43, 0x80000000, v42
	v_bitop3_b32 v24, v46, s19, v46 bitop3:0xc
	v_cndmask_b32_e32 v15, v33, v15, vcc
	v_or_b32_e32 v33, 0xff, v15
	v_not_b32_e32 v15, v42
	v_cmp_gt_i32_e32 vcc, 0, v42
	ds_write2_b32 v5, v21, v24 offset0:30 offset1:31
	s_waitcnt lgkmcnt(0)
; #define CK(i, j) ((f2key(va[i] + vb[j]) & ~255u) | (unsigned)(255 - (16 * (i) + (j))))
; __device__ __forceinline__ void peer_tile(const Args& A, LAS unsigned char* lds, int tile) {
;     ...
;             unsigned Lf[16], Bt[16];
; #pragma unroll
;             for (int j = 0; j < 16; ++j) Lf[j] = CK(0, j);
; #pragma unroll
;             for (int j = 0; j < 8; ++j) Bt[j] = CK(1, j);
; #pragma unroll
;             for (int j = 0; j < 5; ++j) Bt[8 + j] = CK(2, j);
; #pragma unroll
;             for (int j = 0; j < 3; ++j) Bt[13 + j] = CK(4, j);
	s_nop 0
	v_cndmask_b32_e32 v15, v43, v15, vcc
	v_and_b32_e32 v15, 0xffffff00, v15
	v_pk_add_f32 v[42:43], v[20:21], v[2:3] op_sel_hi:[0,1]
	v_or_b32_e32 v44, 0xfe, v15
	v_not_b32_e32 v15, v43
	v_or_b32_e32 v45, 0x80000000, v43
	v_cmp_gt_i32_e32 vcc, 0, v43
	v_or_b32_e32 v43, 0x80000000, v42
	s_nop 0
	v_cndmask_b32_e32 v15, v45, v15, vcc
	v_and_b32_e32 v15, 0xffffff00, v15
	v_or_b32_e32 v45, 0xfd, v15
	v_not_b32_e32 v15, v42
	v_cmp_gt_i32_e32 vcc, 0, v42
	s_nop 1
	v_cndmask_b32_e32 v15, v43, v15, vcc
	v_and_b32_e32 v15, 0xffffff00, v15
	v_pk_add_f32 v[42:43], v[20:21], v[16:17] op_sel_hi:[0,1]
	v_or_b32_e32 v46, 0xfc, v15
	v_not_b32_e32 v15, v43
	v_or_b32_e32 v47, 0x80000000, v43
	v_cmp_gt_i32_e32 vcc, 0, v43
	v_or_b32_e32 v43, 0x80000000, v42
	s_nop 0
	v_cndmask_b32_e32 v15, v47, v15, vcc
	v_and_b32_e32 v15, 0xffffff00, v15
	v_or_b32_e32 v47, 0xfb, v15
	v_not_b32_e32 v15, v42
	v_cmp_gt_i32_e32 vcc, 0, v42
	s_nop 1
	v_cndmask_b32_e32 v15, v43, v15, vcc
	v_and_b32_e32 v15, 0xffffff00, v15
	v_pk_add_f32 v[42:43], v[20:21], v[22:23] op_sel_hi:[0,1]
	v_or_b32_e32 v48, 0xfa, v15
	v_not_b32_e32 v15, v43
	v_or_b32_e32 v49, 0x80000000, v43
	v_cmp_gt_i32_e32 vcc, 0, v43
	v_pk_add_f32 v[22:23], v[18:19], v[22:23] op_sel_hi:[0,1]
	s_nop 0
	v_cndmask_b32_e32 v15, v49, v15, vcc
	v_and_b32_e32 v15, 0xffffff00, v15
	v_or_b32_e32 v43, 0xf9, v15
	v_not_b32_e32 v15, v42
	v_or_b32_e32 v49, 0x80000000, v42
	v_cmp_gt_i32_e32 vcc, 0, v42
	s_nop 1
	v_cndmask_b32_e32 v15, v49, v15, vcc
	v_and_b32_e32 v15, 0xffffff00, v15
	v_or_b32_e32 v42, 0xf8, v15
	v_not_b32_e32 v15, v35
	v_or_b32_e32 v49, 0x80000000, v35
	v_cmp_gt_i32_e32 vcc, 0, v35
	v_or_b32_e32 v35, 0x80000000, v34
	s_nop 0
	v_cndmask_b32_e32 v15, v49, v15, vcc
	v_and_b32_e32 v15, 0xffffff00, v15
	v_or_b32_e32 v49, 0xf7, v15
	v_not_b32_e32 v15, v34
	v_cmp_gt_i32_e32 vcc, 0, v34
	s_nop 1
	v_cndmask_b32_e32 v15, v35, v15, vcc
	v_and_b32_e32 v15, 0xffffff00, v15
	v_pk_add_f32 v[34:35], v[20:21], v[36:37] op_sel_hi:[0,1]
	v_or_b32_e32 v50, 0xf6, v15
	v_not_b32_e32 v15, v35
	v_or_b32_e32 v36, 0x80000000, v35
	v_cmp_gt_i32_e32 vcc, 0, v35
	v_or_b32_e32 v35, 0x80000000, v34
	s_nop 0
	v_cndmask_b32_e32 v15, v36, v15, vcc
	v_and_b32_e32 v15, 0xffffff00, v15
	v_or_b32_e32 v36, 0xf5, v15
	v_not_b32_e32 v15, v34
	v_cmp_gt_i32_e32 vcc, 0, v34
	s_nop 1
	v_cndmask_b32_e32 v15, v35, v15, vcc
	v_and_b32_e32 v15, 0xffffff00, v15
	v_pk_add_f32 v[34:35], v[20:21], v[38:39] op_sel_hi:[0,1]
	v_or_b32_e32 v37, 0xf4, v15
	v_not_b32_e32 v15, v35
	v_or_b32_e32 v38, 0x80000000, v35
	v_cmp_gt_i32_e32 vcc, 0, v35
	v_or_b32_e32 v35, 0x80000000, v34
	s_nop 0
	v_cndmask_b32_e32 v15, v38, v15, vcc
	v_and_b32_e32 v15, 0xffffff00, v15
	v_or_b32_e32 v38, 0xf3, v15
	v_not_b32_e32 v15, v34
	v_cmp_gt_i32_e32 vcc, 0, v34
	s_nop 1
	v_cndmask_b32_e32 v15, v35, v15, vcc
	v_and_b32_e32 v15, 0xffffff00, v15
	v_pk_add_f32 v[34:35], v[20:21], v[40:41] op_sel_hi:[0,1]
	v_or_b32_e32 v39, 0xf2, v15
	v_not_b32_e32 v15, v35
	v_or_b32_e32 v20, 0x80000000, v35
	v_cmp_gt_i32_e32 vcc, 0, v35
	v_or_b32_e32 v35, 0x80000000, v34
	s_nop 0
	v_cndmask_b32_e32 v15, v20, v15, vcc
	v_and_b32_e32 v15, 0xffffff00, v15
	v_or_b32_e32 v20, 0xf1, v15
	v_not_b32_e32 v15, v34
	v_cmp_gt_i32_e32 vcc, 0, v34
	s_nop 1
	v_cndmask_b32_e32 v15, v35, v15, vcc
	v_and_b32_e32 v15, 0xffffff00, v15
	v_pk_add_f32 v[34:35], v[18:19], v[0:1] op_sel_hi:[0,1]
	v_or_b32_e32 v40, 0xf0, v15
	v_not_b32_e32 v15, v35
	v_or_b32_e32 v41, 0x80000000, v35
	v_cmp_gt_i32_e32 vcc, 0, v35
	v_or_b32_e32 v35, 0x80000000, v34
	s_nop 0
	v_cndmask_b32_e32 v15, v41, v15, vcc
	v_and_b32_e32 v15, 0xffffff00, v15
	v_or_b32_e32 v41, 0xef, v15
	v_not_b32_e32 v15, v34
	v_cmp_gt_i32_e32 vcc, 0, v34
	s_nop 1
	v_cndmask_b32_e32 v15, v35, v15, vcc
	v_and_b32_e32 v15, 0xffffff00, v15
	v_pk_add_f32 v[34:35], v[18:19], v[2:3] op_sel_hi:[0,1]
	v_or_b32_e32 v51, 0xee, v15
	v_not_b32_e32 v15, v35
	v_or_b32_e32 v52, 0x80000000, v35
	v_cmp_gt_i32_e32 vcc, 0, v35
	v_or_b32_e32 v35, 0x80000000, v34
	s_nop 0
	v_cndmask_b32_e32 v15, v52, v15, vcc
	v_and_b32_e32 v15, 0xffffff00, v15
	v_or_b32_e32 v52, 0xed, v15
	v_not_b32_e32 v15, v34
	v_cmp_gt_i32_e32 vcc, 0, v34
	s_nop 1
	v_cndmask_b32_e32 v15, v35, v15, vcc
	v_and_b32_e32 v15, 0xffffff00, v15
	v_pk_add_f32 v[34:35], v[18:19], v[16:17] op_sel_hi:[0,1]
	v_or_b32_e32 v53, 0xec, v15
	v_not_b32_e32 v15, v35
	v_or_b32_e32 v16, 0x80000000, v35
	v_cmp_gt_i32_e32 vcc, 0, v35
	s_nop 1
	v_cndmask_b32_e32 v15, v16, v15, vcc
	v_and_b32_e32 v15, 0xffffff00, v15
	v_or_b32_e32 v35, 0xeb, v15
	v_not_b32_e32 v15, v34
	v_or_b32_e32 v16, 0x80000000, v34
	v_cmp_gt_i32_e32 vcc, 0, v34
	s_nop 1
	v_cndmask_b32_e32 v15, v16, v15, vcc
	v_and_b32_e32 v15, 0xffffff00, v15
	v_or_b32_e32 v34, 0xea, v15
	v_not_b32_e32 v15, v23
	v_or_b32_e32 v16, 0x80000000, v23
	v_cmp_gt_i32_e32 vcc, 0, v23
	s_nop 1
	v_cndmask_b32_e32 v15, v16, v15, vcc
	v_and_b32_e32 v15, 0xffffff00, v15
	v_or_b32_e32 v18, 0xe9, v15
	v_not_b32_e32 v15, v22
	v_or_b32_e32 v16, 0x80000000, v22
	v_cmp_gt_i32_e32 vcc, 0, v22
	v_pk_add_f32 v[22:23], v[12:13], v[0:1] op_sel_hi:[0,1]
	s_nop 0
	v_cndmask_b32_e32 v15, v16, v15, vcc
	v_and_b32_e32 v15, 0xffffff00, v15
	v_or_b32_e32 v54, 0xe8, v15
	v_not_b32_e32 v15, v23
	v_or_b32_e32 v16, 0x80000000, v23
	v_cmp_gt_i32_e32 vcc, 0, v23
	s_nop 1
	v_cndmask_b32_e32 v15, v16, v15, vcc
	v_and_b32_e32 v15, 0xffffff00, v15
	v_or_b32_e32 v55, 0xdf, v15
	v_not_b32_e32 v15, v22
	v_or_b32_e32 v16, 0x80000000, v22
	v_cmp_gt_i32_e32 vcc, 0, v22
	v_pk_add_f32 v[22:23], v[12:13], v[2:3] op_sel_hi:[0,1]
	v_lshl_add_u32 v13, v13, 10, s35
	v_cndmask_b32_e32 v15, v16, v15, vcc
	v_and_b32_e32 v15, 0xffffff00, v15
; #define CE_DESC(a, b) do { const unsigned _mx = (a) > (b) ? (a) : (b), _mn = (a) > (b) ? (b) : (a); (a) = _mx; (b) = _mn; } while (0)
; #define CK(i, j) ((f2key(va[i] + vb[j]) & ~255u) | (unsigned)(255 - (16 * (i) + (j))))
; __device__ __forceinline__ void sort16_desc(unsigned (&k)[16]) {
; #pragma unroll
;     for (int size = 2; size <= 16; size <<= 1)
; #pragma unroll
;         for (int stride = size >> 1; stride > 0; stride >>= 1)
; #pragma unroll
;             for (int i = 0; i < 16; ++i) { const int j = i ^ stride;
;                 if (j > i) { if ((i & size) == 0) CE_DESC(k[i], k[j]); else CE_DESC(k[j], k[i]); } }
; }
; __device__ __forceinline__ void peer_tile(const Args& A, LAS unsigned char* lds, int tile) {
;     ...
; #pragma unroll
;             for (int j = 0; j < 5; ++j) Bt[8 + j] = CK(2, j);
; #pragma unroll
;             for (int j = 0; j < 3; ++j) Bt[13 + j] = CK(4, j);
;             sort16_desc(Bt); merge16(Lf, Bt);
	v_or_b32_e32 v56, 0xde, v15
	v_not_b32_e32 v15, v23
	v_or_b32_e32 v16, 0x80000000, v23
	v_cmp_gt_i32_e32 vcc, 0, v23
	s_nop 1
	v_cndmask_b32_e32 v15, v16, v15, vcc
	v_and_b32_e32 v15, 0xffffff00, v15
	v_or_b32_e32 v23, 0xdd, v15
	v_not_b32_e32 v15, v22
	v_or_b32_e32 v16, 0x80000000, v22
	v_cmp_gt_i32_e32 vcc, 0, v22
	s_nop 1
	v_cndmask_b32_e32 v15, v16, v15, vcc
	v_and_b32_e32 v15, 0xffffff00, v15
	v_or_b32_e32 v22, 0xdc, v15
	v_mov_b32_e32 v15, v12
	v_mov_b32_e32 v16, v1
	v_pk_add_f32 v[16:17], v[14:15], v[16:17]
	s_nop 0
	v_not_b32_e32 v12, v17
	v_or_b32_e32 v15, 0x80000000, v17
	v_cmp_gt_i32_e32 vcc, 0, v17
	v_or_b32_e32 v17, 0x80000000, v16
	s_nop 0
	v_cndmask_b32_e32 v12, v15, v12, vcc
	v_not_b32_e32 v15, v16
	v_cmp_gt_i32_e32 vcc, 0, v16
	v_mov_b32_e32 v16, v3
	v_and_b32_e32 v12, 0xffffff00, v12
	v_cndmask_b32_e32 v15, v17, v15, vcc
	v_and_b32_e32 v15, 0xffffff00, v15
	v_mov_b32_e32 v17, v0
	v_or_b32_e32 v57, 0xbf, v15
	v_pk_add_f32 v[14:15], v[14:15], v[16:17] op_sel_hi:[0,1]
	v_not_b32_e32 v16, v15
	v_or_b32_e32 v17, 0x80000000, v15
	v_cmp_gt_i32_e32 vcc, 0, v15
	v_or_b32_e32 v12, 0xdb, v12
	v_pk_add_f32 v[2:3], v[4:5], v[2:3] op_sel_hi:[0,1]
	v_cndmask_b32_e32 v15, v17, v16, vcc
	v_not_b32_e32 v16, v14
	v_or_b32_e32 v17, 0x80000000, v14
	v_cmp_gt_i32_e32 vcc, 0, v14
	v_and_b32_e32 v15, 0xffffff00, v15
	v_or_b32_e32 v15, 0xbe, v15
	v_cndmask_b32_e32 v14, v17, v16, vcc
	v_and_b32_e32 v14, 0xffffff00, v14
	v_or_b32_e32 v14, 0xbd, v14
	v_max_u32_e32 v16, v41, v51
	v_min_u32_e32 v17, v41, v51
	v_max_u32_e32 v41, v53, v52
	v_min_u32_e32 v51, v53, v52
	v_max_u32_e32 v52, v35, v34
	v_min_u32_e32 v34, v35, v34
	v_max_u32_e32 v35, v54, v18
	v_min_u32_e32 v18, v54, v18
	v_max_u32_e32 v53, v55, v56
	v_min_u32_e32 v54, v55, v56
	v_max_u32_e32 v55, v22, v23
	v_min_u32_e32 v22, v22, v23
	v_max_u32_e32 v23, v12, v57
	v_min_u32_e32 v12, v12, v57
	v_max_u32_e32 v56, v14, v15
	v_min_u32_e32 v14, v14, v15
	v_max_u32_e32 v15, v16, v51
	v_min_u32_e32 v16, v16, v51
	v_max_u32_e32 v51, v17, v41
	v_min_u32_e32 v17, v17, v41
	v_max_u32_e32 v41, v18, v52
	v_min_u32_e32 v18, v18, v52
	v_max_u32_e32 v52, v35, v34
	v_min_u32_e32 v34, v35, v34
	v_max_u32_e32 v35, v53, v22
	v_min_u32_e32 v22, v53, v22
	v_max_u32_e32 v53, v54, v55
	v_min_u32_e32 v54, v54, v55
	v_max_u32_e32 v55, v14, v23
	v_min_u32_e32 v14, v14, v23
	v_max_u32_e32 v23, v56, v12
	v_min_u32_e32 v12, v56, v12
	v_max_u32_e32 v56, v15, v51
	v_min_u32_e32 v15, v15, v51
	v_max_u32_e32 v51, v16, v17
	v_min_u32_e32 v16, v16, v17
	v_max_u32_e32 v17, v34, v18
	v_min_u32_e32 v18, v34, v18
	v_max_u32_e32 v34, v52, v41
	v_min_u32_e32 v41, v52, v41
	v_max_u32_e32 v52, v35, v53
	v_min_u32_e32 v35, v35, v53
	v_max_u32_e32 v53, v22, v54
	v_min_u32_e32 v22, v22, v54
	v_max_u32_e32 v54, v12, v14
	v_min_u32_e32 v12, v12, v14
	v_max_u32_e32 v14, v23, v55
	v_min_u32_e32 v23, v23, v55
	v_max_u32_e32 v55, v56, v18
	v_min_u32_e32 v18, v56, v18
	v_max_u32_e32 v56, v15, v17
	v_min_u32_e32 v15, v15, v17
	v_max_u32_e32 v17, v51, v41
	v_min_u32_e32 v41, v51, v41
	v_max_u32_e32 v51, v16, v34
	v_min_u32_e32 v16, v16, v34
	v_max_u32_e32 v34, v12, v52
	v_min_u32_e32 v12, v12, v52
	v_max_u32_e32 v52, v54, v35
	v_min_u32_e32 v35, v54, v35
	v_max_u32_e32 v54, v23, v53
	v_min_u32_e32 v23, v23, v53
	v_max_u32_e32 v53, v14, v22
	v_min_u32_e32 v14, v14, v22
	v_max_u32_e32 v22, v55, v17
	v_min_u32_e32 v17, v55, v17
	v_max_u32_e32 v55, v56, v51
	v_min_u32_e32 v51, v56, v51
	v_max_u32_e32 v56, v18, v41
	v_min_u32_e32 v18, v18, v41
	v_max_u32_e32 v41, v15, v16
	v_min_u32_e32 v15, v15, v16
	v_max_u32_e32 v16, v23, v12
	v_min_u32_e32 v12, v23, v12
	v_max_u32_e32 v23, v14, v35
	v_min_u32_e32 v14, v14, v35
	v_max_u32_e32 v35, v54, v34
	v_min_u32_e32 v34, v54, v34
	v_max_u32_e32 v54, v53, v52
	v_min_u32_e32 v52, v53, v52
	v_max_u32_e32 v53, v22, v55
	v_min_u32_e32 v22, v22, v55
	v_max_u32_e32 v55, v17, v51
	v_min_u32_e32 v17, v17, v51
	v_max_u32_e32 v51, v56, v41
	v_min_u32_e32 v41, v56, v41
	v_max_u32_e32 v56, v18, v15
	v_min_u32_e32 v15, v18, v15
	v_max_u32_e32 v18, v14, v12
	v_min_u32_e32 v12, v14, v12
	v_max_u32_e32 v14, v23, v16
	v_min_u32_e32 v16, v23, v16
	v_max_u32_e32 v23, v52, v34
	v_min_u32_e32 v34, v52, v34
	v_max_u32_e32 v52, v54, v35
	v_min_u32_e32 v35, v54, v35
	v_max_u32_e32 v54, v53, v12
	v_min_u32_e32 v12, v53, v12
	v_max_u32_e32 v53, v22, v18
	v_min_u32_e32 v18, v22, v18
	v_max_u32_e32 v22, v55, v16
	v_min_u32_e32 v16, v55, v16
	v_max_u32_e32 v55, v17, v14
	v_min_u32_e32 v14, v17, v14
	v_max_u32_e32 v17, v51, v34
	v_min_u32_e32 v34, v51, v34
	v_max_u32_e32 v51, v41, v23
	v_min_u32_e32 v23, v41, v23
	v_max_u32_e32 v41, v56, v35
	v_min_u32_e32 v35, v56, v35
	v_max_u32_e32 v56, v15, v52
	v_min_u32_e32 v15, v15, v52
	v_max_u32_e32 v52, v54, v17
	v_min_u32_e32 v17, v54, v17
	v_max_u32_e32 v54, v53, v51
	v_min_u32_e32 v51, v53, v51
	v_max_u32_e32 v53, v22, v41
	v_min_u32_e32 v22, v22, v41
	v_max_u32_e32 v41, v55, v56
	v_min_u32_e32 v55, v55, v56
	v_max_u32_e32 v56, v12, v34
	v_min_u32_e32 v12, v12, v34
	v_max_u32_e32 v34, v18, v23
	v_min_u32_e32 v18, v18, v23
	v_max_u32_e32 v23, v16, v35
	v_min_u32_e32 v16, v16, v35
	v_max_u32_e32 v35, v14, v15
	v_min_u32_e32 v14, v14, v15
	v_max_u32_e32 v15, v52, v53
	v_min_u32_e32 v52, v52, v53
	v_max_u32_e32 v53, v54, v41
	v_min_u32_e32 v41, v54, v41
	v_max_u32_e32 v54, v17, v22
	v_min_u32_e32 v17, v17, v22
	v_max_u32_e32 v22, v51, v55
	v_min_u32_e32 v51, v51, v55
	v_max_u32_e32 v55, v56, v23
	v_min_u32_e32 v23, v56, v23
	v_max_u32_e32 v56, v34, v35
	v_min_u32_e32 v34, v34, v35
	v_max_u32_e32 v35, v12, v16
	v_min_u32_e32 v12, v12, v16
	v_max_u32_e32 v16, v18, v14
	v_min_u32_e32 v14, v18, v14
; #define CE_DESC(a, b) do { const unsigned _mx = (a) > (b) ? (a) : (b), _mn = (a) > (b) ? (b) : (a); (a) = _mx; (b) = _mn; } while (0)
; #define CK(i, j) ((f2key(va[i] + vb[j]) & ~255u) | (unsigned)(255 - (16 * (i) + (j))))
; __device__ __forceinline__ void merge16(unsigned (&a)[16], const unsigned (&b)[16]) {
; #pragma unroll
;     for (int i = 0; i < 16; ++i) a[i] = a[i] > b[15 - i] ? a[i] : b[15 - i];
; #pragma unroll
;     for (int stride = 8; stride > 0; stride >>= 1)
; #pragma unroll
;         for (int i = 0; i < 16; ++i) { const int j = i ^ stride; if (j > i) CE_DESC(a[i], a[j]); }
; }
; __device__ __forceinline__ void peer_tile(const Args& A, LAS unsigned char* lds, int tile) {
;     ...
;             sort16_desc(Bt); merge16(Lf, Bt);
; #pragma unroll
;             for (int j = 0; j < 4; ++j) Bt[j] = CK(3, j);
;             Bt[4] = CK(5, 0); Bt[5] = CK(5, 1); Bt[6] = CK(6, 0); Bt[7] = CK(6, 1); Bt[8] = CK(7, 0); Bt[9] = CK(7, 1);
;             Bt[10] = CK(8, 0); Bt[11] = CK(9, 0); Bt[12] = CK(10, 0); Bt[13] = CK(11, 0); Bt[14] = CK(12, 0); Bt[15] = CK(13, 0);
	v_min_u32_e32 v18, v15, v53
	v_min_u32_e32 v57, v52, v41
	v_min_u32_e32 v58, v54, v22
	v_min_u32_e32 v59, v17, v51
	v_min_u32_e32 v60, v55, v56
	v_min_u32_e32 v61, v23, v34
	v_min_u32_e32 v62, v35, v16
	v_min_u32_e32 v63, v12, v14
	v_max_u32_e32 v33, v33, v63
	v_max3_u32 v12, v44, v12, v14
	v_max_u32_e32 v14, v45, v62
	v_max3_u32 v16, v46, v35, v16
	v_max_u32_e32 v35, v47, v61
	v_max3_u32 v23, v48, v23, v34
	v_max_u32_e32 v34, v43, v60
	v_max3_u32 v42, v42, v55, v56
	v_max_u32_e32 v43, v49, v59
	v_max3_u32 v17, v50, v17, v51
	v_max_u32_e32 v36, v36, v58
	v_max3_u32 v22, v37, v54, v22
	v_max_u32_e32 v37, v38, v57
	v_max3_u32 v38, v39, v52, v41
	v_max_u32_e32 v18, v20, v18
	v_max3_u32 v15, v40, v15, v53
	v_max_u32_e32 v20, v33, v43
	v_min_u32_e32 v33, v33, v43
	v_max_u32_e32 v39, v12, v17
	v_min_u32_e32 v12, v12, v17
	v_max_u32_e32 v17, v14, v36
	v_min_u32_e32 v14, v14, v36
	v_max_u32_e32 v36, v16, v22
	v_min_u32_e32 v16, v16, v22
	v_max_u32_e32 v22, v35, v37
	v_min_u32_e32 v35, v35, v37
	v_max_u32_e32 v37, v23, v38
	v_min_u32_e32 v23, v23, v38
	v_max_u32_e32 v38, v34, v18
	v_min_u32_e32 v18, v34, v18
	v_max_u32_e32 v34, v42, v15
	v_min_u32_e32 v15, v42, v15
	v_max_u32_e32 v40, v20, v22
	v_min_u32_e32 v20, v20, v22
	v_max_u32_e32 v22, v39, v37
	v_min_u32_e32 v37, v39, v37
	v_max_u32_e32 v39, v17, v38
	v_min_u32_e32 v17, v17, v38
	v_max_u32_e32 v38, v36, v34
	v_min_u32_e32 v34, v36, v34
	v_max_u32_e32 v36, v33, v35
	v_min_u32_e32 v33, v33, v35
	v_max_u32_e32 v35, v12, v23
	v_min_u32_e32 v12, v12, v23
	v_max_u32_e32 v23, v14, v18
	v_min_u32_e32 v14, v14, v18
	v_max_u32_e32 v18, v16, v15
	v_min_u32_e32 v15, v16, v15
	v_max_u32_e32 v16, v40, v39
	v_min_u32_e32 v39, v40, v39
	v_max_u32_e32 v40, v22, v38
	v_min_u32_e32 v22, v22, v38
	v_max_u32_e32 v38, v20, v17
	v_min_u32_e32 v17, v20, v17
	v_max_u32_e32 v20, v37, v34
	v_min_u32_e32 v34, v37, v34
	v_max_u32_e32 v37, v36, v23
	v_min_u32_e32 v23, v36, v23
	v_max_u32_e32 v36, v35, v18
	v_min_u32_e32 v18, v35, v18
	v_max_u32_e32 v35, v33, v14
	v_min_u32_e32 v33, v33, v14
	v_max_u32_e32 v41, v12, v15
	v_min_u32_e32 v12, v12, v15
	v_pk_add_f32 v[14:15], v[4:5], v[0:1] op_sel_hi:[0,1]
	v_not_b32_e32 v50, v15
	v_or_b32_e32 v51, 0x80000000, v15
	v_cmp_gt_i32_e32 vcc, 0, v15
	v_not_b32_e32 v4, v3
	v_min_u32_e32 v42, v16, v40
	v_cndmask_b32_e32 v15, v51, v50, vcc
	v_not_b32_e32 v50, v14
	v_or_b32_e32 v51, 0x80000000, v14
	v_cmp_gt_i32_e32 vcc, 0, v14
	v_and_b32_e32 v15, 0xffffff00, v15
	v_or_b32_e32 v15, 0xcf, v15
	v_cndmask_b32_e32 v14, v51, v50, vcc
	v_or_b32_e32 v50, 0x80000000, v3
	v_cmp_gt_i32_e32 vcc, 0, v3
	v_and_b32_e32 v14, 0xffffff00, v14
	v_or_b32_e32 v14, 0xce, v14
	v_cndmask_b32_e32 v3, v50, v4, vcc
	v_and_b32_e32 v3, 0xffffff00, v3
	v_or_b32_e32 v4, 0xcd, v3
	v_not_b32_e32 v3, v2
	v_or_b32_e32 v50, 0x80000000, v2
	v_cmp_gt_i32_e32 vcc, 0, v2
	v_min_u32_e32 v43, v39, v22
	v_min_u32_e32 v44, v38, v20
	v_cndmask_b32_e32 v2, v50, v3, vcc
	v_and_b32_e32 v2, 0xffffff00, v2
	v_or_b32_e32 v50, 0xcc, v2
	v_pk_add_f32 v[2:3], v[10:11], v[0:1] op_sel_hi:[0,1]
	v_not_b32_e32 v10, v3
	v_or_b32_e32 v51, 0x80000000, v3
	v_cmp_gt_i32_e32 vcc, 0, v3
	v_min_u32_e32 v45, v17, v34
	v_min_u32_e32 v46, v37, v36
	v_cndmask_b32_e32 v3, v51, v10, vcc
	v_and_b32_e32 v3, 0xffffff00, v3
	v_or_b32_e32 v10, 0xaf, v3
	v_not_b32_e32 v3, v2
	v_or_b32_e32 v51, 0x80000000, v2
	v_cmp_gt_i32_e32 vcc, 0, v2
	v_min_u32_e32 v47, v23, v18
	v_min_u32_e32 v48, v35, v41
	v_cndmask_b32_e32 v2, v51, v3, vcc
	v_and_b32_e32 v2, 0xffffff00, v2
	v_or_b32_e32 v51, 0xae, v2
	v_pk_add_f32 v[2:3], v[8:9], v[0:1] op_sel_hi:[0,1]
	v_not_b32_e32 v8, v3
	v_or_b32_e32 v52, 0x80000000, v3
	v_cmp_gt_i32_e32 vcc, 0, v3
	v_min_u32_e32 v49, v33, v12
	v_lshlrev_b32_e32 v11, 9, v11
	v_cndmask_b32_e32 v3, v52, v8, vcc
	v_and_b32_e32 v3, 0xffffff00, v3
	v_or_b32_e32 v8, 0x9f, v3
	v_not_b32_e32 v3, v2
	v_or_b32_e32 v52, 0x80000000, v2
	v_cmp_gt_i32_e32 vcc, 0, v2
	s_nop 1
	v_cndmask_b32_e32 v2, v52, v3, vcc
	v_and_b32_e32 v2, 0xffffff00, v2
	v_or_b32_e32 v52, 0x9e, v2
	v_pk_add_f32 v[2:3], v[6:7], v[0:1] op_sel_hi:[0,1]
	v_not_b32_e32 v0, v3
	v_or_b32_e32 v6, 0x80000000, v3
	v_cmp_gt_i32_e32 vcc, 0, v3
	v_not_b32_e32 v3, v2
	s_nop 0
	v_cndmask_b32_e32 v0, v6, v0, vcc
	v_or_b32_e32 v6, 0x80000000, v2
	v_cmp_gt_i32_e32 vcc, 0, v2
	v_and_b32_e32 v0, 0xffffff00, v0
	v_or_b32_e32 v0, 0x8f, v0
	v_cndmask_b32_e32 v2, v6, v3, vcc
	v_add_f32_e32 v3, v27, v1
	v_not_b32_e32 v6, v3
	v_or_b32_e32 v27, 0x80000000, v3
	v_cmp_gt_i32_e32 vcc, 0, v3
	v_and_b32_e32 v2, 0xffffff00, v2
	v_or_b32_e32 v2, 0x8e, v2
	v_cndmask_b32_e32 v3, v27, v6, vcc
	v_add_f32_e32 v6, v28, v1
	v_not_b32_e32 v27, v6
	v_or_b32_e32 v28, 0x80000000, v6
	v_cmp_gt_i32_e32 vcc, 0, v6
	v_and_b32_e32 v3, 0xffffff00, v3
	v_or_b32_e32 v3, 0x7f, v3
	v_cndmask_b32_e32 v6, v28, v27, vcc
	v_add_f32_e32 v27, v29, v1
	v_not_b32_e32 v28, v27
	v_or_b32_e32 v29, 0x80000000, v27
	v_cmp_gt_i32_e32 vcc, 0, v27
	v_and_b32_e32 v6, 0xffffff00, v6
	v_or_b32_e32 v6, 0x6f, v6
	v_cndmask_b32_e32 v27, v29, v28, vcc
	v_add_f32_e32 v28, v30, v1
	v_not_b32_e32 v29, v28
	v_or_b32_e32 v30, 0x80000000, v28
	v_cmp_gt_i32_e32 vcc, 0, v28
	v_and_b32_e32 v27, 0xffffff00, v27
	v_or_b32_e32 v27, 0x5f, v27
	v_cndmask_b32_e32 v28, v30, v29, vcc
	v_add_f32_e32 v29, v31, v1
	v_not_b32_e32 v30, v29
	v_or_b32_e32 v31, 0x80000000, v29
	v_cmp_gt_i32_e32 vcc, 0, v29
	v_and_b32_e32 v28, 0xffffff00, v28
	v_or_b32_e32 v28, 0x4f, v28
	v_cndmask_b32_e32 v29, v31, v30, vcc
	v_add_f32_e32 v30, v32, v1
	v_not_b32_e32 v31, v30
	v_or_b32_e32 v32, 0x80000000, v30
	v_cmp_gt_i32_e32 vcc, 0, v30
	v_and_or_b32 v29, v29, s34, 63
	s_nop 0
	v_cndmask_b32_e32 v30, v32, v31, vcc
; #define CE_DESC(a, b) do { const unsigned _mx = (a) > (b) ? (a) : (b), _mn = (a) > (b) ? (b) : (a); (a) = _mx; (b) = _mn; } while (0)
; __device__ __forceinline__ void sort16_desc(unsigned (&k)[16]) {
; #pragma unroll
;     for (int size = 2; size <= 16; size <<= 1)
; #pragma unroll
;         for (int stride = size >> 1; stride > 0; stride >>= 1)
; #pragma unroll
;             for (int i = 0; i < 16; ++i) { const int j = i ^ stride;
;                 if (j > i) { if ((i & size) == 0) CE_DESC(k[i], k[j]); else CE_DESC(k[j], k[i]); } }
; }
; __device__ __forceinline__ void merge16(unsigned (&a)[16], const unsigned (&b)[16]) {
; #pragma unroll
;     for (int i = 0; i < 16; ++i) a[i] = a[i] > b[15 - i] ? a[i] : b[15 - i];
; #pragma unroll
;     for (int stride = 8; stride > 0; stride >>= 1)
; #pragma unroll
;         for (int i = 0; i < 16; ++i) { const int j = i ^ stride; if (j > i) CE_DESC(a[i], a[j]); }
; }
	v_and_or_b32 v30, v30, s34, 47
	v_max_u32_e32 v31, v15, v14
	v_min_u32_e32 v14, v15, v14
	v_max_u32_e32 v15, v50, v4
	v_min_u32_e32 v4, v50, v4
	v_max_u32_e32 v32, v10, v51
	v_min_u32_e32 v10, v10, v51
	v_max_u32_e32 v50, v52, v8
	v_min_u32_e32 v8, v52, v8
	v_max_u32_e32 v51, v0, v2
	v_min_u32_e32 v0, v0, v2
	v_max_u32_e32 v2, v6, v3
	v_min_u32_e32 v3, v6, v3
	v_max_u32_e32 v6, v27, v28
	v_min_u32_e32 v27, v27, v28
	v_max_u32_e32 v28, v30, v29
	v_min_u32_e32 v29, v30, v29
	v_max_u32_e32 v30, v31, v4
	v_min_u32_e32 v4, v31, v4
	v_max_u32_e32 v31, v14, v15
	v_min_u32_e32 v14, v14, v15
	v_max_u32_e32 v15, v8, v32
	v_min_u32_e32 v8, v8, v32
	v_max_u32_e32 v32, v50, v10
	v_min_u32_e32 v10, v50, v10
	v_max_u32_e32 v50, v51, v3
	v_min_u32_e32 v3, v51, v3
	v_max_u32_e32 v51, v0, v2
	v_min_u32_e32 v0, v0, v2
	v_max_u32_e32 v2, v29, v6
	v_min_u32_e32 v6, v29, v6
	v_max_u32_e32 v29, v28, v27
	v_min_u32_e32 v27, v28, v27
	v_max_u32_e32 v28, v30, v31
	v_min_u32_e32 v30, v30, v31
	v_max_u32_e32 v31, v4, v14
	v_min_u32_e32 v4, v4, v14
	v_max_u32_e32 v14, v10, v8
	v_min_u32_e32 v8, v10, v8
	v_max_u32_e32 v10, v32, v15
	v_min_u32_e32 v15, v32, v15
	v_max_u32_e32 v32, v50, v51
	v_min_u32_e32 v50, v50, v51
	v_max_u32_e32 v51, v3, v0
	v_min_u32_e32 v0, v3, v0
	v_max_u32_e32 v3, v27, v6
	v_min_u32_e32 v6, v27, v6
	v_max_u32_e32 v27, v29, v2
	v_min_u32_e32 v2, v29, v2
	v_max_u32_e32 v29, v28, v8
	v_min_u32_e32 v8, v28, v8
	v_max_u32_e32 v28, v30, v14
	v_min_u32_e32 v14, v30, v14
	v_max_u32_e32 v30, v31, v15
	v_min_u32_e32 v15, v31, v15
	v_max_u32_e32 v31, v4, v10
	v_min_u32_e32 v4, v4, v10
	v_max_u32_e32 v10, v6, v32
	v_min_u32_e32 v6, v6, v32
	v_max_u32_e32 v32, v3, v50
	v_min_u32_e32 v3, v3, v50
	v_max_u32_e32 v50, v2, v51
	v_min_u32_e32 v2, v2, v51
	v_max_u32_e32 v51, v27, v0
	v_min_u32_e32 v0, v27, v0
	v_max_u32_e32 v27, v29, v30
	v_min_u32_e32 v29, v29, v30
	v_max_u32_e32 v30, v28, v31
	v_min_u32_e32 v28, v28, v31
	v_max_u32_e32 v31, v8, v15
	v_min_u32_e32 v8, v8, v15
	v_max_u32_e32 v15, v14, v4
	v_min_u32_e32 v4, v14, v4
	v_max_u32_e32 v14, v2, v6
	v_min_u32_e32 v2, v2, v6
	v_max_u32_e32 v6, v0, v3
	v_min_u32_e32 v0, v0, v3
	v_max_u32_e32 v3, v50, v10
	v_min_u32_e32 v10, v50, v10
	v_max_u32_e32 v50, v51, v32
	v_min_u32_e32 v32, v51, v32
	v_max_u32_e32 v51, v27, v30
	v_min_u32_e32 v27, v27, v30
	v_max_u32_e32 v30, v29, v28
	v_min_u32_e32 v28, v29, v28
	v_max_u32_e32 v29, v31, v15
	v_min_u32_e32 v15, v31, v15
	v_max_u32_e32 v31, v8, v4
	v_min_u32_e32 v4, v8, v4
	v_max_u32_e32 v8, v0, v2
	v_min_u32_e32 v0, v0, v2
	v_max_u32_e32 v2, v6, v14
	v_min_u32_e32 v6, v6, v14
	v_max_u32_e32 v14, v32, v10
	v_min_u32_e32 v10, v32, v10
	v_max_u32_e32 v32, v50, v3
	v_min_u32_e32 v3, v50, v3
	v_max_u32_e32 v50, v51, v0
	v_min_u32_e32 v0, v51, v0
	v_max_u32_e32 v51, v27, v8
	v_min_u32_e32 v8, v27, v8
	v_max_u32_e32 v27, v30, v6
	v_min_u32_e32 v6, v30, v6
	v_max_u32_e32 v30, v28, v2
	v_min_u32_e32 v2, v28, v2
	v_max_u32_e32 v28, v29, v10
	v_min_u32_e32 v10, v29, v10
	v_max_u32_e32 v29, v15, v14
	v_min_u32_e32 v14, v15, v14
	v_max_u32_e32 v15, v31, v3
	v_min_u32_e32 v3, v31, v3
	v_max_u32_e32 v31, v4, v32
	v_min_u32_e32 v4, v4, v32
	v_max_u32_e32 v32, v50, v28
	v_min_u32_e32 v28, v50, v28
	v_max_u32_e32 v50, v51, v29
	v_min_u32_e32 v29, v51, v29
	v_max_u32_e32 v51, v27, v15
	v_min_u32_e32 v15, v27, v15
	v_max_u32_e32 v27, v30, v31
	v_min_u32_e32 v30, v30, v31
	v_max_u32_e32 v31, v0, v10
	v_min_u32_e32 v0, v0, v10
	v_max_u32_e32 v10, v8, v14
	v_min_u32_e32 v8, v8, v14
	v_max_u32_e32 v14, v6, v3
	v_min_u32_e32 v3, v6, v3
	v_max_u32_e32 v6, v2, v4
	v_min_u32_e32 v2, v2, v4
	v_max_u32_e32 v4, v32, v51
	v_min_u32_e32 v32, v32, v51
	v_max_u32_e32 v51, v50, v27
	v_min_u32_e32 v27, v50, v27
	v_max_u32_e32 v50, v28, v15
	v_min_u32_e32 v15, v28, v15
	v_max_u32_e32 v28, v29, v30
	v_min_u32_e32 v29, v29, v30
	v_max_u32_e32 v30, v31, v14
	v_min_u32_e32 v14, v31, v14
	v_max_u32_e32 v31, v10, v6
	v_min_u32_e32 v6, v10, v6
	v_max_u32_e32 v10, v0, v3
	v_min_u32_e32 v0, v0, v3
	v_max_u32_e32 v3, v8, v2
	v_min_u32_e32 v2, v8, v2
	v_min_u32_e32 v8, v4, v51
	v_min_u32_e32 v52, v32, v27
	v_min_u32_e32 v53, v50, v28
	v_min_u32_e32 v54, v15, v29
	v_min_u32_e32 v55, v30, v31
	v_min_u32_e32 v56, v14, v6
	v_min_u32_e32 v57, v10, v3
	v_min_u32_e32 v58, v0, v2
	v_max3_u32 v16, v16, v40, v58
	v_max3_u32 v0, v42, v0, v2
	v_max3_u32 v2, v39, v22, v57
	v_max3_u32 v3, v43, v10, v3
	v_max3_u32 v10, v38, v20, v56
	v_max3_u32 v6, v44, v14, v6
	v_max3_u32 v14, v17, v34, v55
	v_max3_u32 v17, v45, v30, v31
	v_max3_u32 v20, v37, v36, v54
	v_max3_u32 v15, v46, v15, v29
	v_max3_u32 v18, v23, v18, v53
	v_max3_u32 v22, v47, v50, v28
	v_max3_u32 v23, v35, v41, v52
	v_max3_u32 v27, v48, v32, v27
	v_max3_u32 v8, v33, v12, v8
	v_max3_u32 v4, v49, v4, v51
	v_max_u32_e32 v12, v16, v20
	v_min_u32_e32 v16, v16, v20
	v_max_u32_e32 v20, v0, v15
	v_min_u32_e32 v0, v0, v15
	v_max_u32_e32 v15, v2, v18
	v_min_u32_e32 v2, v2, v18
	v_max_u32_e32 v18, v3, v22
	v_min_u32_e32 v3, v3, v22
	v_max_u32_e32 v22, v10, v23
	v_min_u32_e32 v10, v10, v23
	v_max_u32_e32 v23, v6, v27
	v_min_u32_e32 v6, v6, v27
	v_max_u32_e32 v27, v14, v8
	v_min_u32_e32 v8, v14, v8
	v_max_u32_e32 v14, v17, v4
	v_min_u32_e32 v4, v17, v4
	v_max_u32_e32 v17, v12, v22
	v_min_u32_e32 v12, v12, v22
	v_max_u32_e32 v22, v20, v23
	v_min_u32_e32 v20, v20, v23
	v_max_u32_e32 v23, v15, v27
	v_min_u32_e32 v15, v15, v27
	v_max_u32_e32 v27, v18, v14
	v_min_u32_e32 v14, v18, v14
	v_max_u32_e32 v18, v16, v10
	v_min_u32_e32 v10, v16, v10
	v_max_u32_e32 v16, v0, v6
	v_min_u32_e32 v0, v0, v6
	v_max_u32_e32 v6, v2, v8
	v_min_u32_e32 v2, v2, v8
	v_max_u32_e32 v8, v3, v4
; __device__ __forceinline__ float key2f(unsigned k) { const unsigned u = (k & 0x80000000u) ? (k & 0x7fffffffu) : ~k; return __uint_as_float(u); }
; #define CE_DESC(a, b) do { const unsigned _mx = (a) > (b) ? (a) : (b), _mn = (a) > (b) ? (b) : (a); (a) = _mx; (b) = _mn; } while (0)
; #define CK(i, j) ((f2key(va[i] + vb[j]) & ~255u) | (unsigned)(255 - (16 * (i) + (j))))
; __device__ __forceinline__ void peer_tile(const Args& A, LAS unsigned char* lds, int tile) {
;     ...
;             { unsigned x0 = CK(14, 0), x1 = CK(15, 0);
; #pragma unroll
;               for (int i = 0; i < 16; ++i) CE_DESC(Lf[i], x0);
; #pragma unroll
;               for (int i = 0; i < 16; ++i) CE_DESC(Lf[i], x1); }
;     ...
;             float fv[16], den = 0.f; const float f0 = key2f(Lf[0] & ~255u);
; #pragma unroll
;             for (int k = 0; k < 16; ++k) { fv[k] = __expf(key2f(Lf[k] & ~255u) - f0); den += fv[k]; }
;             const float rden = 1.f / den;
	v_min_u32_e32 v3, v3, v4
	v_max_u32_e32 v4, v17, v23
	v_min_u32_e32 v17, v17, v23
	v_max_u32_e32 v23, v22, v27
	v_min_u32_e32 v22, v22, v27
	v_max_u32_e32 v27, v12, v15
	v_min_u32_e32 v12, v12, v15
	v_max_u32_e32 v15, v20, v14
	v_min_u32_e32 v14, v20, v14
	v_max_u32_e32 v20, v18, v6
	v_min_u32_e32 v6, v18, v6
	v_max_u32_e32 v18, v16, v8
	v_min_u32_e32 v8, v16, v8
	v_max_u32_e32 v16, v10, v2
	v_min_u32_e32 v2, v10, v2
	v_max_u32_e32 v10, v0, v3
	v_min_u32_e32 v0, v0, v3
	v_max_u32_e32 v41, v2, v0
	v_min_u32_e32 v0, v2, v0
	v_add_f32_e32 v2, v25, v1
	v_not_b32_e32 v25, v2
	v_or_b32_e32 v42, 0x80000000, v2
	v_cmp_gt_i32_e32 vcc, 0, v2
	v_add_f32_e32 v1, v26, v1
	v_max_u32_e32 v3, v4, v23
	v_cndmask_b32_e32 v2, v42, v25, vcc
	v_and_or_b32 v2, v2, s34, 31
	v_not_b32_e32 v25, v1
	v_or_b32_e32 v26, 0x80000000, v1
	v_cmp_gt_i32_e32 vcc, 0, v1
	v_min_u32_e32 v28, v4, v23
	v_max_u32_e32 v29, v17, v22
	v_cndmask_b32_e32 v1, v26, v25, vcc
	v_max_u32_e32 v25, v3, v2
	v_min_u32_e32 v3, v3, v2
	v_min_u32_e32 v3, v28, v3
	v_min_u32_e32 v30, v17, v22
	v_med3_u32 v2, v4, v23, v2
	v_min_u32_e32 v23, v29, v3
	v_max_u32_e32 v31, v27, v15
	v_max_u32_e32 v4, v29, v3
	v_med3_u32 v3, v17, v22, v3
	v_min_u32_e32 v17, v30, v23
	v_min_u32_e32 v32, v27, v15
	v_min_u32_e32 v23, v31, v17
	v_max_u32_e32 v33, v12, v14
	v_max_u32_e32 v22, v31, v17
	v_med3_u32 v15, v27, v15, v17
	v_min_u32_e32 v17, v32, v23
	v_min_u32_e32 v34, v12, v14
	v_min_u32_e32 v26, v33, v17
	v_max_u32_e32 v35, v20, v18
	v_med3_u32 v12, v12, v14, v17
	v_min_u32_e32 v14, v34, v26
	v_min_u32_e32 v36, v20, v18
	v_min_u32_e32 v26, v35, v14
	v_max_u32_e32 v37, v6, v8
	v_max_u32_e32 v23, v33, v17
	v_max_u32_e32 v17, v35, v14
	v_med3_u32 v14, v20, v18, v14
	v_min_u32_e32 v18, v36, v26
	v_min_u32_e32 v38, v6, v8
	v_min_u32_e32 v26, v37, v18
	v_max_u32_e32 v39, v16, v10
	v_med3_u32 v6, v6, v8, v18
	v_min_u32_e32 v8, v38, v26
	v_min_u32_e32 v40, v16, v10
	v_min_u32_e32 v26, v39, v8
	v_and_or_b32 v1, v1, s34, 15
	v_max_u32_e32 v20, v37, v18
	v_max_u32_e32 v18, v39, v8
	v_med3_u32 v8, v16, v10, v8
	v_min_u32_e32 v10, v40, v26
	v_max_u32_e32 v26, v25, v1
	v_min_u32_e32 v1, v25, v1
	v_max_u32_e32 v25, v2, v1
	v_min_u32_e32 v1, v2, v1
	v_max_u32_e32 v2, v4, v1
	v_min_u32_e32 v1, v4, v1
	v_max_u32_e32 v4, v3, v1
	v_min_u32_e32 v1, v3, v1
	v_max_u32_e32 v3, v22, v1
	v_min_u32_e32 v1, v22, v1
	v_max_u32_e32 v22, v15, v1
	v_min_u32_e32 v1, v15, v1
	v_max_u32_e32 v15, v23, v1
	v_min_u32_e32 v1, v23, v1
	v_max_u32_e32 v23, v12, v1
	v_min_u32_e32 v1, v12, v1
	v_max_u32_e32 v12, v17, v1
	v_min_u32_e32 v1, v17, v1
	v_max_u32_e32 v17, v14, v1
	v_min_u32_e32 v1, v14, v1
	v_max_u32_e32 v14, v20, v1
	v_min_u32_e32 v1, v20, v1
	v_max_u32_e32 v20, v6, v1
	v_min_u32_e32 v1, v6, v1
	v_max_u32_e32 v6, v18, v1
	v_min_u32_e32 v1, v18, v1
	v_max_u32_e32 v16, v41, v10
	v_max_u32_e32 v18, v8, v1
	v_min_u32_e32 v1, v8, v1
	v_min_u32_e32 v10, v41, v10
	v_max_u32_e32 v8, v16, v1
	v_min_u32_e32 v1, v16, v1
	v_max3_u32 v10, v0, v10, v1
	v_and_b32_e32 v0, 0x7fffff00, v26
	v_bitop3_b32 v1, v26, s33, v26 bitop3:0xcf
	v_cmp_gt_i32_e32 vcc, 0, v26
	v_and_b32_e32 v16, 0x7fffff00, v25
	v_bitop3_b32 v27, v25, s33, v25 bitop3:0xcf
	v_cndmask_b32_e32 v0, v1, v0, vcc
	v_cmp_gt_i32_e32 vcc, 0, v25
	v_sub_f32_e32 v1, v0, v0
	v_bitop3_b32 v28, v2, s33, v2 bitop3:0xcf
	v_cndmask_b32_e32 v16, v27, v16, vcc
	v_and_b32_e32 v27, 0x7fffff00, v2
	v_cmp_gt_i32_e32 vcc, 0, v2
	v_mul_f32_e32 v1, 0x3fb8aa3b, v1
	v_sub_f32_e32 v16, v16, v0
	v_cndmask_b32_e32 v27, v28, v27, vcc
	v_and_b32_e32 v28, 0x7fffff00, v4
	v_bitop3_b32 v29, v4, s33, v4 bitop3:0xcf
	v_cmp_gt_i32_e32 vcc, 0, v4
	v_exp_f32_e32 v1, v1
	v_mul_f32_e32 v16, 0x3fb8aa3b, v16
	v_sub_f32_e32 v27, v27, v0
	v_cndmask_b32_e32 v28, v29, v28, vcc
	v_and_b32_e32 v30, 0x7fffff00, v3
	v_bitop3_b32 v31, v3, s33, v3 bitop3:0xcf
	v_cmp_gt_i32_e32 vcc, 0, v3
	v_exp_f32_e32 v16, v16
	v_mul_f32_e32 v27, 0x3fb8aa3b, v27
	v_sub_f32_e32 v28, v28, v0
	v_cndmask_b32_e32 v30, v31, v30, vcc
	v_and_b32_e32 v31, 0x7fffff00, v22
	v_bitop3_b32 v32, v22, s33, v22 bitop3:0xcf
	v_cmp_gt_i32_e32 vcc, 0, v22
	v_exp_f32_e32 v27, v27
	v_mul_f32_e32 v28, 0x3fb8aa3b, v28
	v_sub_f32_e32 v30, v30, v0
	v_cndmask_b32_e32 v31, v32, v31, vcc
	v_and_b32_e32 v32, 0x7fffff00, v15
	v_bitop3_b32 v33, v15, s33, v15 bitop3:0xcf
	v_cmp_gt_i32_e32 vcc, 0, v15
	v_exp_f32_e32 v28, v28
	v_mul_f32_e32 v30, 0x3fb8aa3b, v30
	v_sub_f32_e32 v31, v31, v0
	v_cndmask_b32_e32 v32, v33, v32, vcc
	v_and_b32_e32 v33, 0x7fffff00, v23
	v_bitop3_b32 v34, v23, s33, v23 bitop3:0xcf
	v_cmp_gt_i32_e32 vcc, 0, v23
	v_add_f32_e32 v29, 0, v1
	v_exp_f32_e32 v30, v30
	v_mul_f32_e32 v31, 0x3fb8aa3b, v31
	v_sub_f32_e32 v32, v32, v0
	v_cndmask_b32_e32 v33, v34, v33, vcc
	v_and_b32_e32 v34, 0x7fffff00, v12
	v_bitop3_b32 v35, v12, s33, v12 bitop3:0xcf
	v_cmp_gt_i32_e32 vcc, 0, v12
	v_add_f32_e32 v29, v29, v16
	v_exp_f32_e32 v31, v31
	v_mul_f32_e32 v32, 0x3fb8aa3b, v32
	v_sub_f32_e32 v33, v33, v0
	v_cndmask_b32_e32 v34, v35, v34, vcc
	v_and_b32_e32 v35, 0x7fffff00, v17
	v_bitop3_b32 v36, v17, s33, v17 bitop3:0xcf
	v_cmp_gt_i32_e32 vcc, 0, v17
	v_add_f32_e32 v29, v29, v27
	v_exp_f32_e32 v32, v32
	v_mul_f32_e32 v33, 0x3fb8aa3b, v33
	v_sub_f32_e32 v34, v34, v0
	v_cndmask_b32_e32 v35, v36, v35, vcc
	v_and_b32_e32 v36, 0x7fffff00, v14
	v_bitop3_b32 v37, v14, s33, v14 bitop3:0xcf
	v_cmp_gt_i32_e32 vcc, 0, v14
	v_add_f32_e32 v29, v29, v28
	v_exp_f32_e32 v33, v33
	v_mul_f32_e32 v34, 0x3fb8aa3b, v34
	v_sub_f32_e32 v35, v35, v0
	v_cndmask_b32_e32 v36, v37, v36, vcc
	v_and_b32_e32 v37, 0x7fffff00, v20
	v_bitop3_b32 v38, v20, s33, v20 bitop3:0xcf
	v_cmp_gt_i32_e32 vcc, 0, v20
	v_add_f32_e32 v29, v29, v30
; #define LDS_WAIT() asm volatile("s_waitcnt lgkmcnt(0)" ::: "memory")
; __device__ __forceinline__ void peer_tile(const Args& A, LAS unsigned char* lds, int tile) {
;     ...
;             const float rden = 1.f / den;
;             LDS_WAIT();
; #pragma unroll
;             for (int k = 0; k < 16; ++k) { const unsigned code = 255u - (Lf[k] & 255u); const unsigned e = idx[code >> 4] * 128u + idx[16 + (code & 15u)];
;                 u32x2 sv; sv.x = e; sv.y = __float_as_uint(fv[k] * rden); SEL[(tl * 8 + h) * 16 + k] = sv; }
	v_exp_f32_e32 v34, v34
	v_mul_f32_e32 v35, 0x3fb8aa3b, v35
	v_sub_f32_e32 v36, v36, v0
	v_cndmask_b32_e32 v37, v38, v37, vcc
	v_and_b32_e32 v38, 0x7fffff00, v6
	v_bitop3_b32 v39, v6, s33, v6 bitop3:0xcf
	v_cmp_gt_i32_e32 vcc, 0, v6
	v_add_f32_e32 v29, v29, v31
	v_exp_f32_e32 v35, v35
	v_mul_f32_e32 v36, 0x3fb8aa3b, v36
	v_sub_f32_e32 v37, v37, v0
	v_cndmask_b32_e32 v38, v39, v38, vcc
	v_and_b32_e32 v39, 0x7fffff00, v18
	v_bitop3_b32 v40, v18, s33, v18 bitop3:0xcf
	v_cmp_gt_i32_e32 vcc, 0, v18
	v_add_f32_e32 v29, v29, v32
	v_exp_f32_e32 v36, v36
	v_mul_f32_e32 v37, 0x3fb8aa3b, v37
	v_sub_f32_e32 v38, v38, v0
	v_cndmask_b32_e32 v39, v40, v39, vcc
	v_and_b32_e32 v40, 0x7fffff00, v8
	v_bitop3_b32 v41, v8, s33, v8 bitop3:0xcf
	v_cmp_gt_i32_e32 vcc, 0, v8
	v_add_f32_e32 v29, v29, v33
	v_exp_f32_e32 v37, v37
	v_mul_f32_e32 v38, 0x3fb8aa3b, v38
	v_sub_f32_e32 v39, v39, v0
	v_cndmask_b32_e32 v40, v41, v40, vcc
	v_and_b32_e32 v41, 0x7fffff00, v10
	v_bitop3_b32 v42, v10, s33, v10 bitop3:0xcf
	v_cmp_gt_i32_e32 vcc, 0, v10
	v_add_f32_e32 v29, v29, v34
	v_exp_f32_e32 v38, v38
	v_mul_f32_e32 v39, 0x3fb8aa3b, v39
	v_sub_f32_e32 v40, v40, v0
	v_cndmask_b32_e32 v41, v42, v41, vcc
	v_add_f32_e32 v29, v29, v35
	v_exp_f32_e32 v39, v39
	v_mul_f32_e32 v40, 0x3fb8aa3b, v40
	v_sub_f32_e32 v0, v41, v0
	v_add_f32_e32 v29, v29, v36
	v_exp_f32_e32 v40, v40
	v_mul_f32_e32 v0, 0x3fb8aa3b, v0
	v_add_f32_e32 v29, v29, v37
	v_exp_f32_e32 v41, v0
	v_add_f32_e32 v0, v29, v38
	v_add_f32_e32 v0, v0, v39
	v_add_f32_e32 v0, v0, v40
	v_add_f32_e32 v0, v0, v41
	v_div_scale_f32 v29, s[0:1], v0, v0, 1.0
	v_rcp_f32_e32 v42, v29
	v_not_b32_e32 v21, v26
	v_not_b32_e32 v24, v25
	v_fma_f32 v43, -v29, v42, 1.0
	v_fmac_f32_e32 v42, v43, v42
	v_div_scale_f32 v43, vcc, 1.0, v0, 1.0
	v_mul_f32_e32 v44, v43, v42
	v_fma_f32 v45, -v29, v44, v43
	v_fmac_f32_e32 v44, v45, v42
	v_fma_f32 v29, -v29, v44, v43
	v_div_fmas_f32 v29, v29, v42, v44
	v_div_fixup_f32 v29, v29, v0, 1.0
	v_and_b32_e32 v0, 48, v19
	v_lshrrev_b32_e32 v19, 2, v21
	v_and_b32_e32 v19, 60, v19
	v_bitop3_b32 v21, v26, 15, v26 bitop3:0xc
	v_add_u32_e32 v19, v5, v19
	v_lshl_add_u32 v21, v21, 2, v5
	ds_read_b32 v19, v19
	ds_read_b32 v21, v21 offset:64
	v_lshlrev_b32_e32 v0, 3, v0
	v_add3_u32 v11, v13, v11, v0
	v_mul_f32_e32 v1, v1, v29
	v_not_b32_e32 v13, v2
	s_waitcnt lgkmcnt(0)
	v_lshl_add_u32 v0, v19, 7, v21
	ds_write_b64 v11, v[0:1]
	v_lshrrev_b32_e32 v0, 2, v24
	v_and_b32_e32 v0, 60, v0
	v_bitop3_b32 v1, v25, 15, v25 bitop3:0xc
	v_add_u32_e32 v0, v5, v0
	v_lshl_add_u32 v1, v1, 2, v5
	ds_read_b32 v0, v0
	ds_read_b32 v1, v1 offset:64
	v_cmp_eq_u32_e32 vcc, 0, v9
	s_waitcnt lgkmcnt(0)
	v_lshl_add_u32 v0, v0, 7, v1
	v_mul_f32_e32 v1, v16, v29
	ds_write_b64 v11, v[0:1] offset:8
	v_lshrrev_b32_e32 v0, 2, v13
	v_and_b32_e32 v0, 60, v0
	v_bitop3_b32 v1, v2, 15, v2 bitop3:0xc
	v_add_u32_e32 v0, v5, v0
	v_lshl_add_u32 v1, v1, 2, v5
	ds_read_b32 v0, v0
	ds_read_b32 v1, v1 offset:64
	v_not_b32_e32 v2, v4
	s_waitcnt lgkmcnt(0)
	v_lshl_add_u32 v0, v0, 7, v1
	v_mul_f32_e32 v1, v27, v29
	ds_write_b64 v11, v[0:1] offset:16
	v_lshrrev_b32_e32 v0, 2, v2
	v_and_b32_e32 v0, 60, v0
	v_bitop3_b32 v1, v4, 15, v4 bitop3:0xc
	v_add_u32_e32 v0, v5, v0
	v_lshl_add_u32 v1, v1, 2, v5
	ds_read_b32 v0, v0
	ds_read_b32 v1, v1 offset:64
	v_not_b32_e32 v2, v3
	v_mul_lo_u32 v4, v7, s36
	s_waitcnt lgkmcnt(0)
	v_lshl_add_u32 v0, v0, 7, v1
	v_mul_f32_e32 v1, v28, v29
	ds_write_b64 v11, v[0:1] offset:24
	v_lshrrev_b32_e32 v0, 2, v2
	v_and_b32_e32 v0, 60, v0
	v_bitop3_b32 v1, v3, 15, v3 bitop3:0xc
	v_add_u32_e32 v0, v5, v0
	v_lshl_add_u32 v1, v1, 2, v5
	ds_read_b32 v0, v0
	ds_read_b32 v1, v1 offset:64
	v_not_b32_e32 v2, v22
	s_waitcnt lgkmcnt(0)
	v_lshl_add_u32 v0, v0, 7, v1
	v_mul_f32_e32 v1, v30, v29
	ds_write_b64 v11, v[0:1] offset:32
	v_lshrrev_b32_e32 v0, 2, v2
	v_and_b32_e32 v0, 60, v0
	v_bitop3_b32 v1, v22, 15, v22 bitop3:0xc
	v_add_u32_e32 v0, v5, v0
	v_lshl_add_u32 v1, v1, 2, v5
	ds_read_b32 v0, v0
	ds_read_b32 v1, v1 offset:64
	v_not_b32_e32 v2, v15
	s_waitcnt lgkmcnt(0)
	v_lshl_add_u32 v0, v0, 7, v1
	v_mul_f32_e32 v1, v31, v29
	ds_write_b64 v11, v[0:1] offset:40
	v_lshrrev_b32_e32 v0, 2, v2
	v_and_b32_e32 v0, 60, v0
	v_bitop3_b32 v1, v15, 15, v15 bitop3:0xc
	v_add_u32_e32 v0, v5, v0
	v_lshl_add_u32 v1, v1, 2, v5
	ds_read_b32 v0, v0
	ds_read_b32 v1, v1 offset:64
	v_not_b32_e32 v2, v23
	s_waitcnt lgkmcnt(0)
	v_lshl_add_u32 v0, v0, 7, v1
	v_mul_f32_e32 v1, v32, v29
	ds_write_b64 v11, v[0:1] offset:48
	v_lshrrev_b32_e32 v0, 2, v2
	v_and_b32_e32 v0, 60, v0
	v_bitop3_b32 v1, v23, 15, v23 bitop3:0xc
	v_add_u32_e32 v0, v5, v0
	v_lshl_add_u32 v1, v1, 2, v5
	ds_read_b32 v0, v0
	ds_read_b32 v1, v1 offset:64
	v_not_b32_e32 v2, v12
	s_waitcnt lgkmcnt(0)
	v_lshl_add_u32 v0, v0, 7, v1
	v_mul_f32_e32 v1, v33, v29
	ds_write_b64 v11, v[0:1] offset:56
	v_lshrrev_b32_e32 v0, 2, v2
	v_and_b32_e32 v0, 60, v0
	v_bitop3_b32 v1, v12, 15, v12 bitop3:0xc
	v_add_u32_e32 v0, v5, v0
	v_lshl_add_u32 v1, v1, 2, v5
	ds_read_b32 v0, v0
	ds_read_b32 v1, v1 offset:64
	v_not_b32_e32 v2, v17
	s_waitcnt lgkmcnt(0)
	v_lshl_add_u32 v0, v0, 7, v1
	v_mul_f32_e32 v1, v34, v29
	ds_write_b64 v11, v[0:1] offset:64
	v_lshrrev_b32_e32 v0, 2, v2
	v_and_b32_e32 v0, 60, v0
	v_bitop3_b32 v1, v17, 15, v17 bitop3:0xc
	v_add_u32_e32 v0, v5, v0
	v_lshl_add_u32 v1, v1, 2, v5
	ds_read_b32 v0, v0
	ds_read_b32 v1, v1 offset:64
	v_not_b32_e32 v2, v14
	s_waitcnt lgkmcnt(0)
	v_lshl_add_u32 v0, v0, 7, v1
	v_mul_f32_e32 v1, v35, v29
	ds_write_b64 v11, v[0:1] offset:72
	v_lshrrev_b32_e32 v0, 2, v2
	v_and_b32_e32 v0, 60, v0
	v_bitop3_b32 v1, v14, 15, v14 bitop3:0xc
	v_add_u32_e32 v0, v5, v0
	v_lshl_add_u32 v1, v1, 2, v5
	ds_read_b32 v0, v0
	ds_read_b32 v1, v1 offset:64
	v_not_b32_e32 v2, v20
	s_waitcnt lgkmcnt(0)
; __device__ __forceinline__ unsigned pk2(float lo, float hi) { const f32x2 v = {lo, hi}; const bf16x2_t b = __builtin_convertvector(v, bf16x2_t); return __builtin_bit_cast(unsigned, b); }
; __device__ __forceinline__ float bflo(unsigned u) { return __uint_as_float(u << 16); }
; __device__ __forceinline__ float bfhi(unsigned u) { return __uint_as_float(u & 0xffff0000u); }
; __device__ __forceinline__ void peer_tile(const Args& A, LAS unsigned char* lds, int tile) {
;     ...
;             for (int k = 0; k < 16; ++k) { const unsigned code = 255u - (Lf[k] & 255u); const unsigned e = idx[code >> 4] * 128u + idx[16 + (code & 15u)];
;                 u32x2 sv; sv.x = e; sv.y = __float_as_uint(fv[k] * rden); SEL[(tl * 8 + h) * 16 + k] = sv; }
;         }
;     }
;     __syncthreads();
;     ...
;     const unsigned char* T8v = T8 + (size_t)16384 * 1024;
;     const bf16_t* A3 = (const bf16_t*)(A.ws + WS_A3); const float* RSq = (const float*)(A.ws + WS_RS);
;     for (int pass = 0; pass < 2; ++pass) {
;         const int tb = 8 * w + 4 * pass;
;         u32x4 xpa[4], xpb[4]; f32x2 oacc[4][8];
; #pragma unroll
;         for (int tk = 0; tk < 4; ++tk) { const size_t m = (size_t)tile * 64 + tb + tk;
;             { const u32x4 ra = *(const u32x4*)(A3 + m * 1024 + 16 * lane), rb = *(const u32x4*)(A3 + m * 1024 + 16 * lane + 8);
;               float xr_; { const f32x4 p0 = *(const f32x4*)(RSq + m * 16), p1 = *(const f32x4*)(RSq + m * 16 + 4), p2 = *(const f32x4*)(RSq + m * 16 + 8), p3 = *(const f32x4*)(RSq + m * 16 + 12);
;                 const f32x4 ps = (p0 + p1) + (p2 + p3); xr_ = rsqrtf(((ps[0] + ps[1]) + (ps[2] + ps[3])) * (1.f / 1024.f) + 1e-6f); }
;               const unsigned rr[8] = {ra.x, ra.y, ra.z, ra.w, rb.x, rb.y, rb.z, rb.w}; unsigned hh[8];
;               const float* sp = MOD + (int)(m >> 11) * 6144 + 3072 + 16 * lane;
; #pragma unroll
;               for (int q = 0; q < 8; ++q) { const f32x2 sh = *(const f32x2*)(sp + 2 * q); hh[q] = pk2(bflo(rr[q]) * xr_ + sh[0], bfhi(rr[q]) * xr_ + sh[1]); }
;               xpa[tk] = (u32x4){hh[0], hh[1], hh[2], hh[3]}; xpb[tk] = (u32x4){hh[4], hh[5], hh[6], hh[7]}; }
	v_lshl_add_u32 v0, v0, 7, v1
	v_mul_f32_e32 v1, v36, v29
	ds_write_b64 v11, v[0:1] offset:80
	v_lshrrev_b32_e32 v0, 2, v2
	v_and_b32_e32 v0, 60, v0
	v_bitop3_b32 v1, v20, 15, v20 bitop3:0xc
	v_add_u32_e32 v0, v5, v0
	v_lshl_add_u32 v1, v1, 2, v5
	ds_read_b32 v0, v0
	ds_read_b32 v1, v1 offset:64
	v_not_b32_e32 v2, v6
	s_waitcnt lgkmcnt(0)
	v_lshl_add_u32 v0, v0, 7, v1
	v_mul_f32_e32 v1, v37, v29
	ds_write_b64 v11, v[0:1] offset:88
	v_lshrrev_b32_e32 v0, 2, v2
	v_and_b32_e32 v0, 60, v0
	v_bitop3_b32 v1, v6, 15, v6 bitop3:0xc
	v_add_u32_e32 v0, v5, v0
	v_lshl_add_u32 v1, v1, 2, v5
	ds_read_b32 v0, v0
	ds_read_b32 v1, v1 offset:64
	v_not_b32_e32 v2, v18
	s_waitcnt lgkmcnt(0)
	v_lshl_add_u32 v0, v0, 7, v1
	v_mul_f32_e32 v1, v38, v29
	ds_write_b64 v11, v[0:1] offset:96
	v_lshrrev_b32_e32 v0, 2, v2
	v_and_b32_e32 v0, 60, v0
	v_bitop3_b32 v1, v18, 15, v18 bitop3:0xc
	v_add_u32_e32 v0, v5, v0
	v_lshl_add_u32 v1, v1, 2, v5
	ds_read_b32 v0, v0
	ds_read_b32 v1, v1 offset:64
	v_not_b32_e32 v2, v8
	s_waitcnt lgkmcnt(0)
	v_lshl_add_u32 v0, v0, 7, v1
	v_mul_f32_e32 v1, v39, v29
	ds_write_b64 v11, v[0:1] offset:104
	v_lshrrev_b32_e32 v0, 2, v2
	v_and_b32_e32 v0, 60, v0
	v_bitop3_b32 v1, v8, 15, v8 bitop3:0xc
	v_add_u32_e32 v0, v5, v0
	v_lshl_add_u32 v1, v1, 2, v5
	ds_read_b32 v0, v0
	ds_read_b32 v1, v1 offset:64
	v_not_b32_e32 v2, v10
	s_waitcnt lgkmcnt(0)
	v_lshl_add_u32 v0, v0, 7, v1
	v_mul_f32_e32 v1, v40, v29
	ds_write_b64 v11, v[0:1] offset:112
	v_lshrrev_b32_e32 v0, 2, v2
	v_and_b32_e32 v0, 60, v0
	v_bitop3_b32 v1, v10, 15, v10 bitop3:0xc
	v_add_u32_e32 v0, v5, v0
	v_lshl_add_u32 v1, v1, 2, v5
	ds_read_b32 v0, v0
	ds_read_b32 v1, v1 offset:64
	v_lshlrev_b32_e32 v5, 13, v7
	v_lshl_or_b32 v6, v9, 3, v5
	s_waitcnt lgkmcnt(0)
	v_lshl_add_u32 v0, v0, 7, v1
	v_mul_f32_e32 v1, v41, v29
	ds_write_b64 v11, v[0:1] offset:120
	s_waitcnt lgkmcnt(0)
	s_barrier
	s_mov_b64 exec, -1
	v_and_b32_e32 v240, 63, v214
	v_lshrrev_b32_e32 v242, 6, v214
	v_lshlrev_b32_e32 v240, 4, v240
	v_readfirstlane_b32 s16, v242
	v_lshlrev_b32_e32 v245, 1, v240
	v_lshlrev_b32_e32 v246, 2, v240
	v_lshrrev_b32_e32 v247, 4, v240
	v_and_b32_e32 v247, 48, v247
	v_mov_b32_e32 v244, 0
	v_mov_b32_e32 v243, 0x358637bd
	v_mov_b32_e32 v242, 0xbf3a00e3
	s_add_u32 s4, s50, 0x1000000
	s_addc_u32 s5, s51, 0
	s_add_u32 s6, s50, 0x2000000
	s_addc_u32 s7, s51, 0
	s_add_u32 s8, s50, 0x3000000
	s_addc_u32 s9, s51, 0
	s_add_u32 s52, s50, 0x3010000
	s_addc_u32 s53, s51, 0
	s_add_u32 s12, s50, 0xb000000
	s_addc_u32 s13, s51, 0
	s_add_u32 s14, s50, 0xd000000
	s_addc_u32 s15, s51, 0
	s_lshr_b32 s0, s2, 5
	s_mul_i32 s0, s0, 0x6000
	s_add_u32 s10, s50, s0
	s_addc_u32 s11, s51, 0
	s_add_u32 s80, s10, 0x4000
	s_addc_u32 s81, s11, 0
	s_add_u32 s82, s10, 0x6000
	s_addc_u32 s83, s11, 0
	s_mul_i32 s22, s16, 9920
	s_cmp_eq_u32 s16, 7
	s_cselect_b32 s22, 0x21000, s22
	s_mov_b32 s85, 0xffffffff
	s_mov_b32 s72, 0x3e6d3388
	s_mov_b32 s56, s4
	s_and_b32 s57, s5, 0xffff
	s_or_b32 s57, s57, 0x04000000
	s_mov_b32 s58, 16384
	s_mov_b32 s59, 0x00027000
	s_mov_b32 s60, s6
	s_and_b32 s61, s7, 0xffff
	s_or_b32 s61, s61, 0x04000000
	s_mov_b32 s62, 16384
	s_mov_b32 s63, 0x00027000
	s_lshl_b32 s76, s16, 3
	s_lshl_b32 s0, s2, 6
	s_add_i32 s77, s0, s76
	global_load_dwordx4 v[192:195], v246, s[80:81] offset:0
	global_load_dwordx4 v[196:199], v246, s[80:81] offset:16
	global_load_dwordx4 v[200:203], v246, s[80:81] offset:32
	global_load_dwordx4 v[204:207], v246, s[80:81] offset:48
	s_add_i32 s0, s77, 0
	s_lshl_b32 s1, s0, 11
	s_add_u32 s78, s12, s1
	s_addc_u32 s79, s13, 0
	global_load_dwordx4 v[128:131], v245, s[78:79]
	global_load_dwordx4 v[132:135], v245, s[78:79] offset:16
	global_load_dwordx4 v[136:139], v245, s[78:79] offset:2048
	global_load_dwordx4 v[140:143], v245, s[78:79] offset:2064
	s_lshl_b32 s1, s0, 6
	s_add_u32 s78, s14, s1
	s_addc_u32 s79, s15, 0
	global_load_dwordx4 v[144:147], v244, s[78:79] offset:0
	global_load_dwordx4 v[148:151], v244, s[78:79] offset:16
	global_load_dwordx4 v[152:155], v244, s[78:79] offset:32
	global_load_dwordx4 v[156:159], v244, s[78:79] offset:48
	global_load_dwordx4 v[160:163], v244, s[78:79] offset:64
	global_load_dwordx4 v[164:167], v244, s[78:79] offset:80
	global_load_dwordx4 v[168:171], v244, s[78:79] offset:96
	global_load_dwordx4 v[172:175], v244, s[78:79] offset:112
	s_add_i32 s0, s77, 2
	s_lshl_b32 s1, s0, 11
	s_add_u32 s78, s12, s1
	s_addc_u32 s79, s13, 0
	global_load_dwordx4 v[176:179], v245, s[78:79]
	global_load_dwordx4 v[180:183], v245, s[78:79] offset:16
	global_load_dwordx4 v[184:187], v245, s[78:79] offset:2048
	global_load_dwordx4 v[188:191], v245, s[78:79] offset:2064
	s_lshl_b32 s1, s0, 6
	s_add_u32 s78, s14, s1
	s_addc_u32 s79, s15, 0
	global_load_dwordx4 v[216:219], v244, s[78:79] offset:0
	global_load_dwordx4 v[220:223], v244, s[78:79] offset:16
	global_load_dwordx4 v[224:227], v244, s[78:79] offset:32
	global_load_dwordx4 v[228:231], v244, s[78:79] offset:48
	global_load_dwordx4 v[232:235], v244, s[78:79] offset:64
	global_load_dwordx4 v[236:239], v244, s[78:79] offset:80
	global_load_dwordx4 v[248:251], v244, s[78:79] offset:96
	global_load_dwordx4 v[252:255], v244, s[78:79] offset:112
	s_waitcnt vmcnt(12)
; __device__ __forceinline__ unsigned pk2(float lo, float hi) { const f32x2 v = {lo, hi}; const bf16x2_t b = __builtin_convertvector(v, bf16x2_t); return __builtin_bit_cast(unsigned, b); }
; __device__ __forceinline__ float bflo(unsigned u) { return __uint_as_float(u << 16); }
; __device__ __forceinline__ float bfhi(unsigned u) { return __uint_as_float(u & 0xffff0000u); }
; __device__ __forceinline__ void peer_tile(const Args& A, LAS unsigned char* lds, int tile) {
;     ...
;         for (int tk = 0; tk < 4; ++tk) { const size_t m = (size_t)tile * 64 + tb + tk;
;             { const u32x4 ra = *(const u32x4*)(A3 + m * 1024 + 16 * lane), rb = *(const u32x4*)(A3 + m * 1024 + 16 * lane + 8);
;               float xr_; { const f32x4 p0 = *(const f32x4*)(RSq + m * 16), p1 = *(const f32x4*)(RSq + m * 16 + 4), p2 = *(const f32x4*)(RSq + m * 16 + 8), p3 = *(const f32x4*)(RSq + m * 16 + 12);
;                 const f32x4 ps = (p0 + p1) + (p2 + p3); xr_ = rsqrtf(((ps[0] + ps[1]) + (ps[2] + ps[3])) * (1.f / 1024.f) + 1e-6f); }
;               const unsigned rr[8] = {ra.x, ra.y, ra.z, ra.w, rb.x, rb.y, rb.z, rb.w}; unsigned hh[8];
;               const float* sp = MOD + (int)(m >> 11) * 6144 + 3072 + 16 * lane;
; #pragma unroll
;               for (int q = 0; q < 8; ++q) { const f32x2 sh = *(const f32x2*)(sp + 2 * q); hh[q] = pk2(bflo(rr[q]) * xr_ + sh[0], bfhi(rr[q]) * xr_ + sh[1]); }
;               xpa[tk] = (u32x4){hh[0], hh[1], hh[2], hh[3]}; xpb[tk] = (u32x4){hh[4], hh[5], hh[6], hh[7]}; }
	v_pk_add_f32 v[144:145], v[144:145], v[148:149]
	v_pk_add_f32 v[146:147], v[146:147], v[150:151]
	v_pk_add_f32 v[152:153], v[152:153], v[156:157]
	v_pk_add_f32 v[154:155], v[154:155], v[158:159]
	v_pk_add_f32 v[144:145], v[144:145], v[152:153]
	v_pk_add_f32 v[146:147], v[146:147], v[154:155]
	v_add_f32_e32 v144, v144, v145
	v_add_f32_e32 v146, v146, v147
	v_add_f32_e32 v144, v144, v146
	v_fmamk_f32 v144, v144, 0x3a800000, v243
	v_rsq_f32_e32 v144, v144
	v_pk_add_f32 v[160:161], v[160:161], v[164:165]
	v_pk_add_f32 v[162:163], v[162:163], v[166:167]
	v_pk_add_f32 v[168:169], v[168:169], v[172:173]
	v_pk_add_f32 v[170:171], v[170:171], v[174:175]
	v_pk_add_f32 v[160:161], v[160:161], v[168:169]
	v_pk_add_f32 v[162:163], v[162:163], v[170:171]
	v_add_f32_e32 v160, v160, v161
	v_add_f32_e32 v162, v162, v163
	v_add_f32_e32 v160, v160, v162
	v_fmamk_f32 v160, v160, 0x3a800000, v243
	v_rsq_f32_e32 v160, v160
	v_lshlrev_b32_e32 v208, 16, v128
	v_and_b32_e32 v209, 0xffff0000, v128
	v_fma_f32 v208, v208, v144, v192
	v_fma_f32 v209, v209, v144, v193
	v_cvt_pk_bf16_f32 v210, v208, v209
	v_lshlrev_b32_e32 v0, 16, v210
	v_and_b32_e32 v1, 0xffff0000, v210
	v_lshlrev_b32_e32 v208, 16, v129
	v_and_b32_e32 v209, 0xffff0000, v129
	v_fma_f32 v208, v208, v144, v194
	v_fma_f32 v209, v209, v144, v195
	v_cvt_pk_bf16_f32 v210, v208, v209
	v_lshlrev_b32_e32 v2, 16, v210
	v_and_b32_e32 v3, 0xffff0000, v210
	v_lshlrev_b32_e32 v208, 16, v130
	v_and_b32_e32 v209, 0xffff0000, v130
	v_fma_f32 v208, v208, v144, v196
	v_fma_f32 v209, v209, v144, v197
	v_cvt_pk_bf16_f32 v210, v208, v209
	v_lshlrev_b32_e32 v4, 16, v210
	v_and_b32_e32 v5, 0xffff0000, v210
	v_lshlrev_b32_e32 v208, 16, v131
	v_and_b32_e32 v209, 0xffff0000, v131
	v_fma_f32 v208, v208, v144, v198
	v_fma_f32 v209, v209, v144, v199
	v_cvt_pk_bf16_f32 v210, v208, v209
	v_lshlrev_b32_e32 v6, 16, v210
	v_and_b32_e32 v7, 0xffff0000, v210
	v_lshlrev_b32_e32 v208, 16, v132
	v_and_b32_e32 v209, 0xffff0000, v132
	v_fma_f32 v208, v208, v144, v200
	v_fma_f32 v209, v209, v144, v201
	v_cvt_pk_bf16_f32 v210, v208, v209
	v_lshlrev_b32_e32 v8, 16, v210
	v_and_b32_e32 v9, 0xffff0000, v210
	v_lshlrev_b32_e32 v208, 16, v133
	v_and_b32_e32 v209, 0xffff0000, v133
	v_fma_f32 v208, v208, v144, v202
	v_fma_f32 v209, v209, v144, v203
	v_cvt_pk_bf16_f32 v210, v208, v209
	v_lshlrev_b32_e32 v10, 16, v210
	v_and_b32_e32 v11, 0xffff0000, v210
	v_lshlrev_b32_e32 v208, 16, v134
	v_and_b32_e32 v209, 0xffff0000, v134
	v_fma_f32 v208, v208, v144, v204
	v_fma_f32 v209, v209, v144, v205
	v_cvt_pk_bf16_f32 v210, v208, v209
	v_lshlrev_b32_e32 v12, 16, v210
	v_and_b32_e32 v13, 0xffff0000, v210
	v_lshlrev_b32_e32 v208, 16, v135
	v_and_b32_e32 v209, 0xffff0000, v135
	v_fma_f32 v208, v208, v144, v206
	v_fma_f32 v209, v209, v144, v207
	v_cvt_pk_bf16_f32 v210, v208, v209
	v_lshlrev_b32_e32 v14, 16, v210
	v_and_b32_e32 v15, 0xffff0000, v210
	v_lshlrev_b32_e32 v208, 16, v136
	v_and_b32_e32 v209, 0xffff0000, v136
	v_fma_f32 v208, v208, v160, v192
	v_fma_f32 v209, v209, v160, v193
	v_cvt_pk_bf16_f32 v210, v208, v209
	v_lshlrev_b32_e32 v16, 16, v210
	v_and_b32_e32 v17, 0xffff0000, v210
	v_lshlrev_b32_e32 v208, 16, v137
	v_and_b32_e32 v209, 0xffff0000, v137
	v_fma_f32 v208, v208, v160, v194
	v_fma_f32 v209, v209, v160, v195
	v_cvt_pk_bf16_f32 v210, v208, v209
	v_lshlrev_b32_e32 v18, 16, v210
	v_and_b32_e32 v19, 0xffff0000, v210
	v_lshlrev_b32_e32 v208, 16, v138
	v_and_b32_e32 v209, 0xffff0000, v138
	v_fma_f32 v208, v208, v160, v196
	v_fma_f32 v209, v209, v160, v197
	v_cvt_pk_bf16_f32 v210, v208, v209
	v_lshlrev_b32_e32 v20, 16, v210
	v_and_b32_e32 v21, 0xffff0000, v210
	v_lshlrev_b32_e32 v208, 16, v139
	v_and_b32_e32 v209, 0xffff0000, v139
	v_fma_f32 v208, v208, v160, v198
	v_fma_f32 v209, v209, v160, v199
	v_cvt_pk_bf16_f32 v210, v208, v209
	v_lshlrev_b32_e32 v22, 16, v210
	v_and_b32_e32 v23, 0xffff0000, v210
	v_lshlrev_b32_e32 v208, 16, v140
	v_and_b32_e32 v209, 0xffff0000, v140
	v_fma_f32 v208, v208, v160, v200
	v_fma_f32 v209, v209, v160, v201
	v_cvt_pk_bf16_f32 v210, v208, v209
	v_lshlrev_b32_e32 v24, 16, v210
	v_and_b32_e32 v25, 0xffff0000, v210
	v_lshlrev_b32_e32 v208, 16, v141
	v_and_b32_e32 v209, 0xffff0000, v141
	v_fma_f32 v208, v208, v160, v202
	v_fma_f32 v209, v209, v160, v203
	v_cvt_pk_bf16_f32 v210, v208, v209
	v_lshlrev_b32_e32 v26, 16, v210
	v_and_b32_e32 v27, 0xffff0000, v210
	v_lshlrev_b32_e32 v208, 16, v142
	v_and_b32_e32 v209, 0xffff0000, v142
	v_fma_f32 v208, v208, v160, v204
	v_fma_f32 v209, v209, v160, v205
	v_cvt_pk_bf16_f32 v210, v208, v209
	v_lshlrev_b32_e32 v28, 16, v210
	v_and_b32_e32 v29, 0xffff0000, v210
	v_lshlrev_b32_e32 v208, 16, v143
	v_and_b32_e32 v209, 0xffff0000, v143
	v_fma_f32 v208, v208, v160, v206
	v_fma_f32 v209, v209, v160, v207
	v_cvt_pk_bf16_f32 v210, v208, v209
	v_lshlrev_b32_e32 v30, 16, v210
	v_and_b32_e32 v31, 0xffff0000, v210
	s_nop 0
	s_add_i32 s0, s77, 4
	s_lshl_b32 s1, s0, 11
	s_add_u32 s78, s12, s1
	s_addc_u32 s79, s13, 0
	global_load_dwordx4 v[128:131], v245, s[78:79]
	global_load_dwordx4 v[132:135], v245, s[78:79] offset:16
	global_load_dwordx4 v[136:139], v245, s[78:79] offset:2048
	global_load_dwordx4 v[140:143], v245, s[78:79] offset:2064
	s_lshl_b32 s1, s0, 6
	s_add_u32 s78, s14, s1
	s_addc_u32 s79, s15, 0
	global_load_dwordx4 v[144:147], v244, s[78:79] offset:0
	global_load_dwordx4 v[148:151], v244, s[78:79] offset:16
	global_load_dwordx4 v[152:155], v244, s[78:79] offset:32
	global_load_dwordx4 v[156:159], v244, s[78:79] offset:48
	global_load_dwordx4 v[160:163], v244, s[78:79] offset:64
	global_load_dwordx4 v[164:167], v244, s[78:79] offset:80
	global_load_dwordx4 v[168:171], v244, s[78:79] offset:96
	global_load_dwordx4 v[172:175], v244, s[78:79] offset:112
	s_waitcnt vmcnt(12)
; __device__ __forceinline__ unsigned pk2(float lo, float hi) { const f32x2 v = {lo, hi}; const bf16x2_t b = __builtin_convertvector(v, bf16x2_t); return __builtin_bit_cast(unsigned, b); }
; __device__ __forceinline__ float bflo(unsigned u) { return __uint_as_float(u << 16); }
; __device__ __forceinline__ float bfhi(unsigned u) { return __uint_as_float(u & 0xffff0000u); }
; __device__ __forceinline__ void peer_tile(const Args& A, LAS unsigned char* lds, int tile) {
;     ...
;         for (int tk = 0; tk < 4; ++tk) { const size_t m = (size_t)tile * 64 + tb + tk;
;             { const u32x4 ra = *(const u32x4*)(A3 + m * 1024 + 16 * lane), rb = *(const u32x4*)(A3 + m * 1024 + 16 * lane + 8);
;               float xr_; { const f32x4 p0 = *(const f32x4*)(RSq + m * 16), p1 = *(const f32x4*)(RSq + m * 16 + 4), p2 = *(const f32x4*)(RSq + m * 16 + 8), p3 = *(const f32x4*)(RSq + m * 16 + 12);
;                 const f32x4 ps = (p0 + p1) + (p2 + p3); xr_ = rsqrtf(((ps[0] + ps[1]) + (ps[2] + ps[3])) * (1.f / 1024.f) + 1e-6f); }
;               const unsigned rr[8] = {ra.x, ra.y, ra.z, ra.w, rb.x, rb.y, rb.z, rb.w}; unsigned hh[8];
;               const float* sp = MOD + (int)(m >> 11) * 6144 + 3072 + 16 * lane;
; #pragma unroll
;               for (int q = 0; q < 8; ++q) { const f32x2 sh = *(const f32x2*)(sp + 2 * q); hh[q] = pk2(bflo(rr[q]) * xr_ + sh[0], bfhi(rr[q]) * xr_ + sh[1]); }
;               xpa[tk] = (u32x4){hh[0], hh[1], hh[2], hh[3]}; xpb[tk] = (u32x4){hh[4], hh[5], hh[6], hh[7]}; }
	v_pk_add_f32 v[216:217], v[216:217], v[220:221]
	v_pk_add_f32 v[218:219], v[218:219], v[222:223]
	v_pk_add_f32 v[224:225], v[224:225], v[228:229]
	v_pk_add_f32 v[226:227], v[226:227], v[230:231]
	v_pk_add_f32 v[216:217], v[216:217], v[224:225]
	v_pk_add_f32 v[218:219], v[218:219], v[226:227]
	v_add_f32_e32 v216, v216, v217
	v_add_f32_e32 v218, v218, v219
	v_add_f32_e32 v216, v216, v218
	v_fmamk_f32 v216, v216, 0x3a800000, v243
	v_rsq_f32_e32 v216, v216
	v_pk_add_f32 v[232:233], v[232:233], v[236:237]
	v_pk_add_f32 v[234:235], v[234:235], v[238:239]
	v_pk_add_f32 v[248:249], v[248:249], v[252:253]
	v_pk_add_f32 v[250:251], v[250:251], v[254:255]
	v_pk_add_f32 v[232:233], v[232:233], v[248:249]
	v_pk_add_f32 v[234:235], v[234:235], v[250:251]
	v_add_f32_e32 v232, v232, v233
	v_add_f32_e32 v234, v234, v235
	v_add_f32_e32 v232, v232, v234
	v_fmamk_f32 v232, v232, 0x3a800000, v243
	v_rsq_f32_e32 v232, v232
	v_lshlrev_b32_e32 v208, 16, v176
	v_and_b32_e32 v209, 0xffff0000, v176
	v_fma_f32 v208, v208, v216, v192
	v_fma_f32 v209, v209, v216, v193
	v_cvt_pk_bf16_f32 v210, v208, v209
	v_lshlrev_b32_e32 v32, 16, v210
	v_and_b32_e32 v33, 0xffff0000, v210
	v_lshlrev_b32_e32 v208, 16, v177
	v_and_b32_e32 v209, 0xffff0000, v177
	v_fma_f32 v208, v208, v216, v194
	v_fma_f32 v209, v209, v216, v195
	v_cvt_pk_bf16_f32 v210, v208, v209
	v_lshlrev_b32_e32 v34, 16, v210
	v_and_b32_e32 v35, 0xffff0000, v210
	v_lshlrev_b32_e32 v208, 16, v178
	v_and_b32_e32 v209, 0xffff0000, v178
	v_fma_f32 v208, v208, v216, v196
	v_fma_f32 v209, v209, v216, v197
	v_cvt_pk_bf16_f32 v210, v208, v209
	v_lshlrev_b32_e32 v36, 16, v210
	v_and_b32_e32 v37, 0xffff0000, v210
	v_lshlrev_b32_e32 v208, 16, v179
	v_and_b32_e32 v209, 0xffff0000, v179
	v_fma_f32 v208, v208, v216, v198
	v_fma_f32 v209, v209, v216, v199
	v_cvt_pk_bf16_f32 v210, v208, v209
	v_lshlrev_b32_e32 v38, 16, v210
	v_and_b32_e32 v39, 0xffff0000, v210
	v_lshlrev_b32_e32 v208, 16, v180
	v_and_b32_e32 v209, 0xffff0000, v180
	v_fma_f32 v208, v208, v216, v200
	v_fma_f32 v209, v209, v216, v201
	v_cvt_pk_bf16_f32 v210, v208, v209
	v_lshlrev_b32_e32 v40, 16, v210
	v_and_b32_e32 v41, 0xffff0000, v210
	v_lshlrev_b32_e32 v208, 16, v181
	v_and_b32_e32 v209, 0xffff0000, v181
	v_fma_f32 v208, v208, v216, v202
	v_fma_f32 v209, v209, v216, v203
	v_cvt_pk_bf16_f32 v210, v208, v209
	v_lshlrev_b32_e32 v42, 16, v210
	v_and_b32_e32 v43, 0xffff0000, v210
	v_lshlrev_b32_e32 v208, 16, v182
	v_and_b32_e32 v209, 0xffff0000, v182
	v_fma_f32 v208, v208, v216, v204
	v_fma_f32 v209, v209, v216, v205
	v_cvt_pk_bf16_f32 v210, v208, v209
	v_lshlrev_b32_e32 v44, 16, v210
	v_and_b32_e32 v45, 0xffff0000, v210
	v_lshlrev_b32_e32 v208, 16, v183
	v_and_b32_e32 v209, 0xffff0000, v183
	v_fma_f32 v208, v208, v216, v206
	v_fma_f32 v209, v209, v216, v207
	v_cvt_pk_bf16_f32 v210, v208, v209
	v_lshlrev_b32_e32 v46, 16, v210
	v_and_b32_e32 v47, 0xffff0000, v210
	v_lshlrev_b32_e32 v208, 16, v184
	v_and_b32_e32 v209, 0xffff0000, v184
	v_fma_f32 v208, v208, v232, v192
	v_fma_f32 v209, v209, v232, v193
	v_cvt_pk_bf16_f32 v210, v208, v209
	v_lshlrev_b32_e32 v48, 16, v210
	v_and_b32_e32 v49, 0xffff0000, v210
	v_lshlrev_b32_e32 v208, 16, v185
	v_and_b32_e32 v209, 0xffff0000, v185
	v_fma_f32 v208, v208, v232, v194
	v_fma_f32 v209, v209, v232, v195
	v_cvt_pk_bf16_f32 v210, v208, v209
	v_lshlrev_b32_e32 v50, 16, v210
	v_and_b32_e32 v51, 0xffff0000, v210
	v_lshlrev_b32_e32 v208, 16, v186
	v_and_b32_e32 v209, 0xffff0000, v186
	v_fma_f32 v208, v208, v232, v196
	v_fma_f32 v209, v209, v232, v197
	v_cvt_pk_bf16_f32 v210, v208, v209
	v_lshlrev_b32_e32 v52, 16, v210
	v_and_b32_e32 v53, 0xffff0000, v210
	v_lshlrev_b32_e32 v208, 16, v187
	v_and_b32_e32 v209, 0xffff0000, v187
	v_fma_f32 v208, v208, v232, v198
	v_fma_f32 v209, v209, v232, v199
	v_cvt_pk_bf16_f32 v210, v208, v209
	v_lshlrev_b32_e32 v54, 16, v210
	v_and_b32_e32 v55, 0xffff0000, v210
	v_lshlrev_b32_e32 v208, 16, v188
	v_and_b32_e32 v209, 0xffff0000, v188
	v_fma_f32 v208, v208, v232, v200
	v_fma_f32 v209, v209, v232, v201
	v_cvt_pk_bf16_f32 v210, v208, v209
	v_lshlrev_b32_e32 v56, 16, v210
	v_and_b32_e32 v57, 0xffff0000, v210
	v_lshlrev_b32_e32 v208, 16, v189
	v_and_b32_e32 v209, 0xffff0000, v189
	v_fma_f32 v208, v208, v232, v202
	v_fma_f32 v209, v209, v232, v203
	v_cvt_pk_bf16_f32 v210, v208, v209
	v_lshlrev_b32_e32 v58, 16, v210
	v_and_b32_e32 v59, 0xffff0000, v210
	v_lshlrev_b32_e32 v208, 16, v190
	v_and_b32_e32 v209, 0xffff0000, v190
	v_fma_f32 v208, v208, v232, v204
	v_fma_f32 v209, v209, v232, v205
	v_cvt_pk_bf16_f32 v210, v208, v209
	v_lshlrev_b32_e32 v60, 16, v210
	v_and_b32_e32 v61, 0xffff0000, v210
	v_lshlrev_b32_e32 v208, 16, v191
	v_and_b32_e32 v209, 0xffff0000, v191
	v_fma_f32 v208, v208, v232, v206
	v_fma_f32 v209, v209, v232, v207
	v_cvt_pk_bf16_f32 v210, v208, v209
	v_lshlrev_b32_e32 v62, 16, v210
	v_and_b32_e32 v63, 0xffff0000, v210
	s_nop 0
	s_add_i32 s0, s77, 6
	s_lshl_b32 s1, s0, 11
	s_add_u32 s78, s12, s1
	s_addc_u32 s79, s13, 0
	global_load_dwordx4 v[176:179], v245, s[78:79]
	global_load_dwordx4 v[180:183], v245, s[78:79] offset:16
	global_load_dwordx4 v[184:187], v245, s[78:79] offset:2048
	global_load_dwordx4 v[188:191], v245, s[78:79] offset:2064
	s_lshl_b32 s1, s0, 6
	s_add_u32 s78, s14, s1
	s_addc_u32 s79, s15, 0
	global_load_dwordx4 v[216:219], v244, s[78:79] offset:0
	global_load_dwordx4 v[220:223], v244, s[78:79] offset:16
	global_load_dwordx4 v[224:227], v244, s[78:79] offset:32
	global_load_dwordx4 v[228:231], v244, s[78:79] offset:48
	global_load_dwordx4 v[232:235], v244, s[78:79] offset:64
	global_load_dwordx4 v[236:239], v244, s[78:79] offset:80
	global_load_dwordx4 v[248:251], v244, s[78:79] offset:96
	global_load_dwordx4 v[252:255], v244, s[78:79] offset:112
	s_waitcnt vmcnt(12)
; __device__ __forceinline__ unsigned pk2(float lo, float hi) { const f32x2 v = {lo, hi}; const bf16x2_t b = __builtin_convertvector(v, bf16x2_t); return __builtin_bit_cast(unsigned, b); }
; __device__ __forceinline__ float bflo(unsigned u) { return __uint_as_float(u << 16); }
; __device__ __forceinline__ float bfhi(unsigned u) { return __uint_as_float(u & 0xffff0000u); }
; __device__ __forceinline__ void peer_tile(const Args& A, LAS unsigned char* lds, int tile) {
;     ...
;         for (int tk = 0; tk < 4; ++tk) { const size_t m = (size_t)tile * 64 + tb + tk;
;             { const u32x4 ra = *(const u32x4*)(A3 + m * 1024 + 16 * lane), rb = *(const u32x4*)(A3 + m * 1024 + 16 * lane + 8);
;               float xr_; { const f32x4 p0 = *(const f32x4*)(RSq + m * 16), p1 = *(const f32x4*)(RSq + m * 16 + 4), p2 = *(const f32x4*)(RSq + m * 16 + 8), p3 = *(const f32x4*)(RSq + m * 16 + 12);
;                 const f32x4 ps = (p0 + p1) + (p2 + p3); xr_ = rsqrtf(((ps[0] + ps[1]) + (ps[2] + ps[3])) * (1.f / 1024.f) + 1e-6f); }
;               const unsigned rr[8] = {ra.x, ra.y, ra.z, ra.w, rb.x, rb.y, rb.z, rb.w}; unsigned hh[8];
;               const float* sp = MOD + (int)(m >> 11) * 6144 + 3072 + 16 * lane;
; #pragma unroll
;               for (int q = 0; q < 8; ++q) { const f32x2 sh = *(const f32x2*)(sp + 2 * q); hh[q] = pk2(bflo(rr[q]) * xr_ + sh[0], bfhi(rr[q]) * xr_ + sh[1]); }
;               xpa[tk] = (u32x4){hh[0], hh[1], hh[2], hh[3]}; xpb[tk] = (u32x4){hh[4], hh[5], hh[6], hh[7]}; }
	v_pk_add_f32 v[144:145], v[144:145], v[148:149]
	v_pk_add_f32 v[146:147], v[146:147], v[150:151]
	v_pk_add_f32 v[152:153], v[152:153], v[156:157]
	v_pk_add_f32 v[154:155], v[154:155], v[158:159]
	v_pk_add_f32 v[144:145], v[144:145], v[152:153]
	v_pk_add_f32 v[146:147], v[146:147], v[154:155]
	v_add_f32_e32 v144, v144, v145
	v_add_f32_e32 v146, v146, v147
	v_add_f32_e32 v144, v144, v146
	v_fmamk_f32 v144, v144, 0x3a800000, v243
	v_rsq_f32_e32 v144, v144
	v_pk_add_f32 v[160:161], v[160:161], v[164:165]
	v_pk_add_f32 v[162:163], v[162:163], v[166:167]
	v_pk_add_f32 v[168:169], v[168:169], v[172:173]
	v_pk_add_f32 v[170:171], v[170:171], v[174:175]
	v_pk_add_f32 v[160:161], v[160:161], v[168:169]
	v_pk_add_f32 v[162:163], v[162:163], v[170:171]
	v_add_f32_e32 v160, v160, v161
	v_add_f32_e32 v162, v162, v163
	v_add_f32_e32 v160, v160, v162
	v_fmamk_f32 v160, v160, 0x3a800000, v243
	v_rsq_f32_e32 v160, v160
	v_lshlrev_b32_e32 v208, 16, v128
	v_and_b32_e32 v209, 0xffff0000, v128
	v_fma_f32 v208, v208, v144, v192
	v_fma_f32 v209, v209, v144, v193
	v_cvt_pk_bf16_f32 v210, v208, v209
	v_lshlrev_b32_e32 v64, 16, v210
	v_and_b32_e32 v65, 0xffff0000, v210
	v_lshlrev_b32_e32 v208, 16, v129
	v_and_b32_e32 v209, 0xffff0000, v129
	v_fma_f32 v208, v208, v144, v194
	v_fma_f32 v209, v209, v144, v195
	v_cvt_pk_bf16_f32 v210, v208, v209
	v_lshlrev_b32_e32 v66, 16, v210
	v_and_b32_e32 v67, 0xffff0000, v210
	v_lshlrev_b32_e32 v208, 16, v130
	v_and_b32_e32 v209, 0xffff0000, v130
	v_fma_f32 v208, v208, v144, v196
	v_fma_f32 v209, v209, v144, v197
	v_cvt_pk_bf16_f32 v210, v208, v209
	v_lshlrev_b32_e32 v68, 16, v210
	v_and_b32_e32 v69, 0xffff0000, v210
	v_lshlrev_b32_e32 v208, 16, v131
	v_and_b32_e32 v209, 0xffff0000, v131
	v_fma_f32 v208, v208, v144, v198
	v_fma_f32 v209, v209, v144, v199
	v_cvt_pk_bf16_f32 v210, v208, v209
	v_lshlrev_b32_e32 v70, 16, v210
	v_and_b32_e32 v71, 0xffff0000, v210
	v_lshlrev_b32_e32 v208, 16, v132
	v_and_b32_e32 v209, 0xffff0000, v132
	v_fma_f32 v208, v208, v144, v200
	v_fma_f32 v209, v209, v144, v201
	v_cvt_pk_bf16_f32 v210, v208, v209
	v_lshlrev_b32_e32 v72, 16, v210
	v_and_b32_e32 v73, 0xffff0000, v210
	v_lshlrev_b32_e32 v208, 16, v133
	v_and_b32_e32 v209, 0xffff0000, v133
	v_fma_f32 v208, v208, v144, v202
	v_fma_f32 v209, v209, v144, v203
	v_cvt_pk_bf16_f32 v210, v208, v209
	v_lshlrev_b32_e32 v74, 16, v210
	v_and_b32_e32 v75, 0xffff0000, v210
	v_lshlrev_b32_e32 v208, 16, v134
	v_and_b32_e32 v209, 0xffff0000, v134
	v_fma_f32 v208, v208, v144, v204
	v_fma_f32 v209, v209, v144, v205
	v_cvt_pk_bf16_f32 v210, v208, v209
	v_lshlrev_b32_e32 v76, 16, v210
	v_and_b32_e32 v77, 0xffff0000, v210
	v_lshlrev_b32_e32 v208, 16, v135
	v_and_b32_e32 v209, 0xffff0000, v135
	v_fma_f32 v208, v208, v144, v206
	v_fma_f32 v209, v209, v144, v207
	v_cvt_pk_bf16_f32 v210, v208, v209
	v_lshlrev_b32_e32 v78, 16, v210
	v_and_b32_e32 v79, 0xffff0000, v210
	v_lshlrev_b32_e32 v208, 16, v136
	v_and_b32_e32 v209, 0xffff0000, v136
	v_fma_f32 v208, v208, v160, v192
	v_fma_f32 v209, v209, v160, v193
	v_cvt_pk_bf16_f32 v210, v208, v209
	v_lshlrev_b32_e32 v80, 16, v210
	v_and_b32_e32 v81, 0xffff0000, v210
	v_lshlrev_b32_e32 v208, 16, v137
	v_and_b32_e32 v209, 0xffff0000, v137
	v_fma_f32 v208, v208, v160, v194
	v_fma_f32 v209, v209, v160, v195
	v_cvt_pk_bf16_f32 v210, v208, v209
	v_lshlrev_b32_e32 v82, 16, v210
	v_and_b32_e32 v83, 0xffff0000, v210
	v_lshlrev_b32_e32 v208, 16, v138
	v_and_b32_e32 v209, 0xffff0000, v138
	v_fma_f32 v208, v208, v160, v196
	v_fma_f32 v209, v209, v160, v197
	v_cvt_pk_bf16_f32 v210, v208, v209
	v_lshlrev_b32_e32 v84, 16, v210
	v_and_b32_e32 v85, 0xffff0000, v210
	v_lshlrev_b32_e32 v208, 16, v139
	v_and_b32_e32 v209, 0xffff0000, v139
	v_fma_f32 v208, v208, v160, v198
	v_fma_f32 v209, v209, v160, v199
	v_cvt_pk_bf16_f32 v210, v208, v209
	v_lshlrev_b32_e32 v86, 16, v210
	v_and_b32_e32 v87, 0xffff0000, v210
	v_lshlrev_b32_e32 v208, 16, v140
	v_and_b32_e32 v209, 0xffff0000, v140
	v_fma_f32 v208, v208, v160, v200
	v_fma_f32 v209, v209, v160, v201
	v_cvt_pk_bf16_f32 v210, v208, v209
	v_lshlrev_b32_e32 v88, 16, v210
	v_and_b32_e32 v89, 0xffff0000, v210
	v_lshlrev_b32_e32 v208, 16, v141
	v_and_b32_e32 v209, 0xffff0000, v141
	v_fma_f32 v208, v208, v160, v202
	v_fma_f32 v209, v209, v160, v203
	v_cvt_pk_bf16_f32 v210, v208, v209
	v_lshlrev_b32_e32 v90, 16, v210
	v_and_b32_e32 v91, 0xffff0000, v210
	v_lshlrev_b32_e32 v208, 16, v142
	v_and_b32_e32 v209, 0xffff0000, v142
	v_fma_f32 v208, v208, v160, v204
	v_fma_f32 v209, v209, v160, v205
	v_cvt_pk_bf16_f32 v210, v208, v209
	v_lshlrev_b32_e32 v92, 16, v210
	v_and_b32_e32 v93, 0xffff0000, v210
	v_lshlrev_b32_e32 v208, 16, v143
	v_and_b32_e32 v209, 0xffff0000, v143
	v_fma_f32 v208, v208, v160, v206
	v_fma_f32 v209, v209, v160, v207
	v_cvt_pk_bf16_f32 v210, v208, v209
	v_lshlrev_b32_e32 v94, 16, v210
	v_and_b32_e32 v95, 0xffff0000, v210
	s_nop 0
	s_waitcnt vmcnt(0)
; __device__ __forceinline__ unsigned pk2(float lo, float hi) { const f32x2 v = {lo, hi}; const bf16x2_t b = __builtin_convertvector(v, bf16x2_t); return __builtin_bit_cast(unsigned, b); }
; __device__ __forceinline__ float bflo(unsigned u) { return __uint_as_float(u << 16); }
; __device__ __forceinline__ float bfhi(unsigned u) { return __uint_as_float(u & 0xffff0000u); }
; __device__ __forceinline__ void peer_tile(const Args& A, LAS unsigned char* lds, int tile) {
;     ...
;     for (int ti = 0; ti < 8; ++ti) {
;         const int tl = 8 * w + ti;
;         const u32x2 e0 = SEL[tl * 128 + lane], e1 = SEL[tl * 128 + 64 + lane];
;         const int p0 = (int)(e0.x >> 10), p1 = (int)(e1.x >> 10);
;         int off = 0;
;         for (int p = 0; p < 16; ++p) {
;     ...
;         for (int tk = 0; tk < 4; ++tk) { const size_t m = (size_t)tile * 64 + tb + tk;
;             { const u32x4 ra = *(const u32x4*)(A3 + m * 1024 + 16 * lane), rb = *(const u32x4*)(A3 + m * 1024 + 16 * lane + 8);
;               float xr_; { const f32x4 p0 = *(const f32x4*)(RSq + m * 16), p1 = *(const f32x4*)(RSq + m * 16 + 4), p2 = *(const f32x4*)(RSq + m * 16 + 8), p3 = *(const f32x4*)(RSq + m * 16 + 12);
;                 const f32x4 ps = (p0 + p1) + (p2 + p3); xr_ = rsqrtf(((ps[0] + ps[1]) + (ps[2] + ps[3])) * (1.f / 1024.f) + 1e-6f); }
;               const unsigned rr[8] = {ra.x, ra.y, ra.z, ra.w, rb.x, rb.y, rb.z, rb.w}; unsigned hh[8];
;               const float* sp = MOD + (int)(m >> 11) * 6144 + 3072 + 16 * lane;
; #pragma unroll
;               for (int q = 0; q < 8; ++q) { const f32x2 sh = *(const f32x2*)(sp + 2 * q); hh[q] = pk2(bflo(rr[q]) * xr_ + sh[0], bfhi(rr[q]) * xr_ + sh[1]); }
;               xpa[tk] = (u32x4){hh[0], hh[1], hh[2], hh[3]}; xpb[tk] = (u32x4){hh[4], hh[5], hh[6], hh[7]}; }
	v_pk_add_f32 v[216:217], v[216:217], v[220:221]
	v_pk_add_f32 v[218:219], v[218:219], v[222:223]
	v_pk_add_f32 v[224:225], v[224:225], v[228:229]
	v_pk_add_f32 v[226:227], v[226:227], v[230:231]
	v_pk_add_f32 v[216:217], v[216:217], v[224:225]
	v_pk_add_f32 v[218:219], v[218:219], v[226:227]
	v_add_f32_e32 v216, v216, v217
	v_add_f32_e32 v218, v218, v219
	v_add_f32_e32 v216, v216, v218
	v_fmamk_f32 v216, v216, 0x3a800000, v243
	v_rsq_f32_e32 v216, v216
	v_pk_add_f32 v[232:233], v[232:233], v[236:237]
	v_pk_add_f32 v[234:235], v[234:235], v[238:239]
	v_pk_add_f32 v[248:249], v[248:249], v[252:253]
	v_pk_add_f32 v[250:251], v[250:251], v[254:255]
	v_pk_add_f32 v[232:233], v[232:233], v[248:249]
	v_pk_add_f32 v[234:235], v[234:235], v[250:251]
	v_add_f32_e32 v232, v232, v233
	v_add_f32_e32 v234, v234, v235
	v_add_f32_e32 v232, v232, v234
	v_fmamk_f32 v232, v232, 0x3a800000, v243
	v_rsq_f32_e32 v232, v232
	v_lshlrev_b32_e32 v208, 16, v176
	v_and_b32_e32 v209, 0xffff0000, v176
	v_fma_f32 v208, v208, v216, v192
	v_fma_f32 v209, v209, v216, v193
	v_cvt_pk_bf16_f32 v210, v208, v209
	v_lshlrev_b32_e32 v96, 16, v210
	v_and_b32_e32 v97, 0xffff0000, v210
	v_lshlrev_b32_e32 v208, 16, v177
	v_and_b32_e32 v209, 0xffff0000, v177
	v_fma_f32 v208, v208, v216, v194
	v_fma_f32 v209, v209, v216, v195
	v_cvt_pk_bf16_f32 v210, v208, v209
	v_lshlrev_b32_e32 v98, 16, v210
	v_and_b32_e32 v99, 0xffff0000, v210
	v_lshlrev_b32_e32 v208, 16, v178
	v_and_b32_e32 v209, 0xffff0000, v178
	v_fma_f32 v208, v208, v216, v196
	v_fma_f32 v209, v209, v216, v197
	v_cvt_pk_bf16_f32 v210, v208, v209
	v_lshlrev_b32_e32 v100, 16, v210
	v_and_b32_e32 v101, 0xffff0000, v210
	v_lshlrev_b32_e32 v208, 16, v179
	v_and_b32_e32 v209, 0xffff0000, v179
	v_fma_f32 v208, v208, v216, v198
	v_fma_f32 v209, v209, v216, v199
	v_cvt_pk_bf16_f32 v210, v208, v209
	v_lshlrev_b32_e32 v102, 16, v210
	v_and_b32_e32 v103, 0xffff0000, v210
	v_lshlrev_b32_e32 v208, 16, v180
	v_and_b32_e32 v209, 0xffff0000, v180
	v_fma_f32 v208, v208, v216, v200
	v_fma_f32 v209, v209, v216, v201
	v_cvt_pk_bf16_f32 v210, v208, v209
	v_lshlrev_b32_e32 v104, 16, v210
	v_and_b32_e32 v105, 0xffff0000, v210
	v_lshlrev_b32_e32 v208, 16, v181
	v_and_b32_e32 v209, 0xffff0000, v181
	v_fma_f32 v208, v208, v216, v202
	v_fma_f32 v209, v209, v216, v203
	v_cvt_pk_bf16_f32 v210, v208, v209
	v_lshlrev_b32_e32 v106, 16, v210
	v_and_b32_e32 v107, 0xffff0000, v210
	v_lshlrev_b32_e32 v208, 16, v182
	v_and_b32_e32 v209, 0xffff0000, v182
	v_fma_f32 v208, v208, v216, v204
	v_fma_f32 v209, v209, v216, v205
	v_cvt_pk_bf16_f32 v210, v208, v209
	v_lshlrev_b32_e32 v108, 16, v210
	v_and_b32_e32 v109, 0xffff0000, v210
	v_lshlrev_b32_e32 v208, 16, v183
	v_and_b32_e32 v209, 0xffff0000, v183
	v_fma_f32 v208, v208, v216, v206
	v_fma_f32 v209, v209, v216, v207
	v_cvt_pk_bf16_f32 v210, v208, v209
	v_lshlrev_b32_e32 v110, 16, v210
	v_and_b32_e32 v111, 0xffff0000, v210
	v_lshlrev_b32_e32 v208, 16, v184
	v_and_b32_e32 v209, 0xffff0000, v184
	v_fma_f32 v208, v208, v232, v192
	v_fma_f32 v209, v209, v232, v193
	v_cvt_pk_bf16_f32 v210, v208, v209
	v_lshlrev_b32_e32 v112, 16, v210
	v_and_b32_e32 v113, 0xffff0000, v210
	v_lshlrev_b32_e32 v208, 16, v185
	v_and_b32_e32 v209, 0xffff0000, v185
	v_fma_f32 v208, v208, v232, v194
	v_fma_f32 v209, v209, v232, v195
	v_cvt_pk_bf16_f32 v210, v208, v209
	v_lshlrev_b32_e32 v114, 16, v210
	v_and_b32_e32 v115, 0xffff0000, v210
	v_lshlrev_b32_e32 v208, 16, v186
	v_and_b32_e32 v209, 0xffff0000, v186
	v_fma_f32 v208, v208, v232, v196
	v_fma_f32 v209, v209, v232, v197
	v_cvt_pk_bf16_f32 v210, v208, v209
	v_lshlrev_b32_e32 v116, 16, v210
	v_and_b32_e32 v117, 0xffff0000, v210
	v_lshlrev_b32_e32 v208, 16, v187
	v_and_b32_e32 v209, 0xffff0000, v187
	v_fma_f32 v208, v208, v232, v198
	v_fma_f32 v209, v209, v232, v199
	v_cvt_pk_bf16_f32 v210, v208, v209
	v_lshlrev_b32_e32 v118, 16, v210
	v_and_b32_e32 v119, 0xffff0000, v210
	v_lshlrev_b32_e32 v208, 16, v188
	v_and_b32_e32 v209, 0xffff0000, v188
	v_fma_f32 v208, v208, v232, v200
	v_fma_f32 v209, v209, v232, v201
	v_cvt_pk_bf16_f32 v210, v208, v209
	v_lshlrev_b32_e32 v120, 16, v210
	v_and_b32_e32 v121, 0xffff0000, v210
	v_lshlrev_b32_e32 v208, 16, v189
	v_and_b32_e32 v209, 0xffff0000, v189
	v_fma_f32 v208, v208, v232, v202
	v_fma_f32 v209, v209, v232, v203
	v_cvt_pk_bf16_f32 v210, v208, v209
	v_lshlrev_b32_e32 v122, 16, v210
	v_and_b32_e32 v123, 0xffff0000, v210
	v_lshlrev_b32_e32 v208, 16, v190
	v_and_b32_e32 v209, 0xffff0000, v190
	v_fma_f32 v208, v208, v232, v204
	v_fma_f32 v209, v209, v232, v205
	v_cvt_pk_bf16_f32 v210, v208, v209
	v_lshlrev_b32_e32 v124, 16, v210
	v_and_b32_e32 v125, 0xffff0000, v210
	v_lshlrev_b32_e32 v208, 16, v191
	v_and_b32_e32 v209, 0xffff0000, v191
	v_fma_f32 v208, v208, v232, v206
	v_fma_f32 v209, v209, v232, v207
	v_cvt_pk_bf16_f32 v210, v208, v209
	v_lshlrev_b32_e32 v126, 16, v210
	v_and_b32_e32 v127, 0xffff0000, v210
	s_nop 0
	v_mov_b32_e32 v224, 0x7fffffff
	v_mov_b32_e32 v225, 0x7fffffff
	v_mov_b32_e32 v226, 0x7fffffff
	v_mov_b32_e32 v227, 0x7fffffff
	v_mov_b32_e32 v228, 0
	v_mov_b32_e32 v229, 0
	v_mov_b32_e32 v230, 0
	v_mov_b32_e32 v231, 0
	v_add_u32_e32 v232, s22, v240
	ds_write_b128 v232, v[224:227] offset:0
	ds_write_b128 v232, v[228:231] offset:4992
	ds_write_b128 v232, v[224:227] offset:1024
	ds_write_b128 v232, v[228:231] offset:6016
	ds_write_b128 v232, v[224:227] offset:2048
	ds_write_b128 v232, v[228:231] offset:7040
	ds_write_b128 v232, v[224:227] offset:3072
	ds_write_b128 v232, v[228:231] offset:8064
	s_mov_b32 exec_hi, 0x00ffffff
	ds_write_b128 v232, v[224:227] offset:4096
	s_mov_b32 exec_hi, 0x000fffff
	ds_write_b128 v232, v[228:231] offset:9088
	s_mov_b64 exec, -1
	v_lshrrev_b32_e32 v221, 2, v240
	v_add_u32_e32 v221, s22, v221
	ds_write_b32 v221, v228 offset:4224
	v_lshrrev_b32_e32 v233, 1, v240
	s_lshl_b32 s0, s76, 10
	s_add_i32 s0, s0, 0x11000
	v_add_u32_e32 v233, s0, v233
	ds_read_b64 v[128:129], v233 offset:0
	ds_read_b64 v[130:131], v233 offset:512
	ds_read_b64 v[132:133], v233 offset:1024
	ds_read_b64 v[134:135], v233 offset:1536
	ds_read_b64 v[136:137], v233 offset:2048
	ds_read_b64 v[138:139], v233 offset:2560
	ds_read_b64 v[140:141], v233 offset:3072
	ds_read_b64 v[142:143], v233 offset:3584
	ds_read_b64 v[144:145], v233 offset:4096
	ds_read_b64 v[146:147], v233 offset:4608
	ds_read_b64 v[148:149], v233 offset:5120
	ds_read_b64 v[150:151], v233 offset:5632
	ds_read_b64 v[152:153], v233 offset:6144
	ds_read_b64 v[154:155], v233 offset:6656
	ds_read_b64 v[156:157], v233 offset:7168
	ds_read_b64 v[158:159], v233 offset:7680
	v_mov_b32_e32 v220, 1
	v_lshrrev_b32_e32 v200, 4, v240
	v_lshrrev_b32_e32 v201, 3, v200
	v_and_b32_e32 v200, 7, v200
	s_add_i32 s3, s22, 4224
	s_and_b32 s1, s32, 7
	s_waitcnt lgkmcnt(0)
; __device__ __forceinline__ void peer_tile(const Args& A, LAS unsigned char* lds, int tile) {
;     ...
;     for (int ti = 0; ti < 8; ++ti) {
;         const int tl = 8 * w + ti;
;         const u32x2 e0 = SEL[tl * 128 + lane], e1 = SEL[tl * 128 + 64 + lane];
;         const int p0 = (int)(e0.x >> 10), p1 = (int)(e1.x >> 10);
;         int off = 0;
;         for (int p = 0; p < 16; ++p) {
;             const unsigned long long m0 = __ballot(p0 == p), m1 = __ballot(p1 == p);
;             const int c0 = __popcll(m0), c1 = __popcll(m1);
;             const int r0 = __builtin_amdgcn_mbcnt_hi((unsigned)(m0 >> 32), __builtin_amdgcn_mbcnt_lo((unsigned)m0, 0u));
;             const int r1 = __builtin_amdgcn_mbcnt_hi((unsigned)(m1 >> 32), __builtin_amdgcn_mbcnt_lo((unsigned)m1, 0u));
;             if (p0 == p) SORT[tl * 128 + off + r0] = e0;
;             if (p1 == p) SORT[tl * 128 + off + c0 + r1] = e1;
;             if (lane == 0) OFFS[tl * 17 + p] = off;
;             off += c0 + c1;
;         }
;         if (lane == 0) OFFS[tl * 17 + 16] = off;
;     }
	v_lshrrev_b32_e32 v160, 11, v128
	v_subrev_u32_e32 v160, s1, v160
	v_and_b32_e32 v160, 7, v160
	v_lshl_add_u32 v176, v160, 2, s3
	v_lshrrev_b32_e32 v161, 11, v130
	v_subrev_u32_e32 v161, s1, v161
	v_and_b32_e32 v161, 7, v161
	v_lshl_add_u32 v177, v161, 2, s3
	v_lshrrev_b32_e32 v162, 11, v132
	v_subrev_u32_e32 v162, s1, v162
	v_and_b32_e32 v162, 7, v162
	v_lshl_add_u32 v178, v162, 2, s3
	v_lshrrev_b32_e32 v163, 11, v134
	v_subrev_u32_e32 v163, s1, v163
	v_and_b32_e32 v163, 7, v163
	v_lshl_add_u32 v179, v163, 2, s3
	v_lshrrev_b32_e32 v164, 11, v136
	v_subrev_u32_e32 v164, s1, v164
	v_and_b32_e32 v164, 7, v164
	v_lshl_add_u32 v180, v164, 2, s3
	v_lshrrev_b32_e32 v165, 11, v138
	v_subrev_u32_e32 v165, s1, v165
	v_and_b32_e32 v165, 7, v165
	v_lshl_add_u32 v181, v165, 2, s3
	v_lshrrev_b32_e32 v166, 11, v140
	v_subrev_u32_e32 v166, s1, v166
	v_and_b32_e32 v166, 7, v166
	v_lshl_add_u32 v182, v166, 2, s3
	v_lshrrev_b32_e32 v167, 11, v142
	v_subrev_u32_e32 v167, s1, v167
	v_and_b32_e32 v167, 7, v167
	v_lshl_add_u32 v183, v167, 2, s3
	v_lshrrev_b32_e32 v168, 11, v144
	v_subrev_u32_e32 v168, s1, v168
	v_and_b32_e32 v168, 7, v168
	v_lshl_add_u32 v184, v168, 2, s3
	v_lshrrev_b32_e32 v169, 11, v146
	v_subrev_u32_e32 v169, s1, v169
	v_and_b32_e32 v169, 7, v169
	v_lshl_add_u32 v185, v169, 2, s3
	v_lshrrev_b32_e32 v170, 11, v148
	v_subrev_u32_e32 v170, s1, v170
	v_and_b32_e32 v170, 7, v170
	v_lshl_add_u32 v186, v170, 2, s3
	v_lshrrev_b32_e32 v171, 11, v150
	v_subrev_u32_e32 v171, s1, v171
	v_and_b32_e32 v171, 7, v171
	v_lshl_add_u32 v187, v171, 2, s3
	v_lshrrev_b32_e32 v172, 11, v152
	v_subrev_u32_e32 v172, s1, v172
	v_and_b32_e32 v172, 7, v172
	v_lshl_add_u32 v188, v172, 2, s3
	v_lshrrev_b32_e32 v173, 11, v154
	v_subrev_u32_e32 v173, s1, v173
	v_and_b32_e32 v173, 7, v173
	v_lshl_add_u32 v189, v173, 2, s3
	v_lshrrev_b32_e32 v174, 11, v156
	v_subrev_u32_e32 v174, s1, v174
	v_and_b32_e32 v174, 7, v174
	v_lshl_add_u32 v190, v174, 2, s3
	v_lshrrev_b32_e32 v175, 11, v158
	v_subrev_u32_e32 v175, s1, v175
	v_and_b32_e32 v175, 7, v175
	v_lshl_add_u32 v191, v175, 2, s3
	ds_add_rtn_u32 v176, v176, v220 offset:0
	ds_add_rtn_u32 v177, v177, v220 offset:0
	ds_add_rtn_u32 v178, v178, v220 offset:32
	ds_add_rtn_u32 v179, v179, v220 offset:32
	ds_add_rtn_u32 v180, v180, v220 offset:64
	ds_add_rtn_u32 v181, v181, v220 offset:64
	ds_add_rtn_u32 v182, v182, v220 offset:96
	ds_add_rtn_u32 v183, v183, v220 offset:96
	ds_add_rtn_u32 v184, v184, v220 offset:128
	ds_add_rtn_u32 v185, v185, v220 offset:128
	ds_add_rtn_u32 v186, v186, v220 offset:160
	ds_add_rtn_u32 v187, v187, v220 offset:160
	ds_add_rtn_u32 v188, v188, v220 offset:192
	ds_add_rtn_u32 v189, v189, v220 offset:192
	ds_add_rtn_u32 v190, v190, v220 offset:224
	ds_add_rtn_u32 v191, v191, v220 offset:224
	v_lshl_add_u32 v207, v201, 5, s3
	ds_read_b32 v203, v221 offset:4224
	ds_read_b128 v[192:195], v207
	ds_read_b128 v[196:199], v207 offset:16
	v_mov_b32_e32 v202, 0
	s_waitcnt lgkmcnt(0)
	v_cmp_lt_u32_e64 s[38:39], 0, v200
	v_cmp_lt_u32_e64 s[40:41], 1, v200
	v_cmp_lt_u32_e64 s[42:43], 2, v200
	v_cmp_lt_u32_e64 s[44:45], 3, v200
	v_cmp_lt_u32_e64 s[64:65], 4, v200
	v_cmp_lt_u32_e64 s[66:67], 5, v200
	v_cmp_lt_u32_e64 s[94:95], 6, v200
	v_cndmask_b32_e64 v206, 0, v192, s[38:39]
	v_add_u32_e32 v202, v202, v206
	v_cndmask_b32_e64 v206, 0, v193, s[40:41]
	v_add_u32_e32 v202, v202, v206
	v_cndmask_b32_e64 v206, 0, v194, s[42:43]
	v_add_u32_e32 v202, v202, v206
	v_cndmask_b32_e64 v206, 0, v195, s[44:45]
	v_add_u32_e32 v202, v202, v206
	v_cndmask_b32_e64 v206, 0, v196, s[64:65]
	v_add_u32_e32 v202, v202, v206
	v_cndmask_b32_e64 v206, 0, v197, s[66:67]
	v_add_u32_e32 v202, v202, v206
	v_cndmask_b32_e64 v206, 0, v198, s[94:95]
	v_add_u32_e32 v202, v202, v206
	v_add_u32_e32 v204, 3, v202
	v_add3_u32 v212, v202, v203, 3
	v_lshrrev_b32_e32 v204, 2, v204
	v_lshrrev_b32_e32 v212, 2, v212
	v_sub_u32_e32 v212, v212, v204
	v_lshl_add_u32 v207, v200, 3, v201
	v_lshl_add_u32 v207, v207, 2, s3
	ds_write_b32 v207, v212 offset:256
	v_lshl_add_u32 v208, v200, 5, s3
	ds_read_b128 v[192:195], v208 offset:256
	ds_read_b128 v[196:199], v208 offset:272
	v_mov_b32_e32 v205, 0
	s_waitcnt lgkmcnt(0)
	v_cmp_lt_u32_e64 s[38:39], 0, v201
	v_cmp_lt_u32_e64 s[40:41], 1, v201
	v_cmp_lt_u32_e64 s[42:43], 2, v201
	v_cmp_lt_u32_e64 s[44:45], 3, v201
	v_cmp_lt_u32_e64 s[64:65], 4, v201
	v_cmp_lt_u32_e64 s[66:67], 5, v201
	v_cmp_lt_u32_e64 s[94:95], 6, v201
	v_cndmask_b32_e64 v206, 0, v192, s[38:39]
	v_add_u32_e32 v205, v205, v206
	v_cndmask_b32_e64 v206, 0, v193, s[40:41]
	v_add_u32_e32 v205, v205, v206
	v_cndmask_b32_e64 v206, 0, v194, s[42:43]
	v_add_u32_e32 v205, v205, v206
	v_cndmask_b32_e64 v206, 0, v195, s[44:45]
	v_add_u32_e32 v205, v205, v206
	v_cndmask_b32_e64 v206, 0, v196, s[64:65]
	v_add_u32_e32 v205, v205, v206
	v_cndmask_b32_e64 v206, 0, v197, s[66:67]
	v_add_u32_e32 v205, v205, v206
	v_cndmask_b32_e64 v206, 0, v198, s[94:95]
	v_add_u32_e32 v205, v205, v206
	v_add_u32_e32 v206, v192, v193
	v_add_u32_e32 v206, v206, v194
	v_add_u32_e32 v206, v206, v195
	v_add_u32_e32 v206, v206, v196
	v_add_u32_e32 v206, v206, v197
	v_add_u32_e32 v206, v206, v198
	v_add_u32_e32 v206, v206, v199
	v_lshl_add_u32 v207, v200, 2, s3
	ds_write_b32 v207, v206 offset:512
	v_mov_b32_e32 v207, s3
	ds_read_b128 v[192:195], v207 offset:512
	ds_read_b128 v[196:199], v207 offset:528
	ds_write_b32 v221, v202 offset:4224
	s_waitcnt lgkmcnt(0)
; __device__ __forceinline__ void peer_tile(const Args& A, LAS unsigned char* lds, int tile) {
;     ...
;     for (int ti = 0; ti < 8; ++ti) {
;         const int tl = 8 * w + ti;
;         const u32x2 e0 = SEL[tl * 128 + lane], e1 = SEL[tl * 128 + 64 + lane];
;         const int p0 = (int)(e0.x >> 10), p1 = (int)(e1.x >> 10);
;         int off = 0;
;         for (int p = 0; p < 16; ++p) {
;             const unsigned long long m0 = __ballot(p0 == p), m1 = __ballot(p1 == p);
;             const int c0 = __popcll(m0), c1 = __popcll(m1);
;             const int r0 = __builtin_amdgcn_mbcnt_hi((unsigned)(m0 >> 32), __builtin_amdgcn_mbcnt_lo((unsigned)m0, 0u));
;             const int r1 = __builtin_amdgcn_mbcnt_hi((unsigned)(m1 >> 32), __builtin_amdgcn_mbcnt_lo((unsigned)m1, 0u));
;             if (p0 == p) SORT[tl * 128 + off + r0] = e0;
;             if (p1 == p) SORT[tl * 128 + off + c0 + r1] = e1;
;             if (lane == 0) OFFS[tl * 17 + p] = off;
;             off += c0 + c1;
;         }
;         if (lane == 0) OFFS[tl * 17 + 16] = off;
;     }
	v_cmp_lt_u32_e64 s[38:39], 0, v200
	v_cmp_lt_u32_e64 s[40:41], 1, v200
	v_cmp_lt_u32_e64 s[42:43], 2, v200
	v_cmp_lt_u32_e64 s[44:45], 3, v200
	v_cmp_lt_u32_e64 s[64:65], 4, v200
	v_cmp_lt_u32_e64 s[66:67], 5, v200
	v_cmp_lt_u32_e64 s[94:95], 6, v200
	v_cndmask_b32_e64 v206, 0, v192, s[38:39]
	v_add_u32_e32 v205, v205, v206
	v_cndmask_b32_e64 v206, 0, v193, s[40:41]
	v_add_u32_e32 v205, v205, v206
	v_cndmask_b32_e64 v206, 0, v194, s[42:43]
	v_add_u32_e32 v205, v205, v206
	v_cndmask_b32_e64 v206, 0, v195, s[44:45]
	v_add_u32_e32 v205, v205, v206
	v_cndmask_b32_e64 v206, 0, v196, s[64:65]
	v_add_u32_e32 v205, v205, v206
	v_cndmask_b32_e64 v206, 0, v197, s[66:67]
	v_add_u32_e32 v205, v205, v206
	v_cndmask_b32_e64 v206, 0, v198, s[94:95]
	v_add_u32_e32 v205, v205, v206
	v_sub_u32_e32 v205, v205, v204
	v_lshrrev_b32_e32 v208, 4, v240
	v_and_b32_e32 v222, 31, v208
	v_lshrrev_b32_e32 v208, 5, v208
	v_add_u32_e32 v207, 0, v208
	v_lshl_add_u32 v206, v207, 5, s3
	ds_read_b128 v[192:195], v206
	ds_read_b128 v[196:199], v206 offset:16
	v_lshlrev_b32_e32 v206, 2, v222
	v_lshlrev_b32_e32 v223, 3, v207
	s_waitcnt lgkmcnt(0)
	v_cmp_le_u32_e64 s[38:39], v193, v206
	v_cmp_le_u32_e64 s[40:41], v194, v206
	v_cmp_le_u32_e64 s[42:43], v195, v206
	v_cmp_le_u32_e64 s[44:45], v196, v206
	v_cmp_le_u32_e64 s[64:65], v197, v206
	v_cmp_le_u32_e64 s[66:67], v198, v206
	v_cmp_le_u32_e64 s[94:95], v199, v206
	v_addc_co_u32_e64 v223, s[92:93], 0, v223, s[38:39]
	v_addc_co_u32_e64 v223, s[92:93], 0, v223, s[40:41]
	v_addc_co_u32_e64 v223, s[92:93], 0, v223, s[42:43]
	v_addc_co_u32_e64 v223, s[92:93], 0, v223, s[44:45]
	v_addc_co_u32_e64 v223, s[92:93], 0, v223, s[64:65]
	v_addc_co_u32_e64 v223, s[92:93], 0, v223, s[66:67]
	v_addc_co_u32_e64 v223, s[92:93], 0, v223, s[94:95]
	v_lshlrev_b32_e32 v223, 2, v223
	ds_bpermute_b32 v216, v223, v205
	v_add_u32_e32 v207, 2, v208
	v_lshl_add_u32 v206, v207, 5, s3
	ds_read_b128 v[192:195], v206
	ds_read_b128 v[196:199], v206 offset:16
	v_lshlrev_b32_e32 v206, 2, v222
	v_lshlrev_b32_e32 v223, 3, v207
	s_waitcnt lgkmcnt(0)
	v_cmp_le_u32_e64 s[38:39], v193, v206
	v_cmp_le_u32_e64 s[40:41], v194, v206
	v_cmp_le_u32_e64 s[42:43], v195, v206
	v_cmp_le_u32_e64 s[44:45], v196, v206
	v_cmp_le_u32_e64 s[64:65], v197, v206
	v_cmp_le_u32_e64 s[66:67], v198, v206
	v_cmp_le_u32_e64 s[94:95], v199, v206
	v_addc_co_u32_e64 v223, s[92:93], 0, v223, s[38:39]
	v_addc_co_u32_e64 v223, s[92:93], 0, v223, s[40:41]
	v_addc_co_u32_e64 v223, s[92:93], 0, v223, s[42:43]
	v_addc_co_u32_e64 v223, s[92:93], 0, v223, s[44:45]
	v_addc_co_u32_e64 v223, s[92:93], 0, v223, s[64:65]
	v_addc_co_u32_e64 v223, s[92:93], 0, v223, s[66:67]
	v_addc_co_u32_e64 v223, s[92:93], 0, v223, s[94:95]
	v_lshlrev_b32_e32 v223, 2, v223
	ds_bpermute_b32 v217, v223, v205
	v_add_u32_e32 v207, 4, v208
	v_lshl_add_u32 v206, v207, 5, s3
	ds_read_b128 v[192:195], v206
	ds_read_b128 v[196:199], v206 offset:16
	v_lshlrev_b32_e32 v206, 2, v222
	v_lshlrev_b32_e32 v223, 3, v207
	s_waitcnt lgkmcnt(0)
	v_cmp_le_u32_e64 s[38:39], v193, v206
	v_cmp_le_u32_e64 s[40:41], v194, v206
	v_cmp_le_u32_e64 s[42:43], v195, v206
	v_cmp_le_u32_e64 s[44:45], v196, v206
	v_cmp_le_u32_e64 s[64:65], v197, v206
	v_cmp_le_u32_e64 s[66:67], v198, v206
	v_cmp_le_u32_e64 s[94:95], v199, v206
	v_addc_co_u32_e64 v223, s[92:93], 0, v223, s[38:39]
	v_addc_co_u32_e64 v223, s[92:93], 0, v223, s[40:41]
	v_addc_co_u32_e64 v223, s[92:93], 0, v223, s[42:43]
	v_addc_co_u32_e64 v223, s[92:93], 0, v223, s[44:45]
	v_addc_co_u32_e64 v223, s[92:93], 0, v223, s[64:65]
	v_addc_co_u32_e64 v223, s[92:93], 0, v223, s[66:67]
	v_addc_co_u32_e64 v223, s[92:93], 0, v223, s[94:95]
	v_lshlrev_b32_e32 v223, 2, v223
	ds_bpermute_b32 v218, v223, v205
	v_add_u32_e32 v207, 6, v208
	v_lshl_add_u32 v206, v207, 5, s3
	ds_read_b128 v[192:195], v206
	ds_read_b128 v[196:199], v206 offset:16
	v_lshlrev_b32_e32 v206, 2, v222
	v_lshlrev_b32_e32 v223, 3, v207
	s_waitcnt lgkmcnt(0)
	v_cmp_le_u32_e64 s[38:39], v193, v206
	v_cmp_le_u32_e64 s[40:41], v194, v206
	v_cmp_le_u32_e64 s[42:43], v195, v206
	v_cmp_le_u32_e64 s[44:45], v196, v206
	v_cmp_le_u32_e64 s[64:65], v197, v206
	v_cmp_le_u32_e64 s[66:67], v198, v206
	v_cmp_le_u32_e64 s[94:95], v199, v206
	v_addc_co_u32_e64 v223, s[92:93], 0, v223, s[38:39]
	v_addc_co_u32_e64 v223, s[92:93], 0, v223, s[40:41]
	v_addc_co_u32_e64 v223, s[92:93], 0, v223, s[42:43]
	v_addc_co_u32_e64 v223, s[92:93], 0, v223, s[44:45]
	v_addc_co_u32_e64 v223, s[92:93], 0, v223, s[64:65]
	v_addc_co_u32_e64 v223, s[92:93], 0, v223, s[66:67]
	v_addc_co_u32_e64 v223, s[92:93], 0, v223, s[94:95]
	v_lshlrev_b32_e32 v223, 2, v223
	ds_bpermute_b32 v219, v223, v205
	s_waitcnt lgkmcnt(0)
	v_add_u32_e32 v216, v216, v222
	v_add_u32_e32 v217, v217, v222
	v_add_u32_e32 v218, v218, v222
	v_add_u32_e32 v219, v219, v222
	v_lshlrev_b32_e32 v160, 2, v160
	ds_bpermute_b32 v160, v160, v202
	v_lshlrev_b32_e32 v161, 2, v161
	ds_bpermute_b32 v161, v161, v202
	v_lshlrev_b32_e32 v162, 2, v162
	v_add_u32_e32 v162, 32, v162
	ds_bpermute_b32 v162, v162, v202
	v_lshlrev_b32_e32 v163, 2, v163
	v_add_u32_e32 v163, 32, v163
	ds_bpermute_b32 v163, v163, v202
	v_lshlrev_b32_e32 v164, 2, v164
	v_add_u32_e32 v164, 64, v164
	ds_bpermute_b32 v164, v164, v202
	v_lshlrev_b32_e32 v165, 2, v165
	v_add_u32_e32 v165, 64, v165
	ds_bpermute_b32 v165, v165, v202
	v_lshlrev_b32_e32 v166, 2, v166
	v_add_u32_e32 v166, 96, v166
	ds_bpermute_b32 v166, v166, v202
	v_lshlrev_b32_e32 v167, 2, v167
	v_add_u32_e32 v167, 96, v167
	ds_bpermute_b32 v167, v167, v202
	v_lshlrev_b32_e32 v168, 2, v168
	v_add_u32_e32 v168, 128, v168
	ds_bpermute_b32 v168, v168, v202
	v_lshlrev_b32_e32 v169, 2, v169
	v_add_u32_e32 v169, 128, v169
	ds_bpermute_b32 v169, v169, v202
	v_lshlrev_b32_e32 v170, 2, v170
	v_add_u32_e32 v170, 160, v170
	ds_bpermute_b32 v170, v170, v202
	v_lshlrev_b32_e32 v171, 2, v171
	v_add_u32_e32 v171, 160, v171
	ds_bpermute_b32 v171, v171, v202
	v_lshlrev_b32_e32 v172, 2, v172
	v_add_u32_e32 v172, 192, v172
	ds_bpermute_b32 v172, v172, v202
	v_lshlrev_b32_e32 v173, 2, v173
	v_add_u32_e32 v173, 192, v173
	ds_bpermute_b32 v173, v173, v202
	v_lshlrev_b32_e32 v174, 2, v174
	v_add_u32_e32 v174, 224, v174
	ds_bpermute_b32 v174, v174, v202
	v_lshlrev_b32_e32 v175, 2, v175
	v_add_u32_e32 v175, 224, v175
	ds_bpermute_b32 v175, v175, v202
	s_waitcnt lgkmcnt(0)
; __device__ __forceinline__ void peer_tile(const Args& A, LAS unsigned char* lds, int tile) {
;     ...
;             if (p0 == p) SORT[tl * 128 + off + r0] = e0;
;             if (p1 == p) SORT[tl * 128 + off + c0 + r1] = e1;
;             if (lane == 0) OFFS[tl * 17 + p] = off;
;             off += c0 + c1;
;         }
;         if (lane == 0) OFFS[tl * 17 + 16] = off;
;     }
	v_add_u32_e32 v176, v176, v160
	v_lshrrev_b32_e32 v160, 2, v176
	v_and_b32_e32 v176, 3, v176
	v_lshlrev_b32_e32 v160, 2, v160
	ds_bpermute_b32 v160, v160, v216
	v_add_u32_e32 v177, v177, v161
	v_lshrrev_b32_e32 v161, 2, v177
	v_and_b32_e32 v177, 3, v177
	v_lshlrev_b32_e32 v161, 2, v161
	ds_bpermute_b32 v161, v161, v216
	v_add_u32_e32 v178, v178, v162
	v_lshrrev_b32_e32 v162, 2, v178
	v_and_b32_e32 v178, 3, v178
	v_lshlrev_b32_e32 v162, 2, v162
	v_add_u32_e32 v162, 128, v162
	ds_bpermute_b32 v162, v162, v216
	v_add_u32_e32 v179, v179, v163
	v_lshrrev_b32_e32 v163, 2, v179
	v_and_b32_e32 v179, 3, v179
	v_lshlrev_b32_e32 v163, 2, v163
	v_add_u32_e32 v163, 128, v163
	ds_bpermute_b32 v163, v163, v216
	v_add_u32_e32 v180, v180, v164
	v_lshrrev_b32_e32 v164, 2, v180
	v_and_b32_e32 v180, 3, v180
	v_lshlrev_b32_e32 v164, 2, v164
	ds_bpermute_b32 v164, v164, v217
	v_add_u32_e32 v181, v181, v165
	v_lshrrev_b32_e32 v165, 2, v181
	v_and_b32_e32 v181, 3, v181
	v_lshlrev_b32_e32 v165, 2, v165
	ds_bpermute_b32 v165, v165, v217
	v_add_u32_e32 v182, v182, v166
	v_lshrrev_b32_e32 v166, 2, v182
	v_and_b32_e32 v182, 3, v182
	v_lshlrev_b32_e32 v166, 2, v166
	v_add_u32_e32 v166, 128, v166
	ds_bpermute_b32 v166, v166, v217
	v_add_u32_e32 v183, v183, v167
	v_lshrrev_b32_e32 v167, 2, v183
	v_and_b32_e32 v183, 3, v183
	v_lshlrev_b32_e32 v167, 2, v167
	v_add_u32_e32 v167, 128, v167
	ds_bpermute_b32 v167, v167, v217
	v_add_u32_e32 v184, v184, v168
	v_lshrrev_b32_e32 v168, 2, v184
	v_and_b32_e32 v184, 3, v184
	v_lshlrev_b32_e32 v168, 2, v168
	ds_bpermute_b32 v168, v168, v218
	v_add_u32_e32 v185, v185, v169
	v_lshrrev_b32_e32 v169, 2, v185
	v_and_b32_e32 v185, 3, v185
	v_lshlrev_b32_e32 v169, 2, v169
	ds_bpermute_b32 v169, v169, v218
	v_add_u32_e32 v186, v186, v170
	v_lshrrev_b32_e32 v170, 2, v186
	v_and_b32_e32 v186, 3, v186
	v_lshlrev_b32_e32 v170, 2, v170
	v_add_u32_e32 v170, 128, v170
	ds_bpermute_b32 v170, v170, v218
	v_add_u32_e32 v187, v187, v171
	v_lshrrev_b32_e32 v171, 2, v187
	v_and_b32_e32 v187, 3, v187
	v_lshlrev_b32_e32 v171, 2, v171
	v_add_u32_e32 v171, 128, v171
	ds_bpermute_b32 v171, v171, v218
	v_add_u32_e32 v188, v188, v172
	v_lshrrev_b32_e32 v172, 2, v188
	v_and_b32_e32 v188, 3, v188
	v_lshlrev_b32_e32 v172, 2, v172
	ds_bpermute_b32 v172, v172, v219
	v_add_u32_e32 v189, v189, v173
	v_lshrrev_b32_e32 v173, 2, v189
	v_and_b32_e32 v189, 3, v189
	v_lshlrev_b32_e32 v173, 2, v173
	ds_bpermute_b32 v173, v173, v219
	v_add_u32_e32 v190, v190, v174
	v_lshrrev_b32_e32 v174, 2, v190
	v_and_b32_e32 v190, 3, v190
	v_lshlrev_b32_e32 v174, 2, v174
	v_add_u32_e32 v174, 128, v174
	ds_bpermute_b32 v174, v174, v219
	v_add_u32_e32 v191, v191, v175
	v_lshrrev_b32_e32 v175, 2, v191
	v_and_b32_e32 v191, 3, v191
	v_lshlrev_b32_e32 v175, 2, v175
	v_add_u32_e32 v175, 128, v175
	ds_bpermute_b32 v175, v175, v219
	s_waitcnt lgkmcnt(0)
; #define IT_ADVANCE() do { it_j += 4; while (it_j >= it_end) { if (it_done) break; ++it_tk; if (it_tk == 4) { it_tk = 0; ++it_p; if (it_p == 16) { it_done = true; it_p = 15; it_j = 0; it_end = 1; break; } } \
;             it_j = __builtin_amdgcn_readfirstlane(OFFS[(tb + it_tk) * 17 + it_p]); it_end = __builtin_amdgcn_readfirstlane(OFFS[(tb + it_tk) * 17 + it_p + 1]); } } while (0)
; __device__ __forceinline__ void peer_tile(const Args& A, LAS unsigned char* lds, int tile) {
;     ...
;             if (p0 == p) SORT[tl * 128 + off + r0] = e0;
;             if (p1 == p) SORT[tl * 128 + off + c0 + r1] = e1;
;             if (lane == 0) OFFS[tl * 17 + p] = off;
;             off += c0 + c1;
;         }
;         if (lane == 0) OFFS[tl * 17 + 16] = off;
;     }
;     ...
;         int it_p = 0, it_tk = -1, it_j = 0, it_end = 0; bool it_done = false;
;     ...
;         u32x4 uA[4], vA[4], uB[4], vB[4]; float cgA = 0.f, suA = 0.f, svA = 0.f, cgB = 0.f, suB = 0.f, svB = 0.f;
; #pragma unroll
;         for (int k = 0; k < 4; ++k) { uA[k] = (u32x4){0u, 0u, 0u, 0u}; vA[k] = uA[k]; uB[k] = uA[k]; vB[k] = uA[k]; }
;         IT_ADVANCE();
;         LOAD_SET(uA, vA, cgA, suA, svA);
	v_lshl_add_u32 v160, v160, 4, s22
	v_lshl_add_u32 v160, v176, 2, v160
	ds_write_b32 v160, v128
	ds_write_b32 v160, v129 offset:4992
	v_lshl_add_u32 v161, v161, 4, s22
	v_lshl_add_u32 v161, v177, 2, v161
	ds_write_b32 v161, v130
	ds_write_b32 v161, v131 offset:4992
	v_lshl_add_u32 v162, v162, 4, s22
	v_lshl_add_u32 v162, v178, 2, v162
	ds_write_b32 v162, v132
	ds_write_b32 v162, v133 offset:4992
	v_lshl_add_u32 v163, v163, 4, s22
	v_lshl_add_u32 v163, v179, 2, v163
	ds_write_b32 v163, v134
	ds_write_b32 v163, v135 offset:4992
	v_lshl_add_u32 v164, v164, 4, s22
	v_lshl_add_u32 v164, v180, 2, v164
	ds_write_b32 v164, v136
	ds_write_b32 v164, v137 offset:4992
	v_lshl_add_u32 v165, v165, 4, s22
	v_lshl_add_u32 v165, v181, 2, v165
	ds_write_b32 v165, v138
	ds_write_b32 v165, v139 offset:4992
	v_lshl_add_u32 v166, v166, 4, s22
	v_lshl_add_u32 v166, v182, 2, v166
	ds_write_b32 v166, v140
	ds_write_b32 v166, v141 offset:4992
	v_lshl_add_u32 v167, v167, 4, s22
	v_lshl_add_u32 v167, v183, 2, v167
	ds_write_b32 v167, v142
	ds_write_b32 v167, v143 offset:4992
	v_lshl_add_u32 v168, v168, 4, s22
	v_lshl_add_u32 v168, v184, 2, v168
	ds_write_b32 v168, v144
	ds_write_b32 v168, v145 offset:4992
	v_lshl_add_u32 v169, v169, 4, s22
	v_lshl_add_u32 v169, v185, 2, v169
	ds_write_b32 v169, v146
	ds_write_b32 v169, v147 offset:4992
	v_lshl_add_u32 v170, v170, 4, s22
	v_lshl_add_u32 v170, v186, 2, v170
	ds_write_b32 v170, v148
	ds_write_b32 v170, v149 offset:4992
	v_lshl_add_u32 v171, v171, 4, s22
	v_lshl_add_u32 v171, v187, 2, v171
	ds_write_b32 v171, v150
	ds_write_b32 v171, v151 offset:4992
	v_lshl_add_u32 v172, v172, 4, s22
	v_lshl_add_u32 v172, v188, 2, v172
	ds_write_b32 v172, v152
	ds_write_b32 v172, v153 offset:4992
	v_lshl_add_u32 v173, v173, 4, s22
	v_lshl_add_u32 v173, v189, 2, v173
	ds_write_b32 v173, v154
	ds_write_b32 v173, v155 offset:4992
	v_lshl_add_u32 v174, v174, 4, s22
	v_lshl_add_u32 v174, v190, 2, v174
	ds_write_b32 v174, v156
	ds_write_b32 v174, v157 offset:4992
	v_lshl_add_u32 v175, v175, 4, s22
	v_lshl_add_u32 v175, v191, 2, v175
	ds_write_b32 v175, v158
	ds_write_b32 v175, v159 offset:4992
	v_mov_b32_e32 v206, 0x7fffffff
	ds_write_b32 v221, v206 offset:4224
	ds_write_b32 v221, v206 offset:4480
	ds_write_b32 v221, v206 offset:4736
	s_mov_b32 s91, 256
	s_add_i32 s20, s91, 3
	s_and_b32 s20, s20, -4
	s_mov_b32 s24, s8
	s_and_b32 s25, s9, 0xffff
	s_mov_b32 s26, 0x10000
	s_mov_b32 s27, 0x00027000
	s_mov_b32 s28, s52
	s_and_b32 s29, s53, 0xffff
	s_mov_b32 s30, 0x10000
	s_mov_b32 s31, 0x00027000
	s_waitcnt vmcnt(0) lgkmcnt(0)
	v_mov_b32_e32 v213, s22
	v_mov_b32_e32 v233, v240
	v_mov_b32_e32 v235, v240
	v_mov_b32_e32 v237, v240
	v_mov_b32_e32 v239, v240
	ds_read_b32 v232, v213 offset:0
	ds_read_b32 v234, v213 offset:4
	ds_read_b32 v236, v213 offset:8
	ds_read_b32 v238, v213 offset:12
	s_waitcnt lgkmcnt(0)
	buffer_load_dwordx4 v[128:131], v[232:233], s[56:59], 0 idxen offen
	buffer_load_dwordx4 v[132:135], v[234:235], s[56:59], 0 idxen offen
	buffer_load_dwordx4 v[136:139], v[236:237], s[56:59], 0 idxen offen
	buffer_load_dwordx4 v[140:143], v[238:239], s[56:59], 0 idxen offen
	ds_read_b32 v232, v213 offset:16
	ds_read_b32 v234, v213 offset:20
	ds_read_b32 v236, v213 offset:24
	ds_read_b32 v238, v213 offset:28
	s_waitcnt lgkmcnt(0)
	buffer_load_dwordx4 v[144:147], v[232:233], s[56:59], 0 idxen offen
	buffer_load_dwordx4 v[148:151], v[234:235], s[56:59], 0 idxen offen
	buffer_load_dwordx4 v[152:155], v[236:237], s[56:59], 0 idxen offen
	buffer_load_dwordx4 v[156:159], v[238:239], s[56:59], 0 idxen offen
	ds_read_b32 v232, v213 offset:32
	ds_read_b32 v234, v213 offset:36
	ds_read_b32 v236, v213 offset:40
	ds_read_b32 v238, v213 offset:44
	s_waitcnt lgkmcnt(0)
	buffer_load_dwordx4 v[160:163], v[232:233], s[56:59], 0 idxen offen
	buffer_load_dwordx4 v[164:167], v[234:235], s[56:59], 0 idxen offen
	buffer_load_dwordx4 v[168:171], v[236:237], s[56:59], 0 idxen offen
	buffer_load_dwordx4 v[172:175], v[238:239], s[56:59], 0 idxen offen
	ds_read_b32 v232, v213 offset:48
	ds_read_b32 v234, v213 offset:52
	ds_read_b32 v236, v213 offset:56
	ds_read_b32 v238, v213 offset:60
	s_mov_b32 s21, 0
	s_mov_b32 s89, -1
	s_mov_b32 s86, 0
	v_lshrrev_b32_e32 v208, 6, v240
	v_and_b32_e32 v208, 3, v208
	v_lshrrev_b32_e32 v209, 1, v208
	v_lshlrev_b32_e32 v208, 1, v208
	v_and_b32_e32 v208, 2, v208
	v_or_b32_e32 v208, v208, v209
	v_lshlrev_b32_e32 v208, 2, v208
	v_add3_u32 v211, v208, v247, s22
	ds_read_b32 v248, v211
	ds_read_b32 v249, v211 offset:4992
	s_branch .LU_sw0
